# v66 + LRU passes: sigmoid (acc+bias)*-log2e folded into one fma with prescaled bias, log2e folded into k8 decay scale (f32, same ops)
# speedup vs baseline: 1.0048x; 1.0023x over previous
; __device__ __forceinline__ void lru_conv_tile(const Args& a, LAS bf16_t* cxb, int l, const Tile& T) {
;     ...
;     for (int i = 0; i < 11; ++i) {
;         const int tg = T.t0 + grp * 8 + i - 2;
;         u32x4 rv = raw[i]; if (!(tg >= 0 && tg < T.seqlen)) rv = (u32x4){0u, 0u, 0u, 0u};
; template <int MODE>
; __device__ __forceinline__ void lru_unit(const Args& a, LAS unsigned char* lds, int l, int tt) {
;     ...
;     for (int nt = 0; nt < 2; ++nt) { prm0[nt][2] = -8.0f * log1pf(__expf(-prm0[nt][2])); prm1[nt][2] = -8.0f * log1pf(__expf(-prm1[nt][2])); }
;     __syncthreads();
.LBB0_545:
	s_nop 1
	s_or_b64 exec, exec, s[4:5]
	s_waitcnt vmcnt(0)
	v_add_u32_e32 v146, 1, v158
	v_cmp_lt_i32_e32 vcc, 1, v146
	v_add_u32_e32 v146, -1, v158
	v_cmp_gt_u32_e64 s[0:1], s34, v146
	s_and_b64 vcc, vcc, s[0:1]
	v_add_u32_e32 v144, 2, v158
	s_nop 3
	v_cmp_lt_i32_e32 vcc, 1, v144
	v_cmp_ge_i32_e64 s[0:1], s34, v144
	s_and_b64 vcc, vcc, s[0:1]
	v_or_b32_e32 v190, 3, v160
	s_nop 0
	v_add_u32_e32 v136, s72, v190
	s_nop 2
	v_cmp_lt_i32_e32 vcc, 1, v136
	v_add_u32_e32 v136, -2, v136
	v_cmp_gt_u32_e64 s[0:1], s34, v136
	s_and_b64 vcc, vcc, s[0:1]
	v_add_u32_e32 v66, 4, v158
	s_nop 4
	v_cmp_lt_i32_e32 vcc, 1, v66
	v_cmp_ge_i32_e64 s[0:1], s34, v66
	s_and_b64 vcc, vcc, s[0:1]
	v_add_u32_e32 v74, 5, v158
	s_nop 4
	v_cmp_lt_i32_e32 vcc, 1, v74
	v_add_u32_e32 v74, 3, v158
	v_cmp_gt_u32_e64 s[0:1], s34, v74
	s_and_b64 vcc, vcc, s[0:1]
	v_add_u32_e32 v126, 6, v158
	s_nop 4
	v_cmp_lt_i32_e32 vcc, 1, v126
	v_cmp_ge_i32_e64 s[0:1], s34, v126
	s_and_b64 vcc, vcc, s[0:1]
	v_or_b32_e32 v159, 7, v159
	s_nop 0
	v_add_u32_e32 v122, s72, v159
	s_nop 2
	v_cmp_lt_i32_e32 vcc, 1, v122
	v_add_u32_e32 v122, -2, v122
	v_cmp_gt_u32_e64 s[0:1], s34, v122
	s_and_b64 vcc, vcc, s[0:1]
	s_nop 4
	s_movk_i32 s0, 0xf9d0
	v_add_u32_e32 v66, 8, v158
	v_cmp_lt_i32_e32 vcc, 1, v66
	s_nop 3
	v_cmp_ge_i32_e64 s[0:1], s34, v66
	s_and_b64 vcc, vcc, s[0:1]
	v_add_u32_e32 v74, 9, v158
	s_nop 4
	v_cmp_lt_i32_e32 vcc, 1, v74
	v_add_u32_e32 v74, 7, v158
	s_nop 1
	v_cmp_gt_u32_e64 s[0:1], s34, v74
	s_nop 1
	s_and_b64 vcc, vcc, s[0:1]
	v_add_u32_e32 v110, 10, v158
	s_nop 4
	v_cmp_lt_i32_e32 vcc, 1, v110
	v_cmp_ge_i32_e64 s[0:1], s34, v110
	s_and_b64 vcc, vcc, s[0:1]
	v_mul_f32_e32 v72, 0xbfb8aa3b, v157
	s_nop 2
	v_exp_f32_e32 v72, v72
	s_nop 5
	v_add_f32_e32 v68, 1.0, v72
	v_add_f32_e32 v66, -1.0, v68
	v_sub_f32_e32 v67, v66, v68
	v_add_f32_e32 v67, 1.0, v67
	v_sub_f32_e32 v66, v72, v66
	v_add_f32_e32 v69, v66, v67
	v_frexp_mant_f32_e32 v70, v68
	v_cvt_f64_f32_e32 v[66:67], v68
	s_mov_b32 s0, 0x3f2aaaab
	v_frexp_exp_i32_f64_e32 v66, v[66:67]
	v_cmp_gt_f32_e32 vcc, s0, v70
	s_mov_b32 s5, 0x3f317218
	v_mov_b32_e32 v85, 0x3ecc95a3
	v_subbrev_co_u32_e32 v66, vcc, 0, v66, vcc
	v_sub_u32_e32 v67, 0, v66
	v_ldexp_f32 v68, v68, v67
	v_ldexp_f32 v67, v69, v67
	v_add_f32_e32 v69, -1.0, v68
	v_add_f32_e32 v73, 1.0, v68
	v_add_f32_e32 v70, 1.0, v69
	v_add_f32_e32 v74, -1.0, v73
	v_sub_f32_e32 v70, v68, v70
	v_sub_f32_e32 v68, v68, v74
	v_add_f32_e32 v70, v67, v70
	v_add_f32_e32 v67, v67, v68
	v_add_f32_e32 v68, v73, v67
	v_rcp_f32_e32 v74, v68
	v_add_f32_e32 v71, v69, v70
	v_sub_f32_e32 v69, v71, v69
	v_sub_f32_e32 v69, v70, v69
	v_sub_f32_e32 v70, v68, v73
	v_sub_f32_e32 v67, v67, v70
	v_mul_f32_e32 v70, v71, v74
	v_mul_f32_e32 v73, v68, v70
	v_fma_f32 v75, v70, v68, -v73
	v_fmac_f32_e32 v75, v70, v67
	v_add_f32_e32 v76, v73, v75
	v_sub_f32_e32 v77, v71, v76
	v_sub_f32_e32 v71, v71, v77
	v_sub_f32_e32 v73, v76, v73
	v_sub_f32_e32 v71, v71, v76
	v_add_f32_e32 v69, v69, v71
	v_sub_f32_e32 v71, v73, v75
	v_add_f32_e32 v69, v71, v69
	v_add_f32_e32 v71, v77, v69
	v_mul_f32_e32 v73, v74, v71
	v_mul_f32_e32 v75, v68, v73
	v_fma_f32 v68, v73, v68, -v75
	v_fmac_f32_e32 v68, v73, v67
	v_sub_f32_e32 v67, v77, v71
	v_add_f32_e32 v67, v69, v67
	v_add_f32_e32 v69, v75, v68
	v_sub_f32_e32 v76, v71, v69
	v_sub_f32_e32 v71, v71, v76
	v_sub_f32_e32 v75, v69, v75
	v_sub_f32_e32 v69, v71, v69
	v_add_f32_e32 v67, v67, v69
	v_sub_f32_e32 v68, v75, v68
	v_cvt_f32_i32_e32 v66, v66
	v_add_f32_e32 v67, v68, v67
	v_add_f32_e32 v68, v70, v73
	v_add_f32_e32 v67, v76, v67
	v_sub_f32_e32 v69, v68, v70
	v_mul_f32_e32 v67, v74, v67
	v_sub_f32_e32 v69, v73, v69
	v_add_f32_e32 v67, v69, v67
	v_mul_f32_e32 v73, 0x3f317218, v66
	v_add_f32_e32 v69, v68, v67
	v_fma_f32 v74, v66, s5, -v73
	v_mul_f32_e32 v70, v69, v69
	v_fmac_f32_e32 v74, 0xb102e308, v66
	v_sub_f32_e32 v66, v69, v68
	v_fmamk_f32 v71, v70, 0x3e9b6dac, v85
	v_sub_f32_e32 v66, v67, v66
	v_add_f32_e32 v67, v73, v74
	v_fmaak_f32 v71, v70, v71, 0x3f2aaada
	v_sub_f32_e32 v68, v67, v73
	v_ldexp_f32 v73, v69, 1
	v_mul_f32_e32 v69, v69, v70
	v_mul_f32_e32 v69, v69, v71
	v_add_f32_e32 v70, v73, v69
	v_sub_f32_e32 v71, v70, v73
	v_ldexp_f32 v66, v66, 1
	v_sub_f32_e32 v69, v69, v71
	v_add_f32_e32 v66, v66, v69
	v_add_f32_e32 v69, v70, v66
	v_sub_f32_e32 v70, v69, v70
	v_sub_f32_e32 v66, v66, v70
	v_add_f32_e32 v70, v67, v69
	v_sub_f32_e32 v71, v70, v67
	v_sub_f32_e32 v73, v70, v71
	v_sub_f32_e32 v68, v74, v68
	v_sub_f32_e32 v67, v67, v73
	v_sub_f32_e32 v69, v69, v71
	v_add_f32_e32 v67, v69, v67
	v_add_f32_e32 v69, v68, v66
	v_sub_f32_e32 v71, v69, v68
	v_sub_f32_e32 v73, v69, v71
	v_sub_f32_e32 v68, v68, v73
	v_sub_f32_e32 v66, v66, v71
	v_add_f32_e32 v67, v69, v67
	v_add_f32_e32 v66, v66, v68
	v_add_f32_e32 v68, v70, v67
	v_sub_f32_e32 v69, v68, v70
	v_sub_f32_e32 v67, v67, v69
	v_add_f32_e32 v66, v66, v67
	s_mov_b32 s1, 0x7f800000
	v_add_f32_e32 v66, v68, v66
	v_cmp_neq_f32_e32 vcc, s1, v72
	v_mov_b32_e32 v67, 0x7f800000
	s_mov_b32 s1, 0x33800000
	v_cndmask_b32_e32 v66, v67, v66, vcc
	v_cmp_ngt_f32_e32 vcc, -1.0, v72
	v_mov_b32_e32 v67, 0x7fc00000
	s_waitcnt lgkmcnt(0)
	v_cndmask_b32_e32 v66, v67, v66, vcc
	v_cmp_neq_f32_e32 vcc, -1.0, v72
	v_mov_b32_e32 v67, 0xff800000
	s_barrier
; template <int DIR, int MODE>
; __device__ __forceinline__ void lru_pass(const Args& a, const LAS bf16_t* cxb, LAS bf16_t* gyb, const LAS float* carry, const bf16x8 (&Bw)[2][2][2], const float (&prm)[2][3], int l, int tt, float (&hf)[8][2][4]) {
;     ...
;     for (int nt = 0; nt < 2; ++nt) {
;         const int c = 64 * h + 32 * nh + 16 * nt + fr; cc[nt] = c;
;         ba[nt] = prm[nt][0]; bxv[nt] = prm[nt][1]; k8[nt] = prm[nt][2];
;         C[nt] = MODE == 1 ? carry[DIR * 256 + c] : 0.f; At[nt] = 1.f;
; template <int MODE>
; __device__ __forceinline__ void lru_unit(const Args& a, LAS unsigned char* lds, int l, int tt) {
;     ...
;     for (int nt = 0; nt < 2; ++nt) { prm0[nt][2] = -8.0f * log1pf(__expf(-prm0[nt][2])); prm1[nt][2] = -8.0f * log1pf(__expf(-prm1[nt][2])); }
	s_mov_b32 s98, 0xbfb8aa3b
	v_mul_f32_e32 v168, 0xbfb8aa3b, v168
	v_mul_f32_e32 v169, 0xbfb8aa3b, v169
	v_mul_f32_e32 v170, 0xbfb8aa3b, v170
	v_mul_f32_e32 v171, 0xbfb8aa3b, v171
	v_mul_f32_e32 v150, 0xbfb8aa3b, v150
	v_mul_f32_e32 v151, 0xbfb8aa3b, v151
	v_mul_f32_e32 v152, 0xbfb8aa3b, v152
	v_mul_f32_e32 v153, 0xbfb8aa3b, v153
	v_cndmask_b32_e32 v66, v67, v66, vcc
	v_mul_f32_e32 v67, 0xbfb8aa3b, v156
	v_exp_f32_e32 v183, v67
	v_cmp_lt_f32_e64 vcc, |v72|, s1
	s_movk_i32 s28, 0x210
	s_nop 0
	v_cndmask_b32_e32 v66, v66, v72, vcc
	v_add_f32_e32 v68, 1.0, v183
	v_mul_f32_e32 v214, 0xc138aa3b, v66
	v_add_f32_e32 v66, -1.0, v68
	v_sub_f32_e32 v67, v66, v68
	v_add_f32_e32 v67, 1.0, v67
	v_sub_f32_e32 v66, v183, v66
	v_add_f32_e32 v69, v66, v67
	v_frexp_mant_f32_e32 v70, v68
	v_cvt_f64_f32_e32 v[66:67], v68
	v_frexp_exp_i32_f64_e32 v66, v[66:67]
	v_cmp_gt_f32_e32 vcc, s0, v70
	s_nop 1
	v_subbrev_co_u32_e32 v66, vcc, 0, v66, vcc
	v_sub_u32_e32 v67, 0, v66
	v_ldexp_f32 v68, v68, v67
	v_ldexp_f32 v67, v69, v67
	v_add_f32_e32 v69, -1.0, v68
	v_add_f32_e32 v72, 1.0, v68
	v_add_f32_e32 v70, 1.0, v69
	v_add_f32_e32 v73, -1.0, v72
	v_sub_f32_e32 v70, v68, v70
	v_sub_f32_e32 v68, v68, v73
	v_add_f32_e32 v70, v67, v70
	v_add_f32_e32 v67, v67, v68
	v_add_f32_e32 v68, v72, v67
	v_rcp_f32_e32 v73, v68
	v_add_f32_e32 v71, v69, v70
	v_sub_f32_e32 v69, v71, v69
	v_sub_f32_e32 v69, v70, v69
	v_sub_f32_e32 v70, v68, v72
	v_sub_f32_e32 v67, v67, v70
	v_mul_f32_e32 v70, v71, v73
	v_mul_f32_e32 v72, v68, v70
	v_fma_f32 v74, v70, v68, -v72
	v_fmac_f32_e32 v74, v70, v67
	v_add_f32_e32 v75, v72, v74
	v_sub_f32_e32 v76, v71, v75
	v_sub_f32_e32 v71, v71, v76
	v_sub_f32_e32 v72, v75, v72
	v_sub_f32_e32 v71, v71, v75
	v_add_f32_e32 v69, v69, v71
	v_sub_f32_e32 v71, v72, v74
	v_add_f32_e32 v69, v71, v69
	v_add_f32_e32 v71, v76, v69
	v_mul_f32_e32 v72, v73, v71
	v_mul_f32_e32 v74, v68, v72
	v_fma_f32 v68, v72, v68, -v74
	v_fmac_f32_e32 v68, v72, v67
	v_sub_f32_e32 v67, v76, v71
	v_add_f32_e32 v67, v69, v67
	v_add_f32_e32 v69, v74, v68
	v_sub_f32_e32 v75, v71, v69
	v_sub_f32_e32 v71, v71, v75
	v_sub_f32_e32 v74, v69, v74
	v_sub_f32_e32 v69, v71, v69
	v_add_f32_e32 v67, v67, v69
	v_sub_f32_e32 v68, v74, v68
	v_cvt_f32_i32_e32 v66, v66
	v_add_f32_e32 v67, v68, v67
	v_add_f32_e32 v68, v70, v72
	v_add_f32_e32 v67, v75, v67
	v_sub_f32_e32 v69, v68, v70
	v_mul_f32_e32 v67, v73, v67
	v_sub_f32_e32 v69, v72, v69
	v_add_f32_e32 v67, v69, v67
	v_mul_f32_e32 v194, 0x3f317218, v66
	v_add_f32_e32 v191, v68, v67
	v_fma_f32 v195, v66, s5, -v194
	v_fmac_f32_e32 v195, 0xb102e308, v66
	v_sub_f32_e32 v66, v191, v68
	v_sub_f32_e32 v66, v67, v66
	v_mul_f32_e32 v67, 0xbfb8aa3b, v155
	v_exp_f32_e32 v76, v67
	v_ldexp_f32 v196, v66, 1
	v_mul_f32_e32 v192, v191, v191
	v_fmamk_f32 v69, v192, 0x3e9b6dac, v85
	v_add_f32_e32 v68, 1.0, v76
	v_add_f32_e32 v66, -1.0, v68
	v_sub_f32_e32 v67, v66, v68
	v_add_f32_e32 v67, 1.0, v67
	v_sub_f32_e32 v66, v76, v66
	v_fmaak_f32 v193, v192, v69, 0x3f2aaada
	v_add_f32_e32 v69, v66, v67
	v_frexp_mant_f32_e32 v70, v68
	v_cvt_f64_f32_e32 v[66:67], v68
	v_frexp_exp_i32_f64_e32 v66, v[66:67]
	v_cmp_gt_f32_e32 vcc, s0, v70
	v_ldexp_f32 v197, v191, 1
	s_nop 0
	v_subbrev_co_u32_e32 v66, vcc, 0, v66, vcc
	v_sub_u32_e32 v67, 0, v66
	v_ldexp_f32 v68, v68, v67
	v_ldexp_f32 v67, v69, v67
	v_add_f32_e32 v69, -1.0, v68
	v_add_f32_e32 v72, 1.0, v68
	v_add_f32_e32 v70, 1.0, v69
	v_add_f32_e32 v73, -1.0, v72
	v_sub_f32_e32 v70, v68, v70
	v_sub_f32_e32 v68, v68, v73
	v_add_f32_e32 v70, v67, v70
	v_add_f32_e32 v67, v67, v68
	v_add_f32_e32 v68, v72, v67
	v_rcp_f32_e32 v73, v68
	v_add_f32_e32 v71, v69, v70
	v_sub_f32_e32 v69, v71, v69
	v_sub_f32_e32 v69, v70, v69
	v_sub_f32_e32 v70, v68, v72
	v_sub_f32_e32 v67, v67, v70
	v_mul_f32_e32 v70, v71, v73
	v_mul_f32_e32 v72, v68, v70
	v_fma_f32 v74, v70, v68, -v72
	v_fmac_f32_e32 v74, v70, v67
	v_add_f32_e32 v75, v72, v74
	v_sub_f32_e32 v77, v71, v75
	v_sub_f32_e32 v71, v71, v77
	v_sub_f32_e32 v72, v75, v72
	v_sub_f32_e32 v71, v71, v75
	v_add_f32_e32 v69, v69, v71
	v_sub_f32_e32 v71, v72, v74
	v_add_f32_e32 v69, v71, v69
	v_add_f32_e32 v71, v77, v69
	v_mul_f32_e32 v72, v73, v71
	v_mul_f32_e32 v74, v68, v72
	v_fma_f32 v68, v72, v68, -v74
	v_fmac_f32_e32 v68, v72, v67
	v_sub_f32_e32 v67, v77, v71
	v_add_f32_e32 v67, v69, v67
	v_add_f32_e32 v69, v74, v68
	v_sub_f32_e32 v75, v71, v69
	v_sub_f32_e32 v71, v71, v75
	v_sub_f32_e32 v74, v69, v74
	v_sub_f32_e32 v69, v71, v69
	v_add_f32_e32 v67, v67, v69
	v_sub_f32_e32 v68, v74, v68
	v_cvt_f32_i32_e32 v66, v66
	v_add_f32_e32 v67, v68, v67
	v_add_f32_e32 v68, v70, v72
	v_add_f32_e32 v67, v75, v67
	v_sub_f32_e32 v69, v68, v70
	v_mul_f32_e32 v67, v73, v67
	v_sub_f32_e32 v69, v72, v69
	v_add_f32_e32 v67, v69, v67
	v_mul_f32_e32 v81, 0x3f317218, v66
	v_add_f32_e32 v78, v68, v67
	v_fma_f32 v82, v66, s5, -v81
	v_fmac_f32_e32 v82, 0xb102e308, v66
	v_sub_f32_e32 v66, v78, v68
	v_sub_f32_e32 v66, v67, v66
	v_mul_f32_e32 v67, 0xbfb8aa3b, v154
	v_exp_f32_e32 v181, v67
	v_ldexp_f32 v83, v66, 1
	v_mul_f32_e32 v79, v78, v78
	v_fmamk_f32 v69, v79, 0x3e9b6dac, v85
	v_add_f32_e32 v68, 1.0, v181
	v_add_f32_e32 v66, -1.0, v68
	v_sub_f32_e32 v67, v66, v68
	v_add_f32_e32 v67, 1.0, v67
	v_sub_f32_e32 v66, v181, v66
	v_fmaak_f32 v80, v79, v69, 0x3f2aaada
	v_add_f32_e32 v69, v66, v67
	v_frexp_mant_f32_e32 v70, v68
	v_cvt_f64_f32_e32 v[66:67], v68
	v_frexp_exp_i32_f64_e32 v66, v[66:67]
	v_cmp_gt_f32_e32 vcc, s0, v70
	v_ldexp_f32 v92, v78, 1
	v_and_b32_e32 v77, 0x7fffffff, v76
	v_subbrev_co_u32_e32 v66, vcc, 0, v66, vcc
	v_sub_u32_e32 v67, 0, v66
	v_ldexp_f32 v68, v68, v67
	v_ldexp_f32 v67, v69, v67
	v_add_f32_e32 v69, -1.0, v68
; template <int DIR, int MODE>
; __device__ __forceinline__ void lru_pass(const Args& a, const LAS bf16_t* cxb, LAS bf16_t* gyb, const LAS float* carry, const bf16x8 (&Bw)[2][2][2], const float (&prm)[2][3], int l, int tt, float (&hf)[8][2][4]) {
;     ...
;     for (int mi = 0; mi < 8; ++mi) {
;         const int m = DIR ? 7 - mi : mi;
;         bf16x8 Af[2];
; #pragma unroll
;         for (int ks = 0; ks < 2; ++ks) Af[ks] = *(const LAS bf16x8*)(cxb + (m * 16 + fr) * CXS + 64 * h + 32 * ks + 8 * fq);
; #pragma unroll
;         for (int nt = 0; nt < 2; ++nt) {
;             f32x4 pr = (f32x4){0.f, 0.f, 0.f, 0.f}, pi = (f32x4){0.f, 0.f, 0.f, 0.f};
; #pragma unroll
;             for (int ks = 0; ks < 2; ++ks) { pr = __builtin_amdgcn_mfma_f32_16x16x32_bf16(Af[ks], Bw[0][nt][ks], pr, 0, 0, 0); pi = __builtin_amdgcn_mfma_f32_16x16x32_bf16(Af[ks], Bw[1][nt][ks], pi, 0, 0, 0); }
;             float av[4], bv[4];
; #pragma unroll
;             for (int reg = 0; reg < 4; ++reg) {
;                 const int tok = m * 16 + 4 * fq + reg;
;                 const float x = bf2f(cxb[tok * CXS + cc[nt]]);
;                 const float r = fsig(pr[reg] + ba[nt]), ig = fsig(pi[reg] + bxv[nt]);
;                 const float aa = __expf(k8[nt] * r);
;                 av[reg] = aa; bv[reg] = __builtin_amdgcn_sqrtf(fmaxf(1.0f - aa * aa, 0.f)) * ig * x;
;             }
;             float cum[4], hl[4];
;             if (DIR == 0) { cum[0] = av[0]; hl[0] = bv[0];
; #pragma unroll
;                 for (int reg = 1; reg < 4; ++reg) { cum[reg] = cum[reg - 1] * av[reg]; hl[reg] = av[reg] * hl[reg - 1] + bv[reg]; } }
;             else { cum[3] = av[3]; hl[3] = bv[3];
; #pragma unroll
;     ...
;             const float A4 = DIR ? cum[0] : cum[3], H4 = DIR ? hl[0] : hl[3];
;             float Aq[4], Hq[4];
; #pragma unroll
;             for (int q = 0; q < 4; ++q) { Aq[q] = __shfl(A4, fr + 16 * q); Hq[q] = __shfl(H4, fr + 16 * q); }
;             float hin;
;             if (DIR == 0) { const float s0 = C[nt], s1 = Aq[0] * s0 + Hq[0], s2 = Aq[1] * s1 + Hq[1], s3 = Aq[2] * s2 + Hq[2]; C[nt] = Aq[3] * s3 + Hq[3]; hin = fq == 0 ? s0 : (fq == 1 ? s1 : (fq == 2 ? s2 : s3)); }
;             else { const float s3 = C[nt], s2 = Aq[3] * s3 + Hq[3], s1 = Aq[2] * s2 + Hq[2], s0 = Aq[1] * s1 + Hq[1]; C[nt] = Aq[0] * s0 + Hq[0]; hin = fq == 3 ? s3 : (fq == 2 ? s2 : (fq == 1 ? s1 : s0)); }
	v_add_f32_e32 v72, 1.0, v68
	v_add_f32_e32 v70, 1.0, v69
	v_add_f32_e32 v73, -1.0, v72
	v_sub_f32_e32 v70, v68, v70
	v_sub_f32_e32 v68, v68, v73
	v_add_f32_e32 v70, v67, v70
	v_add_f32_e32 v67, v67, v68
	v_add_f32_e32 v68, v72, v67
	v_rcp_f32_e32 v73, v68
	v_add_f32_e32 v71, v69, v70
	v_sub_f32_e32 v69, v71, v69
	v_sub_f32_e32 v69, v70, v69
	v_sub_f32_e32 v70, v68, v72
	v_sub_f32_e32 v67, v67, v70
	v_mul_f32_e32 v70, v71, v73
	v_mul_f32_e32 v72, v68, v70
	v_fma_f32 v74, v70, v68, -v72
	v_fmac_f32_e32 v74, v70, v67
	v_add_f32_e32 v75, v72, v74
	v_sub_f32_e32 v84, v71, v75
	v_sub_f32_e32 v71, v71, v84
	v_sub_f32_e32 v72, v75, v72
	v_sub_f32_e32 v71, v71, v75
	v_add_f32_e32 v69, v69, v71
	v_sub_f32_e32 v71, v72, v74
	v_add_f32_e32 v69, v71, v69
	v_add_f32_e32 v71, v84, v69
	v_mul_f32_e32 v72, v73, v71
	v_mul_f32_e32 v74, v68, v72
	v_fma_f32 v68, v72, v68, -v74
	v_fmac_f32_e32 v68, v72, v67
	v_sub_f32_e32 v67, v84, v71
	v_add_f32_e32 v67, v69, v67
	v_add_f32_e32 v69, v74, v68
	v_sub_f32_e32 v75, v71, v69
	v_sub_f32_e32 v71, v71, v75
	v_sub_f32_e32 v74, v69, v74
	v_sub_f32_e32 v69, v71, v69
	v_add_f32_e32 v67, v67, v69
	v_sub_f32_e32 v68, v74, v68
	v_add_f32_e32 v67, v68, v67
	v_add_f32_e32 v68, v70, v72
	v_add_f32_e32 v67, v75, v67
	v_sub_f32_e32 v69, v68, v70
	v_mul_f32_e32 v67, v73, v67
	v_sub_f32_e32 v69, v72, v69
	v_add_f32_e32 v67, v69, v67
	v_mov_b32_e32 v69, v0
	v_cvt_f32_i32_e32 v66, v66
	v_readfirstlane_b32 s0, v69
	s_bfe_u32 s1, s0, 0x20006
	s_lshl_b32 s4, s1, 7
	v_bfe_u32 v200, v69, 4, 2
	s_add_i32 s4, s4, 0
	v_and_b32_e32 v75, 15, v69
	v_lshl_add_u32 v93, v200, 4, s4
	v_mad_u32_u24 v69, v75, s29, v93
	ds_read_b128 v[70:73], v69
	v_add_f32_e32 v184, v68, v67
	v_mul_f32_e32 v187, 0x3f317218, v66
	v_mul_f32_e32 v185, v184, v184
	v_fma_f32 v188, v66, s5, -v187
	v_fmamk_f32 v74, v185, 0x3e9b6dac, v85
	v_fmac_f32_e32 v188, 0xb102e308, v66
	v_sub_f32_e32 v66, v184, v68
	v_fmaak_f32 v186, v185, v74, 0x3f2aaada
	v_sub_f32_e32 v74, v67, v66
	ds_read_b128 v[66:69], v69 offset:64
	s_waitcnt lgkmcnt(1)
	v_mfma_f32_16x16x32_bf16 v[84:87], v[70:73], v[50:53], 0
	s_ashr_i32 s0, s0, 3
	s_lshl_b32 s1, s1, 6
	s_andn2_b32 s0, s0, 31
	s_waitcnt lgkmcnt(0)
	v_mfma_f32_16x16x32_bf16 v[94:97], v[66:69], v[54:57], v[84:87]
	s_nop 2
	v_and_b32_e32 v84, 64, v227
	v_or_b32_e32 v98, v84, v75
	s_add_i32 s1, s1, s0
	s_nop 1
	v_fma_f32 v84, v94, s98, v171
	s_nop 0
	v_exp_f32_e32 v84, v84
	v_mfma_f32_16x16x32_bf16 v[88:91], v[70:73], v[58:61], 0
	v_ldexp_f32 v189, v74, 1
	v_or_b32_e32 v74, s1, v75
	v_add_f32_e32 v84, 1.0, v84
	v_rcp_f32_e32 v84, v84
	v_mfma_f32_16x16x32_bf16 v[88:91], v[66:69], v[62:65], v[88:91]
	v_lshlrev_b32_e32 v85, 1, v74
	v_mul_u32_u24_e32 v86, 0x840, v200
	v_mul_f32_e32 v84, v214, v84
	v_add3_u32 v213, 0, v85, v86
	s_nop 0
	s_nop 2
	v_fma_f32 v85, v88, s98, v170
	s_nop 0
	v_exp_f32_e32 v87, v84
	v_exp_f32_e32 v85, v85
	ds_read_u16 v84, v213
	v_fma_f32 v88, v89, s98, v170
	v_fma_f32 v86, -v87, v87, 1.0
	v_add_f32_e32 v85, 1.0, v85
	v_max_f32_e32 v86, 0, v86
	v_rcp_f32_e32 v85, v85
	v_sqrt_f32_e32 v86, v86
	s_waitcnt lgkmcnt(0)
	v_lshlrev_b32_e32 v84, 16, v84
	s_nop 0
	v_exp_f32_e32 v89, v88
	v_mul_f32_e32 v85, v85, v86
	v_fma_f32 v86, v95, s98, v171
	s_nop 0
	v_exp_f32_e32 v86, v86
	v_mul_f32_e32 v88, v85, v84
	v_add_f32_e32 v84, 1.0, v89
	v_fma_f32 v90, v90, s98, v170
	v_add_f32_e32 v86, 1.0, v86
	v_rcp_f32_e32 v86, v86
	s_nop 0
	v_rcp_f32_e32 v84, v84
	v_exp_f32_e32 v90, v90
	v_mul_f32_e32 v85, v214, v86
	v_fma_f32 v86, v96, s98, v171
	s_nop 0
	v_exp_f32_e32 v86, v86
	s_nop 0
	v_exp_f32_e32 v85, v85
	v_fma_f32 v91, v91, s98, v170
	v_add_f32_e32 v86, 1.0, v86
	v_rcp_f32_e32 v86, v86
	v_fma_f32 v89, -v85, v85, 1.0
	v_max_f32_e32 v89, 0, v89
	v_sqrt_f32_e32 v89, v89
	v_mul_f32_e32 v86, v214, v86
	s_nop 0
	v_exp_f32_e32 v95, v86
	v_fma_f32 v86, v97, s98, v171
	s_nop 0
	v_exp_f32_e32 v86, v86
	s_nop 0
	v_mul_f32_e32 v84, v84, v89
	v_add_f32_e32 v89, 1.0, v90
	v_add_f32_e32 v86, 1.0, v86
	v_rcp_f32_e32 v86, v86
	v_fma_f32 v90, -v95, v95, 1.0
	v_exp_f32_e32 v91, v91
	v_max_f32_e32 v90, 0, v90
	v_mul_f32_e32 v86, v214, v86
	s_nop 0
	v_exp_f32_e32 v96, v86
	ds_read_u16 v94, v213 offset:528
	ds_read_u16 v99, v213 offset:1056
	ds_read_u16 v100, v213 offset:1584
	v_rcp_f32_e32 v89, v89
	v_sqrt_f32_e32 v86, v90
	v_add_f32_e32 v90, 1.0, v91
	v_fma_f32 v91, -v96, v96, 1.0
	v_max_f32_e32 v91, 0, v91
	s_waitcnt lgkmcnt(2)
	v_lshlrev_b32_e32 v94, 16, v94
	v_rcp_f32_e32 v90, v90
	v_sqrt_f32_e32 v91, v91
	s_waitcnt lgkmcnt(1)
	v_lshlrev_b32_e32 v97, 16, v99
	v_mul_f32_e32 v99, v89, v86
	v_mul_f32_e32 v86, v85, v88
	v_fmac_f32_e32 v86, v84, v94
	v_mul_f32_e32 v89, v85, v87
	v_mul_f32_e32 v85, v95, v86
	v_fmac_f32_e32 v85, v99, v97
	s_waitcnt lgkmcnt(0)
	v_lshlrev_b32_e32 v100, 16, v100
	v_mul_f32_e32 v101, v90, v91
	v_mul_f32_e32 v90, v95, v89
	v_mul_f32_e32 v84, v96, v85
	v_lshl_add_u32 v74, v74, 2, 0
	v_mul_f32_e32 v91, v96, v90
	v_fmac_f32_e32 v84, v101, v100
	v_lshlrev_b32_e32 v210, 2, v98
	v_add_u32_e32 v74, 0x21000, v74
	ds_bpermute_b32 v99, v210, v91
	ds_bpermute_b32 v97, v210, v84
	v_mul_u32_u24_e32 v96, 0x210, v75
	ds_read2_b32 v[74:75], v74 offset1:16
	ds_bpermute_b32 v100, v210, v91 offset:64
	ds_bpermute_b32 v98, v210, v84 offset:64
	ds_bpermute_b32 v102, v210, v91 offset:128
	ds_bpermute_b32 v94, v210, v84 offset:128
	ds_bpermute_b32 v95, v210, v91 offset:192
	ds_bpermute_b32 v101, v210, v84 offset:192
	s_waitcnt lgkmcnt(6)
	v_fmac_f32_e32 v97, v74, v99
	s_waitcnt lgkmcnt(4)
	v_fmac_f32_e32 v98, v97, v100
	v_ldexp_f32 v190, v184, 1
	v_or_b32_e32 v212, 64, v210
	v_or_b32_e32 v211, 0x80, v210
	v_or_b32_e32 v218, 0xc0, v210
	v_cmp_eq_u32_e32 vcc, 2, v200
	s_waitcnt lgkmcnt(2)
	v_fmac_f32_e32 v94, v98, v102
	v_cmp_lt_i32_e64 s[0:1], 0, v200
	s_and_saveexec_b64 s[4:5], s[0:1]
	s_cbranch_execz .LBB0_551
	v_cmp_ne_u32_e64 s[0:1], 1, v200
	s_and_saveexec_b64 s[34:35], s[0:1]
	s_xor_b64 s[0:1], exec, s[34:35]
	v_cndmask_b32_e32 v74, v94, v98, vcc
	s_andn2_saveexec_b64 s[0:1], s[0:1]
	v_mov_b32_e32 v74, v97
	s_or_b64 exec, exec, s[0:1]
; template <int DIR, int MODE>
; __device__ __forceinline__ void lru_pass(const Args& a, const LAS bf16_t* cxb, LAS bf16_t* gyb, const LAS float* carry, const bf16x8 (&Bw)[2][2][2], const float (&prm)[2][3], int l, int tt, float (&hf)[8][2][4]) {
;     ...
;         for (int nt = 0; nt < 2; ++nt) {
;             f32x4 pr = (f32x4){0.f, 0.f, 0.f, 0.f}, pi = (f32x4){0.f, 0.f, 0.f, 0.f};
; #pragma unroll
;             for (int ks = 0; ks < 2; ++ks) { pr = __builtin_amdgcn_mfma_f32_16x16x32_bf16(Af[ks], Bw[0][nt][ks], pr, 0, 0, 0); pi = __builtin_amdgcn_mfma_f32_16x16x32_bf16(Af[ks], Bw[1][nt][ks], pi, 0, 0, 0); }
;             float av[4], bv[4];
; #pragma unroll
;             for (int reg = 0; reg < 4; ++reg) {
;                 const int tok = m * 16 + 4 * fq + reg;
;                 const float x = bf2f(cxb[tok * CXS + cc[nt]]);
;                 const float r = fsig(pr[reg] + ba[nt]), ig = fsig(pi[reg] + bxv[nt]);
;                 const float aa = __expf(k8[nt] * r);
;                 av[reg] = aa; bv[reg] = __builtin_amdgcn_sqrtf(fmaxf(1.0f - aa * aa, 0.f)) * ig * x;
;             }
;             float cum[4], hl[4];
;             if (DIR == 0) { cum[0] = av[0]; hl[0] = bv[0];
; #pragma unroll
;                 for (int reg = 1; reg < 4; ++reg) { cum[reg] = cum[reg - 1] * av[reg]; hl[reg] = av[reg] * hl[reg - 1] + bv[reg]; } }
;             else { cum[3] = av[3]; hl[3] = bv[3];
; #pragma unroll
;     ...
;             const float A4 = DIR ? cum[0] : cum[3], H4 = DIR ? hl[0] : hl[3];
;             float Aq[4], Hq[4];
; #pragma unroll
;             for (int q = 0; q < 4; ++q) { Aq[q] = __shfl(A4, fr + 16 * q); Hq[q] = __shfl(H4, fr + 16 * q); }
;             float hin;
;             if (DIR == 0) { const float s0 = C[nt], s1 = Aq[0] * s0 + Hq[0], s2 = Aq[1] * s1 + Hq[1], s3 = Aq[2] * s2 + Hq[2]; C[nt] = Aq[3] * s3 + Hq[3]; hin = fq == 0 ? s0 : (fq == 1 ? s1 : (fq == 2 ? s2 : s3)); }
;             else { const float s3 = C[nt], s2 = Aq[3] * s3 + Hq[3], s1 = Aq[2] * s2 + Hq[2], s0 = Aq[1] * s1 + Hq[1]; C[nt] = Aq[0] * s0 + Hq[0]; hin = fq == 3 ? s3 : (fq == 2 ? s2 : (fq == 1 ? s1 : s0)); }
; template <int MODE>
; __device__ __forceinline__ void lru_unit(const Args& a, LAS unsigned char* lds, int l, int tt) {
;     ...
;     for (int nt = 0; nt < 2; ++nt) { prm0[nt][2] = -8.0f * log1pf(__expf(-prm0[nt][2])); prm1[nt][2] = -8.0f * log1pf(__expf(-prm1[nt][2])); }
.LBB0_551:
	s_or_b64 exec, exec, s[4:5]
	v_mul_f32_e32 v78, v78, v79
	v_mul_f32_e32 v78, v78, v80
	v_add_f32_e32 v79, v92, v78
	v_sub_f32_e32 v80, v79, v92
	v_sub_f32_e32 v78, v78, v80
	v_add_f32_e32 v78, v83, v78
	v_add_f32_e32 v80, v79, v78
	v_add_f32_e32 v97, v81, v82
	v_sub_f32_e32 v79, v80, v79
	v_sub_f32_e32 v81, v97, v81
	v_sub_f32_e32 v78, v78, v79
	v_add_f32_e32 v79, v97, v80
	v_sub_f32_e32 v81, v82, v81
	v_sub_f32_e32 v82, v79, v97
	v_sub_f32_e32 v83, v79, v82
	v_sub_f32_e32 v83, v97, v83
	v_sub_f32_e32 v80, v80, v82
	v_add_f32_e32 v82, v81, v78
	v_add_f32_e32 v80, v80, v83
	v_sub_f32_e32 v83, v82, v81
	v_sub_f32_e32 v92, v82, v83
	v_sub_f32_e32 v81, v81, v92
	v_sub_f32_e32 v78, v78, v83
	v_add_f32_e32 v80, v82, v80
	v_add_f32_e32 v78, v78, v81
	v_add_f32_e32 v81, v79, v80
	v_sub_f32_e32 v79, v81, v79
	v_sub_f32_e32 v79, v80, v79
	v_add_f32_e32 v78, v78, v79
	s_mov_b32 s0, 0x7f800000
	v_add_f32_e32 v82, v81, v78
	v_cmp_neq_f32_e64 s[0:1], s0, v76
	v_mov_b32_e32 v83, 0x7f800000
	v_mfma_f32_16x16x32_bf16 v[78:81], v[70:73], v[34:37], 0
	v_cndmask_b32_e64 v82, v83, v82, s[0:1]
	v_cmp_ngt_f32_e64 s[0:1], -1.0, v76
	v_mov_b32_e32 v83, 0x7fc00000
	v_mfma_f32_16x16x32_bf16 v[70:73], v[70:73], v[42:45], 0
	v_cndmask_b32_e64 v82, v83, v82, s[0:1]
	v_cmp_neq_f32_e64 s[0:1], -1.0, v76
	v_mov_b32_e32 v83, 0xff800000
	s_nop 0
	v_cndmask_b32_e64 v82, v83, v82, s[0:1]
	s_mov_b32 s0, 0x33800000
	v_cmp_gt_f32_e64 s[0:1], s0, v77
	s_nop 1
	v_cndmask_b32_e64 v76, v82, v76, s[0:1]
	v_mfma_f32_16x16x32_bf16 v[80:83], v[66:69], v[38:41], v[78:81]
	v_mul_f32_e32 v215, 0xc138aa3b, v76
	v_cmp_lt_i32_e64 s[0:1], 0, v200
	v_mfma_f32_16x16x32_bf16 v[66:69], v[66:69], v[46:49], v[70:73]
	s_nop 4
	v_fma_f32 v77, v80, s98, v169
	s_nop 0
	v_exp_f32_e32 v77, v77
	v_fma_f32 v66, v66, s98, v168
	s_nop 0
	v_exp_f32_e32 v66, v66
	v_add_f32_e32 v70, 1.0, v77
	v_rcp_f32_e32 v70, v70
	v_fma_f32 v67, v67, s98, v168
	v_add_f32_e32 v66, 1.0, v66
	v_rcp_f32_e32 v66, v66
	v_mul_f32_e32 v70, v215, v70
	s_nop 0
	v_exp_f32_e32 v79, v70
	ds_read_u16 v70, v213 offset:32
	s_nop 0
	v_exp_f32_e32 v67, v67
	v_fma_f32 v71, -v79, v79, 1.0
	v_max_f32_e32 v71, 0, v71
	v_sqrt_f32_e32 v71, v71
	s_waitcnt lgkmcnt(0)
	v_lshlrev_b32_e32 v70, 16, v70
	v_fma_f32 v69, v69, s98, v168
	s_nop 0
	v_mul_f32_e32 v66, v66, v71
	v_fma_f32 v71, v81, s98, v169
	s_nop 0
	v_exp_f32_e32 v71, v71
	v_mul_f32_e32 v226, v66, v70
	v_add_f32_e32 v66, 1.0, v67
	v_rcp_f32_e32 v66, v66
	v_add_f32_e32 v71, 1.0, v71
	v_rcp_f32_e32 v71, v71
	v_fma_f32 v70, v82, s98, v169
	s_nop 0
	v_exp_f32_e32 v70, v70
	v_mul_f32_e32 v67, v215, v71
	s_nop 0
	v_exp_f32_e32 v67, v67
	v_add_f32_e32 v70, 1.0, v70
	v_rcp_f32_e32 v70, v70
	v_fma_f32 v68, v68, s98, v168
	v_fma_f32 v71, -v67, v67, 1.0
	v_max_f32_e32 v71, 0, v71
	v_sqrt_f32_e32 v71, v71
	v_mul_f32_e32 v70, v215, v70
	s_nop 0
	v_exp_f32_e32 v69, v69
	v_mul_f32_e32 v66, v66, v71
	v_fma_f32 v71, v83, s98, v169
	s_nop 0
	v_exp_f32_e32 v71, v71
	s_nop 0
	v_exp_f32_e32 v70, v70
	v_exp_f32_e32 v68, v68
	v_add_f32_e32 v71, 1.0, v71
	v_rcp_f32_e32 v71, v71
	v_add_f32_e32 v69, 1.0, v69
	v_fma_f32 v77, -v70, v70, 1.0
	v_rcp_f32_e32 v69, v69
	v_mul_f32_e32 v71, v215, v71
	s_nop 0
	v_exp_f32_e32 v71, v71
	ds_read_u16 v72, v213 offset:560
	ds_read_u16 v73, v213 offset:1088
	ds_read_u16 v76, v213 offset:1616
	v_add_f32_e32 v68, 1.0, v68
	v_max_f32_e32 v77, 0, v77
	v_fma_f32 v78, -v71, v71, 1.0
	v_max_f32_e32 v78, 0, v78
	v_sqrt_f32_e32 v78, v78
	v_rcp_f32_e32 v68, v68
	v_sqrt_f32_e32 v77, v77
	s_waitcnt lgkmcnt(2)
	v_lshlrev_b32_e32 v72, 16, v72
	v_mul_f32_e32 v69, v69, v78
	v_mul_f32_e32 v78, v67, v226
	v_fmac_f32_e32 v78, v66, v72
	s_waitcnt lgkmcnt(1)
	v_lshlrev_b32_e32 v73, 16, v73
	v_mul_f32_e32 v68, v68, v77
	v_mul_f32_e32 v77, v70, v78
	v_mul_f32_e32 v244, v67, v79
	v_fmac_f32_e32 v77, v68, v73
	s_waitcnt lgkmcnt(0)
	v_lshlrev_b32_e32 v80, 16, v76
	v_mul_f32_e32 v245, v70, v244
	v_mul_f32_e32 v76, v71, v77
	v_mul_f32_e32 v237, v71, v245
	v_fmac_f32_e32 v76, v69, v80
	ds_bpermute_b32 v68, v210, v237
	ds_bpermute_b32 v66, v210, v76
	ds_bpermute_b32 v69, v212, v237
	ds_bpermute_b32 v67, v212, v76
	ds_bpermute_b32 v70, v211, v237
	ds_bpermute_b32 v112, v211, v76
	ds_bpermute_b32 v114, v218, v237
	ds_bpermute_b32 v92, v218, v76
	s_waitcnt lgkmcnt(6)
	v_fmac_f32_e32 v66, v75, v68
	s_waitcnt lgkmcnt(4)
	v_fmac_f32_e32 v67, v66, v69
	s_waitcnt lgkmcnt(2)
	v_fmac_f32_e32 v112, v67, v70
	s_and_saveexec_b64 s[4:5], s[0:1]
	s_cbranch_execz .LBB0_557
	v_cmp_ne_u32_e64 s[0:1], 1, v200
	s_and_saveexec_b64 s[34:35], s[0:1]
	s_xor_b64 s[0:1], exec, s[34:35]
	v_cndmask_b32_e32 v75, v112, v67, vcc
	s_andn2_saveexec_b64 s[0:1], s[0:1]
	v_mov_b32_e32 v75, v66
	s_or_b64 exec, exec, s[0:1]
; template <int DIR, int MODE>
; __device__ __forceinline__ void lru_pass(const Args& a, const LAS bf16_t* cxb, LAS bf16_t* gyb, const LAS float* carry, const bf16x8 (&Bw)[2][2][2], const float (&prm)[2][3], int l, int tt, float (&hf)[8][2][4]) {
;     ...
;     for (int mi = 0; mi < 8; ++mi) {
;         const int m = DIR ? 7 - mi : mi;
;         bf16x8 Af[2];
; #pragma unroll
;         for (int ks = 0; ks < 2; ++ks) Af[ks] = *(const LAS bf16x8*)(cxb + (m * 16 + fr) * CXS + 64 * h + 32 * ks + 8 * fq);
; #pragma unroll
;         for (int nt = 0; nt < 2; ++nt) {
;             f32x4 pr = (f32x4){0.f, 0.f, 0.f, 0.f}, pi = (f32x4){0.f, 0.f, 0.f, 0.f};
; #pragma unroll
;             for (int ks = 0; ks < 2; ++ks) { pr = __builtin_amdgcn_mfma_f32_16x16x32_bf16(Af[ks], Bw[0][nt][ks], pr, 0, 0, 0); pi = __builtin_amdgcn_mfma_f32_16x16x32_bf16(Af[ks], Bw[1][nt][ks], pi, 0, 0, 0); }
;             float av[4], bv[4];
; #pragma unroll
;             for (int reg = 0; reg < 4; ++reg) {
;                 const int tok = m * 16 + 4 * fq + reg;
;                 const float x = bf2f(cxb[tok * CXS + cc[nt]]);
;                 const float r = fsig(pr[reg] + ba[nt]), ig = fsig(pi[reg] + bxv[nt]);
;                 const float aa = __expf(k8[nt] * r);
;                 av[reg] = aa; bv[reg] = __builtin_amdgcn_sqrtf(fmaxf(1.0f - aa * aa, 0.f)) * ig * x;
;             }
;             float cum[4], hl[4];
;             if (DIR == 0) { cum[0] = av[0]; hl[0] = bv[0];
; #pragma unroll
;                 for (int reg = 1; reg < 4; ++reg) { cum[reg] = cum[reg - 1] * av[reg]; hl[reg] = av[reg] * hl[reg - 1] + bv[reg]; } }
;             else { cum[3] = av[3]; hl[3] = bv[3];
; #pragma unroll
;     ...
;             const float A4 = DIR ? cum[0] : cum[3], H4 = DIR ? hl[0] : hl[3];
;             float Aq[4], Hq[4];
; #pragma unroll
;             for (int q = 0; q < 4; ++q) { Aq[q] = __shfl(A4, fr + 16 * q); Hq[q] = __shfl(H4, fr + 16 * q); }
;             float hin;
;             if (DIR == 0) { const float s0 = C[nt], s1 = Aq[0] * s0 + Hq[0], s2 = Aq[1] * s1 + Hq[1], s3 = Aq[2] * s2 + Hq[2]; C[nt] = Aq[3] * s3 + Hq[3]; hin = fq == 0 ? s0 : (fq == 1 ? s1 : (fq == 2 ? s2 : s3)); }
;             else { const float s3 = C[nt], s2 = Aq[3] * s3 + Hq[3], s1 = Aq[2] * s2 + Hq[2], s0 = Aq[1] * s1 + Hq[1]; C[nt] = Aq[0] * s0 + Hq[0]; hin = fq == 3 ? s3 : (fq == 2 ? s2 : (fq == 1 ? s1 : s0)); }
.LBB0_557:
	s_or_b64 exec, exec, s[4:5]
	v_add_u32_e32 v220, v93, v96
	ds_read_b128 v[70:73], v220 offset:8448
	ds_read_b128 v[66:69], v220 offset:8512
	ds_read_u16 v80, v213 offset:8448
	ds_read_u16 v81, v213 offset:8976
	ds_read_u16 v82, v213 offset:9504
	ds_read_u16 v83, v213 offset:10032
	v_fmac_f32_e32 v101, v94, v95
	s_waitcnt lgkmcnt(5)
	v_mfma_f32_16x16x32_bf16 v[96:99], v[70:73], v[50:53], 0
	s_waitcnt lgkmcnt(2)
	v_lshlrev_b32_e32 v81, 16, v81
	v_lshlrev_b32_e32 v80, 16, v80
	s_waitcnt lgkmcnt(1)
	v_lshlrev_b32_e32 v82, 16, v82
	v_mfma_f32_16x16x32_bf16 v[96:99], v[66:69], v[54:57], v[96:99]
	s_waitcnt lgkmcnt(0)
	v_lshlrev_b32_e32 v83, 16, v83
	v_cmp_lt_i32_e64 s[0:1], 0, v200
	v_mfma_f32_16x16x32_bf16 v[102:105], v[70:73], v[58:61], 0
	v_mfma_f32_16x16x32_bf16 v[106:109], v[66:69], v[62:65], v[102:105]
	s_nop 2
	v_fma_f32 v93, v96, s98, v171
	s_nop 0
	v_exp_f32_e32 v93, v93
	v_fma_f32 v97, v97, s98, v171
	s_nop 0
	v_fma_f32 v96, v106, s98, v170
	v_add_f32_e32 v93, 1.0, v93
	v_rcp_f32_e32 v93, v93
	s_nop 0
	v_exp_f32_e32 v96, v96
	v_exp_f32_e32 v97, v97
	v_fma_f32 v100, v107, s98, v170
	s_nop 0
	v_mul_f32_e32 v93, v214, v93
	v_exp_f32_e32 v100, v100
	s_nop 0
	v_add_f32_e32 v96, 1.0, v96
	v_add_f32_e32 v97, 1.0, v97
	v_exp_f32_e32 v106, v93
	v_rcp_f32_e32 v93, v96
	v_rcp_f32_e32 v96, v97
	v_add_f32_e32 v100, 1.0, v100
	v_rcp_f32_e32 v97, v100
	v_fma_f32 v100, -v106, v106, 1.0
	v_max_f32_e32 v100, 0, v100
	v_mul_f32_e32 v96, v214, v96
	v_sqrt_f32_e32 v100, v100
	s_nop 0
	v_exp_f32_e32 v96, v96
	v_mul_f32_e32 v93, v93, v100
	v_mul_f32_e32 v105, v93, v80
	v_fma_f32 v80, v98, s98, v171
	v_fma_f32 v93, -v96, v96, 1.0
	v_fma_f32 v98, v108, s98, v170
	v_max_f32_e32 v93, 0, v93
	s_nop 0
	v_sqrt_f32_e32 v93, v93
	v_exp_f32_e32 v98, v98
	s_nop 0
	v_exp_f32_e32 v80, v80
	v_mul_f32_e32 v93, v97, v93
	v_add_f32_e32 v97, 1.0, v98
	v_fma_f32 v98, v99, s98, v171
	s_nop 0
	v_exp_f32_e32 v98, v98
	v_add_f32_e32 v80, 1.0, v80
	v_rcp_f32_e32 v80, v80
	v_fma_f32 v100, v109, s98, v170
	v_add_f32_e32 v98, 1.0, v98
	v_rcp_f32_e32 v98, v98
	v_mul_f32_e32 v80, v214, v80
	s_nop 0
	v_exp_f32_e32 v80, v80
	v_mul_f32_e32 v98, v214, v98
	s_nop 0
	s_nop 0
	v_exp_f32_e32 v98, v98
	v_exp_f32_e32 v100, v100
	v_fma_f32 v99, -v80, v80, 1.0
	v_max_f32_e32 v99, 0, v99
	v_rcp_f32_e32 v97, v97
	v_sqrt_f32_e32 v99, v99
	v_fma_f32 v102, -v98, v98, 1.0
	v_add_f32_e32 v100, 1.0, v100
	v_max_f32_e32 v102, 0, v102
	v_rcp_f32_e32 v100, v100
	v_sqrt_f32_e32 v102, v102
	v_mul_f32_e32 v104, v96, v105
	v_fmac_f32_e32 v104, v93, v81
	v_mul_f32_e32 v97, v97, v99
	v_mul_f32_e32 v103, v80, v104
	v_mul_f32_e32 v107, v96, v106
	v_fmac_f32_e32 v103, v97, v82
	v_mul_f32_e32 v99, v100, v102
	v_mul_f32_e32 v108, v80, v107
	v_mul_f32_e32 v102, v98, v103
	v_mul_f32_e32 v109, v98, v108
	v_fmac_f32_e32 v102, v99, v83
	ds_bpermute_b32 v97, v210, v109
	ds_bpermute_b32 v93, v210, v102
	ds_bpermute_b32 v98, v212, v109
	ds_bpermute_b32 v96, v212, v102
	ds_bpermute_b32 v99, v211, v109
	ds_bpermute_b32 v111, v211, v102
	ds_bpermute_b32 v113, v218, v109
	ds_bpermute_b32 v119, v218, v102
	s_waitcnt lgkmcnt(6)
	v_fmac_f32_e32 v93, v101, v97
	s_waitcnt lgkmcnt(4)
	v_fmac_f32_e32 v96, v93, v98
	s_waitcnt lgkmcnt(2)
	v_fmac_f32_e32 v111, v96, v99
	s_and_saveexec_b64 s[4:5], s[0:1]
	s_cbranch_execz .LBB0_563
	v_cmp_ne_u32_e64 s[0:1], 1, v200
	s_and_saveexec_b64 s[34:35], s[0:1]
	s_xor_b64 s[0:1], exec, s[34:35]
	v_cndmask_b32_e32 v101, v111, v96, vcc
	s_andn2_saveexec_b64 s[0:1], s[0:1]
	v_mov_b32_e32 v101, v93
	s_or_b64 exec, exec, s[0:1]
.LBB0_563:
	s_or_b64 exec, exec, s[4:5]
	v_mfma_f32_16x16x32_bf16 v[94:97], v[70:73], v[34:37], 0
	ds_read_u16 v80, v213 offset:8480
	v_fmac_f32_e32 v92, v112, v114
	v_cmp_lt_i32_e64 s[0:1], 0, v200
	v_mfma_f32_16x16x32_bf16 v[120:123], v[70:73], v[42:45], 0
	v_mfma_f32_16x16x32_bf16 v[70:73], v[66:69], v[38:41], v[94:97]
	v_mfma_f32_16x16x32_bf16 v[66:69], v[66:69], v[46:49], v[120:123]
	s_nop 6
	v_fma_f32 v70, v70, s98, v169
	s_nop 0
	v_exp_f32_e32 v70, v70
	v_fma_f32 v66, v66, s98, v168
	s_nop 0
	v_exp_f32_e32 v66, v66
	v_add_f32_e32 v70, 1.0, v70
	v_rcp_f32_e32 v70, v70
	v_fma_f32 v72, v72, s98, v169
	v_add_f32_e32 v66, 1.0, v66
	v_rcp_f32_e32 v66, v66
	v_mul_f32_e32 v70, v215, v70
	s_nop 0
	v_exp_f32_e32 v94, v70
	s_nop 0
	v_exp_f32_e32 v72, v72
	v_fma_f32 v67, v67, s98, v168
	v_fma_f32 v70, -v94, v94, 1.0
	v_max_f32_e32 v70, 0, v70
	v_sqrt_f32_e32 v70, v70
	v_fma_f32 v73, v73, s98, v169
	s_nop 0
	v_add_f32_e32 v72, 1.0, v72
	v_mul_f32_e32 v66, v66, v70
	v_fma_f32 v70, v71, s98, v169
	s_nop 0
	v_exp_f32_e32 v70, v70
	s_nop 0
	v_exp_f32_e32 v67, v67
	v_rcp_f32_e32 v72, v72
	v_add_f32_e32 v70, 1.0, v70
	v_rcp_f32_e32 v70, v70
	v_exp_f32_e32 v73, v73
	v_add_f32_e32 v67, 1.0, v67
	v_mul_f32_e32 v72, v215, v72
	v_mul_f32_e32 v70, v215, v70
	s_nop 0
	v_exp_f32_e32 v70, v70
	v_add_f32_e32 v73, 1.0, v73
	v_rcp_f32_e32 v67, v67
	v_fma_f32 v68, v68, s98, v168
	v_fma_f32 v71, -v70, v70, 1.0
	v_max_f32_e32 v71, 0, v71
	v_sqrt_f32_e32 v71, v71
	s_nop 0
	v_rcp_f32_e32 v73, v73
	s_nop 0
	v_exp_f32_e32 v72, v72
	v_exp_f32_e32 v68, v68
	v_mul_f32_e32 v67, v67, v71
	ds_read_u16 v71, v213 offset:9536
	s_waitcnt lgkmcnt(1)
	v_lshlrev_b32_e32 v80, 16, v80
	v_mul_f32_e32 v73, v215, v73
	v_mul_f32_e32 v93, v66, v80
	v_fma_f32 v80, -v72, v72, 1.0
	v_fma_f32 v69, v69, s98, v168
	s_nop 0
	v_add_f32_e32 v68, 1.0, v68
	v_max_f32_e32 v80, 0, v80
	s_nop 0
	v_exp_f32_e32 v73, v73
	ds_read_u16 v66, v213 offset:9008
	v_rcp_f32_e32 v68, v68
	v_sqrt_f32_e32 v80, v80
	v_exp_f32_e32 v69, v69
	v_fma_f32 v81, -v73, v73, 1.0
	v_max_f32_e32 v81, 0, v81
	v_mul_f32_e32 v68, v68, v80
	ds_read_u16 v80, v213 offset:10064
	v_add_f32_e32 v69, 1.0, v69
	s_waitcnt lgkmcnt(1)
	v_lshlrev_b32_e32 v66, 16, v66
	v_rcp_f32_e32 v69, v69
	v_sqrt_f32_e32 v81, v81
	v_mul_f32_e32 v97, v70, v93
	v_fmac_f32_e32 v97, v67, v66
	v_lshlrev_b32_e32 v71, 16, v71
	v_mul_f32_e32 v96, v72, v97
	v_mul_f32_e32 v98, v70, v94
	v_fmac_f32_e32 v96, v68, v71
	s_waitcnt lgkmcnt(0)
	v_lshlrev_b32_e32 v80, 16, v80
	v_mul_f32_e32 v69, v69, v81
	v_mul_f32_e32 v99, v72, v98
	v_mul_f32_e32 v95, v73, v96
	v_mul_f32_e32 v100, v73, v99
	v_fmac_f32_e32 v95, v69, v80
	ds_bpermute_b32 v68, v210, v100
	ds_bpermute_b32 v66, v210, v95
	ds_bpermute_b32 v69, v212, v100
	ds_bpermute_b32 v67, v212, v95
	ds_bpermute_b32 v70, v211, v100
	ds_bpermute_b32 v129, v211, v95
	ds_bpermute_b32 v131, v218, v100
	ds_bpermute_b32 v110, v218, v95
	s_waitcnt lgkmcnt(6)
	v_fmac_f32_e32 v66, v92, v68
	s_waitcnt lgkmcnt(4)
	v_fmac_f32_e32 v67, v66, v69
	s_waitcnt lgkmcnt(2)
	v_fmac_f32_e32 v129, v67, v70
	s_and_saveexec_b64 s[4:5], s[0:1]
	s_cbranch_execz .LBB0_569
	v_cmp_ne_u32_e64 s[0:1], 1, v200
	s_and_saveexec_b64 s[34:35], s[0:1]
	s_xor_b64 s[0:1], exec, s[34:35]
	v_cndmask_b32_e32 v92, v129, v67, vcc
	s_andn2_saveexec_b64 s[0:1], s[0:1]
	v_mov_b32_e32 v92, v66
	s_or_b64 exec, exec, s[0:1]
; template <int DIR, int MODE>
; __device__ __forceinline__ void lru_pass(const Args& a, const LAS bf16_t* cxb, LAS bf16_t* gyb, const LAS float* carry, const bf16x8 (&Bw)[2][2][2], const float (&prm)[2][3], int l, int tt, float (&hf)[8][2][4]) {
;     ...
;     for (int mi = 0; mi < 8; ++mi) {
;         const int m = DIR ? 7 - mi : mi;
;         bf16x8 Af[2];
; #pragma unroll
;         for (int ks = 0; ks < 2; ++ks) Af[ks] = *(const LAS bf16x8*)(cxb + (m * 16 + fr) * CXS + 64 * h + 32 * ks + 8 * fq);
; #pragma unroll
;         for (int nt = 0; nt < 2; ++nt) {
;             f32x4 pr = (f32x4){0.f, 0.f, 0.f, 0.f}, pi = (f32x4){0.f, 0.f, 0.f, 0.f};
; #pragma unroll
;             for (int ks = 0; ks < 2; ++ks) { pr = __builtin_amdgcn_mfma_f32_16x16x32_bf16(Af[ks], Bw[0][nt][ks], pr, 0, 0, 0); pi = __builtin_amdgcn_mfma_f32_16x16x32_bf16(Af[ks], Bw[1][nt][ks], pi, 0, 0, 0); }
;             float av[4], bv[4];
; #pragma unroll
;             for (int reg = 0; reg < 4; ++reg) {
;                 const int tok = m * 16 + 4 * fq + reg;
;                 const float x = bf2f(cxb[tok * CXS + cc[nt]]);
;                 const float r = fsig(pr[reg] + ba[nt]), ig = fsig(pi[reg] + bxv[nt]);
;                 const float aa = __expf(k8[nt] * r);
;                 av[reg] = aa; bv[reg] = __builtin_amdgcn_sqrtf(fmaxf(1.0f - aa * aa, 0.f)) * ig * x;
;             }
;             float cum[4], hl[4];
;             if (DIR == 0) { cum[0] = av[0]; hl[0] = bv[0];
; #pragma unroll
;                 for (int reg = 1; reg < 4; ++reg) { cum[reg] = cum[reg - 1] * av[reg]; hl[reg] = av[reg] * hl[reg - 1] + bv[reg]; } }
;             else { cum[3] = av[3]; hl[3] = bv[3];
; #pragma unroll
;     ...
;             const float A4 = DIR ? cum[0] : cum[3], H4 = DIR ? hl[0] : hl[3];
;             float Aq[4], Hq[4];
; #pragma unroll
;             for (int q = 0; q < 4; ++q) { Aq[q] = __shfl(A4, fr + 16 * q); Hq[q] = __shfl(H4, fr + 16 * q); }
;             float hin;
;             if (DIR == 0) { const float s0 = C[nt], s1 = Aq[0] * s0 + Hq[0], s2 = Aq[1] * s1 + Hq[1], s3 = Aq[2] * s2 + Hq[2]; C[nt] = Aq[3] * s3 + Hq[3]; hin = fq == 0 ? s0 : (fq == 1 ? s1 : (fq == 2 ? s2 : s3)); }
;             else { const float s3 = C[nt], s2 = Aq[3] * s3 + Hq[3], s1 = Aq[2] * s2 + Hq[2], s0 = Aq[1] * s1 + Hq[1]; C[nt] = Aq[0] * s0 + Hq[0]; hin = fq == 3 ? s3 : (fq == 2 ? s2 : (fq == 1 ? s1 : s0)); }
.LBB0_569:
	s_or_b64 exec, exec, s[4:5]
	ds_read_b128 v[70:73], v220 offset:16896
	ds_read_b128 v[66:69], v220 offset:16960
	ds_read_u16 v80, v213 offset:16896
	ds_read_u16 v81, v213 offset:17424
	ds_read_u16 v82, v213 offset:17952
	ds_read_u16 v83, v213 offset:18480
	v_fmac_f32_e32 v119, v111, v113
	s_waitcnt lgkmcnt(5)
	v_mfma_f32_16x16x32_bf16 v[114:117], v[70:73], v[50:53], 0
	s_waitcnt lgkmcnt(2)
	v_lshlrev_b32_e32 v81, 16, v81
	v_lshlrev_b32_e32 v80, 16, v80
	s_waitcnt lgkmcnt(1)
	v_lshlrev_b32_e32 v82, 16, v82
	v_mfma_f32_16x16x32_bf16 v[114:117], v[66:69], v[54:57], v[114:117]
	s_waitcnt lgkmcnt(0)
	v_lshlrev_b32_e32 v83, 16, v83
	v_cmp_lt_i32_e64 s[0:1], 0, v200
	v_mfma_f32_16x16x32_bf16 v[120:123], v[70:73], v[58:61], 0
	v_mfma_f32_16x16x32_bf16 v[124:127], v[66:69], v[62:65], v[120:123]
	s_nop 2
	v_fma_f32 v112, v114, s98, v171
	s_nop 0
	v_exp_f32_e32 v112, v112
	v_fma_f32 v115, v115, s98, v171
	s_nop 0
	v_fma_f32 v114, v124, s98, v170
	v_add_f32_e32 v112, 1.0, v112
	v_rcp_f32_e32 v112, v112
	s_nop 0
	v_exp_f32_e32 v114, v114
	v_exp_f32_e32 v115, v115
	v_fma_f32 v118, v125, s98, v170
	s_nop 0
	v_mul_f32_e32 v112, v214, v112
	v_exp_f32_e32 v118, v118
	s_nop 0
	v_add_f32_e32 v114, 1.0, v114
	v_add_f32_e32 v115, 1.0, v115
	v_exp_f32_e32 v124, v112
	v_rcp_f32_e32 v112, v114
	v_rcp_f32_e32 v114, v115
	v_add_f32_e32 v118, 1.0, v118
	v_rcp_f32_e32 v115, v118
	v_fma_f32 v118, -v124, v124, 1.0
	v_max_f32_e32 v118, 0, v118
	v_mul_f32_e32 v114, v214, v114
	v_sqrt_f32_e32 v118, v118
	s_nop 0
	v_exp_f32_e32 v114, v114
	v_mul_f32_e32 v112, v112, v118
	v_mul_f32_e32 v123, v112, v80
	v_fma_f32 v80, v116, s98, v171
	v_fma_f32 v112, -v114, v114, 1.0
	v_fma_f32 v116, v126, s98, v170
	v_max_f32_e32 v112, 0, v112
	s_nop 0
	v_sqrt_f32_e32 v112, v112
	v_exp_f32_e32 v116, v116
	s_nop 0
	v_exp_f32_e32 v80, v80
	v_mul_f32_e32 v112, v115, v112
	v_add_f32_e32 v115, 1.0, v116
	v_fma_f32 v116, v117, s98, v171
	s_nop 0
	v_exp_f32_e32 v116, v116
	v_add_f32_e32 v80, 1.0, v80
	v_rcp_f32_e32 v80, v80
	v_fma_f32 v118, v127, s98, v170
	v_add_f32_e32 v116, 1.0, v116
	v_rcp_f32_e32 v116, v116
	v_mul_f32_e32 v80, v214, v80
	s_nop 0
	v_exp_f32_e32 v80, v80
	v_mul_f32_e32 v116, v214, v116
	s_nop 0
	s_nop 0
	v_exp_f32_e32 v116, v116
	v_exp_f32_e32 v118, v118
	v_fma_f32 v117, -v80, v80, 1.0
	v_max_f32_e32 v117, 0, v117
	v_rcp_f32_e32 v115, v115
	v_sqrt_f32_e32 v117, v117
	v_fma_f32 v120, -v116, v116, 1.0
	v_add_f32_e32 v118, 1.0, v118
	v_max_f32_e32 v120, 0, v120
	v_rcp_f32_e32 v118, v118
	v_sqrt_f32_e32 v120, v120
	v_mul_f32_e32 v122, v114, v123
	v_fmac_f32_e32 v122, v112, v81
	v_mul_f32_e32 v115, v115, v117
	v_mul_f32_e32 v121, v80, v122
	v_mul_f32_e32 v125, v114, v124
	v_fmac_f32_e32 v121, v115, v82
	v_mul_f32_e32 v117, v118, v120
	v_mul_f32_e32 v126, v80, v125
	v_mul_f32_e32 v120, v116, v121
	v_mul_f32_e32 v127, v116, v126
	v_fmac_f32_e32 v120, v117, v83
	ds_bpermute_b32 v115, v210, v127
	ds_bpermute_b32 v112, v210, v120
	ds_bpermute_b32 v116, v212, v127
	ds_bpermute_b32 v114, v212, v120
	ds_bpermute_b32 v117, v211, v127
	ds_bpermute_b32 v130, v211, v120
	ds_bpermute_b32 v132, v218, v127
	ds_bpermute_b32 v137, v218, v120
	s_waitcnt lgkmcnt(6)
	v_fmac_f32_e32 v112, v119, v115
	s_waitcnt lgkmcnt(4)
	v_fmac_f32_e32 v114, v112, v116
	s_waitcnt lgkmcnt(2)
	v_fmac_f32_e32 v130, v114, v117
	s_and_saveexec_b64 s[4:5], s[0:1]
	s_cbranch_execz .LBB0_575
	v_cmp_ne_u32_e64 s[0:1], 1, v200
	s_and_saveexec_b64 s[34:35], s[0:1]
	s_xor_b64 s[0:1], exec, s[34:35]
	v_cndmask_b32_e32 v119, v130, v114, vcc
	s_andn2_saveexec_b64 s[0:1], s[0:1]
	v_mov_b32_e32 v119, v112
	s_or_b64 exec, exec, s[0:1]
.LBB0_575:
	s_or_b64 exec, exec, s[4:5]
	v_mfma_f32_16x16x32_bf16 v[112:115], v[70:73], v[34:37], 0
	ds_read_u16 v80, v213 offset:16928
	v_fmac_f32_e32 v110, v129, v131
	v_cmp_lt_i32_e64 s[0:1], 0, v200
	v_mfma_f32_16x16x32_bf16 v[138:141], v[70:73], v[42:45], 0
	v_mfma_f32_16x16x32_bf16 v[70:73], v[66:69], v[38:41], v[112:115]
	v_mfma_f32_16x16x32_bf16 v[66:69], v[66:69], v[46:49], v[138:141]
	s_nop 6
	v_fma_f32 v70, v70, s98, v169
	s_nop 0
	v_exp_f32_e32 v70, v70
	v_fma_f32 v66, v66, s98, v168
	s_nop 0
	v_exp_f32_e32 v66, v66
	v_add_f32_e32 v70, 1.0, v70
	v_rcp_f32_e32 v70, v70
	v_fma_f32 v72, v72, s98, v169
	v_add_f32_e32 v66, 1.0, v66
	v_rcp_f32_e32 v66, v66
	v_mul_f32_e32 v70, v215, v70
	s_nop 0
	v_exp_f32_e32 v112, v70
	s_nop 0
	v_exp_f32_e32 v72, v72
	v_fma_f32 v67, v67, s98, v168
	v_fma_f32 v70, -v112, v112, 1.0
	v_max_f32_e32 v70, 0, v70
	v_sqrt_f32_e32 v70, v70
	v_fma_f32 v73, v73, s98, v169
	s_nop 0
	v_add_f32_e32 v72, 1.0, v72
	v_mul_f32_e32 v66, v66, v70
	v_fma_f32 v70, v71, s98, v169
	s_nop 0
	v_exp_f32_e32 v70, v70
	s_nop 0
	v_exp_f32_e32 v67, v67
	v_rcp_f32_e32 v72, v72
	v_add_f32_e32 v70, 1.0, v70
	v_rcp_f32_e32 v70, v70
	v_exp_f32_e32 v73, v73
	v_add_f32_e32 v67, 1.0, v67
	v_mul_f32_e32 v72, v215, v72
	v_mul_f32_e32 v70, v215, v70
	s_nop 0
	v_exp_f32_e32 v70, v70
	v_add_f32_e32 v73, 1.0, v73
	v_rcp_f32_e32 v67, v67
	v_fma_f32 v68, v68, s98, v168
	v_fma_f32 v71, -v70, v70, 1.0
	v_max_f32_e32 v71, 0, v71
	v_sqrt_f32_e32 v71, v71
	s_nop 0
	v_rcp_f32_e32 v73, v73
	s_nop 0
	v_exp_f32_e32 v72, v72
	v_exp_f32_e32 v68, v68
	v_mul_f32_e32 v67, v67, v71
	ds_read_u16 v71, v213 offset:17984
	s_waitcnt lgkmcnt(1)
	v_lshlrev_b32_e32 v80, 16, v80
	v_mul_f32_e32 v73, v215, v73
	v_mul_f32_e32 v111, v66, v80
	v_fma_f32 v80, -v72, v72, 1.0
	v_fma_f32 v69, v69, s98, v168
	s_nop 0
	v_add_f32_e32 v68, 1.0, v68
	v_max_f32_e32 v80, 0, v80
	s_nop 0
	v_exp_f32_e32 v73, v73
	ds_read_u16 v66, v213 offset:17456
	v_rcp_f32_e32 v68, v68
	v_sqrt_f32_e32 v80, v80
	v_exp_f32_e32 v69, v69
	v_fma_f32 v81, -v73, v73, 1.0
	v_max_f32_e32 v81, 0, v81
	v_mul_f32_e32 v68, v68, v80
	ds_read_u16 v80, v213 offset:18512
	v_add_f32_e32 v69, 1.0, v69
	s_waitcnt lgkmcnt(1)
	v_lshlrev_b32_e32 v66, 16, v66
	v_rcp_f32_e32 v69, v69
	v_sqrt_f32_e32 v81, v81
	v_mul_f32_e32 v115, v70, v111
	v_fmac_f32_e32 v115, v67, v66
	v_lshlrev_b32_e32 v71, 16, v71
	v_mul_f32_e32 v114, v72, v115
	v_mul_f32_e32 v116, v70, v112
	v_fmac_f32_e32 v114, v68, v71
	s_waitcnt lgkmcnt(0)
	v_lshlrev_b32_e32 v80, 16, v80
	v_mul_f32_e32 v69, v69, v81
	v_mul_f32_e32 v117, v72, v116
	v_mul_f32_e32 v113, v73, v114
	v_mul_f32_e32 v118, v73, v117
	v_fmac_f32_e32 v113, v69, v80
	ds_bpermute_b32 v68, v210, v118
	ds_bpermute_b32 v66, v210, v113
	ds_bpermute_b32 v69, v212, v118
	ds_bpermute_b32 v67, v212, v113
	ds_bpermute_b32 v70, v211, v118
	ds_bpermute_b32 v147, v211, v113
	ds_bpermute_b32 v149, v218, v118
	ds_bpermute_b32 v128, v218, v113
	s_waitcnt lgkmcnt(6)
	v_fmac_f32_e32 v66, v110, v68
	s_waitcnt lgkmcnt(4)
	v_fmac_f32_e32 v67, v66, v69
	s_waitcnt lgkmcnt(2)
	v_fmac_f32_e32 v147, v67, v70
	s_and_saveexec_b64 s[4:5], s[0:1]
	s_cbranch_execz .LBB0_581
	v_cmp_ne_u32_e64 s[0:1], 1, v200
	s_and_saveexec_b64 s[34:35], s[0:1]
	s_xor_b64 s[0:1], exec, s[34:35]
	v_cndmask_b32_e32 v110, v147, v67, vcc
	s_andn2_saveexec_b64 s[0:1], s[0:1]
	v_mov_b32_e32 v110, v66
	s_or_b64 exec, exec, s[0:1]
; template <int DIR, int MODE>
; __device__ __forceinline__ void lru_pass(const Args& a, const LAS bf16_t* cxb, LAS bf16_t* gyb, const LAS float* carry, const bf16x8 (&Bw)[2][2][2], const float (&prm)[2][3], int l, int tt, float (&hf)[8][2][4]) {
;     ...
;     for (int mi = 0; mi < 8; ++mi) {
;         const int m = DIR ? 7 - mi : mi;
;         bf16x8 Af[2];
; #pragma unroll
;         for (int ks = 0; ks < 2; ++ks) Af[ks] = *(const LAS bf16x8*)(cxb + (m * 16 + fr) * CXS + 64 * h + 32 * ks + 8 * fq);
; #pragma unroll
;         for (int nt = 0; nt < 2; ++nt) {
;             f32x4 pr = (f32x4){0.f, 0.f, 0.f, 0.f}, pi = (f32x4){0.f, 0.f, 0.f, 0.f};
; #pragma unroll
;             for (int ks = 0; ks < 2; ++ks) { pr = __builtin_amdgcn_mfma_f32_16x16x32_bf16(Af[ks], Bw[0][nt][ks], pr, 0, 0, 0); pi = __builtin_amdgcn_mfma_f32_16x16x32_bf16(Af[ks], Bw[1][nt][ks], pi, 0, 0, 0); }
;             float av[4], bv[4];
; #pragma unroll
;             for (int reg = 0; reg < 4; ++reg) {
;                 const int tok = m * 16 + 4 * fq + reg;
;                 const float x = bf2f(cxb[tok * CXS + cc[nt]]);
;                 const float r = fsig(pr[reg] + ba[nt]), ig = fsig(pi[reg] + bxv[nt]);
;                 const float aa = __expf(k8[nt] * r);
;                 av[reg] = aa; bv[reg] = __builtin_amdgcn_sqrtf(fmaxf(1.0f - aa * aa, 0.f)) * ig * x;
;             }
;             float cum[4], hl[4];
;             if (DIR == 0) { cum[0] = av[0]; hl[0] = bv[0];
; #pragma unroll
;                 for (int reg = 1; reg < 4; ++reg) { cum[reg] = cum[reg - 1] * av[reg]; hl[reg] = av[reg] * hl[reg - 1] + bv[reg]; } }
;             else { cum[3] = av[3]; hl[3] = bv[3];
; #pragma unroll
;     ...
;             const float A4 = DIR ? cum[0] : cum[3], H4 = DIR ? hl[0] : hl[3];
;             float Aq[4], Hq[4];
; #pragma unroll
;             for (int q = 0; q < 4; ++q) { Aq[q] = __shfl(A4, fr + 16 * q); Hq[q] = __shfl(H4, fr + 16 * q); }
;             float hin;
;             if (DIR == 0) { const float s0 = C[nt], s1 = Aq[0] * s0 + Hq[0], s2 = Aq[1] * s1 + Hq[1], s3 = Aq[2] * s2 + Hq[2]; C[nt] = Aq[3] * s3 + Hq[3]; hin = fq == 0 ? s0 : (fq == 1 ? s1 : (fq == 2 ? s2 : s3)); }
;             else { const float s3 = C[nt], s2 = Aq[3] * s3 + Hq[3], s1 = Aq[2] * s2 + Hq[2], s0 = Aq[1] * s1 + Hq[1]; C[nt] = Aq[0] * s0 + Hq[0]; hin = fq == 3 ? s3 : (fq == 2 ? s2 : (fq == 1 ? s1 : s0)); }
.LBB0_581:
	s_or_b64 exec, exec, s[4:5]
	ds_read_b128 v[70:73], v220 offset:25344
	ds_read_b128 v[66:69], v220 offset:25408
	ds_read_u16 v80, v213 offset:25344
	ds_read_u16 v81, v213 offset:25872
	ds_read_u16 v82, v213 offset:26400
	ds_read_u16 v83, v213 offset:26928
	v_fmac_f32_e32 v137, v130, v132
	s_waitcnt lgkmcnt(5)
	v_mfma_f32_16x16x32_bf16 v[138:141], v[70:73], v[50:53], 0
	s_waitcnt lgkmcnt(2)
	v_lshlrev_b32_e32 v81, 16, v81
	v_lshlrev_b32_e32 v80, 16, v80
	s_waitcnt lgkmcnt(1)
	v_lshlrev_b32_e32 v82, 16, v82
	v_mfma_f32_16x16x32_bf16 v[154:157], v[66:69], v[54:57], v[138:141]
	s_waitcnt lgkmcnt(0)
	v_lshlrev_b32_e32 v83, 16, v83
	v_cmp_lt_i32_e64 s[0:1], 0, v200
	v_mfma_f32_16x16x32_bf16 v[142:145], v[70:73], v[58:61], 0
	v_mfma_f32_16x16x32_bf16 v[142:145], v[66:69], v[62:65], v[142:145]
	s_nop 2
	v_fma_f32 v129, v154, s98, v171
	s_nop 0
	v_exp_f32_e32 v129, v129
	v_fma_f32 v133, v155, s98, v171
	s_nop 0
	v_fma_f32 v131, v142, s98, v170
	v_add_f32_e32 v129, 1.0, v129
	v_rcp_f32_e32 v129, v129
	s_nop 0
	v_exp_f32_e32 v131, v131
	v_exp_f32_e32 v133, v133
	v_fma_f32 v134, v143, s98, v170
	s_nop 0
	v_mul_f32_e32 v129, v214, v129
	v_exp_f32_e32 v134, v134
	s_nop 0
	v_add_f32_e32 v131, 1.0, v131
	v_add_f32_e32 v133, 1.0, v133
	v_exp_f32_e32 v142, v129
	v_rcp_f32_e32 v129, v131
	v_rcp_f32_e32 v131, v133
	v_add_f32_e32 v134, 1.0, v134
	v_rcp_f32_e32 v133, v134
	v_fma_f32 v134, -v142, v142, 1.0
	v_max_f32_e32 v134, 0, v134
	v_mul_f32_e32 v131, v214, v131
	v_sqrt_f32_e32 v134, v134
	s_nop 0
	v_exp_f32_e32 v131, v131
	v_fma_f32 v136, v145, s98, v170
	v_mul_f32_e32 v129, v129, v134
	v_mul_f32_e32 v141, v129, v80
	v_fma_f32 v129, -v131, v131, 1.0
	v_fma_f32 v134, v144, s98, v170
	v_max_f32_e32 v129, 0, v129
	s_nop 0
	v_sqrt_f32_e32 v129, v129
	v_exp_f32_e32 v134, v134
	v_fma_f32 v80, v156, s98, v171
	s_nop 0
	v_exp_f32_e32 v80, v80
	v_mul_f32_e32 v129, v133, v129
	v_add_f32_e32 v133, 1.0, v134
	v_fma_f32 v134, v157, s98, v171
	s_nop 0
	v_exp_f32_e32 v134, v134
	v_add_f32_e32 v80, 1.0, v80
	v_rcp_f32_e32 v80, v80
	s_nop 0
	v_add_f32_e32 v134, 1.0, v134
	v_rcp_f32_e32 v134, v134
	v_mul_f32_e32 v80, v214, v80
	s_nop 0
	v_exp_f32_e32 v80, v80
	v_mul_f32_e32 v134, v214, v134
	s_nop 0
	v_exp_f32_e32 v134, v134
	v_exp_f32_e32 v136, v136
	v_fma_f32 v135, -v80, v80, 1.0
	v_max_f32_e32 v135, 0, v135
	v_rcp_f32_e32 v133, v133
	v_sqrt_f32_e32 v135, v135
	v_fma_f32 v138, -v134, v134, 1.0
	v_add_f32_e32 v136, 1.0, v136
	v_max_f32_e32 v138, 0, v138
	v_rcp_f32_e32 v136, v136
	v_sqrt_f32_e32 v138, v138
	v_mul_f32_e32 v140, v131, v141
	v_fmac_f32_e32 v140, v129, v81
	v_mul_f32_e32 v133, v133, v135
	v_mul_f32_e32 v139, v80, v140
	v_mul_f32_e32 v143, v131, v142
	v_fmac_f32_e32 v139, v133, v82
	v_mul_f32_e32 v135, v136, v138
	v_mul_f32_e32 v144, v80, v143
	v_mul_f32_e32 v138, v134, v139
	v_mul_f32_e32 v145, v134, v144
	v_fmac_f32_e32 v138, v135, v83
	ds_bpermute_b32 v133, v210, v145
	ds_bpermute_b32 v129, v210, v138
	ds_bpermute_b32 v134, v212, v145
	ds_bpermute_b32 v131, v212, v138
	ds_bpermute_b32 v135, v211, v145
	ds_bpermute_b32 v148, v211, v138
	ds_bpermute_b32 v154, v218, v145
	ds_bpermute_b32 v159, v218, v138
	s_waitcnt lgkmcnt(6)
	v_fmac_f32_e32 v129, v137, v133
	s_waitcnt lgkmcnt(4)
	v_fmac_f32_e32 v131, v129, v134
	s_waitcnt lgkmcnt(2)
	v_fmac_f32_e32 v148, v131, v135
	s_and_saveexec_b64 s[4:5], s[0:1]
	s_cbranch_execz .LBB0_587
	v_cmp_ne_u32_e64 s[0:1], 1, v200
	s_and_saveexec_b64 s[34:35], s[0:1]
	s_xor_b64 s[0:1], exec, s[34:35]
	v_cndmask_b32_e32 v137, v148, v131, vcc
	s_andn2_saveexec_b64 s[0:1], s[0:1]
	v_mov_b32_e32 v137, v129
	s_or_b64 exec, exec, s[0:1]
.LBB0_587:
	s_or_b64 exec, exec, s[4:5]
	v_mfma_f32_16x16x32_bf16 v[130:133], v[70:73], v[34:37], 0
	ds_read_u16 v80, v213 offset:25376
	v_fmac_f32_e32 v128, v147, v149
	v_cmp_lt_i32_e64 s[0:1], 0, v200
	v_mfma_f32_16x16x32_bf16 v[160:163], v[70:73], v[42:45], 0
	v_mfma_f32_16x16x32_bf16 v[70:73], v[66:69], v[38:41], v[130:133]
	v_mfma_f32_16x16x32_bf16 v[66:69], v[66:69], v[46:49], v[160:163]
	s_nop 6
	v_fma_f32 v70, v70, s98, v169
	s_nop 0
	v_exp_f32_e32 v70, v70
	v_fma_f32 v66, v66, s98, v168
	s_nop 0
	v_exp_f32_e32 v66, v66
	v_add_f32_e32 v70, 1.0, v70
	v_rcp_f32_e32 v70, v70
	v_fma_f32 v72, v72, s98, v169
	v_add_f32_e32 v66, 1.0, v66
	v_rcp_f32_e32 v66, v66
	v_mul_f32_e32 v70, v215, v70
	s_nop 0
	v_exp_f32_e32 v130, v70
	s_nop 0
	v_exp_f32_e32 v72, v72
	v_fma_f32 v67, v67, s98, v168
	v_fma_f32 v70, -v130, v130, 1.0
	v_max_f32_e32 v70, 0, v70
	v_sqrt_f32_e32 v70, v70
	v_fma_f32 v73, v73, s98, v169
	s_nop 0
	v_add_f32_e32 v72, 1.0, v72
	v_mul_f32_e32 v66, v66, v70
	v_fma_f32 v70, v71, s98, v169
	s_nop 0
	v_exp_f32_e32 v70, v70
	s_nop 0
	v_exp_f32_e32 v67, v67
	v_rcp_f32_e32 v72, v72
	v_add_f32_e32 v70, 1.0, v70
	v_rcp_f32_e32 v70, v70
	v_exp_f32_e32 v73, v73
	v_add_f32_e32 v67, 1.0, v67
	v_mul_f32_e32 v72, v215, v72
	v_mul_f32_e32 v70, v215, v70
	s_nop 0
	v_exp_f32_e32 v70, v70
	v_add_f32_e32 v73, 1.0, v73
	v_rcp_f32_e32 v67, v67
	v_fma_f32 v68, v68, s98, v168
	v_fma_f32 v71, -v70, v70, 1.0
	v_max_f32_e32 v71, 0, v71
	v_sqrt_f32_e32 v71, v71
	s_nop 0
	v_rcp_f32_e32 v73, v73
	s_nop 0
	v_exp_f32_e32 v72, v72
	v_exp_f32_e32 v68, v68
	v_mul_f32_e32 v67, v67, v71
	ds_read_u16 v71, v213 offset:26432
	s_waitcnt lgkmcnt(1)
	v_lshlrev_b32_e32 v80, 16, v80
	v_mul_f32_e32 v73, v215, v73
	v_mul_f32_e32 v129, v66, v80
	v_fma_f32 v80, -v72, v72, 1.0
	v_fma_f32 v69, v69, s98, v168
	s_nop 0
	v_add_f32_e32 v68, 1.0, v68
	v_max_f32_e32 v80, 0, v80
	s_nop 0
	v_exp_f32_e32 v73, v73
	ds_read_u16 v66, v213 offset:25904
	v_rcp_f32_e32 v68, v68
	v_sqrt_f32_e32 v80, v80
	v_exp_f32_e32 v69, v69
	v_fma_f32 v81, -v73, v73, 1.0
	v_max_f32_e32 v81, 0, v81
	v_mul_f32_e32 v68, v68, v80
	ds_read_u16 v80, v213 offset:26960
	v_add_f32_e32 v69, 1.0, v69
	s_waitcnt lgkmcnt(1)
	v_lshlrev_b32_e32 v66, 16, v66
	v_rcp_f32_e32 v69, v69
	v_sqrt_f32_e32 v81, v81
	v_mul_f32_e32 v133, v70, v129
	v_fmac_f32_e32 v133, v67, v66
	v_lshlrev_b32_e32 v71, 16, v71
	v_mul_f32_e32 v132, v72, v133
	v_mul_f32_e32 v134, v70, v130
	v_fmac_f32_e32 v132, v68, v71
	s_waitcnt lgkmcnt(0)
	v_lshlrev_b32_e32 v80, 16, v80
	v_mul_f32_e32 v69, v69, v81
	v_mul_f32_e32 v135, v72, v134
	v_mul_f32_e32 v131, v73, v132
	v_mul_f32_e32 v136, v73, v135
	v_fmac_f32_e32 v131, v69, v80
	ds_bpermute_b32 v68, v210, v136
	ds_bpermute_b32 v66, v210, v131
	ds_bpermute_b32 v69, v212, v136
	ds_bpermute_b32 v67, v212, v131
	ds_bpermute_b32 v70, v211, v136
	ds_bpermute_b32 v173, v211, v131
	ds_bpermute_b32 v175, v218, v136
	ds_bpermute_b32 v146, v218, v131
	s_waitcnt lgkmcnt(6)
	v_fmac_f32_e32 v66, v128, v68
	s_waitcnt lgkmcnt(4)
	v_fmac_f32_e32 v67, v66, v69
	s_waitcnt lgkmcnt(2)
	v_fmac_f32_e32 v173, v67, v70
	s_and_saveexec_b64 s[4:5], s[0:1]
	s_cbranch_execz .LBB0_593
	v_cmp_ne_u32_e64 s[0:1], 1, v200
	s_and_saveexec_b64 s[34:35], s[0:1]
	s_xor_b64 s[0:1], exec, s[34:35]
	v_cndmask_b32_e32 v128, v173, v67, vcc
	s_andn2_saveexec_b64 s[0:1], s[0:1]
	v_mov_b32_e32 v128, v66
	s_or_b64 exec, exec, s[0:1]
; template <int DIR, int MODE>
; __device__ __forceinline__ void lru_pass(const Args& a, const LAS bf16_t* cxb, LAS bf16_t* gyb, const LAS float* carry, const bf16x8 (&Bw)[2][2][2], const float (&prm)[2][3], int l, int tt, float (&hf)[8][2][4]) {
;     ...
;     for (int mi = 0; mi < 8; ++mi) {
;         const int m = DIR ? 7 - mi : mi;
;         bf16x8 Af[2];
; #pragma unroll
;         for (int ks = 0; ks < 2; ++ks) Af[ks] = *(const LAS bf16x8*)(cxb + (m * 16 + fr) * CXS + 64 * h + 32 * ks + 8 * fq);
; #pragma unroll
;         for (int nt = 0; nt < 2; ++nt) {
;             f32x4 pr = (f32x4){0.f, 0.f, 0.f, 0.f}, pi = (f32x4){0.f, 0.f, 0.f, 0.f};
; #pragma unroll
;             for (int ks = 0; ks < 2; ++ks) { pr = __builtin_amdgcn_mfma_f32_16x16x32_bf16(Af[ks], Bw[0][nt][ks], pr, 0, 0, 0); pi = __builtin_amdgcn_mfma_f32_16x16x32_bf16(Af[ks], Bw[1][nt][ks], pi, 0, 0, 0); }
;             float av[4], bv[4];
; #pragma unroll
;             for (int reg = 0; reg < 4; ++reg) {
;                 const int tok = m * 16 + 4 * fq + reg;
;                 const float x = bf2f(cxb[tok * CXS + cc[nt]]);
;                 const float r = fsig(pr[reg] + ba[nt]), ig = fsig(pi[reg] + bxv[nt]);
;                 const float aa = __expf(k8[nt] * r);
;                 av[reg] = aa; bv[reg] = __builtin_amdgcn_sqrtf(fmaxf(1.0f - aa * aa, 0.f)) * ig * x;
;             }
;             float cum[4], hl[4];
;             if (DIR == 0) { cum[0] = av[0]; hl[0] = bv[0];
; #pragma unroll
;                 for (int reg = 1; reg < 4; ++reg) { cum[reg] = cum[reg - 1] * av[reg]; hl[reg] = av[reg] * hl[reg - 1] + bv[reg]; } }
;             else { cum[3] = av[3]; hl[3] = bv[3];
; #pragma unroll
;     ...
;             const float A4 = DIR ? cum[0] : cum[3], H4 = DIR ? hl[0] : hl[3];
;             float Aq[4], Hq[4];
; #pragma unroll
;             for (int q = 0; q < 4; ++q) { Aq[q] = __shfl(A4, fr + 16 * q); Hq[q] = __shfl(H4, fr + 16 * q); }
;             float hin;
;             if (DIR == 0) { const float s0 = C[nt], s1 = Aq[0] * s0 + Hq[0], s2 = Aq[1] * s1 + Hq[1], s3 = Aq[2] * s2 + Hq[2]; C[nt] = Aq[3] * s3 + Hq[3]; hin = fq == 0 ? s0 : (fq == 1 ? s1 : (fq == 2 ? s2 : s3)); }
;             else { const float s3 = C[nt], s2 = Aq[3] * s3 + Hq[3], s1 = Aq[2] * s2 + Hq[2], s0 = Aq[1] * s1 + Hq[1]; C[nt] = Aq[0] * s0 + Hq[0]; hin = fq == 3 ? s3 : (fq == 2 ? s2 : (fq == 1 ? s1 : s0)); }
.LBB0_593:
	s_or_b64 exec, exec, s[4:5]
	ds_read_b128 v[70:73], v220 offset:33792
	ds_read_b128 v[66:69], v220 offset:33856
	ds_read_u16 v80, v213 offset:33792
	ds_read_u16 v81, v213 offset:34320
	ds_read_u16 v82, v213 offset:34848
	ds_read_u16 v83, v213 offset:35376
	v_fmac_f32_e32 v159, v148, v154
	s_waitcnt lgkmcnt(5)
	v_mfma_f32_16x16x32_bf16 v[160:163], v[70:73], v[50:53], 0
	s_waitcnt lgkmcnt(2)
	v_lshlrev_b32_e32 v81, 16, v81
	v_lshlrev_b32_e32 v80, 16, v80
	s_waitcnt lgkmcnt(1)
	v_lshlrev_b32_e32 v82, 16, v82
	v_mfma_f32_16x16x32_bf16 v[176:179], v[66:69], v[54:57], v[160:163]
	s_waitcnt lgkmcnt(0)
	v_lshlrev_b32_e32 v83, 16, v83
	v_cmp_lt_i32_e64 s[0:1], 0, v200
	v_mfma_f32_16x16x32_bf16 v[164:167], v[70:73], v[58:61], 0
	v_mfma_f32_16x16x32_bf16 v[164:167], v[66:69], v[62:65], v[164:167]
	s_nop 2
	v_fma_f32 v147, v176, s98, v171
	s_nop 0
	v_exp_f32_e32 v147, v147
	v_fma_f32 v155, v177, s98, v171
	s_nop 0
	v_fma_f32 v149, v164, s98, v170
	v_add_f32_e32 v147, 1.0, v147
	v_rcp_f32_e32 v147, v147
	s_nop 0
	v_exp_f32_e32 v149, v149
	v_exp_f32_e32 v155, v155
	v_fma_f32 v156, v165, s98, v170
	s_nop 0
	v_mul_f32_e32 v147, v214, v147
	v_exp_f32_e32 v156, v156
	s_nop 0
	v_add_f32_e32 v149, 1.0, v149
	v_add_f32_e32 v155, 1.0, v155
	v_exp_f32_e32 v164, v147
	v_rcp_f32_e32 v147, v149
	v_rcp_f32_e32 v149, v155
	v_add_f32_e32 v156, 1.0, v156
	v_rcp_f32_e32 v155, v156
	v_fma_f32 v156, -v164, v164, 1.0
	v_max_f32_e32 v156, 0, v156
	v_mul_f32_e32 v149, v214, v149
	v_sqrt_f32_e32 v156, v156
	s_nop 0
	v_exp_f32_e32 v149, v149
	v_fma_f32 v158, v167, s98, v170
	v_mul_f32_e32 v147, v147, v156
	v_mul_f32_e32 v163, v147, v80
	v_fma_f32 v147, -v149, v149, 1.0
	v_fma_f32 v156, v166, s98, v170
	v_max_f32_e32 v147, 0, v147
	s_nop 0
	v_sqrt_f32_e32 v147, v147
	v_exp_f32_e32 v156, v156
	v_fma_f32 v80, v178, s98, v171
	s_nop 0
	v_exp_f32_e32 v80, v80
	v_mul_f32_e32 v147, v155, v147
	v_add_f32_e32 v155, 1.0, v156
	v_fma_f32 v156, v179, s98, v171
	s_nop 0
	v_exp_f32_e32 v156, v156
	v_add_f32_e32 v80, 1.0, v80
	v_rcp_f32_e32 v80, v80
	s_nop 0
	v_add_f32_e32 v156, 1.0, v156
	v_rcp_f32_e32 v156, v156
	v_mul_f32_e32 v80, v214, v80
	s_nop 0
	v_exp_f32_e32 v80, v80
	v_mul_f32_e32 v156, v214, v156
	s_nop 0
	v_exp_f32_e32 v156, v156
	v_exp_f32_e32 v158, v158
	v_fma_f32 v157, -v80, v80, 1.0
	v_max_f32_e32 v157, 0, v157
	v_rcp_f32_e32 v155, v155
	v_sqrt_f32_e32 v157, v157
	v_fma_f32 v160, -v156, v156, 1.0
	v_add_f32_e32 v158, 1.0, v158
	v_max_f32_e32 v160, 0, v160
	v_rcp_f32_e32 v158, v158
	v_sqrt_f32_e32 v160, v160
	v_mul_f32_e32 v162, v149, v163
	v_fmac_f32_e32 v162, v147, v81
	v_mul_f32_e32 v155, v155, v157
	v_mul_f32_e32 v161, v80, v162
	v_mul_f32_e32 v165, v149, v164
	v_fmac_f32_e32 v161, v155, v82
	v_mul_f32_e32 v157, v158, v160
	v_mul_f32_e32 v166, v80, v165
	v_mul_f32_e32 v160, v156, v161
	v_mul_f32_e32 v167, v156, v166
	v_fmac_f32_e32 v160, v157, v83
	ds_bpermute_b32 v155, v210, v167
	ds_bpermute_b32 v147, v210, v160
	ds_bpermute_b32 v156, v212, v167
	ds_bpermute_b32 v149, v212, v160
	ds_bpermute_b32 v157, v211, v167
	ds_bpermute_b32 v174, v211, v160
	ds_bpermute_b32 v176, v218, v167
	ds_bpermute_b32 v182, v218, v160
	s_waitcnt lgkmcnt(6)
	v_fmac_f32_e32 v147, v159, v155
	s_waitcnt lgkmcnt(4)
	v_fmac_f32_e32 v149, v147, v156
	s_waitcnt lgkmcnt(2)
	v_fmac_f32_e32 v174, v149, v157
	s_and_saveexec_b64 s[4:5], s[0:1]
	s_cbranch_execz .LBB0_599
	v_cmp_ne_u32_e64 s[0:1], 1, v200
	s_and_saveexec_b64 s[34:35], s[0:1]
	s_xor_b64 s[0:1], exec, s[34:35]
	v_cndmask_b32_e32 v159, v174, v149, vcc
	s_andn2_saveexec_b64 s[0:1], s[0:1]
	v_mov_b32_e32 v159, v147
	s_or_b64 exec, exec, s[0:1]
.LBB0_599:
	s_or_b64 exec, exec, s[4:5]
	v_mfma_f32_16x16x32_bf16 v[154:157], v[70:73], v[34:37], 0
	ds_read_u16 v80, v213 offset:33824
	v_fmac_f32_e32 v146, v173, v175
	v_cmp_lt_i32_e64 s[0:1], 0, v200
	v_mfma_f32_16x16x32_bf16 v[202:205], v[70:73], v[42:45], 0
	v_mfma_f32_16x16x32_bf16 v[70:73], v[66:69], v[38:41], v[154:157]
	v_mfma_f32_16x16x32_bf16 v[66:69], v[66:69], v[46:49], v[202:205]
	s_nop 6
	v_fma_f32 v70, v70, s98, v169
	s_nop 0
	v_exp_f32_e32 v70, v70
	v_fma_f32 v66, v66, s98, v168
	s_nop 0
	v_exp_f32_e32 v66, v66
	v_add_f32_e32 v70, 1.0, v70
	v_rcp_f32_e32 v70, v70
	v_fma_f32 v72, v72, s98, v169
	v_add_f32_e32 v66, 1.0, v66
	v_rcp_f32_e32 v66, v66
	v_mul_f32_e32 v70, v215, v70
	s_nop 0
	v_exp_f32_e32 v148, v70
	s_nop 0
	v_exp_f32_e32 v72, v72
	v_fma_f32 v67, v67, s98, v168
	v_fma_f32 v70, -v148, v148, 1.0
	v_max_f32_e32 v70, 0, v70
	v_sqrt_f32_e32 v70, v70
	v_fma_f32 v73, v73, s98, v169
	s_nop 0
	v_add_f32_e32 v72, 1.0, v72
	v_mul_f32_e32 v66, v66, v70
	v_fma_f32 v70, v71, s98, v169
	s_nop 0
	v_exp_f32_e32 v70, v70
	s_nop 0
	v_exp_f32_e32 v67, v67
	v_rcp_f32_e32 v72, v72
	v_add_f32_e32 v70, 1.0, v70
	v_rcp_f32_e32 v70, v70
	v_exp_f32_e32 v73, v73
	v_add_f32_e32 v67, 1.0, v67
	v_mul_f32_e32 v72, v215, v72
	v_mul_f32_e32 v70, v215, v70
	s_nop 0
	v_exp_f32_e32 v70, v70
	v_add_f32_e32 v73, 1.0, v73
	v_rcp_f32_e32 v67, v67
	v_fma_f32 v68, v68, s98, v168
	v_fma_f32 v71, -v70, v70, 1.0
	v_max_f32_e32 v71, 0, v71
	v_sqrt_f32_e32 v71, v71
	s_nop 0
	v_rcp_f32_e32 v73, v73
	s_nop 0
	v_exp_f32_e32 v72, v72
	v_exp_f32_e32 v68, v68
	v_mul_f32_e32 v67, v67, v71
	ds_read_u16 v71, v213 offset:34880
	s_waitcnt lgkmcnt(1)
	v_lshlrev_b32_e32 v80, 16, v80
	v_mul_f32_e32 v73, v215, v73
	v_mul_f32_e32 v147, v66, v80
	v_fma_f32 v80, -v72, v72, 1.0
	v_fma_f32 v69, v69, s98, v168
	s_nop 0
	v_add_f32_e32 v68, 1.0, v68
	v_max_f32_e32 v80, 0, v80
	s_nop 0
	v_exp_f32_e32 v73, v73
	ds_read_u16 v66, v213 offset:34352
	v_rcp_f32_e32 v68, v68
	v_sqrt_f32_e32 v80, v80
	v_exp_f32_e32 v69, v69
	v_fma_f32 v81, -v73, v73, 1.0
	v_max_f32_e32 v81, 0, v81
	v_mul_f32_e32 v68, v68, v80
	ds_read_u16 v80, v213 offset:35408
	v_add_f32_e32 v69, 1.0, v69
	s_waitcnt lgkmcnt(1)
	v_lshlrev_b32_e32 v66, 16, v66
	v_rcp_f32_e32 v69, v69
	v_sqrt_f32_e32 v81, v81
	v_mul_f32_e32 v155, v70, v147
	v_fmac_f32_e32 v155, v67, v66
	v_lshlrev_b32_e32 v71, 16, v71
	v_mul_f32_e32 v154, v72, v155
	v_mul_f32_e32 v156, v70, v148
	v_fmac_f32_e32 v154, v68, v71
	s_waitcnt lgkmcnt(0)
	v_lshlrev_b32_e32 v80, 16, v80
	v_mul_f32_e32 v69, v69, v81
	v_mul_f32_e32 v157, v72, v156
	v_mul_f32_e32 v149, v73, v154
	v_mul_f32_e32 v158, v73, v157
	v_fmac_f32_e32 v149, v69, v80
	ds_bpermute_b32 v68, v210, v158
	ds_bpermute_b32 v66, v210, v149
	ds_bpermute_b32 v69, v212, v158
	ds_bpermute_b32 v67, v212, v149
	ds_bpermute_b32 v70, v211, v158
	ds_bpermute_b32 v208, v211, v149
	ds_bpermute_b32 v209, v218, v158
	ds_bpermute_b32 v172, v218, v149
	s_waitcnt lgkmcnt(6)
	v_fmac_f32_e32 v66, v146, v68
	s_waitcnt lgkmcnt(4)
	v_fmac_f32_e32 v67, v66, v69
	s_waitcnt lgkmcnt(2)
	v_fmac_f32_e32 v208, v67, v70
	s_and_saveexec_b64 s[4:5], s[0:1]
	s_cbranch_execz .LBB0_605
	v_cmp_ne_u32_e64 s[0:1], 1, v200
	s_and_saveexec_b64 s[34:35], s[0:1]
	s_xor_b64 s[0:1], exec, s[34:35]
	v_cndmask_b32_e32 v146, v208, v67, vcc
	s_andn2_saveexec_b64 s[0:1], s[0:1]
	v_mov_b32_e32 v146, v66
	s_or_b64 exec, exec, s[0:1]
; template <int DIR, int MODE>
; __device__ __forceinline__ void lru_pass(const Args& a, const LAS bf16_t* cxb, LAS bf16_t* gyb, const LAS float* carry, const bf16x8 (&Bw)[2][2][2], const float (&prm)[2][3], int l, int tt, float (&hf)[8][2][4]) {
;     ...
;     for (int mi = 0; mi < 8; ++mi) {
;         const int m = DIR ? 7 - mi : mi;
;         bf16x8 Af[2];
; #pragma unroll
;         for (int ks = 0; ks < 2; ++ks) Af[ks] = *(const LAS bf16x8*)(cxb + (m * 16 + fr) * CXS + 64 * h + 32 * ks + 8 * fq);
; #pragma unroll
;         for (int nt = 0; nt < 2; ++nt) {
;             f32x4 pr = (f32x4){0.f, 0.f, 0.f, 0.f}, pi = (f32x4){0.f, 0.f, 0.f, 0.f};
; #pragma unroll
;             for (int ks = 0; ks < 2; ++ks) { pr = __builtin_amdgcn_mfma_f32_16x16x32_bf16(Af[ks], Bw[0][nt][ks], pr, 0, 0, 0); pi = __builtin_amdgcn_mfma_f32_16x16x32_bf16(Af[ks], Bw[1][nt][ks], pi, 0, 0, 0); }
;             float av[4], bv[4];
; #pragma unroll
;             for (int reg = 0; reg < 4; ++reg) {
;                 const int tok = m * 16 + 4 * fq + reg;
;                 const float x = bf2f(cxb[tok * CXS + cc[nt]]);
;                 const float r = fsig(pr[reg] + ba[nt]), ig = fsig(pi[reg] + bxv[nt]);
;                 const float aa = __expf(k8[nt] * r);
;                 av[reg] = aa; bv[reg] = __builtin_amdgcn_sqrtf(fmaxf(1.0f - aa * aa, 0.f)) * ig * x;
;             }
;             float cum[4], hl[4];
;             if (DIR == 0) { cum[0] = av[0]; hl[0] = bv[0];
; #pragma unroll
;                 for (int reg = 1; reg < 4; ++reg) { cum[reg] = cum[reg - 1] * av[reg]; hl[reg] = av[reg] * hl[reg - 1] + bv[reg]; } }
;             else { cum[3] = av[3]; hl[3] = bv[3];
; #pragma unroll
;     ...
;             const float A4 = DIR ? cum[0] : cum[3], H4 = DIR ? hl[0] : hl[3];
;             float Aq[4], Hq[4];
; #pragma unroll
;             for (int q = 0; q < 4; ++q) { Aq[q] = __shfl(A4, fr + 16 * q); Hq[q] = __shfl(H4, fr + 16 * q); }
;             float hin;
;             if (DIR == 0) { const float s0 = C[nt], s1 = Aq[0] * s0 + Hq[0], s2 = Aq[1] * s1 + Hq[1], s3 = Aq[2] * s2 + Hq[2]; C[nt] = Aq[3] * s3 + Hq[3]; hin = fq == 0 ? s0 : (fq == 1 ? s1 : (fq == 2 ? s2 : s3)); }
;             else { const float s3 = C[nt], s2 = Aq[3] * s3 + Hq[3], s1 = Aq[2] * s2 + Hq[2], s0 = Aq[1] * s1 + Hq[1]; C[nt] = Aq[0] * s0 + Hq[0]; hin = fq == 3 ? s3 : (fq == 2 ? s2 : (fq == 1 ? s1 : s0)); }
.LBB0_605:
	s_or_b64 exec, exec, s[4:5]
	ds_read_b128 v[70:73], v220 offset:42240
	ds_read_b128 v[66:69], v220 offset:42304
	ds_read_u16 v80, v213 offset:42240
	ds_read_u16 v81, v213 offset:42768
	ds_read_u16 v82, v213 offset:43296
	ds_read_u16 v83, v213 offset:43824
	v_fmac_f32_e32 v182, v174, v176
	s_waitcnt lgkmcnt(5)
	v_mfma_f32_16x16x32_bf16 v[202:205], v[70:73], v[50:53], 0
	s_waitcnt lgkmcnt(2)
	v_lshlrev_b32_e32 v81, 16, v81
	v_lshlrev_b32_e32 v80, 16, v80
	s_waitcnt lgkmcnt(1)
	v_lshlrev_b32_e32 v82, 16, v82
	v_mfma_f32_16x16x32_bf16 v[202:205], v[66:69], v[54:57], v[202:205]
	s_waitcnt lgkmcnt(0)
	v_lshlrev_b32_e32 v83, 16, v83
	v_cmp_lt_i32_e64 s[0:1], 0, v200
	v_mfma_f32_16x16x32_bf16 v[230:233], v[70:73], v[58:61], 0
	v_mfma_f32_16x16x32_bf16 v[230:233], v[66:69], v[62:65], v[230:233]
	s_nop 2
	v_fma_f32 v173, v202, s98, v171
	s_nop 0
	v_exp_f32_e32 v173, v173
	v_fma_f32 v177, v203, s98, v171
	s_nop 0
	v_fma_f32 v175, v230, s98, v170
	v_add_f32_e32 v173, 1.0, v173
	v_rcp_f32_e32 v173, v173
	s_nop 0
	v_exp_f32_e32 v175, v175
	v_exp_f32_e32 v177, v177
	v_fma_f32 v178, v231, s98, v170
	s_nop 0
	v_mul_f32_e32 v173, v214, v173
	v_exp_f32_e32 v178, v178
	s_nop 0
	v_add_f32_e32 v175, 1.0, v175
	v_add_f32_e32 v177, 1.0, v177
	v_exp_f32_e32 v203, v173
	v_rcp_f32_e32 v173, v175
	v_rcp_f32_e32 v175, v177
	v_add_f32_e32 v178, 1.0, v178
	v_rcp_f32_e32 v177, v178
	v_fma_f32 v178, -v203, v203, 1.0
	v_max_f32_e32 v178, 0, v178
	v_mul_f32_e32 v175, v214, v175
	v_sqrt_f32_e32 v178, v178
	s_nop 0
	v_exp_f32_e32 v175, v175
	v_fma_f32 v180, v233, s98, v170
	v_mul_f32_e32 v173, v173, v178
	v_mul_f32_e32 v202, v173, v80
	v_fma_f32 v173, -v175, v175, 1.0
	v_fma_f32 v178, v232, s98, v170
	v_max_f32_e32 v173, 0, v173
	s_nop 0
	v_sqrt_f32_e32 v173, v173
	v_exp_f32_e32 v178, v178
	v_fma_f32 v80, v204, s98, v171
	s_nop 0
	v_exp_f32_e32 v80, v80
	v_mul_f32_e32 v173, v177, v173
	v_add_f32_e32 v177, 1.0, v178
	v_fma_f32 v178, v205, s98, v171
	s_nop 0
	v_exp_f32_e32 v178, v178
	v_add_f32_e32 v80, 1.0, v80
	v_rcp_f32_e32 v80, v80
	s_nop 0
	v_add_f32_e32 v178, 1.0, v178
	v_rcp_f32_e32 v178, v178
	v_mul_f32_e32 v80, v214, v80
	s_nop 0
	v_exp_f32_e32 v80, v80
	v_mul_f32_e32 v178, v214, v178
	s_nop 0
	v_exp_f32_e32 v178, v178
	v_exp_f32_e32 v180, v180
	v_fma_f32 v179, -v80, v80, 1.0
	v_max_f32_e32 v179, 0, v179
	v_rcp_f32_e32 v177, v177
	v_sqrt_f32_e32 v179, v179
	v_fma_f32 v198, -v178, v178, 1.0
	v_add_f32_e32 v180, 1.0, v180
	v_max_f32_e32 v198, 0, v198
	v_rcp_f32_e32 v180, v180
	v_sqrt_f32_e32 v198, v198
	v_mul_f32_e32 v201, v175, v202
	v_fmac_f32_e32 v201, v173, v81
	v_mul_f32_e32 v177, v177, v179
	v_mul_f32_e32 v199, v80, v201
	v_mul_f32_e32 v204, v175, v203
	v_fmac_f32_e32 v199, v177, v82
	v_mul_f32_e32 v179, v180, v198
	v_mul_f32_e32 v205, v80, v204
	v_mul_f32_e32 v198, v178, v199
	v_mul_f32_e32 v206, v178, v205
	v_fmac_f32_e32 v198, v179, v83
	ds_bpermute_b32 v177, v210, v206
	ds_bpermute_b32 v173, v210, v198
	ds_bpermute_b32 v178, v212, v206
	ds_bpermute_b32 v175, v212, v198
	ds_bpermute_b32 v179, v211, v206
	ds_bpermute_b32 v217, v211, v198
	ds_bpermute_b32 v219, v218, v206
	ds_bpermute_b32 v224, v218, v198
	s_waitcnt lgkmcnt(6)
	v_fmac_f32_e32 v173, v182, v177
	s_waitcnt lgkmcnt(4)
	v_fmac_f32_e32 v175, v173, v178
	s_waitcnt lgkmcnt(2)
	v_fmac_f32_e32 v217, v175, v179
	s_and_saveexec_b64 s[4:5], s[0:1]
	s_cbranch_execz .LBB0_611
	v_cmp_ne_u32_e64 s[0:1], 1, v200
	s_and_saveexec_b64 s[34:35], s[0:1]
	s_xor_b64 s[0:1], exec, s[34:35]
	v_cndmask_b32_e32 v182, v217, v175, vcc
	s_andn2_saveexec_b64 s[0:1], s[0:1]
	v_mov_b32_e32 v182, v173
	s_or_b64 exec, exec, s[0:1]
.LBB0_611:
	s_or_b64 exec, exec, s[4:5]
	v_mfma_f32_16x16x32_bf16 v[174:177], v[70:73], v[34:37], 0
	ds_read_u16 v80, v213 offset:42272
	v_fmac_f32_e32 v172, v208, v209
	v_cmp_lt_i32_e64 s[0:1], 0, v200
	v_mfma_f32_16x16x32_bf16 v[230:233], v[70:73], v[42:45], 0
	v_mfma_f32_16x16x32_bf16 v[70:73], v[66:69], v[38:41], v[174:177]
	v_mfma_f32_16x16x32_bf16 v[66:69], v[66:69], v[46:49], v[230:233]
	s_nop 6
	v_fma_f32 v70, v70, s98, v169
	s_nop 0
	v_exp_f32_e32 v70, v70
	v_fma_f32 v66, v66, s98, v168
	s_nop 0
	v_exp_f32_e32 v66, v66
	v_add_f32_e32 v70, 1.0, v70
	v_rcp_f32_e32 v70, v70
	v_fma_f32 v72, v72, s98, v169
	v_add_f32_e32 v66, 1.0, v66
	v_rcp_f32_e32 v66, v66
	v_mul_f32_e32 v70, v215, v70
	s_nop 0
	v_exp_f32_e32 v174, v70
	s_nop 0
	v_exp_f32_e32 v72, v72
	v_fma_f32 v67, v67, s98, v168
	v_fma_f32 v70, -v174, v174, 1.0
	v_max_f32_e32 v70, 0, v70
	v_sqrt_f32_e32 v70, v70
	v_fma_f32 v73, v73, s98, v169
	s_nop 0
	v_add_f32_e32 v72, 1.0, v72
	v_mul_f32_e32 v66, v66, v70
	v_fma_f32 v70, v71, s98, v169
	s_nop 0
	v_exp_f32_e32 v70, v70
	s_nop 0
	v_exp_f32_e32 v67, v67
	v_rcp_f32_e32 v72, v72
	v_add_f32_e32 v70, 1.0, v70
	v_rcp_f32_e32 v70, v70
	v_exp_f32_e32 v73, v73
	v_add_f32_e32 v67, 1.0, v67
	v_mul_f32_e32 v72, v215, v72
	v_mul_f32_e32 v70, v215, v70
	s_nop 0
	v_exp_f32_e32 v70, v70
	v_add_f32_e32 v73, 1.0, v73
	v_rcp_f32_e32 v67, v67
	v_fma_f32 v68, v68, s98, v168
	v_fma_f32 v71, -v70, v70, 1.0
	v_max_f32_e32 v71, 0, v71
	v_sqrt_f32_e32 v71, v71
	s_nop 0
	v_rcp_f32_e32 v73, v73
	s_nop 0
	v_exp_f32_e32 v72, v72
	v_exp_f32_e32 v68, v68
	v_mul_f32_e32 v67, v67, v71
	ds_read_u16 v71, v213 offset:43328
	s_waitcnt lgkmcnt(1)
	v_lshlrev_b32_e32 v80, 16, v80
	v_mul_f32_e32 v73, v215, v73
	v_mul_f32_e32 v173, v66, v80
	v_fma_f32 v80, -v72, v72, 1.0
	v_fma_f32 v69, v69, s98, v168
	s_nop 0
	v_add_f32_e32 v68, 1.0, v68
	v_max_f32_e32 v80, 0, v80
	s_nop 0
	v_exp_f32_e32 v73, v73
	ds_read_u16 v66, v213 offset:42800
	v_rcp_f32_e32 v68, v68
	v_sqrt_f32_e32 v80, v80
	v_exp_f32_e32 v69, v69
	v_fma_f32 v81, -v73, v73, 1.0
	v_max_f32_e32 v81, 0, v81
	v_mul_f32_e32 v68, v68, v80
	ds_read_u16 v80, v213 offset:43856
	v_add_f32_e32 v69, 1.0, v69
	s_waitcnt lgkmcnt(1)
	v_lshlrev_b32_e32 v66, 16, v66
	v_rcp_f32_e32 v69, v69
	v_sqrt_f32_e32 v81, v81
	v_mul_f32_e32 v177, v70, v173
	v_fmac_f32_e32 v177, v67, v66
	v_lshlrev_b32_e32 v71, 16, v71
	v_mul_f32_e32 v176, v72, v177
	v_mul_f32_e32 v178, v70, v174
	v_fmac_f32_e32 v176, v68, v71
	s_waitcnt lgkmcnt(0)
	v_lshlrev_b32_e32 v80, 16, v80
	v_mul_f32_e32 v69, v69, v81
	v_mul_f32_e32 v179, v72, v178
	v_mul_f32_e32 v175, v73, v176
	v_mul_f32_e32 v180, v73, v179
	v_fmac_f32_e32 v175, v69, v80
	ds_bpermute_b32 v68, v210, v180
	ds_bpermute_b32 v66, v210, v175
	ds_bpermute_b32 v69, v212, v180
	ds_bpermute_b32 v67, v212, v175
	ds_bpermute_b32 v70, v211, v180
	ds_bpermute_b32 v243, v211, v175
	ds_bpermute_b32 v236, v218, v180
	ds_bpermute_b32 v216, v218, v175
	s_waitcnt lgkmcnt(6)
	v_fmac_f32_e32 v66, v172, v68
	s_waitcnt lgkmcnt(4)
	v_fmac_f32_e32 v67, v66, v69
	s_waitcnt lgkmcnt(2)
	v_fmac_f32_e32 v243, v67, v70
	s_and_saveexec_b64 s[4:5], s[0:1]
	s_cbranch_execz .LBB0_617
	v_cmp_ne_u32_e64 s[0:1], 1, v200
	s_and_saveexec_b64 s[34:35], s[0:1]
	s_xor_b64 s[0:1], exec, s[34:35]
	v_cndmask_b32_e32 v172, v243, v67, vcc
	s_andn2_saveexec_b64 s[0:1], s[0:1]
	v_mov_b32_e32 v172, v66
	s_or_b64 exec, exec, s[0:1]
; template <int DIR, int MODE>
; __device__ __forceinline__ void lru_pass(const Args& a, const LAS bf16_t* cxb, LAS bf16_t* gyb, const LAS float* carry, const bf16x8 (&Bw)[2][2][2], const float (&prm)[2][3], int l, int tt, float (&hf)[8][2][4]) {
;     ...
;     for (int mi = 0; mi < 8; ++mi) {
;         const int m = DIR ? 7 - mi : mi;
;         bf16x8 Af[2];
; #pragma unroll
;         for (int ks = 0; ks < 2; ++ks) Af[ks] = *(const LAS bf16x8*)(cxb + (m * 16 + fr) * CXS + 64 * h + 32 * ks + 8 * fq);
; #pragma unroll
;         for (int nt = 0; nt < 2; ++nt) {
;             f32x4 pr = (f32x4){0.f, 0.f, 0.f, 0.f}, pi = (f32x4){0.f, 0.f, 0.f, 0.f};
; #pragma unroll
;             for (int ks = 0; ks < 2; ++ks) { pr = __builtin_amdgcn_mfma_f32_16x16x32_bf16(Af[ks], Bw[0][nt][ks], pr, 0, 0, 0); pi = __builtin_amdgcn_mfma_f32_16x16x32_bf16(Af[ks], Bw[1][nt][ks], pi, 0, 0, 0); }
;             float av[4], bv[4];
; #pragma unroll
;             for (int reg = 0; reg < 4; ++reg) {
;                 const int tok = m * 16 + 4 * fq + reg;
;                 const float x = bf2f(cxb[tok * CXS + cc[nt]]);
;                 const float r = fsig(pr[reg] + ba[nt]), ig = fsig(pi[reg] + bxv[nt]);
;                 const float aa = __expf(k8[nt] * r);
;                 av[reg] = aa; bv[reg] = __builtin_amdgcn_sqrtf(fmaxf(1.0f - aa * aa, 0.f)) * ig * x;
;             }
;             float cum[4], hl[4];
;             if (DIR == 0) { cum[0] = av[0]; hl[0] = bv[0];
; #pragma unroll
;                 for (int reg = 1; reg < 4; ++reg) { cum[reg] = cum[reg - 1] * av[reg]; hl[reg] = av[reg] * hl[reg - 1] + bv[reg]; } }
;             else { cum[3] = av[3]; hl[3] = bv[3];
; #pragma unroll
;     ...
;             const float A4 = DIR ? cum[0] : cum[3], H4 = DIR ? hl[0] : hl[3];
;             float Aq[4], Hq[4];
; #pragma unroll
;             for (int q = 0; q < 4; ++q) { Aq[q] = __shfl(A4, fr + 16 * q); Hq[q] = __shfl(H4, fr + 16 * q); }
;             float hin;
;             if (DIR == 0) { const float s0 = C[nt], s1 = Aq[0] * s0 + Hq[0], s2 = Aq[1] * s1 + Hq[1], s3 = Aq[2] * s2 + Hq[2]; C[nt] = Aq[3] * s3 + Hq[3]; hin = fq == 0 ? s0 : (fq == 1 ? s1 : (fq == 2 ? s2 : s3)); }
;             else { const float s3 = C[nt], s2 = Aq[3] * s3 + Hq[3], s1 = Aq[2] * s2 + Hq[2], s0 = Aq[1] * s1 + Hq[1]; C[nt] = Aq[0] * s0 + Hq[0]; hin = fq == 3 ? s3 : (fq == 2 ? s2 : (fq == 1 ? s1 : s0)); }
.LBB0_617:
	s_or_b64 exec, exec, s[4:5]
	ds_read_b128 v[70:73], v220 offset:50688
	ds_read_b128 v[66:69], v220 offset:50752
	ds_read_u16 v80, v213 offset:50688
	ds_read_u16 v81, v213 offset:51216
	ds_read_u16 v82, v213 offset:51744
	ds_read_u16 v83, v213 offset:52272
	v_fmac_f32_e32 v224, v217, v219
	s_waitcnt lgkmcnt(5)
	v_mfma_f32_16x16x32_bf16 v[230:233], v[70:73], v[50:53], 0
	s_waitcnt lgkmcnt(2)
	v_lshlrev_b32_e32 v81, 16, v81
	v_lshlrev_b32_e32 v80, 16, v80
	s_waitcnt lgkmcnt(1)
	v_lshlrev_b32_e32 v82, 16, v82
	v_mfma_f32_16x16x32_bf16 v[238:241], v[66:69], v[54:57], v[230:233]
	s_waitcnt lgkmcnt(0)
	v_lshlrev_b32_e32 v83, 16, v83
	v_cmp_lt_i32_e64 s[0:1], 0, v200
	v_mfma_f32_16x16x32_bf16 v[246:249], v[70:73], v[58:61], 0
	v_mfma_f32_16x16x32_bf16 v[246:249], v[66:69], v[62:65], v[246:249]
	s_nop 2
	v_fma_f32 v208, v238, s98, v171
	s_nop 0
	v_exp_f32_e32 v208, v208
	v_fma_f32 v221, v239, s98, v171
	s_nop 0
	v_fma_f32 v209, v246, s98, v170
	v_add_f32_e32 v208, 1.0, v208
	v_rcp_f32_e32 v208, v208
	s_nop 0
	v_exp_f32_e32 v209, v209
	v_exp_f32_e32 v221, v221
	v_fma_f32 v223, v247, s98, v170
	s_nop 0
	v_mul_f32_e32 v208, v214, v208
	v_exp_f32_e32 v223, v223
	s_nop 0
	v_add_f32_e32 v209, 1.0, v209
	v_add_f32_e32 v221, 1.0, v221
	v_exp_f32_e32 v233, v208
	v_rcp_f32_e32 v208, v209
	v_rcp_f32_e32 v209, v221
	v_add_f32_e32 v223, 1.0, v223
	v_rcp_f32_e32 v221, v223
	v_fma_f32 v223, -v233, v233, 1.0
	v_max_f32_e32 v223, 0, v223
	v_mul_f32_e32 v209, v214, v209
	v_sqrt_f32_e32 v223, v223
	s_nop 0
	v_exp_f32_e32 v209, v209
	v_fma_f32 v228, v249, s98, v170
	v_mul_f32_e32 v208, v208, v223
	v_mul_f32_e32 v232, v208, v80
	v_fma_f32 v208, -v209, v209, 1.0
	v_fma_f32 v223, v248, s98, v170
	v_max_f32_e32 v208, 0, v208
	s_nop 0
	v_sqrt_f32_e32 v208, v208
	v_exp_f32_e32 v223, v223
	v_fma_f32 v80, v240, s98, v171
	s_nop 0
	v_exp_f32_e32 v80, v80
	v_mul_f32_e32 v221, v221, v208
	v_add_f32_e32 v208, 1.0, v223
	v_fma_f32 v223, v241, s98, v171
	s_nop 0
	v_exp_f32_e32 v223, v223
	v_add_f32_e32 v80, 1.0, v80
	v_rcp_f32_e32 v80, v80
	s_nop 0
	v_add_f32_e32 v223, 1.0, v223
	v_rcp_f32_e32 v223, v223
	v_mul_f32_e32 v80, v214, v80
	s_nop 0
	v_exp_f32_e32 v80, v80
	v_mul_f32_e32 v223, v214, v223
	s_nop 0
	v_exp_f32_e32 v223, v223
	v_exp_f32_e32 v228, v228
	v_fma_f32 v225, -v80, v80, 1.0
	v_max_f32_e32 v225, 0, v225
	v_rcp_f32_e32 v208, v208
	v_sqrt_f32_e32 v225, v225
	v_fma_f32 v230, -v223, v223, 1.0
	v_add_f32_e32 v228, 1.0, v228
	v_max_f32_e32 v230, 0, v230
	v_rcp_f32_e32 v228, v228
	v_sqrt_f32_e32 v230, v230
	v_mul_f32_e32 v239, v209, v232
	v_fmac_f32_e32 v239, v221, v81
	v_mul_f32_e32 v225, v208, v225
	v_mul_f32_e32 v238, v80, v239
	v_mul_f32_e32 v208, v209, v233
	v_fmac_f32_e32 v238, v225, v82
	v_mul_f32_e32 v230, v228, v230
	v_mul_f32_e32 v209, v80, v208
	v_mul_f32_e32 v225, v223, v238
	v_mul_f32_e32 v228, v223, v209
	v_fmac_f32_e32 v225, v230, v83
	ds_bpermute_b32 v242, v210, v228
	ds_bpermute_b32 v221, v210, v225
	ds_bpermute_b32 v246, v212, v228
	ds_bpermute_b32 v241, v212, v225
	ds_bpermute_b32 v247, v211, v228
	ds_bpermute_b32 v231, v211, v225
	ds_bpermute_b32 v223, v218, v228
	ds_bpermute_b32 v230, v218, v225
	s_waitcnt lgkmcnt(6)
	v_fmac_f32_e32 v221, v224, v242
	s_waitcnt lgkmcnt(4)
	v_fmac_f32_e32 v241, v221, v246
	s_waitcnt lgkmcnt(2)
	v_fmac_f32_e32 v231, v241, v247
	s_and_saveexec_b64 s[4:5], s[0:1]
	s_cbranch_execz .LBB0_623
	v_cmp_ne_u32_e64 s[0:1], 1, v200
	s_and_saveexec_b64 s[34:35], s[0:1]
	s_xor_b64 s[0:1], exec, s[34:35]
	v_cndmask_b32_e32 v224, v231, v241, vcc
	s_andn2_saveexec_b64 s[0:1], s[0:1]
	v_mov_b32_e32 v224, v221
	s_or_b64 exec, exec, s[0:1]
; template <int DIR, int MODE>
; __device__ __forceinline__ void lru_pass(const Args& a, const LAS bf16_t* cxb, LAS bf16_t* gyb, const LAS float* carry, const bf16x8 (&Bw)[2][2][2], const float (&prm)[2][3], int l, int tt, float (&hf)[8][2][4]) {
;     ...
;     for (int mi = 0; mi < 8; ++mi) {
;         const int m = DIR ? 7 - mi : mi;
;         bf16x8 Af[2];
; #pragma unroll
;         for (int ks = 0; ks < 2; ++ks) Af[ks] = *(const LAS bf16x8*)(cxb + (m * 16 + fr) * CXS + 64 * h + 32 * ks + 8 * fq);
; #pragma unroll
;         for (int nt = 0; nt < 2; ++nt) {
;             f32x4 pr = (f32x4){0.f, 0.f, 0.f, 0.f}, pi = (f32x4){0.f, 0.f, 0.f, 0.f};
; #pragma unroll
;             for (int ks = 0; ks < 2; ++ks) { pr = __builtin_amdgcn_mfma_f32_16x16x32_bf16(Af[ks], Bw[0][nt][ks], pr, 0, 0, 0); pi = __builtin_amdgcn_mfma_f32_16x16x32_bf16(Af[ks], Bw[1][nt][ks], pi, 0, 0, 0); }
;             float av[4], bv[4];
; #pragma unroll
;             for (int reg = 0; reg < 4; ++reg) {
;                 const int tok = m * 16 + 4 * fq + reg;
;                 const float x = bf2f(cxb[tok * CXS + cc[nt]]);
;                 const float r = fsig(pr[reg] + ba[nt]), ig = fsig(pi[reg] + bxv[nt]);
;                 const float aa = __expf(k8[nt] * r);
;                 av[reg] = aa; bv[reg] = __builtin_amdgcn_sqrtf(fmaxf(1.0f - aa * aa, 0.f)) * ig * x;
;             }
;             float cum[4], hl[4];
;             if (DIR == 0) { cum[0] = av[0]; hl[0] = bv[0];
; #pragma unroll
;                 for (int reg = 1; reg < 4; ++reg) { cum[reg] = cum[reg - 1] * av[reg]; hl[reg] = av[reg] * hl[reg - 1] + bv[reg]; } }
;             else { cum[3] = av[3]; hl[3] = bv[3];
; #pragma unroll
;     ...
;             const float A4 = DIR ? cum[0] : cum[3], H4 = DIR ? hl[0] : hl[3];
;             float Aq[4], Hq[4];
; #pragma unroll
;             for (int q = 0; q < 4; ++q) { Aq[q] = __shfl(A4, fr + 16 * q); Hq[q] = __shfl(H4, fr + 16 * q); }
;             float hin;
;             if (DIR == 0) { const float s0 = C[nt], s1 = Aq[0] * s0 + Hq[0], s2 = Aq[1] * s1 + Hq[1], s3 = Aq[2] * s2 + Hq[2]; C[nt] = Aq[3] * s3 + Hq[3]; hin = fq == 0 ? s0 : (fq == 1 ? s1 : (fq == 2 ? s2 : s3)); }
;             else { const float s3 = C[nt], s2 = Aq[3] * s3 + Hq[3], s1 = Aq[2] * s2 + Hq[2], s0 = Aq[1] * s1 + Hq[1]; C[nt] = Aq[0] * s0 + Hq[0]; hin = fq == 3 ? s3 : (fq == 2 ? s2 : (fq == 1 ? s1 : s0)); }
.LBB0_623:
	s_or_b64 exec, exec, s[4:5]
	v_mfma_f32_16x16x32_bf16 v[246:249], v[70:73], v[34:37], 0
	v_fmac_f32_e32 v216, v243, v236
	v_cmp_lt_i32_e64 s[0:1], 0, v200
	v_mfma_f32_16x16x32_bf16 v[80:83], v[70:73], v[42:45], 0
	v_mfma_f32_16x16x32_bf16 v[70:73], v[66:69], v[38:41], v[246:249]
	v_mfma_f32_16x16x32_bf16 v[66:69], v[66:69], v[46:49], v[80:83]
	s_nop 5
	ds_read_u16 v80, v213 offset:50720
	v_fma_f32 v70, v70, s98, v169
	s_nop 0
	v_exp_f32_e32 v70, v70
	v_fma_f32 v66, v66, s98, v168
	s_nop 0
	v_exp_f32_e32 v66, v66
	v_add_f32_e32 v70, 1.0, v70
	v_rcp_f32_e32 v70, v70
	v_fma_f32 v72, v72, s98, v169
	v_add_f32_e32 v66, 1.0, v66
	v_rcp_f32_e32 v66, v66
	v_mul_f32_e32 v70, v215, v70
	s_nop 0
	v_exp_f32_e32 v219, v70
	s_nop 0
	v_exp_f32_e32 v72, v72
	v_fma_f32 v67, v67, s98, v168
	v_fma_f32 v70, -v219, v219, 1.0
	v_max_f32_e32 v70, 0, v70
	v_sqrt_f32_e32 v70, v70
	v_fma_f32 v73, v73, s98, v169
	s_nop 0
	v_add_f32_e32 v72, 1.0, v72
	v_mul_f32_e32 v66, v66, v70
	v_fma_f32 v70, v71, s98, v169
	s_nop 0
	v_exp_f32_e32 v70, v70
	s_nop 0
	v_exp_f32_e32 v67, v67
	v_rcp_f32_e32 v72, v72
	v_add_f32_e32 v70, 1.0, v70
	v_rcp_f32_e32 v70, v70
	v_exp_f32_e32 v73, v73
	v_add_f32_e32 v67, 1.0, v67
	v_mul_f32_e32 v72, v215, v72
	v_mul_f32_e32 v70, v215, v70
	s_nop 0
	v_exp_f32_e32 v70, v70
	v_add_f32_e32 v73, 1.0, v73
	v_rcp_f32_e32 v67, v67
	v_fma_f32 v68, v68, s98, v168
	v_fma_f32 v71, -v70, v70, 1.0
	v_max_f32_e32 v71, 0, v71
	v_sqrt_f32_e32 v71, v71
	s_nop 0
	v_rcp_f32_e32 v73, v73
	s_nop 0
	v_exp_f32_e32 v72, v72
	v_exp_f32_e32 v68, v68
	v_mul_f32_e32 v67, v67, v71
	ds_read_u16 v71, v213 offset:51776
	s_waitcnt lgkmcnt(1)
	v_lshlrev_b32_e32 v80, 16, v80
	v_mul_f32_e32 v73, v215, v73
	v_mul_f32_e32 v217, v66, v80
	v_fma_f32 v80, -v72, v72, 1.0
	v_fma_f32 v69, v69, s98, v168
	s_nop 0
	v_add_f32_e32 v68, 1.0, v68
	v_max_f32_e32 v80, 0, v80
	s_nop 0
	v_exp_f32_e32 v73, v73
	ds_read_u16 v66, v213 offset:51248
	v_rcp_f32_e32 v68, v68
	v_sqrt_f32_e32 v80, v80
	v_exp_f32_e32 v69, v69
	v_fma_f32 v81, -v73, v73, 1.0
	v_max_f32_e32 v81, 0, v81
	v_mul_f32_e32 v68, v68, v80
	ds_read_u16 v80, v213 offset:52304
	v_add_f32_e32 v69, 1.0, v69
	s_waitcnt lgkmcnt(1)
	v_lshlrev_b32_e32 v66, 16, v66
	v_rcp_f32_e32 v69, v69
	v_sqrt_f32_e32 v81, v81
	v_mul_f32_e32 v247, v70, v217
	v_fmac_f32_e32 v247, v67, v66
	v_lshlrev_b32_e32 v71, 16, v71
	v_mul_f32_e32 v246, v72, v247
	v_mul_f32_e32 v248, v70, v219
	v_fmac_f32_e32 v246, v68, v71
	s_waitcnt lgkmcnt(0)
	v_lshlrev_b32_e32 v80, 16, v80
	v_mul_f32_e32 v69, v69, v81
	v_mul_f32_e32 v249, v72, v248
	v_mul_f32_e32 v221, v73, v246
	v_mul_f32_e32 v250, v73, v249
	v_fmac_f32_e32 v221, v69, v80
	ds_bpermute_b32 v68, v210, v250
	ds_bpermute_b32 v66, v210, v221
	ds_bpermute_b32 v69, v212, v250
	ds_bpermute_b32 v67, v212, v221
	ds_bpermute_b32 v70, v211, v250
	ds_bpermute_b32 v241, v211, v221
	ds_bpermute_b32 v242, v218, v250
	ds_bpermute_b32 v218, v218, v221
	s_waitcnt lgkmcnt(6)
	v_fmac_f32_e32 v66, v216, v68
	s_waitcnt lgkmcnt(4)
	v_fmac_f32_e32 v67, v66, v69
	s_waitcnt lgkmcnt(2)
	v_fmac_f32_e32 v241, v67, v70
	s_and_saveexec_b64 s[4:5], s[0:1]
	s_cbranch_execz .LBB0_629
	v_cmp_ne_u32_e64 s[0:1], 1, v200
	s_and_saveexec_b64 s[34:35], s[0:1]
	s_xor_b64 s[0:1], exec, s[34:35]
	v_cndmask_b32_e32 v216, v241, v67, vcc
	s_andn2_saveexec_b64 s[0:1], s[0:1]
	v_mov_b32_e32 v216, v66
	s_or_b64 exec, exec, s[0:1]
.LBB0_629:
	s_or_b64 exec, exec, s[4:5]
	ds_read_b128 v[70:73], v220 offset:59136
	ds_read_b128 v[66:69], v220 offset:59200
	v_fmac_f32_e32 v230, v231, v223
	v_cmp_lt_i32_e64 s[0:1], 0, v200
	s_waitcnt lgkmcnt(1)
	v_mfma_f32_16x16x32_bf16 v[50:53], v[70:73], v[50:53], 0
	s_waitcnt lgkmcnt(0)
	v_mfma_f32_16x16x32_bf16 v[54:57], v[66:69], v[54:57], v[50:53]
	v_mfma_f32_16x16x32_bf16 v[58:61], v[70:73], v[58:61], 0
	v_mfma_f32_16x16x32_bf16 v[50:53], v[66:69], v[62:65], v[58:61]
	s_nop 5
	v_fma_f32 v54, v54, s98, v171
	s_nop 0
	v_exp_f32_e32 v54, v54
	v_fma_f32 v56, v56, s98, v171
	s_nop 0
	v_fma_f32 v50, v50, s98, v170
	v_add_f32_e32 v54, 1.0, v54
	v_rcp_f32_e32 v54, v54
	s_nop 0
	v_exp_f32_e32 v50, v50
	v_exp_f32_e32 v56, v56
	v_mul_f32_e32 v54, v214, v54
	s_nop 0
	v_exp_f32_e32 v59, v54
	v_add_f32_e32 v50, 1.0, v50
	v_rcp_f32_e32 v50, v50
	v_fma_f32 v57, v57, s98, v171
	v_fma_f32 v54, -v59, v59, 1.0
	v_max_f32_e32 v54, 0, v54
	v_sqrt_f32_e32 v54, v54
	v_fma_f32 v51, v51, s98, v170
	s_nop 0
	s_nop 0
	v_mul_f32_e32 v50, v50, v54
	v_fma_f32 v54, v55, s98, v171
	s_nop 0
	v_exp_f32_e32 v54, v54
	v_add_f32_e32 v56, 1.0, v56
	v_exp_f32_e32 v57, v57
	v_exp_f32_e32 v51, v51
	v_add_f32_e32 v54, 1.0, v54
	v_rcp_f32_e32 v54, v54
	v_rcp_f32_e32 v56, v56
	v_add_f32_e32 v57, 1.0, v57
	ds_read_u16 v58, v213 offset:59136
	v_mul_f32_e32 v54, v214, v54
	s_nop 0
	v_exp_f32_e32 v54, v54
	v_add_f32_e32 v51, 1.0, v51
	v_mul_f32_e32 v56, v214, v56
	v_rcp_f32_e32 v57, v57
	v_fma_f32 v55, -v54, v54, 1.0
	v_max_f32_e32 v55, 0, v55
	v_rcp_f32_e32 v51, v51
	v_sqrt_f32_e32 v55, v55
	v_fma_f32 v52, v52, s98, v170
	s_nop 0
	s_nop 0
	v_exp_f32_e32 v56, v56
	v_exp_f32_e32 v52, v52
	v_mul_f32_e32 v57, v214, v57
	v_mul_f32_e32 v51, v51, v55
	ds_read_u16 v55, v213 offset:60192
	s_waitcnt lgkmcnt(1)
	v_lshlrev_b32_e32 v58, 16, v58
	v_fma_f32 v53, v53, s98, v170
	s_nop 0
	v_mul_f32_e32 v62, v50, v58
	v_fma_f32 v58, -v56, v56, 1.0
	s_nop 0
	v_exp_f32_e32 v60, v57
	v_add_f32_e32 v52, 1.0, v52
	v_max_f32_e32 v58, 0, v58
	v_exp_f32_e32 v53, v53
	ds_read_u16 v50, v213 offset:59664
	v_rcp_f32_e32 v52, v52
	v_sqrt_f32_e32 v58, v58
	v_fma_f32 v57, -v60, v60, 1.0
	v_add_f32_e32 v53, 1.0, v53
	v_max_f32_e32 v57, 0, v57
	v_mul_f32_e32 v52, v52, v58
	ds_read_u16 v58, v213 offset:60720
	v_rcp_f32_e32 v53, v53
	v_sqrt_f32_e32 v57, v57
	s_waitcnt lgkmcnt(1)
	v_lshlrev_b32_e32 v50, 16, v50
	v_mul_f32_e32 v64, v54, v62
	v_fmac_f32_e32 v64, v51, v50
	v_lshlrev_b32_e32 v55, 16, v55
	v_mul_f32_e32 v63, v56, v64
	v_mul_f32_e32 v53, v53, v57
	v_mul_f32_e32 v57, v54, v59
	v_fmac_f32_e32 v63, v52, v55
	s_waitcnt lgkmcnt(0)
	v_lshlrev_b32_e32 v58, 16, v58
	v_mul_f32_e32 v65, v56, v57
	v_mul_f32_e32 v52, v60, v63
	v_mul_f32_e32 v170, v60, v65
	v_fmac_f32_e32 v52, v53, v58
	ds_bpermute_b32 v56, v210, v170
	ds_bpermute_b32 v50, v210, v52
	ds_bpermute_b32 v53, v212, v170
	ds_bpermute_b32 v51, v212, v52
	ds_bpermute_b32 v54, v211, v170
	ds_bpermute_b32 v55, v211, v52
	s_and_saveexec_b64 s[4:5], s[0:1]
	s_cbranch_execz .LBB0_635
	s_waitcnt lgkmcnt(4)
	v_fmac_f32_e32 v50, v230, v56
	v_cmp_ne_u32_e64 s[0:1], 1, v200
	s_and_saveexec_b64 s[34:35], s[0:1]
	s_xor_b64 s[0:1], exec, s[34:35]
	s_cbranch_execz .LBB0_632
	s_waitcnt lgkmcnt(2)
	v_fmac_f32_e32 v51, v50, v53
	s_waitcnt lgkmcnt(0)
	v_fmac_f32_e32 v55, v51, v54
	v_cndmask_b32_e32 v230, v55, v51, vcc

; __device__ __forceinline__ float fsig(float x) { return frcp(1.0f + __expf(-x)); }
; template <int DIR, int MODE>
; __device__ __forceinline__ void lru_pass(const Args& a, const LAS bf16_t* cxb, LAS bf16_t* gyb, const LAS float* carry, const bf16x8 (&Bw)[2][2][2], const float (&prm)[2][3], int l, int tt, float (&hf)[8][2][4]) {
;     ...
;         for (int nt = 0; nt < 2; ++nt) {
;             f32x4 pr = (f32x4){0.f, 0.f, 0.f, 0.f}, pi = (f32x4){0.f, 0.f, 0.f, 0.f};
; #pragma unroll
;             for (int ks = 0; ks < 2; ++ks) { pr = __builtin_amdgcn_mfma_f32_16x16x32_bf16(Af[ks], Bw[0][nt][ks], pr, 0, 0, 0); pi = __builtin_amdgcn_mfma_f32_16x16x32_bf16(Af[ks], Bw[1][nt][ks], pi, 0, 0, 0); }
;             float av[4], bv[4];
; #pragma unroll
;             for (int reg = 0; reg < 4; ++reg) {
;                 const int tok = m * 16 + 4 * fq + reg;
;                 const float x = bf2f(cxb[tok * CXS + cc[nt]]);
;                 const float r = fsig(pr[reg] + ba[nt]), ig = fsig(pi[reg] + bxv[nt]);
;                 const float aa = __expf(k8[nt] * r);
;                 av[reg] = aa; bv[reg] = __builtin_amdgcn_sqrtf(fmaxf(1.0f - aa * aa, 0.f)) * ig * x;
;             }
;             float cum[4], hl[4];
;             if (DIR == 0) { cum[0] = av[0]; hl[0] = bv[0];
; #pragma unroll
;                 for (int reg = 1; reg < 4; ++reg) { cum[reg] = cum[reg - 1] * av[reg]; hl[reg] = av[reg] * hl[reg - 1] + bv[reg]; } }
;             else { cum[3] = av[3]; hl[3] = bv[3];
; #pragma unroll
;     ...
;             const float A4 = DIR ? cum[0] : cum[3], H4 = DIR ? hl[0] : hl[3];
;             float Aq[4], Hq[4];
; #pragma unroll
;             for (int q = 0; q < 4; ++q) { Aq[q] = __shfl(A4, fr + 16 * q); Hq[q] = __shfl(H4, fr + 16 * q); }
;             float hin;
;             if (DIR == 0) { const float s0 = C[nt], s1 = Aq[0] * s0 + Hq[0], s2 = Aq[1] * s1 + Hq[1], s3 = Aq[2] * s2 + Hq[2]; C[nt] = Aq[3] * s3 + Hq[3]; hin = fq == 0 ? s0 : (fq == 1 ? s1 : (fq == 2 ? s2 : s3)); }
;             else { const float s3 = C[nt], s2 = Aq[3] * s3 + Hq[3], s1 = Aq[2] * s2 + Hq[2], s0 = Aq[1] * s1 + Hq[1]; C[nt] = Aq[0] * s0 + Hq[0]; hin = fq == 3 ? s3 : (fq == 2 ? s2 : (fq == 1 ? s1 : s0)); }
.LBB0_635:
	s_or_b64 exec, exec, s[4:5]
	v_mfma_f32_16x16x32_bf16 v[34:37], v[70:73], v[34:37], 0
	v_fmac_f32_e32 v218, v241, v242
	v_cmp_lt_i32_e64 s[0:1], 0, v200
	v_mfma_f32_16x16x32_bf16 v[38:41], v[66:69], v[38:41], v[34:37]
	v_mfma_f32_16x16x32_bf16 v[42:45], v[70:73], v[42:45], 0
	v_mfma_f32_16x16x32_bf16 v[34:37], v[66:69], v[46:49], v[42:45]
	s_nop 5
	v_fma_f32 v38, v38, s98, v169
	s_nop 0
	v_exp_f32_e32 v38, v38
	v_fma_f32 v40, v40, s98, v169
	s_nop 0
	v_fma_f32 v34, v34, s98, v168
	v_add_f32_e32 v38, 1.0, v38
	v_rcp_f32_e32 v38, v38
	s_nop 0
	v_exp_f32_e32 v34, v34
	v_exp_f32_e32 v40, v40
	v_mul_f32_e32 v38, v215, v38
	s_nop 0
	v_exp_f32_e32 v43, v38
	v_add_f32_e32 v34, 1.0, v34
	v_rcp_f32_e32 v34, v34
	v_add_f32_e32 v40, 1.0, v40
	v_fma_f32 v38, -v43, v43, 1.0
	v_max_f32_e32 v38, 0, v38
	v_sqrt_f32_e32 v38, v38
	v_rcp_f32_e32 v40, v40
	v_fma_f32 v35, v35, s98, v168
	v_fma_f32 v41, v41, s98, v169
	v_mul_f32_e32 v34, v34, v38
	v_fma_f32 v38, v39, s98, v169
	s_nop 0
	v_exp_f32_e32 v38, v38
	v_mul_f32_e32 v40, v215, v40
	s_nop 0
	v_fma_f32 v36, v36, s98, v168
	v_add_f32_e32 v38, 1.0, v38
	v_rcp_f32_e32 v38, v38
	s_nop 0
	s_nop 0
	v_exp_f32_e32 v35, v35
	v_mul_f32_e32 v38, v215, v38
	s_nop 0
	v_exp_f32_e32 v38, v38
	s_nop 0
	v_exp_f32_e32 v40, v40
	v_exp_f32_e32 v41, v41
	v_exp_f32_e32 v36, v36
	v_fma_f32 v39, -v38, v38, 1.0
	ds_read_u16 v42, v213 offset:59168
	v_add_f32_e32 v35, 1.0, v35
	v_max_f32_e32 v39, 0, v39
	v_fma_f32 v44, -v40, v40, 1.0
	v_add_f32_e32 v41, 1.0, v41
	v_rcp_f32_e32 v35, v35
	v_sqrt_f32_e32 v39, v39
	v_add_f32_e32 v36, 1.0, v36
	v_max_f32_e32 v44, 0, v44
	v_rcp_f32_e32 v41, v41
	v_rcp_f32_e32 v36, v36
	v_sqrt_f32_e32 v44, v44
	v_mul_f32_e32 v35, v35, v39
	ds_read_u16 v39, v213 offset:60224
	s_waitcnt lgkmcnt(1)
	v_lshlrev_b32_e32 v42, 16, v42
	v_mul_f32_e32 v41, v215, v41
	v_mul_f32_e32 v42, v34, v42
	ds_read_u16 v34, v213 offset:59696
	v_mul_f32_e32 v36, v36, v44
	ds_read_u16 v44, v213 offset:60752
	v_fma_f32 v37, v37, s98, v168
	s_nop 0
	s_nop 0
	v_exp_f32_e32 v41, v41
	v_exp_f32_e32 v37, v37
	s_waitcnt lgkmcnt(0)
	v_lshlrev_b32_e32 v46, 16, v44
	v_lshlrev_b32_e32 v34, 16, v34
	v_fma_f32 v44, -v41, v41, 1.0
	v_add_f32_e32 v37, 1.0, v37
	v_max_f32_e32 v44, 0, v44
	v_rcp_f32_e32 v37, v37
	v_sqrt_f32_e32 v44, v44
	v_mul_f32_e32 v47, v38, v42
	v_fmac_f32_e32 v47, v35, v34
	v_lshlrev_b32_e32 v39, 16, v39
	v_mul_f32_e32 v45, v40, v47
	v_mul_f32_e32 v49, v38, v43
	v_fmac_f32_e32 v45, v36, v39
	v_mul_f32_e32 v37, v37, v44
	v_mul_f32_e32 v69, v40, v49
	v_mul_f32_e32 v44, v41, v45
	v_mul_f32_e32 v70, v41, v69
	v_fmac_f32_e32 v44, v37, v46
	ds_bpermute_b32 v39, v210, v70
	ds_bpermute_b32 v34, v210, v44
	ds_bpermute_b32 v36, v212, v70
	ds_bpermute_b32 v35, v212, v44
	ds_bpermute_b32 v37, v211, v70
	ds_bpermute_b32 v38, v211, v44
	s_and_saveexec_b64 s[4:5], s[0:1]
	s_cbranch_execz .LBB0_641
	s_waitcnt lgkmcnt(4)
	v_fmac_f32_e32 v34, v218, v39
	v_cmp_ne_u32_e64 s[0:1], 1, v200
	s_and_saveexec_b64 s[34:35], s[0:1]
	s_xor_b64 s[0:1], exec, s[34:35]
	s_cbranch_execz .LBB0_638
	s_waitcnt lgkmcnt(2)
	v_fmac_f32_e32 v35, v34, v36
	s_waitcnt lgkmcnt(0)
	v_fmac_f32_e32 v38, v35, v37
	v_cndmask_b32_e32 v218, v38, v35, vcc

; template <int DIR, int MODE>
; __device__ __forceinline__ void lru_pass(const Args& a, const LAS bf16_t* cxb, LAS bf16_t* gyb, const LAS float* carry, const bf16x8 (&Bw)[2][2][2], const float (&prm)[2][3], int l, int tt, float (&hf)[8][2][4]) {
;     const int tid = opaque_tid(), lane = tid & 63, w = __builtin_amdgcn_readfirstlane(tid >> 6), h = w & 3, nh = w >> 2, fr = lane & 15, fq = lane >> 4;
;     float* SUM = (float*)(a.ws + WS_SUM);
;     float ba[2], bxv[2], k8[2], C[2], At[2]; int cc[2];
; #pragma unroll
;     for (int nt = 0; nt < 2; ++nt) {
;         const int c = 64 * h + 32 * nh + 16 * nt + fr; cc[nt] = c;
;         ba[nt] = prm[nt][0]; bxv[nt] = prm[nt][1]; k8[nt] = prm[nt][2];
;         C[nt] = MODE == 1 ? carry[DIR * 256 + c] : 0.f; At[nt] = 1.f;
;     }
; #pragma unroll
;     for (int mi = 0; mi < 8; ++mi) {
;         const int m = DIR ? 7 - mi : mi;
;         bf16x8 Af[2];
; #pragma unroll
;         for (int ks = 0; ks < 2; ++ks) Af[ks] = *(const LAS bf16x8*)(cxb + (m * 16 + fr) * CXS + 64 * h + 32 * ks + 8 * fq);
; #pragma unroll
;         for (int nt = 0; nt < 2; ++nt) {
;             f32x4 pr = (f32x4){0.f, 0.f, 0.f, 0.f}, pi = (f32x4){0.f, 0.f, 0.f, 0.f};
; #pragma unroll
;             for (int ks = 0; ks < 2; ++ks) { pr = __builtin_amdgcn_mfma_f32_16x16x32_bf16(Af[ks], Bw[0][nt][ks], pr, 0, 0, 0); pi = __builtin_amdgcn_mfma_f32_16x16x32_bf16(Af[ks], Bw[1][nt][ks], pi, 0, 0, 0); }
;             float av[4], bv[4];
; #pragma unroll
;             for (int reg = 0; reg < 4; ++reg) {
;                 const int tok = m * 16 + 4 * fq + reg;
;                 const float x = bf2f(cxb[tok * CXS + cc[nt]]);
;                 const float r = fsig(pr[reg] + ba[nt]), ig = fsig(pi[reg] + bxv[nt]);
;                 const float aa = __expf(k8[nt] * r);
;                 av[reg] = aa; bv[reg] = __builtin_amdgcn_sqrtf(fmaxf(1.0f - aa * aa, 0.f)) * ig * x;
;             }
;             float cum[4], hl[4];
;             if (DIR == 0) { cum[0] = av[0]; hl[0] = bv[0];
; #pragma unroll
;                 for (int reg = 1; reg < 4; ++reg) { cum[reg] = cum[reg - 1] * av[reg]; hl[reg] = av[reg] * hl[reg - 1] + bv[reg]; } }
;             else { cum[3] = av[3]; hl[3] = bv[3];
; #pragma unroll
;     ...
;             const float A4 = DIR ? cum[0] : cum[3], H4 = DIR ? hl[0] : hl[3];
;             float Aq[4], Hq[4];
; #pragma unroll
.LBB0_641:
	s_or_b64 exec, exec, s[4:5]
	s_waitcnt lgkmcnt(3)
	v_mul_f32_e32 v36, v191, v192
	v_mul_f32_e32 v36, v36, v193
	s_waitcnt lgkmcnt(1)
	v_add_f32_e32 v37, v197, v36
	s_waitcnt lgkmcnt(0)
	v_sub_f32_e32 v38, v37, v197
	v_sub_f32_e32 v36, v36, v38
	v_add_f32_e32 v36, v196, v36
	v_add_f32_e32 v38, v37, v36
	v_add_f32_e32 v34, v194, v195
	v_sub_f32_e32 v37, v38, v37
	v_sub_f32_e32 v36, v36, v37
	v_add_f32_e32 v37, v34, v38
	v_sub_f32_e32 v39, v37, v34
	v_sub_f32_e32 v35, v34, v194
	v_sub_f32_e32 v40, v37, v39
	v_sub_f32_e32 v35, v195, v35
	v_sub_f32_e32 v34, v34, v40
	v_sub_f32_e32 v38, v38, v39
	v_add_f32_e32 v34, v38, v34
	v_add_f32_e32 v38, v35, v36
	v_sub_f32_e32 v39, v38, v35
	v_sub_f32_e32 v40, v38, v39
	v_add_f32_e32 v34, v38, v34
	v_sub_f32_e32 v35, v35, v40
	v_sub_f32_e32 v36, v36, v39
	v_add_f32_e32 v38, v37, v34
	v_add_f32_e32 v35, v36, v35
	v_sub_f32_e32 v36, v38, v37
	v_sub_f32_e32 v34, v34, v36
	v_add_f32_e32 v39, v35, v34
	v_mov_b32_e32 v34, v0
	v_add_f32_e32 v38, v38, v39
	v_readfirstlane_b32 s0, v34
	s_bfe_u32 s1, s0, 0x20006
	s_lshl_b32 s4, s1, 7
	v_bfe_u32 v51, v34, 4, 2
	s_add_i32 s4, s4, 0
	v_and_b32_e32 v48, 15, v34
	v_lshl_add_u32 v46, v51, 4, s4
	v_mad_u32_u24 v40, v48, s28, v46
	ds_read_b128 v[34:37], v40 offset:59136
	s_mov_b32 s4, 0x7f800000
	v_cmp_neq_f32_e32 vcc, s4, v183
	v_mov_b32_e32 v39, 0x7f800000
	s_waitcnt lgkmcnt(0)
	v_mfma_f32_16x16x32_bf16 v[80:83], v[34:37], v[22:25], 0
	v_cndmask_b32_e32 v38, v39, v38, vcc
	v_cmp_ngt_f32_e32 vcc, -1.0, v183
	v_mov_b32_e32 v39, 0x7fc00000
	v_and_b32_e32 v53, 0x7fffffff, v183
	v_cndmask_b32_e32 v38, v39, v38, vcc
	v_cmp_neq_f32_e32 vcc, -1.0, v183
	v_mov_b32_e32 v39, 0xff800000
	s_mov_b32 s4, 0x33800000
	v_cndmask_b32_e32 v50, v39, v38, vcc
	ds_read_b128 v[38:41], v40 offset:59200
	s_waitcnt lgkmcnt(0)
	v_mfma_f32_16x16x32_bf16 v[80:83], v[38:41], v[18:21], v[80:83]
	v_cmp_gt_f32_e32 vcc, s4, v53
	s_ashr_i32 s0, s0, 3
	s_lshl_b32 s1, s1, 6
	v_cndmask_b32_e32 v50, v50, v183, vcc
	v_mul_f32_e32 v60, 0xc138aa3b, v50
	v_and_b32_e32 v50, 64, v227
	v_or_b32_e32 v53, v48, v50
	s_nop 0
	v_fma_f32 v50, v80, s98, v153
	s_nop 0
	v_exp_f32_e32 v55, v50
	v_mfma_f32_16x16x32_bf16 v[210:213], v[34:37], v[30:33], 0
	v_fma_f32 v71, v81, s98, v153
	s_nop 0
	v_add_f32_e32 v55, 1.0, v55
	v_rcp_f32_e32 v55, v55
	v_mfma_f32_16x16x32_bf16 v[210:213], v[38:41], v[26:29], v[210:213]
	v_exp_f32_e32 v71, v71
	s_andn2_b32 s0, s0, 31
	v_mul_f32_e32 v55, v60, v55
	s_nop 0
	v_exp_f32_e32 v55, v55
	s_nop 2
	v_fma_f32 v56, v210, s98, v152
	s_nop 0
	v_exp_f32_e32 v56, v56
	v_fma_f32 v68, -v55, v55, 1.0
	v_fma_f32 v72, v211, s98, v152
	v_max_f32_e32 v68, 0, v68
	v_add_f32_e32 v56, 1.0, v56
	s_nop 0
	v_rcp_f32_e32 v56, v56
	v_sqrt_f32_e32 v68, v68
	v_exp_f32_e32 v72, v72
	v_add_f32_e32 v71, 1.0, v71
	v_rcp_f32_e32 v71, v71
	v_mul_f32_e32 v56, v56, v68
	v_add_f32_e32 v68, 1.0, v72
	v_fma_f32 v72, v82, s98, v153
	v_mul_f32_e32 v71, v60, v71
	s_nop 0
	s_nop 0
	v_exp_f32_e32 v72, v72
	v_exp_f32_e32 v71, v71
	v_fma_f32 v80, v212, s98, v152
	s_nop 0
	v_add_f32_e32 v72, 1.0, v72
	v_fma_f32 v73, -v71, v71, 1.0
	v_rcp_f32_e32 v72, v72
	v_max_f32_e32 v73, 0, v73
	v_rcp_f32_e32 v68, v68
	v_sqrt_f32_e32 v73, v73
	v_exp_f32_e32 v80, v80
	v_mul_f32_e32 v72, v60, v72
	s_nop 0
	v_mul_f32_e32 v68, v68, v73
	v_add_f32_e32 v73, 1.0, v80
	v_exp_f32_e32 v80, v72
	v_fma_f32 v72, v83, s98, v153
	s_nop 0
	v_exp_f32_e32 v72, v72
	v_fma_f32 v82, v213, s98, v152
	s_nop 0
	s_add_i32 s1, s1, s0
	v_add_f32_e32 v72, 1.0, v72
	v_rcp_f32_e32 v72, v72
	v_exp_f32_e32 v82, v82
	v_or_b32_e32 v194, s1, v48
	v_lshlrev_b32_e32 v54, 1, v194
	v_mul_f32_e32 v72, v60, v72
	s_nop 0
	v_exp_f32_e32 v72, v72
	v_mul_u32_u24_e32 v50, 0x840, v51
	v_add3_u32 v58, 0, v54, v50
	v_fma_f32 v81, -v80, v80, 1.0
	v_fma_f32 v83, -v72, v72, 1.0
	ds_read_u16 v54, v58 offset:59136
	ds_read_u16 v61, v58 offset:59664
	ds_read_u16 v66, v58 offset:60192
	ds_read_u16 v67, v58 offset:60720
	v_max_f32_e32 v81, 0, v81
	v_add_f32_e32 v82, 1.0, v82
	v_max_f32_e32 v83, 0, v83
	v_rcp_f32_e32 v73, v73
	v_sqrt_f32_e32 v81, v81
	v_rcp_f32_e32 v82, v82
	v_sqrt_f32_e32 v83, v83
	s_waitcnt lgkmcnt(0)
	v_lshlrev_b32_e32 v67, 16, v67
	v_mul_f32_e32 v81, v73, v81
	v_lshlrev_b32_e32 v66, 16, v66
	v_mul_f32_e32 v73, v82, v83
	v_mul_f32_e32 v73, v73, v67
	v_mul_f32_e32 v169, v80, v73
	v_fmac_f32_e32 v169, v81, v66
	v_lshlrev_b32_e32 v61, 16, v61
	v_mul_f32_e32 v191, v71, v169
	v_mul_f32_e32 v168, v80, v72
	v_fmac_f32_e32 v191, v68, v61
	v_lshlrev_b32_e32 v54, 16, v54
	v_mul_f32_e32 v183, v71, v168
	v_mul_f32_e32 v193, v55, v191
	s_add_i32 s0, 0, 0x21000
	v_mul_f32_e32 v192, v55, v183
	v_fmac_f32_e32 v193, v56, v54
	v_lshlrev_b32_e32 v61, 2, v53
	v_lshl_add_u32 v53, v194, 2, s0
	ds_bpermute_b32 v210, v61, v192 offset:192
	ds_bpermute_b32 v195, v61, v193 offset:192
	ds_read_b32 v171, v53 offset:1024
	ds_bpermute_b32 v200, v61, v192 offset:128
	ds_bpermute_b32 v196, v61, v193 offset:128
	v_or_b32_e32 v53, 16, v194
	ds_bpermute_b32 v197, v61, v192 offset:64
	ds_bpermute_b32 v68, v61, v193 offset:64
	v_lshl_add_u32 v71, v53, 2, s0
	ds_bpermute_b32 v67, v61, v192
	ds_bpermute_b32 v66, v61, v193
	ds_read_b32 v71, v71 offset:1024
	s_waitcnt lgkmcnt(7)
	v_fmac_f32_e32 v195, v171, v210
	s_waitcnt lgkmcnt(5)
	v_fmac_f32_e32 v196, v195, v200
	v_mul_u32_u24_e32 v48, 0x210, v48
	v_or_b32_e32 v56, 64, v61
	v_or_b32_e32 v55, 0x80, v61
	v_or_b32_e32 v54, 0xc0, v61
	v_cmp_eq_u32_e32 vcc, 1, v51
	s_waitcnt lgkmcnt(3)
	v_fmac_f32_e32 v68, v196, v197
	v_cmp_gt_i32_e64 s[0:1], 3, v51
	s_and_saveexec_b64 s[4:5], s[0:1]
	s_cbranch_execz .LBB0_647
	v_cmp_ne_u32_e64 s[0:1], 2, v51
	s_and_saveexec_b64 s[34:35], s[0:1]
	s_xor_b64 s[0:1], exec, s[34:35]
	v_cndmask_b32_e32 v171, v68, v196, vcc
	s_andn2_saveexec_b64 s[0:1], s[0:1]
	v_mov_b32_e32 v171, v195
	s_or_b64 exec, exec, s[0:1]
; template <int DIR, int MODE>
; __device__ __forceinline__ void lru_pass(const Args& a, const LAS bf16_t* cxb, LAS bf16_t* gyb, const LAS float* carry, const bf16x8 (&Bw)[2][2][2], const float (&prm)[2][3], int l, int tt, float (&hf)[8][2][4]) {
;     ...
;         for (int nt = 0; nt < 2; ++nt) {
;             f32x4 pr = (f32x4){0.f, 0.f, 0.f, 0.f}, pi = (f32x4){0.f, 0.f, 0.f, 0.f};
; #pragma unroll
;             for (int ks = 0; ks < 2; ++ks) { pr = __builtin_amdgcn_mfma_f32_16x16x32_bf16(Af[ks], Bw[0][nt][ks], pr, 0, 0, 0); pi = __builtin_amdgcn_mfma_f32_16x16x32_bf16(Af[ks], Bw[1][nt][ks], pi, 0, 0, 0); }
;             float av[4], bv[4];
; #pragma unroll
;             for (int reg = 0; reg < 4; ++reg) {
;                 const int tok = m * 16 + 4 * fq + reg;
;                 const float x = bf2f(cxb[tok * CXS + cc[nt]]);
;                 const float r = fsig(pr[reg] + ba[nt]), ig = fsig(pi[reg] + bxv[nt]);
;                 const float aa = __expf(k8[nt] * r);
;                 av[reg] = aa; bv[reg] = __builtin_amdgcn_sqrtf(fmaxf(1.0f - aa * aa, 0.f)) * ig * x;
;             }
;             float cum[4], hl[4];
;             if (DIR == 0) { cum[0] = av[0]; hl[0] = bv[0];
; #pragma unroll
;                 for (int reg = 1; reg < 4; ++reg) { cum[reg] = cum[reg - 1] * av[reg]; hl[reg] = av[reg] * hl[reg - 1] + bv[reg]; } }
;             else { cum[3] = av[3]; hl[3] = bv[3];
; #pragma unroll
;     ...
;             const float A4 = DIR ? cum[0] : cum[3], H4 = DIR ? hl[0] : hl[3];
;             float Aq[4], Hq[4];
; #pragma unroll
;             for (int q = 0; q < 4; ++q) { Aq[q] = __shfl(A4, fr + 16 * q); Hq[q] = __shfl(H4, fr + 16 * q); }
;             float hin;
;             if (DIR == 0) { const float s0 = C[nt], s1 = Aq[0] * s0 + Hq[0], s2 = Aq[1] * s1 + Hq[1], s3 = Aq[2] * s2 + Hq[2]; C[nt] = Aq[3] * s3 + Hq[3]; hin = fq == 0 ? s0 : (fq == 1 ? s1 : (fq == 2 ? s2 : s3)); }
;             else { const float s3 = C[nt], s2 = Aq[3] * s3 + Hq[3], s1 = Aq[2] * s2 + Hq[2], s0 = Aq[1] * s1 + Hq[1]; C[nt] = Aq[0] * s0 + Hq[0]; hin = fq == 3 ? s3 : (fq == 2 ? s2 : (fq == 1 ? s1 : s0)); }
;             if (MODE == 0) At[nt] *= (Aq[0] * Aq[1]) * (Aq[2] * Aq[3]);
;             else {
; #pragma unroll
;                 for (int reg = 0; reg < 4; ++reg) {
;                     const float hv = hl[reg] + cum[reg] * hin;
;                     if (DIR == 0) hf[m][nt][reg] = hv;
.LBB0_647:
	s_or_b64 exec, exec, s[4:5]
	v_fmac_f32_e32 v63, v65, v230
	v_mul_f32_e32 v65, v184, v185
	v_mul_f32_e32 v65, v65, v186
	v_add_f32_e32 v80, v190, v65
	v_sub_f32_e32 v81, v80, v190
	v_sub_f32_e32 v65, v65, v81
	v_add_f32_e32 v65, v189, v65
	v_add_f32_e32 v81, v80, v65
	v_fmac_f32_e32 v64, v57, v230
	v_add_f32_e32 v57, v187, v188
	v_sub_f32_e32 v80, v81, v80
	v_sub_f32_e32 v65, v65, v80
	v_add_f32_e32 v80, v57, v81
	v_sub_f32_e32 v82, v80, v57
	v_fmac_f32_e32 v62, v59, v230
	v_sub_f32_e32 v59, v57, v187
	v_sub_f32_e32 v83, v80, v82
	v_sub_f32_e32 v59, v188, v59
	v_sub_f32_e32 v57, v57, v83
	v_sub_f32_e32 v81, v81, v82
	v_add_f32_e32 v57, v81, v57
	v_add_f32_e32 v81, v59, v65
	v_sub_f32_e32 v82, v81, v59
	v_sub_f32_e32 v83, v81, v82
	v_sub_f32_e32 v59, v59, v83
	v_sub_f32_e32 v65, v65, v82
	v_add_f32_e32 v57, v81, v57
	v_add_f32_e32 v59, v65, v59
	v_add_f32_e32 v65, v80, v57
	v_sub_f32_e32 v80, v65, v80
	v_sub_f32_e32 v57, v57, v80
	v_add_f32_e32 v57, v59, v57
	s_mov_b32 s0, 0x7f800000
	v_add_f32_e32 v57, v65, v57
	v_cmp_neq_f32_e64 s[0:1], s0, v181
	v_mov_b32_e32 v59, 0x7f800000
	v_fmac_f32_e32 v52, v170, v230
	v_cndmask_b32_e64 v57, v59, v57, s[0:1]
	v_cmp_ngt_f32_e64 s[0:1], -1.0, v181
	v_mov_b32_e32 v59, 0x7fc00000
	v_and_b32_e32 v187, 0x7fffffff, v181
	v_cndmask_b32_e64 v57, v59, v57, s[0:1]
	v_cmp_neq_f32_e64 s[0:1], -1.0, v181
	v_mov_b32_e32 v59, 0xff800000
	v_fmac_f32_e32 v193, v192, v171
	v_cndmask_b32_e64 v57, v59, v57, s[0:1]
	v_lshl_add_u32 v59, v194, 1, s38
	v_add_u32_e32 v59, v59, v50
	ds_read_u16 v65, v59 offset:59136
	ds_read_u16 v80, v59 offset:59664
	ds_read_u16 v81, v59 offset:60192
	ds_read_u16 v82, v59 offset:60720
	ds_read_u16 v83, v58 offset:59168
	ds_read_u16 v170, v58 offset:59696
	ds_read_u16 v184, v58 offset:60224
	ds_read_u16 v185, v58 offset:60752
	s_waitcnt lgkmcnt(7)
	v_lshlrev_b32_e32 v65, 16, v65
	v_mul_f32_e32 v186, 0x3d372713, v65
	v_mul_f32_e32 v186, v186, v65
	v_fma_f32 v186, v186, v65, v65
	v_mul_f32_e32 v186, 0x3f4c422a, v186
	v_add_f32_e32 v186, v186, v186
	v_mul_f32_e32 v186, 0x3fb8aa3b, v186
	v_exp_f32_e32 v186, v186
	s_mov_b32 s0, 0x33800000
	v_cmp_gt_f32_e64 s[0:1], s0, v187
	v_mul_f32_e32 v65, 0.5, v65
	v_add_f32_e32 v62, v62, v193
	v_cndmask_b32_e64 v57, v57, v181, s[0:1]
	v_add_f32_e32 v181, 1.0, v186
	v_rcp_f32_e32 v181, v181
	v_fmac_f32_e32 v191, v183, v171
	v_add_f32_e32 v64, v64, v191
	v_fmac_f32_e32 v169, v168, v171
	v_fma_f32 v181, v181, -2.0, 2.0
	v_mul_f32_e32 v65, v65, v181
	v_mul_f32_e32 v62, v62, v65
	s_waitcnt lgkmcnt(6)
	v_lshlrev_b32_e32 v65, 16, v80
	v_mul_f32_e32 v80, 0x3d372713, v65
	v_mul_f32_e32 v80, v80, v65
	v_fma_f32 v80, v80, v65, v65
	v_mul_f32_e32 v80, 0x3f4c422a, v80
	v_add_f32_e32 v80, v80, v80
	v_mul_f32_e32 v80, 0x3fb8aa3b, v80
	v_exp_f32_e32 v80, v80
	v_bfe_u32 v181, v62, 16, 1
	v_add3_u32 v62, v62, v181, s27
	ds_write_b16_d16_hi v59, v62 offset:59136
	v_add_f32_e32 v62, 1.0, v80
	v_rcp_f32_e32 v62, v62
	v_mul_f32_e32 v65, 0.5, v65
	v_add_f32_e32 v63, v63, v169
	v_mul_f32_e32 v57, 0xc138aa3b, v57
	v_fma_f32 v62, v62, -2.0, 2.0
	v_mul_f32_e32 v62, v65, v62
	v_mul_f32_e32 v62, v64, v62
	s_waitcnt lgkmcnt(6)
	v_lshlrev_b32_e32 v64, 16, v81
	v_mul_f32_e32 v65, 0x3d372713, v64
	v_mul_f32_e32 v65, v65, v64
	v_fma_f32 v65, v65, v64, v64
	v_mul_f32_e32 v65, 0x3f4c422a, v65
	v_add_f32_e32 v65, v65, v65
	v_mul_f32_e32 v65, 0x3fb8aa3b, v65
	v_exp_f32_e32 v65, v65
	v_bfe_u32 v80, v62, 16, 1
	v_add3_u32 v62, v62, v80, s27
	ds_write_b16_d16_hi v59, v62 offset:59664
	v_add_f32_e32 v62, 1.0, v65
	v_rcp_f32_e32 v62, v62
	v_mul_f32_e32 v64, 0.5, v64
	s_waitcnt lgkmcnt(6)
	v_lshlrev_b32_e32 v80, 16, v82
	v_fmac_f32_e32 v73, v72, v171
	v_fma_f32 v62, v62, -2.0, 2.0
	v_mul_f32_e32 v62, v64, v62
	v_mul_f32_e32 v62, v63, v62
	v_bfe_u32 v63, v62, 16, 1
	v_add3_u32 v62, v62, v63, s27
	v_mul_f32_e32 v63, 0x3d372713, v80
	v_mul_f32_e32 v63, v63, v80
	v_fma_f32 v63, v63, v80, v80
	v_mul_f32_e32 v63, 0x3f4c422a, v63
	v_add_f32_e32 v63, v63, v63
	v_mul_f32_e32 v63, 0x3fb8aa3b, v63
	v_exp_f32_e32 v81, v63
	ds_write_b16_d16_hi v59, v62 offset:60192
	v_mfma_f32_16x16x32_bf16 v[62:65], v[34:37], v[6:9], 0
	v_cmp_gt_i32_e64 s[0:1], 3, v51
	v_add_f32_e32 v72, 1.0, v81
	v_rcp_f32_e32 v72, v72
	v_mfma_f32_16x16x32_bf16 v[62:65], v[38:41], v[2:5], v[62:65]
	v_add_f32_e32 v81, v52, v73
	v_mul_f32_e32 v52, 0.5, v80
	v_fma_f32 v72, v72, -2.0, 2.0
	v_mfma_f32_16x16x32_bf16 v[34:37], v[34:37], v[14:17], 0
	v_mul_f32_e32 v80, v52, v72
	s_nop 2
	v_fma_f32 v62, v62, s98, v151
	s_nop 0
	v_exp_f32_e32 v62, v62
	v_mfma_f32_16x16x32_bf16 v[34:37], v[38:41], v[10:13], v[34:37]
	v_fma_f32 v39, v63, s98, v151
	s_nop 0
	v_add_f32_e32 v38, 1.0, v62
	v_rcp_f32_e32 v38, v38
	v_exp_f32_e32 v39, v39
	s_nop 2
	v_fma_f32 v34, v34, s98, v150
	s_nop 0
	v_mul_f32_e32 v38, v57, v38
	s_nop 0
	v_exp_f32_e32 v40, v38
	v_exp_f32_e32 v34, v34
	v_fma_f32 v35, v35, s98, v150
	s_nop 0
	v_fma_f32 v38, -v40, v40, 1.0
	v_add_f32_e32 v34, 1.0, v34
	v_max_f32_e32 v38, 0, v38
	v_add_f32_e32 v39, 1.0, v39
	v_rcp_f32_e32 v34, v34
	v_sqrt_f32_e32 v38, v38
	v_exp_f32_e32 v35, v35
	v_rcp_f32_e32 v39, v39
	v_fma_f32 v36, v36, s98, v150
	v_mul_f32_e32 v62, v34, v38
	v_add_f32_e32 v34, 1.0, v35
	v_mul_f32_e32 v35, v57, v39
	s_nop 0
	v_exp_f32_e32 v38, v35
	v_fma_f32 v35, v64, s98, v151
	s_nop 0
	v_exp_f32_e32 v35, v35
	v_fma_f32 v39, -v38, v38, 1.0
	v_max_f32_e32 v39, 0, v39
	s_nop 0
	v_add_f32_e32 v35, 1.0, v35
	v_rcp_f32_e32 v35, v35
	v_rcp_f32_e32 v34, v34
	v_sqrt_f32_e32 v39, v39
	v_exp_f32_e32 v36, v36
	v_mul_f32_e32 v35, v57, v35
	s_nop 0
	v_mul_f32_e32 v63, v34, v39
	v_add_f32_e32 v34, 1.0, v36
	v_exp_f32_e32 v36, v35
	v_fma_f32 v35, v65, s98, v151
	s_nop 0
	v_exp_f32_e32 v35, v35
	v_fma_f32 v37, v37, s98, v150
	s_nop 0
	v_exp_f32_e32 v37, v37
	v_add_f32_e32 v35, 1.0, v35
	v_rcp_f32_e32 v35, v35
	v_fma_f32 v39, -v36, v36, 1.0
	v_max_f32_e32 v39, 0, v39
	v_add_f32_e32 v37, 1.0, v37
	v_mul_f32_e32 v35, v57, v35
	s_nop 0
	v_exp_f32_e32 v35, v35
	v_rcp_f32_e32 v34, v34
	v_sqrt_f32_e32 v39, v39
	v_rcp_f32_e32 v37, v37
	v_fma_f32 v64, -v35, v35, 1.0
	v_max_f32_e32 v64, 0, v64
	v_sqrt_f32_e32 v64, v64
	v_mul_f32_e32 v39, v34, v39
	s_waitcnt lgkmcnt(3)
; template <int DIR, int MODE>
; __device__ __forceinline__ void lru_pass(const Args& a, const LAS bf16_t* cxb, LAS bf16_t* gyb, const LAS float* carry, const bf16x8 (&Bw)[2][2][2], const float (&prm)[2][3], int l, int tt, float (&hf)[8][2][4]) {
;     ...
;     for (int mi = 0; mi < 8; ++mi) {
;         const int m = DIR ? 7 - mi : mi;
;         bf16x8 Af[2];
; #pragma unroll
;         for (int ks = 0; ks < 2; ++ks) Af[ks] = *(const LAS bf16x8*)(cxb + (m * 16 + fr) * CXS + 64 * h + 32 * ks + 8 * fq);
; #pragma unroll
;         for (int nt = 0; nt < 2; ++nt) {
;             f32x4 pr = (f32x4){0.f, 0.f, 0.f, 0.f}, pi = (f32x4){0.f, 0.f, 0.f, 0.f};
; #pragma unroll
;             for (int ks = 0; ks < 2; ++ks) { pr = __builtin_amdgcn_mfma_f32_16x16x32_bf16(Af[ks], Bw[0][nt][ks], pr, 0, 0, 0); pi = __builtin_amdgcn_mfma_f32_16x16x32_bf16(Af[ks], Bw[1][nt][ks], pi, 0, 0, 0); }
;             float av[4], bv[4];
; #pragma unroll
;             for (int reg = 0; reg < 4; ++reg) {
;                 const int tok = m * 16 + 4 * fq + reg;
;                 const float x = bf2f(cxb[tok * CXS + cc[nt]]);
;                 const float r = fsig(pr[reg] + ba[nt]), ig = fsig(pi[reg] + bxv[nt]);
;                 const float aa = __expf(k8[nt] * r);
;                 av[reg] = aa; bv[reg] = __builtin_amdgcn_sqrtf(fmaxf(1.0f - aa * aa, 0.f)) * ig * x;
;             }
;             float cum[4], hl[4];
;             if (DIR == 0) { cum[0] = av[0]; hl[0] = bv[0];
; #pragma unroll
;                 for (int reg = 1; reg < 4; ++reg) { cum[reg] = cum[reg - 1] * av[reg]; hl[reg] = av[reg] * hl[reg - 1] + bv[reg]; } }
;             else { cum[3] = av[3]; hl[3] = bv[3];
; #pragma unroll
;     ...
;             const float A4 = DIR ? cum[0] : cum[3], H4 = DIR ? hl[0] : hl[3];
;             float Aq[4], Hq[4];
; #pragma unroll
;             for (int q = 0; q < 4; ++q) { Aq[q] = __shfl(A4, fr + 16 * q); Hq[q] = __shfl(H4, fr + 16 * q); }
;             float hin;
;             if (DIR == 0) { const float s0 = C[nt], s1 = Aq[0] * s0 + Hq[0], s2 = Aq[1] * s1 + Hq[1], s3 = Aq[2] * s2 + Hq[2]; C[nt] = Aq[3] * s3 + Hq[3]; hin = fq == 0 ? s0 : (fq == 1 ? s1 : (fq == 2 ? s2 : s3)); }
;             else { const float s3 = C[nt], s2 = Aq[3] * s3 + Hq[3], s1 = Aq[2] * s2 + Hq[2], s0 = Aq[1] * s1 + Hq[1]; C[nt] = Aq[0] * s0 + Hq[0]; hin = fq == 3 ? s3 : (fq == 2 ? s2 : (fq == 1 ? s1 : s0)); }
	v_lshlrev_b32_e32 v34, 16, v185
	v_lshlrev_b32_e32 v65, 16, v184
	v_mul_f32_e32 v37, v37, v64
	v_mul_f32_e32 v34, v37, v34
	v_mul_f32_e32 v37, v36, v35
	v_mul_f32_e32 v36, v36, v34
	v_fmac_f32_e32 v36, v39, v65
	v_lshlrev_b32_e32 v41, 16, v170
	v_mul_f32_e32 v39, v38, v37
	v_mul_f32_e32 v38, v38, v36
	v_fmac_f32_e32 v38, v63, v41
	v_lshlrev_b32_e32 v52, 16, v83
	v_mul_f32_e32 v41, v40, v39
	v_mul_f32_e32 v40, v40, v38
	v_fmac_f32_e32 v40, v62, v52
	ds_bpermute_b32 v168, v54, v41
	ds_bpermute_b32 v52, v54, v40
	ds_bpermute_b32 v73, v55, v41
	ds_bpermute_b32 v62, v55, v40
	ds_bpermute_b32 v72, v56, v41
	ds_bpermute_b32 v65, v56, v40
	ds_bpermute_b32 v64, v61, v41
	ds_bpermute_b32 v63, v61, v40
	v_mul_f32_e32 v80, v81, v80
	s_waitcnt lgkmcnt(6)
	v_fmac_f32_e32 v52, v71, v168
	v_bfe_u32 v81, v80, 16, 1
	s_waitcnt lgkmcnt(4)
	v_fmac_f32_e32 v62, v52, v73
	v_add3_u32 v80, v80, v81, s27
	s_waitcnt lgkmcnt(2)
	v_fmac_f32_e32 v65, v62, v72
	ds_write_b16_d16_hi v59, v80 offset:60720
	s_and_saveexec_b64 s[4:5], s[0:1]
	s_cbranch_execz .LBB0_653
	v_cmp_ne_u32_e64 s[0:1], 2, v51
	s_and_saveexec_b64 s[34:35], s[0:1]
	s_xor_b64 s[0:1], exec, s[34:35]
	v_cndmask_b32_e32 v71, v65, v62, vcc
	s_andn2_saveexec_b64 s[0:1], s[0:1]
	v_mov_b32_e32 v71, v52
	s_or_b64 exec, exec, s[0:1]
.LBB0_653:
	s_or_b64 exec, exec, s[4:5]
	v_fmac_f32_e32 v42, v43, v218
	v_lshl_add_u32 v43, v53, 1, s38
	v_add_u32_e32 v52, v43, v50
	v_fmac_f32_e32 v40, v41, v71
	ds_read_u16 v41, v52 offset:59136
	v_fmac_f32_e32 v38, v39, v71
	ds_read_u16 v39, v52 offset:59664
	v_fmac_f32_e32 v36, v37, v71
	ds_read_u16 v37, v52 offset:60192
	v_fmac_f32_e32 v34, v35, v71
	ds_read_u16 v35, v52 offset:60720
	s_waitcnt lgkmcnt(3)
	v_lshlrev_b32_e32 v41, 16, v41
	v_add_f32_e32 v40, v42, v40
	v_mul_f32_e32 v42, 0x3d372713, v41
	v_mul_f32_e32 v42, v42, v41
	v_fma_f32 v42, v42, v41, v41
	v_mul_f32_e32 v42, 0x3f4c422a, v42
	v_add_f32_e32 v42, v42, v42
	v_mul_f32_e32 v42, 0x3fb8aa3b, v42
	v_exp_f32_e32 v42, v42
	v_mul_f32_e32 v41, 0.5, v41
	s_waitcnt lgkmcnt(2)
	v_lshlrev_b32_e32 v39, 16, v39
	v_fmac_f32_e32 v47, v49, v218
	v_add_f32_e32 v42, 1.0, v42
	v_rcp_f32_e32 v42, v42
	v_add_f32_e32 v38, v47, v38
	s_waitcnt lgkmcnt(1)
	v_lshlrev_b32_e32 v37, 16, v37
	v_fmac_f32_e32 v45, v69, v218
	v_fma_f32 v42, v42, -2.0, 2.0
	v_mul_f32_e32 v41, v41, v42
	v_mul_f32_e32 v40, v40, v41
	v_bfe_u32 v41, v40, 16, 1
	v_add3_u32 v40, v40, v41, s27
	ds_write_b16_d16_hi v52, v40 offset:59136
	v_mul_f32_e32 v40, 0x3d372713, v39
	v_mul_f32_e32 v40, v40, v39
	v_fma_f32 v40, v40, v39, v39
	v_mul_f32_e32 v40, 0x3f4c422a, v40
	v_add_f32_e32 v40, v40, v40
	v_mul_f32_e32 v40, 0x3fb8aa3b, v40
	v_exp_f32_e32 v40, v40
	v_mul_f32_e32 v39, 0.5, v39
	v_add_f32_e32 v36, v45, v36
	s_waitcnt lgkmcnt(1)
	v_lshlrev_b32_e32 v35, 16, v35
	v_add_f32_e32 v40, 1.0, v40
	v_rcp_f32_e32 v40, v40
	v_fmac_f32_e32 v44, v70, v218
	v_add_f32_e32 v34, v44, v34
	v_add_u32_e32 v62, v46, v48
	v_fma_f32 v40, v40, -2.0, 2.0
	v_mul_f32_e32 v39, v39, v40
	v_mul_f32_e32 v38, v38, v39
	v_bfe_u32 v39, v38, 16, 1
	v_add3_u32 v38, v38, v39, s27
	ds_write_b16_d16_hi v52, v38 offset:59664
	v_mul_f32_e32 v38, 0x3d372713, v37
	v_mul_f32_e32 v38, v38, v37
	v_fma_f32 v38, v38, v37, v37
	v_mul_f32_e32 v38, 0x3f4c422a, v38
	v_add_f32_e32 v38, v38, v38
	v_mul_f32_e32 v38, 0x3fb8aa3b, v38
	v_exp_f32_e32 v38, v38
	v_mul_f32_e32 v37, 0.5, v37
	v_fmac_f32_e32 v66, v68, v67
	v_cmp_gt_i32_e64 s[0:1], 3, v51
	v_add_f32_e32 v38, 1.0, v38
	v_rcp_f32_e32 v38, v38
	s_nop 0
	v_fma_f32 v38, v38, -2.0, 2.0
	v_mul_f32_e32 v37, v37, v38
	v_mul_f32_e32 v36, v36, v37
	v_bfe_u32 v37, v36, 16, 1
	v_add3_u32 v36, v36, v37, s27
	ds_write_b16_d16_hi v52, v36 offset:60192
	v_mul_f32_e32 v36, 0x3d372713, v35
	v_mul_f32_e32 v36, v36, v35
	v_fma_f32 v36, v36, v35, v35
	v_mul_f32_e32 v36, 0x3f4c422a, v36
	v_add_f32_e32 v36, v36, v36
	v_mul_f32_e32 v36, 0x3fb8aa3b, v36
	v_exp_f32_e32 v36, v36
	v_mul_f32_e32 v35, 0.5, v35
	v_add_f32_e32 v36, 1.0, v36
	v_rcp_f32_e32 v36, v36
	s_nop 0
	v_fma_f32 v36, v36, -2.0, 2.0
	v_mul_f32_e32 v35, v35, v36
	v_mul_f32_e32 v34, v34, v35
	v_bfe_u32 v35, v34, 16, 1
	v_add3_u32 v34, v34, v35, s27
	ds_write_b16_d16_hi v52, v34 offset:60720
	ds_read_b128 v[38:41], v62 offset:50688
	ds_read_b128 v[34:37], v62 offset:50752
	s_waitcnt lgkmcnt(1)
	v_mfma_f32_16x16x32_bf16 v[42:45], v[38:41], v[22:25], 0
	ds_read_u16 v69, v58 offset:50688
	v_mfma_f32_16x16x32_bf16 v[70:73], v[38:41], v[30:33], 0
	s_waitcnt lgkmcnt(1)
	v_mfma_f32_16x16x32_bf16 v[46:49], v[34:37], v[18:21], v[42:45]
	v_mfma_f32_16x16x32_bf16 v[42:45], v[34:37], v[26:29], v[70:73]
	s_nop 6
	v_fma_f32 v46, v46, s98, v153
	v_fma_f32 v47, v47, s98, v153
	v_fma_f32 v48, v48, s98, v153
	s_nop 0
	s_nop 0
	s_nop 0
	v_exp_f32_e32 v46, v46
	v_exp_f32_e32 v47, v47
	v_exp_f32_e32 v48, v48
	v_fma_f32 v42, v42, s98, v152
	v_fma_f32 v43, v43, s98, v152
	v_fma_f32 v44, v44, s98, v152
	s_nop 0
	s_nop 0
	s_nop 0
	v_fma_f32 v49, v49, s98, v153
	v_add_f32_e32 v46, 1.0, v46
	v_exp_f32_e32 v42, v42
	v_add_f32_e32 v47, 1.0, v47
	v_exp_f32_e32 v43, v43
	v_add_f32_e32 v48, 1.0, v48
	v_exp_f32_e32 v44, v44
	s_nop 0
	v_rcp_f32_e32 v46, v46
	v_rcp_f32_e32 v47, v47
	v_rcp_f32_e32 v48, v48
	v_exp_f32_e32 v49, v49
	v_add_f32_e32 v42, 1.0, v42
	v_add_f32_e32 v43, 1.0, v43
	v_add_f32_e32 v44, 1.0, v44
	v_rcp_f32_e32 v70, v42
	v_mul_f32_e32 v42, v60, v46
	v_rcp_f32_e32 v71, v43
	v_mul_f32_e32 v43, v60, v47
	v_rcp_f32_e32 v72, v44
	v_mul_f32_e32 v44, v60, v48
	v_add_f32_e32 v49, 1.0, v49
	s_nop 0
	s_nop 0
	s_nop 0
	v_rcp_f32_e32 v49, v49
	v_exp_f32_e32 v42, v42
	v_exp_f32_e32 v43, v43
	v_exp_f32_e32 v44, v44
	v_mul_f32_e32 v49, v60, v49
	v_fma_f32 v46, -v42, v42, 1.0
	v_fma_f32 v47, -v43, v43, 1.0
	v_fma_f32 v48, -v44, v44, 1.0
	v_fma_f32 v45, v45, s98, v152
	s_nop 0
	v_max_f32_e32 v46, 0, v46
	v_max_f32_e32 v47, 0, v47
	v_max_f32_e32 v48, 0, v48
	s_nop 0
	v_exp_f32_e32 v49, v49
	v_sqrt_f32_e32 v46, v46
	v_sqrt_f32_e32 v47, v47
	v_sqrt_f32_e32 v48, v48
	v_exp_f32_e32 v45, v45
	v_fma_f32 v73, -v49, v49, 1.0
	v_mul_f32_e32 v46, v70, v46
	ds_read_u16 v70, v58 offset:51216
	v_mul_f32_e32 v47, v71, v47
	ds_read_u16 v71, v58 offset:51744
	v_mul_f32_e32 v48, v72, v48
	ds_read_u16 v72, v58 offset:52272
	v_add_f32_e32 v45, 1.0, v45
	v_max_f32_e32 v73, 0, v73
	v_rcp_f32_e32 v45, v45
	v_sqrt_f32_e32 v73, v73
	s_waitcnt lgkmcnt(0)
; template <int DIR, int MODE>
; __device__ __forceinline__ void lru_pass(const Args& a, const LAS bf16_t* cxb, LAS bf16_t* gyb, const LAS float* carry, const bf16x8 (&Bw)[2][2][2], const float (&prm)[2][3], int l, int tt, float (&hf)[8][2][4]) {
;     ...
;     for (int mi = 0; mi < 8; ++mi) {
;         const int m = DIR ? 7 - mi : mi;
;         bf16x8 Af[2];
; #pragma unroll
;         for (int ks = 0; ks < 2; ++ks) Af[ks] = *(const LAS bf16x8*)(cxb + (m * 16 + fr) * CXS + 64 * h + 32 * ks + 8 * fq);
; #pragma unroll
;         for (int nt = 0; nt < 2; ++nt) {
;             f32x4 pr = (f32x4){0.f, 0.f, 0.f, 0.f}, pi = (f32x4){0.f, 0.f, 0.f, 0.f};
; #pragma unroll
;             for (int ks = 0; ks < 2; ++ks) { pr = __builtin_amdgcn_mfma_f32_16x16x32_bf16(Af[ks], Bw[0][nt][ks], pr, 0, 0, 0); pi = __builtin_amdgcn_mfma_f32_16x16x32_bf16(Af[ks], Bw[1][nt][ks], pi, 0, 0, 0); }
;             float av[4], bv[4];
; #pragma unroll
;             for (int reg = 0; reg < 4; ++reg) {
;                 const int tok = m * 16 + 4 * fq + reg;
;                 const float x = bf2f(cxb[tok * CXS + cc[nt]]);
;                 const float r = fsig(pr[reg] + ba[nt]), ig = fsig(pi[reg] + bxv[nt]);
;                 const float aa = __expf(k8[nt] * r);
;                 av[reg] = aa; bv[reg] = __builtin_amdgcn_sqrtf(fmaxf(1.0f - aa * aa, 0.f)) * ig * x;
;             }
;             float cum[4], hl[4];
;             if (DIR == 0) { cum[0] = av[0]; hl[0] = bv[0];
; #pragma unroll
;                 for (int reg = 1; reg < 4; ++reg) { cum[reg] = cum[reg - 1] * av[reg]; hl[reg] = av[reg] * hl[reg - 1] + bv[reg]; } }
;             else { cum[3] = av[3]; hl[3] = bv[3];
; #pragma unroll
;     ...
;             const float A4 = DIR ? cum[0] : cum[3], H4 = DIR ? hl[0] : hl[3];
;             float Aq[4], Hq[4];
; #pragma unroll
;             for (int q = 0; q < 4; ++q) { Aq[q] = __shfl(A4, fr + 16 * q); Hq[q] = __shfl(H4, fr + 16 * q); }
;             float hin;
;             if (DIR == 0) { const float s0 = C[nt], s1 = Aq[0] * s0 + Hq[0], s2 = Aq[1] * s1 + Hq[1], s3 = Aq[2] * s2 + Hq[2]; C[nt] = Aq[3] * s3 + Hq[3]; hin = fq == 0 ? s0 : (fq == 1 ? s1 : (fq == 2 ? s2 : s3)); }
;             else { const float s3 = C[nt], s2 = Aq[3] * s3 + Hq[3], s1 = Aq[2] * s2 + Hq[2], s0 = Aq[1] * s1 + Hq[1]; C[nt] = Aq[0] * s0 + Hq[0]; hin = fq == 3 ? s3 : (fq == 2 ? s2 : (fq == 1 ? s1 : s0)); }
	v_lshlrev_b32_e32 v72, 16, v72
	v_lshlrev_b32_e32 v71, 16, v71
	v_lshlrev_b32_e32 v70, 16, v70
	v_mul_f32_e32 v45, v45, v73
	v_mul_f32_e32 v45, v45, v72
	v_mul_f32_e32 v72, v44, v49
	v_mul_f32_e32 v44, v44, v45
	v_fmac_f32_e32 v44, v48, v71
	v_mul_f32_e32 v71, v43, v44
	v_mul_f32_e32 v73, v43, v72
	v_fmac_f32_e32 v71, v47, v70
	v_lshlrev_b32_e32 v69, 16, v69
	v_mul_f32_e32 v47, v42, v73
	v_mul_f32_e32 v42, v42, v71
	v_fmac_f32_e32 v42, v46, v69
	ds_bpermute_b32 v170, v54, v47
	ds_bpermute_b32 v69, v54, v42
	ds_bpermute_b32 v169, v55, v47
	ds_bpermute_b32 v70, v55, v42
	ds_bpermute_b32 v168, v56, v47
	ds_bpermute_b32 v48, v56, v42
	ds_bpermute_b32 v46, v61, v47
	ds_bpermute_b32 v43, v61, v42
	s_waitcnt lgkmcnt(6)
	v_fmac_f32_e32 v69, v66, v170
	s_waitcnt lgkmcnt(4)
	v_fmac_f32_e32 v70, v69, v169
	s_waitcnt lgkmcnt(2)
	v_fmac_f32_e32 v48, v70, v168
	s_and_saveexec_b64 s[4:5], s[0:1]
	s_cbranch_execz .LBB0_659
	v_cmp_ne_u32_e64 s[0:1], 2, v51
	s_and_saveexec_b64 s[34:35], s[0:1]
	s_xor_b64 s[0:1], exec, s[34:35]
	v_cndmask_b32_e32 v66, v48, v70, vcc
	s_andn2_saveexec_b64 s[0:1], s[0:1]
	v_mov_b32_e32 v66, v69
	s_or_b64 exec, exec, s[0:1]
.LBB0_659:
	s_or_b64 exec, exec, s[4:5]
	v_fmac_f32_e32 v42, v47, v66
	ds_read_u16 v47, v59 offset:50688
	v_fmac_f32_e32 v232, v233, v224
	v_add_f32_e32 v42, v232, v42
	v_fmac_f32_e32 v239, v208, v224
	v_fmac_f32_e32 v71, v73, v66
	s_waitcnt lgkmcnt(0)
	v_lshlrev_b32_e32 v47, 16, v47
	v_mul_f32_e32 v67, 0x3d372713, v47
	v_mul_f32_e32 v67, v67, v47
	v_fma_f32 v67, v67, v47, v47
	v_mul_f32_e32 v67, 0x3f4c422a, v67
	v_add_f32_e32 v67, v67, v67
	v_mul_f32_e32 v67, 0x3fb8aa3b, v67
	v_exp_f32_e32 v67, v67
	v_mul_f32_e32 v47, 0.5, v47
	v_fmac_f32_e32 v238, v209, v224
	v_fmac_f32_e32 v44, v72, v66
	v_add_f32_e32 v67, 1.0, v67
	v_rcp_f32_e32 v67, v67
	v_add_f32_e32 v44, v238, v44
	v_fmac_f32_e32 v225, v228, v224
	v_fmac_f32_e32 v45, v49, v66
	v_fma_f32 v67, v67, -2.0, 2.0
	v_mul_f32_e32 v47, v47, v67
	v_mul_f32_e32 v42, v42, v47
	v_bfe_u32 v47, v42, 16, 1
	v_add3_u32 v42, v42, v47, s27
	ds_write_b16_d16_hi v59, v42 offset:50688
	ds_read_u16 v42, v59 offset:51216
	v_add_f32_e32 v47, v239, v71
	v_mfma_f32_16x16x32_bf16 v[70:73], v[38:41], v[14:17], 0
	v_fmac_f32_e32 v63, v65, v64
	v_cmp_gt_i32_e64 s[0:1], 3, v51
	s_waitcnt lgkmcnt(0)
	v_lshlrev_b32_e32 v42, 16, v42
	v_mul_f32_e32 v67, 0x3d372713, v42
	v_mul_f32_e32 v67, v67, v42
	v_fma_f32 v67, v67, v42, v42
	v_mul_f32_e32 v67, 0x3f4c422a, v67
	v_add_f32_e32 v67, v67, v67
	v_mul_f32_e32 v67, 0x3fb8aa3b, v67
	v_exp_f32_e32 v67, v67
	v_mul_f32_e32 v42, 0.5, v42
	v_add_f32_e32 v67, 1.0, v67
	v_rcp_f32_e32 v67, v67
	s_nop 0
	v_fma_f32 v67, v67, -2.0, 2.0
	v_mul_f32_e32 v42, v42, v67
	v_mul_f32_e32 v42, v47, v42
	v_bfe_u32 v47, v42, 16, 1
	v_add3_u32 v42, v42, v47, s27
	ds_write_b16_d16_hi v59, v42 offset:51216
	ds_read_u16 v42, v59 offset:51744
	v_mfma_f32_16x16x32_bf16 v[66:69], v[38:41], v[6:9], 0
	s_waitcnt lgkmcnt(0)
	v_lshlrev_b32_e32 v42, 16, v42
	v_mul_f32_e32 v47, 0x3d372713, v42
	v_mul_f32_e32 v47, v47, v42
	v_fma_f32 v47, v47, v42, v42
	v_mul_f32_e32 v47, 0x3f4c422a, v47
	v_add_f32_e32 v47, v47, v47
	v_mul_f32_e32 v47, 0x3fb8aa3b, v47
	v_exp_f32_e32 v47, v47
	v_mul_f32_e32 v42, 0.5, v42
	v_mfma_f32_16x16x32_bf16 v[38:41], v[34:37], v[2:5], v[66:69]
	v_add_f32_e32 v47, 1.0, v47
	v_rcp_f32_e32 v47, v47
	v_mfma_f32_16x16x32_bf16 v[34:37], v[34:37], v[10:13], v[70:73]
	v_fma_f32 v47, v47, -2.0, 2.0
	v_mul_f32_e32 v42, v42, v47
	v_mul_f32_e32 v42, v44, v42
	v_bfe_u32 v44, v42, 16, 1
	v_add3_u32 v42, v42, v44, s27
	ds_write_b16_d16_hi v59, v42 offset:51744
	ds_read_u16 v42, v59 offset:52272
	v_add_f32_e32 v44, v225, v45
	v_fma_f32 v38, v38, s98, v151
	v_fma_f32 v39, v39, s98, v151
	v_fma_f32 v40, v40, s98, v151
	s_waitcnt lgkmcnt(0)
	v_lshlrev_b32_e32 v42, 16, v42
	v_mul_f32_e32 v45, 0x3d372713, v42
	v_mul_f32_e32 v45, v45, v42
	v_fma_f32 v45, v45, v42, v42
	v_mul_f32_e32 v45, 0x3f4c422a, v45
	v_add_f32_e32 v45, v45, v45
	v_mul_f32_e32 v45, 0x3fb8aa3b, v45
	v_exp_f32_e32 v45, v45
	s_nop 0
	s_nop 0
	s_nop 0
	v_add_f32_e32 v45, 1.0, v45
	v_exp_f32_e32 v38, v38
	v_exp_f32_e32 v39, v39
	v_exp_f32_e32 v40, v40
	v_rcp_f32_e32 v45, v45
	v_fma_f32 v34, v34, s98, v150
	v_fma_f32 v35, v35, s98, v150
	v_fma_f32 v36, v36, s98, v150
	s_nop 0
	s_nop 0
	s_nop 0
	v_fma_f32 v41, v41, s98, v151
	v_add_f32_e32 v38, 1.0, v38
	v_exp_f32_e32 v34, v34
	v_add_f32_e32 v39, 1.0, v39
	v_exp_f32_e32 v35, v35
	v_add_f32_e32 v40, 1.0, v40
	v_exp_f32_e32 v36, v36
	s_nop 0
	v_mul_f32_e32 v42, 0.5, v42
	v_fma_f32 v45, v45, -2.0, 2.0
	v_rcp_f32_e32 v38, v38
	v_rcp_f32_e32 v39, v39
	v_rcp_f32_e32 v40, v40
	v_exp_f32_e32 v41, v41
	v_mul_f32_e32 v42, v42, v45
	v_mul_f32_e32 v42, v44, v42
	v_fma_f32 v37, v37, s98, v150
	v_bfe_u32 v44, v42, 16, 1
	v_add_f32_e32 v34, 1.0, v34
	v_add_f32_e32 v35, 1.0, v35
	v_add_f32_e32 v36, 1.0, v36
	s_nop 0
	v_add3_u32 v42, v42, v44, s27
	v_rcp_f32_e32 v44, v34
	v_mul_f32_e32 v34, v57, v38
	v_rcp_f32_e32 v45, v35
	v_mul_f32_e32 v35, v57, v39
	v_rcp_f32_e32 v47, v36
	v_mul_f32_e32 v36, v57, v40
	v_add_f32_e32 v41, 1.0, v41
	v_exp_f32_e32 v37, v37
	s_nop 0
	s_nop 0
	s_nop 0
	v_rcp_f32_e32 v41, v41
	v_exp_f32_e32 v34, v34
	v_exp_f32_e32 v35, v35
	v_exp_f32_e32 v36, v36
	v_add_f32_e32 v37, 1.0, v37
	v_rcp_f32_e32 v49, v37
	v_mul_f32_e32 v37, v57, v41
	v_fma_f32 v38, -v34, v34, 1.0
	v_fma_f32 v39, -v35, v35, 1.0
	v_fma_f32 v40, -v36, v36, 1.0
	s_nop 0
	v_max_f32_e32 v38, 0, v38
	v_max_f32_e32 v39, 0, v39
	v_max_f32_e32 v40, 0, v40
	v_exp_f32_e32 v37, v37
	v_sqrt_f32_e32 v38, v38
	v_sqrt_f32_e32 v39, v39
	v_sqrt_f32_e32 v40, v40
	v_fma_f32 v41, -v37, v37, 1.0
	ds_write_b16_d16_hi v59, v42 offset:52272
	ds_read_u16 v42, v58 offset:50720
	v_mul_f32_e32 v38, v44, v38
	ds_read_u16 v44, v58 offset:51248
	v_mul_f32_e32 v39, v45, v39
	ds_read_u16 v45, v58 offset:51776
	v_mul_f32_e32 v40, v47, v40
	ds_read_u16 v47, v58 offset:52304
	v_max_f32_e32 v41, 0, v41
	v_sqrt_f32_e32 v41, v41
	s_waitcnt lgkmcnt(1)
	v_lshlrev_b32_e32 v45, 16, v45
	v_lshlrev_b32_e32 v44, 16, v44
	s_waitcnt lgkmcnt(0)
	v_lshlrev_b32_e32 v47, 16, v47
	v_mul_f32_e32 v41, v49, v41
	v_mul_f32_e32 v41, v41, v47
	v_mul_f32_e32 v49, v36, v37
	v_mul_f32_e32 v36, v36, v41
	v_fmac_f32_e32 v36, v40, v45
	v_mul_f32_e32 v40, v35, v49
	v_mul_f32_e32 v35, v35, v36
	v_fmac_f32_e32 v35, v39, v44
	v_lshlrev_b32_e32 v42, 16, v42
	v_mul_f32_e32 v39, v34, v40
	v_mul_f32_e32 v34, v34, v35
	v_fmac_f32_e32 v34, v38, v42
	ds_bpermute_b32 v68, v54, v39
	ds_bpermute_b32 v38, v54, v34
	ds_bpermute_b32 v67, v55, v39
	ds_bpermute_b32 v44, v55, v34
	ds_bpermute_b32 v66, v56, v39
	ds_bpermute_b32 v47, v56, v34
	ds_bpermute_b32 v45, v61, v39
	ds_bpermute_b32 v42, v61, v34
	s_waitcnt lgkmcnt(6)
	v_fmac_f32_e32 v38, v63, v68
	s_waitcnt lgkmcnt(4)
	v_fmac_f32_e32 v44, v38, v67
	s_waitcnt lgkmcnt(2)
	v_fmac_f32_e32 v47, v44, v66
	s_and_saveexec_b64 s[4:5], s[0:1]
	s_cbranch_execz .LBB0_665
; template <int DIR, int MODE>
; __device__ __forceinline__ void lru_pass(const Args& a, const LAS bf16_t* cxb, LAS bf16_t* gyb, const LAS float* carry, const bf16x8 (&Bw)[2][2][2], const float (&prm)[2][3], int l, int tt, float (&hf)[8][2][4]) {
;     ...
;     for (int mi = 0; mi < 8; ++mi) {
;         const int m = DIR ? 7 - mi : mi;
;         bf16x8 Af[2];
; #pragma unroll
;         for (int ks = 0; ks < 2; ++ks) Af[ks] = *(const LAS bf16x8*)(cxb + (m * 16 + fr) * CXS + 64 * h + 32 * ks + 8 * fq);
; #pragma unroll
;         for (int nt = 0; nt < 2; ++nt) {
;             f32x4 pr = (f32x4){0.f, 0.f, 0.f, 0.f}, pi = (f32x4){0.f, 0.f, 0.f, 0.f};
; #pragma unroll
;             for (int ks = 0; ks < 2; ++ks) { pr = __builtin_amdgcn_mfma_f32_16x16x32_bf16(Af[ks], Bw[0][nt][ks], pr, 0, 0, 0); pi = __builtin_amdgcn_mfma_f32_16x16x32_bf16(Af[ks], Bw[1][nt][ks], pi, 0, 0, 0); }
;             float av[4], bv[4];
; #pragma unroll
;             for (int reg = 0; reg < 4; ++reg) {
;                 const int tok = m * 16 + 4 * fq + reg;
;                 const float x = bf2f(cxb[tok * CXS + cc[nt]]);
;                 const float r = fsig(pr[reg] + ba[nt]), ig = fsig(pi[reg] + bxv[nt]);
;                 const float aa = __expf(k8[nt] * r);
;                 av[reg] = aa; bv[reg] = __builtin_amdgcn_sqrtf(fmaxf(1.0f - aa * aa, 0.f)) * ig * x;
;             }
;             float cum[4], hl[4];
;             if (DIR == 0) { cum[0] = av[0]; hl[0] = bv[0];
; #pragma unroll
;                 for (int reg = 1; reg < 4; ++reg) { cum[reg] = cum[reg - 1] * av[reg]; hl[reg] = av[reg] * hl[reg - 1] + bv[reg]; } }
;             else { cum[3] = av[3]; hl[3] = bv[3];
; #pragma unroll
;     ...
;             const float A4 = DIR ? cum[0] : cum[3], H4 = DIR ? hl[0] : hl[3];
;             float Aq[4], Hq[4];
; #pragma unroll
;             for (int q = 0; q < 4; ++q) { Aq[q] = __shfl(A4, fr + 16 * q); Hq[q] = __shfl(H4, fr + 16 * q); }
;             float hin;
;             if (DIR == 0) { const float s0 = C[nt], s1 = Aq[0] * s0 + Hq[0], s2 = Aq[1] * s1 + Hq[1], s3 = Aq[2] * s2 + Hq[2]; C[nt] = Aq[3] * s3 + Hq[3]; hin = fq == 0 ? s0 : (fq == 1 ? s1 : (fq == 2 ? s2 : s3)); }
;             else { const float s3 = C[nt], s2 = Aq[3] * s3 + Hq[3], s1 = Aq[2] * s2 + Hq[2], s0 = Aq[1] * s1 + Hq[1]; C[nt] = Aq[0] * s0 + Hq[0]; hin = fq == 3 ? s3 : (fq == 2 ? s2 : (fq == 1 ? s1 : s0)); }
	v_cmp_ne_u32_e64 s[0:1], 2, v51
	s_and_saveexec_b64 s[34:35], s[0:1]
	s_xor_b64 s[0:1], exec, s[34:35]
	v_cndmask_b32_e32 v63, v47, v44, vcc
	s_andn2_saveexec_b64 s[0:1], s[0:1]
	v_mov_b32_e32 v63, v38
	s_or_b64 exec, exec, s[0:1]
.LBB0_665:
	s_or_b64 exec, exec, s[4:5]
	ds_read_u16 v38, v52 offset:50688
	ds_read_u16 v44, v52 offset:51216
	ds_read_u16 v64, v52 offset:51744
	ds_read_u16 v65, v52 offset:52272
	ds_read_u16 v72, v58 offset:43824
	s_waitcnt lgkmcnt(4)
	v_lshlrev_b32_e32 v38, 16, v38
	v_mul_f32_e32 v66, 0x3d372713, v38
	v_mul_f32_e32 v66, v66, v38
	v_fma_f32 v66, v66, v38, v38
	v_mul_f32_e32 v66, 0x3f4c422a, v66
	v_add_f32_e32 v66, v66, v66
	v_mul_f32_e32 v66, 0x3fb8aa3b, v66
	v_exp_f32_e32 v66, v66
	v_fmac_f32_e32 v217, v219, v216
	v_fmac_f32_e32 v34, v39, v63
	v_mul_f32_e32 v38, 0.5, v38
	v_add_f32_e32 v66, 1.0, v66
	v_rcp_f32_e32 v66, v66
	v_add_f32_e32 v34, v217, v34
	v_fmac_f32_e32 v247, v248, v216
	v_fmac_f32_e32 v35, v40, v63
	v_fma_f32 v39, v66, -2.0, 2.0
	v_mul_f32_e32 v38, v38, v39
	v_mul_f32_e32 v34, v34, v38
	s_waitcnt lgkmcnt(3)
	v_lshlrev_b32_e32 v38, 16, v44
	v_mul_f32_e32 v39, 0x3d372713, v38
	v_mul_f32_e32 v39, v39, v38
	v_fma_f32 v39, v39, v38, v38
	v_mul_f32_e32 v39, 0x3f4c422a, v39
	v_add_f32_e32 v39, v39, v39
	v_mul_f32_e32 v39, 0x3fb8aa3b, v39
	v_exp_f32_e32 v39, v39
	v_bfe_u32 v44, v34, 16, 1
	v_add3_u32 v34, v34, v44, s27
	ds_write_b16_d16_hi v52, v34 offset:50688
	v_add_f32_e32 v34, 1.0, v39
	v_rcp_f32_e32 v34, v34
	v_mul_f32_e32 v38, 0.5, v38
	v_add_f32_e32 v35, v247, v35
	v_fmac_f32_e32 v246, v249, v216
	v_fma_f32 v34, v34, -2.0, 2.0
	v_mul_f32_e32 v34, v38, v34
	v_mul_f32_e32 v34, v35, v34
	s_waitcnt lgkmcnt(3)
	v_lshlrev_b32_e32 v35, 16, v64
	v_mul_f32_e32 v38, 0x3d372713, v35
	v_mul_f32_e32 v38, v38, v35
	v_fma_f32 v38, v38, v35, v35
	v_mul_f32_e32 v38, 0x3f4c422a, v38
	v_add_f32_e32 v38, v38, v38
	v_mul_f32_e32 v38, 0x3fb8aa3b, v38
	v_exp_f32_e32 v38, v38
	v_bfe_u32 v39, v34, 16, 1
	v_add3_u32 v34, v34, v39, s27
	ds_write_b16_d16_hi v52, v34 offset:51216
	v_add_f32_e32 v34, 1.0, v38
	v_rcp_f32_e32 v34, v34
	v_fmac_f32_e32 v36, v49, v63
	v_mul_f32_e32 v35, 0.5, v35
	v_add_f32_e32 v36, v246, v36
	v_fma_f32 v34, v34, -2.0, 2.0
	v_mul_f32_e32 v34, v35, v34
	s_waitcnt lgkmcnt(3)
	v_lshlrev_b32_e32 v35, 16, v65
	v_mul_f32_e32 v34, v36, v34
	v_mul_f32_e32 v36, 0x3d372713, v35
	v_mul_f32_e32 v36, v36, v35
	v_fma_f32 v36, v36, v35, v35
	v_mul_f32_e32 v36, 0x3f4c422a, v36
	v_add_f32_e32 v36, v36, v36
	v_mul_f32_e32 v36, 0x3fb8aa3b, v36
	v_exp_f32_e32 v36, v36
	v_bfe_u32 v38, v34, 16, 1
	v_add3_u32 v34, v34, v38, s27
	ds_write_b16_d16_hi v52, v34 offset:51744
	v_add_f32_e32 v34, 1.0, v36
	v_rcp_f32_e32 v34, v34
	v_fmac_f32_e32 v221, v250, v216
	v_fmac_f32_e32 v41, v37, v63
	v_mul_f32_e32 v35, 0.5, v35
	v_fma_f32 v34, v34, -2.0, 2.0
	v_add_f32_e32 v36, v221, v41
	v_mul_f32_e32 v34, v35, v34
	v_mul_f32_e32 v34, v36, v34
	v_bfe_u32 v35, v34, 16, 1
	v_add3_u32 v34, v34, v35, s27
	ds_write_b16_d16_hi v52, v34 offset:52272
	ds_read_b128 v[38:41], v62 offset:42240
	ds_read_b128 v[34:37], v62 offset:42304
	s_waitcnt lgkmcnt(1)
	v_mfma_f32_16x16x32_bf16 v[64:67], v[38:41], v[22:25], 0
	v_fmac_f32_e32 v43, v48, v46
	v_cmp_gt_i32_e64 s[0:1], 3, v51
	s_waitcnt lgkmcnt(0)
	v_mfma_f32_16x16x32_bf16 v[64:67], v[34:37], v[18:21], v[64:67]
	v_mfma_f32_16x16x32_bf16 v[68:71], v[38:41], v[30:33], 0
	v_mfma_f32_16x16x32_bf16 v[68:71], v[34:37], v[26:29], v[68:71]
	s_nop 5
	v_fma_f32 v44, v64, s98, v153
	s_nop 0
	v_exp_f32_e32 v44, v44
	v_fma_f32 v65, v65, s98, v153
	s_nop 0
	v_exp_f32_e32 v65, v65
	v_add_f32_e32 v44, 1.0, v44
	v_rcp_f32_e32 v44, v44
	v_fma_f32 v68, v68, s98, v152
	v_add_f32_e32 v65, 1.0, v65
	v_rcp_f32_e32 v65, v65
	v_mul_f32_e32 v44, v60, v44
	s_nop 0
	s_nop 0
	v_exp_f32_e32 v44, v44
	v_mul_f32_e32 v65, v60, v65
	v_exp_f32_e32 v68, v68
	s_nop 0
	v_exp_f32_e32 v80, v65
	v_fma_f32 v65, v66, s98, v153
	s_nop 0
	v_fma_f32 v73, -v44, v44, 1.0
	v_fma_f32 v69, v69, s98, v152
	v_exp_f32_e32 v65, v65
	v_add_f32_e32 v68, 1.0, v68
	v_max_f32_e32 v73, 0, v73
	s_nop 0
	v_rcp_f32_e32 v68, v68
	v_sqrt_f32_e32 v73, v73
	v_exp_f32_e32 v69, v69
	v_add_f32_e32 v65, 1.0, v65
	v_fma_f32 v66, -v80, v80, 1.0
	v_rcp_f32_e32 v65, v65
	v_mul_f32_e32 v73, v68, v73
	v_add_f32_e32 v68, 1.0, v69
	v_max_f32_e32 v66, 0, v66
	v_rcp_f32_e32 v68, v68
	v_sqrt_f32_e32 v66, v66
	v_mul_f32_e32 v65, v60, v65
	s_nop 0
	v_fma_f32 v69, v70, s98, v152
	v_mul_f32_e32 v81, v68, v66
	v_exp_f32_e32 v66, v65
	v_fma_f32 v65, v67, s98, v153
	s_nop 0
	v_exp_f32_e32 v65, v65
	s_nop 0
	v_fma_f32 v68, v71, s98, v152
	ds_read_u16 v49, v58 offset:42240
	ds_read_u16 v63, v58 offset:42768
	ds_read_u16 v64, v58 offset:43296
	v_add_f32_e32 v65, 1.0, v65
	v_rcp_f32_e32 v65, v65
	v_exp_f32_e32 v69, v69
	s_nop 0
	v_exp_f32_e32 v68, v68
	v_mul_f32_e32 v65, v60, v65
	s_nop 0
	v_exp_f32_e32 v65, v65
	s_waitcnt lgkmcnt(1)
	v_lshlrev_b32_e32 v70, 16, v63
	v_add_f32_e32 v63, 1.0, v69
	v_fma_f32 v67, -v66, v66, 1.0
	v_fma_f32 v69, -v65, v65, 1.0
	v_max_f32_e32 v67, 0, v67
	v_add_f32_e32 v68, 1.0, v68
	v_max_f32_e32 v69, 0, v69
	v_rcp_f32_e32 v63, v63
	v_sqrt_f32_e32 v67, v67
	v_rcp_f32_e32 v68, v68
	v_sqrt_f32_e32 v69, v69
	s_waitcnt lgkmcnt(0)
	v_lshlrev_b32_e32 v64, 16, v64
	v_mul_f32_e32 v71, v63, v67
	v_lshlrev_b32_e32 v63, 16, v72
	v_mul_f32_e32 v67, v68, v69
	v_mul_f32_e32 v63, v67, v63
	v_mul_f32_e32 v67, v66, v65
	v_mul_f32_e32 v66, v66, v63
	v_fmac_f32_e32 v66, v71, v64
	v_mul_f32_e32 v68, v80, v66
	v_fmac_f32_e32 v68, v81, v70
	v_lshlrev_b32_e32 v49, 16, v49
	v_mul_f32_e32 v69, v80, v67
	v_mul_f32_e32 v70, v44, v68
	v_mul_f32_e32 v71, v44, v69
	v_fmac_f32_e32 v70, v73, v49
	ds_bpermute_b32 v170, v54, v71
	ds_bpermute_b32 v72, v54, v70
	ds_bpermute_b32 v169, v55, v71
	ds_bpermute_b32 v73, v55, v70
	ds_bpermute_b32 v168, v56, v71
	ds_bpermute_b32 v64, v56, v70
	ds_bpermute_b32 v49, v61, v71
	ds_bpermute_b32 v44, v61, v70
	s_waitcnt lgkmcnt(6)
	v_fmac_f32_e32 v72, v43, v170
	s_waitcnt lgkmcnt(4)
	v_fmac_f32_e32 v73, v72, v169
	s_waitcnt lgkmcnt(2)
	v_fmac_f32_e32 v64, v73, v168
	s_and_saveexec_b64 s[4:5], s[0:1]
	s_cbranch_execz .LBB0_671
	v_cmp_ne_u32_e64 s[0:1], 2, v51
	s_and_saveexec_b64 s[34:35], s[0:1]
	s_xor_b64 s[0:1], exec, s[34:35]
	v_cndmask_b32_e32 v43, v64, v73, vcc
	s_andn2_saveexec_b64 s[0:1], s[0:1]
	v_mov_b32_e32 v43, v72
	s_or_b64 exec, exec, s[0:1]
; template <int DIR, int MODE>
; __device__ __forceinline__ void lru_pass(const Args& a, const LAS bf16_t* cxb, LAS bf16_t* gyb, const LAS float* carry, const bf16x8 (&Bw)[2][2][2], const float (&prm)[2][3], int l, int tt, float (&hf)[8][2][4]) {
;     ...
;     for (int mi = 0; mi < 8; ++mi) {
;         const int m = DIR ? 7 - mi : mi;
;         bf16x8 Af[2];
; #pragma unroll
;         for (int ks = 0; ks < 2; ++ks) Af[ks] = *(const LAS bf16x8*)(cxb + (m * 16 + fr) * CXS + 64 * h + 32 * ks + 8 * fq);
; #pragma unroll
;         for (int nt = 0; nt < 2; ++nt) {
;             f32x4 pr = (f32x4){0.f, 0.f, 0.f, 0.f}, pi = (f32x4){0.f, 0.f, 0.f, 0.f};
; #pragma unroll
;             for (int ks = 0; ks < 2; ++ks) { pr = __builtin_amdgcn_mfma_f32_16x16x32_bf16(Af[ks], Bw[0][nt][ks], pr, 0, 0, 0); pi = __builtin_amdgcn_mfma_f32_16x16x32_bf16(Af[ks], Bw[1][nt][ks], pi, 0, 0, 0); }
;             float av[4], bv[4];
; #pragma unroll
;             for (int reg = 0; reg < 4; ++reg) {
;                 const int tok = m * 16 + 4 * fq + reg;
;                 const float x = bf2f(cxb[tok * CXS + cc[nt]]);
;                 const float r = fsig(pr[reg] + ba[nt]), ig = fsig(pi[reg] + bxv[nt]);
;                 const float aa = __expf(k8[nt] * r);
;                 av[reg] = aa; bv[reg] = __builtin_amdgcn_sqrtf(fmaxf(1.0f - aa * aa, 0.f)) * ig * x;
;             }
;             float cum[4], hl[4];
;             if (DIR == 0) { cum[0] = av[0]; hl[0] = bv[0];
; #pragma unroll
;                 for (int reg = 1; reg < 4; ++reg) { cum[reg] = cum[reg - 1] * av[reg]; hl[reg] = av[reg] * hl[reg - 1] + bv[reg]; } }
;             else { cum[3] = av[3]; hl[3] = bv[3];
; #pragma unroll
;     ...
;             const float A4 = DIR ? cum[0] : cum[3], H4 = DIR ? hl[0] : hl[3];
;             float Aq[4], Hq[4];
; #pragma unroll
;             for (int q = 0; q < 4; ++q) { Aq[q] = __shfl(A4, fr + 16 * q); Hq[q] = __shfl(H4, fr + 16 * q); }
;             float hin;
;             if (DIR == 0) { const float s0 = C[nt], s1 = Aq[0] * s0 + Hq[0], s2 = Aq[1] * s1 + Hq[1], s3 = Aq[2] * s2 + Hq[2]; C[nt] = Aq[3] * s3 + Hq[3]; hin = fq == 0 ? s0 : (fq == 1 ? s1 : (fq == 2 ? s2 : s3)); }
;             else { const float s3 = C[nt], s2 = Aq[3] * s3 + Hq[3], s1 = Aq[2] * s2 + Hq[2], s0 = Aq[1] * s1 + Hq[1]; C[nt] = Aq[0] * s0 + Hq[0]; hin = fq == 3 ? s3 : (fq == 2 ? s2 : (fq == 1 ? s1 : s0)); }
.LBB0_671:
	s_or_b64 exec, exec, s[4:5]
	ds_read_u16 v46, v59 offset:42240
	v_fmac_f32_e32 v202, v203, v182
	v_fmac_f32_e32 v70, v71, v43
	v_fmac_f32_e32 v68, v69, v43
	v_fmac_f32_e32 v66, v67, v43
	v_fmac_f32_e32 v63, v65, v43
	ds_read_u16 v43, v59 offset:43824
	s_waitcnt lgkmcnt(1)
	v_lshlrev_b32_e32 v46, 16, v46
	v_add_f32_e32 v48, v202, v70
	v_mul_f32_e32 v70, 0x3d372713, v46
	v_mul_f32_e32 v70, v70, v46
	v_fma_f32 v70, v70, v46, v46
	v_mul_f32_e32 v70, 0x3f4c422a, v70
	v_add_f32_e32 v70, v70, v70
	v_mul_f32_e32 v70, 0x3fb8aa3b, v70
	v_exp_f32_e32 v70, v70
	v_mul_f32_e32 v46, 0.5, v46
	v_fmac_f32_e32 v201, v204, v182
	v_fmac_f32_e32 v199, v205, v182
	v_add_f32_e32 v70, 1.0, v70
	v_rcp_f32_e32 v70, v70
	s_waitcnt lgkmcnt(0)
	v_lshlrev_b32_e32 v43, 16, v43
	v_fmac_f32_e32 v198, v206, v182
	v_fmac_f32_e32 v42, v47, v45
	v_fma_f32 v70, v70, -2.0, 2.0
	v_mul_f32_e32 v46, v46, v70
	v_mul_f32_e32 v46, v48, v46
	v_bfe_u32 v48, v46, 16, 1
	v_add3_u32 v46, v46, v48, s27
	ds_write_b16_d16_hi v59, v46 offset:42240
	ds_read_u16 v46, v59 offset:42768
	v_add_f32_e32 v48, v201, v68
	v_mfma_f32_16x16x32_bf16 v[70:73], v[38:41], v[14:17], 0
	v_cmp_gt_i32_e64 s[0:1], 3, v51
	s_waitcnt lgkmcnt(0)
	v_lshlrev_b32_e32 v46, 16, v46
	v_mul_f32_e32 v68, 0x3d372713, v46
	v_mul_f32_e32 v68, v68, v46
	v_fma_f32 v68, v68, v46, v46
	v_mul_f32_e32 v68, 0x3f4c422a, v68
	v_add_f32_e32 v68, v68, v68
	v_mul_f32_e32 v68, 0x3fb8aa3b, v68
	v_exp_f32_e32 v68, v68
	v_mul_f32_e32 v46, 0.5, v46
	v_add_f32_e32 v68, 1.0, v68
	v_rcp_f32_e32 v68, v68
	s_nop 0
	v_fma_f32 v68, v68, -2.0, 2.0
	v_mul_f32_e32 v46, v46, v68
	v_mul_f32_e32 v46, v48, v46
	v_bfe_u32 v48, v46, 16, 1
	v_add3_u32 v46, v46, v48, s27
	ds_write_b16_d16_hi v59, v46 offset:42768
	ds_read_u16 v46, v59 offset:43296
	v_add_f32_e32 v48, v199, v66
	s_waitcnt lgkmcnt(0)
	v_lshlrev_b32_e32 v46, 16, v46
	v_mul_f32_e32 v66, 0x3d372713, v46
	v_mul_f32_e32 v66, v66, v46
	v_fma_f32 v66, v66, v46, v46
	v_mul_f32_e32 v66, 0x3f4c422a, v66
	v_add_f32_e32 v66, v66, v66
	v_mul_f32_e32 v66, 0x3fb8aa3b, v66
	v_exp_f32_e32 v66, v66
	v_mul_f32_e32 v46, 0.5, v46
	v_add_f32_e32 v66, 1.0, v66
	v_rcp_f32_e32 v66, v66
	s_nop 0
	v_fma_f32 v66, v66, -2.0, 2.0
	v_mul_f32_e32 v46, v46, v66
	v_mul_f32_e32 v46, v48, v46
	v_bfe_u32 v48, v46, 16, 1
	v_add3_u32 v46, v46, v48, s27
	v_mul_f32_e32 v48, 0x3d372713, v43
	v_mfma_f32_16x16x32_bf16 v[66:69], v[38:41], v[6:9], 0
	v_mul_f32_e32 v48, v48, v43
	v_fma_f32 v48, v48, v43, v43
	v_mul_f32_e32 v48, 0x3f4c422a, v48
	v_add_f32_e32 v48, v48, v48
	v_mfma_f32_16x16x32_bf16 v[38:41], v[34:37], v[2:5], v[66:69]
	v_mul_f32_e32 v48, 0x3fb8aa3b, v48
	v_exp_f32_e32 v48, v48
	v_mul_f32_e32 v43, 0.5, v43
	v_mfma_f32_16x16x32_bf16 v[34:37], v[34:37], v[10:13], v[70:73]
	ds_write_b16_d16_hi v59, v46 offset:43296
	s_nop 2
	v_fma_f32 v38, v38, s98, v151
	v_fma_f32 v39, v39, s98, v151
	v_fma_f32 v40, v40, s98, v151
	s_nop 0
	s_nop 0
	s_nop 0
	v_add_f32_e32 v48, 1.0, v48
	v_exp_f32_e32 v38, v38
	v_exp_f32_e32 v39, v39
	v_exp_f32_e32 v40, v40
	v_rcp_f32_e32 v48, v48
	v_fma_f32 v34, v34, s98, v150
	v_fma_f32 v35, v35, s98, v150
	v_fma_f32 v36, v36, s98, v150
	s_nop 0
	s_nop 0
	s_nop 0
	v_fma_f32 v41, v41, s98, v151
	v_add_f32_e32 v38, 1.0, v38
	v_exp_f32_e32 v34, v34
	v_add_f32_e32 v39, 1.0, v39
	v_exp_f32_e32 v35, v35
	v_add_f32_e32 v40, 1.0, v40
	v_exp_f32_e32 v36, v36
	s_nop 0
	v_fma_f32 v48, v48, -2.0, 2.0
	v_rcp_f32_e32 v38, v38
	v_rcp_f32_e32 v39, v39
	v_rcp_f32_e32 v40, v40
	v_exp_f32_e32 v41, v41
	v_add_f32_e32 v46, v198, v63
	v_mul_f32_e32 v43, v43, v48
	v_mul_f32_e32 v43, v46, v43
	v_fma_f32 v37, v37, s98, v150
	v_bfe_u32 v46, v43, 16, 1
	v_add_f32_e32 v34, 1.0, v34
	v_add_f32_e32 v35, 1.0, v35
	v_add_f32_e32 v36, 1.0, v36
	s_nop 0
	v_add3_u32 v43, v43, v46, s27
	v_rcp_f32_e32 v46, v34
	v_mul_f32_e32 v34, v57, v38
	v_rcp_f32_e32 v48, v35
	v_mul_f32_e32 v35, v57, v39
	v_rcp_f32_e32 v63, v36
	v_mul_f32_e32 v36, v57, v40
	v_add_f32_e32 v41, 1.0, v41
	v_exp_f32_e32 v37, v37
	s_nop 0
	s_nop 0
	s_nop 0
	v_rcp_f32_e32 v41, v41
	v_exp_f32_e32 v34, v34
	v_exp_f32_e32 v35, v35
	v_exp_f32_e32 v36, v36
	v_add_f32_e32 v37, 1.0, v37
	v_rcp_f32_e32 v65, v37
	v_mul_f32_e32 v37, v57, v41
	v_fma_f32 v38, -v34, v34, 1.0
	v_fma_f32 v39, -v35, v35, 1.0
	v_fma_f32 v40, -v36, v36, 1.0
	s_nop 0
	v_max_f32_e32 v38, 0, v38
	v_max_f32_e32 v39, 0, v39
	v_max_f32_e32 v40, 0, v40
	v_exp_f32_e32 v37, v37
	v_sqrt_f32_e32 v38, v38
	v_sqrt_f32_e32 v39, v39
	v_sqrt_f32_e32 v40, v40
	v_fma_f32 v41, -v37, v37, 1.0
	ds_write_b16_d16_hi v59, v43 offset:43824
	ds_read_u16 v43, v58 offset:42272
	v_mul_f32_e32 v38, v46, v38
	ds_read_u16 v46, v58 offset:42800
	v_mul_f32_e32 v39, v48, v39
	ds_read_u16 v48, v58 offset:43328
	v_mul_f32_e32 v40, v63, v40
	ds_read_u16 v63, v58 offset:43856
	v_max_f32_e32 v41, 0, v41
	v_sqrt_f32_e32 v41, v41
	s_waitcnt lgkmcnt(1)
	v_lshlrev_b32_e32 v48, 16, v48
	v_lshlrev_b32_e32 v46, 16, v46
	s_waitcnt lgkmcnt(0)
	v_lshlrev_b32_e32 v63, 16, v63
	v_mul_f32_e32 v41, v65, v41
	v_mul_f32_e32 v41, v41, v63
	v_mul_f32_e32 v63, v36, v37
	v_mul_f32_e32 v36, v36, v41
	v_fmac_f32_e32 v36, v40, v48
	v_mul_f32_e32 v40, v35, v63
	v_mul_f32_e32 v35, v35, v36
	v_fmac_f32_e32 v35, v39, v46
	v_lshlrev_b32_e32 v43, 16, v43
	v_mul_f32_e32 v39, v34, v40
	v_mul_f32_e32 v34, v34, v35
	v_fmac_f32_e32 v34, v38, v43
	ds_bpermute_b32 v68, v54, v39
	ds_bpermute_b32 v38, v54, v34
	ds_bpermute_b32 v67, v55, v39
	ds_bpermute_b32 v65, v55, v34
	ds_bpermute_b32 v66, v56, v39
	ds_bpermute_b32 v48, v56, v34
	ds_bpermute_b32 v46, v61, v39
	ds_bpermute_b32 v43, v61, v34
	s_waitcnt lgkmcnt(6)
	v_fmac_f32_e32 v38, v42, v68
	s_waitcnt lgkmcnt(4)
	v_fmac_f32_e32 v65, v38, v67
	s_waitcnt lgkmcnt(2)
	v_fmac_f32_e32 v48, v65, v66
	s_and_saveexec_b64 s[4:5], s[0:1]
	s_cbranch_execz .LBB0_677
	v_cmp_ne_u32_e64 s[0:1], 2, v51
	s_and_saveexec_b64 s[34:35], s[0:1]
	s_xor_b64 s[0:1], exec, s[34:35]
	v_cndmask_b32_e32 v42, v48, v65, vcc
	s_andn2_saveexec_b64 s[0:1], s[0:1]
	v_mov_b32_e32 v42, v38
	s_or_b64 exec, exec, s[0:1]
; template <int DIR, int MODE>
; __device__ __forceinline__ void lru_pass(const Args& a, const LAS bf16_t* cxb, LAS bf16_t* gyb, const LAS float* carry, const bf16x8 (&Bw)[2][2][2], const float (&prm)[2][3], int l, int tt, float (&hf)[8][2][4]) {
;     ...
;     for (int mi = 0; mi < 8; ++mi) {
;         const int m = DIR ? 7 - mi : mi;
;         bf16x8 Af[2];
; #pragma unroll
;         for (int ks = 0; ks < 2; ++ks) Af[ks] = *(const LAS bf16x8*)(cxb + (m * 16 + fr) * CXS + 64 * h + 32 * ks + 8 * fq);
; #pragma unroll
;         for (int nt = 0; nt < 2; ++nt) {
;             f32x4 pr = (f32x4){0.f, 0.f, 0.f, 0.f}, pi = (f32x4){0.f, 0.f, 0.f, 0.f};
; #pragma unroll
;             for (int ks = 0; ks < 2; ++ks) { pr = __builtin_amdgcn_mfma_f32_16x16x32_bf16(Af[ks], Bw[0][nt][ks], pr, 0, 0, 0); pi = __builtin_amdgcn_mfma_f32_16x16x32_bf16(Af[ks], Bw[1][nt][ks], pi, 0, 0, 0); }
;             float av[4], bv[4];
; #pragma unroll
;             for (int reg = 0; reg < 4; ++reg) {
;                 const int tok = m * 16 + 4 * fq + reg;
;                 const float x = bf2f(cxb[tok * CXS + cc[nt]]);
;                 const float r = fsig(pr[reg] + ba[nt]), ig = fsig(pi[reg] + bxv[nt]);
;                 const float aa = __expf(k8[nt] * r);
;                 av[reg] = aa; bv[reg] = __builtin_amdgcn_sqrtf(fmaxf(1.0f - aa * aa, 0.f)) * ig * x;
;             }
;             float cum[4], hl[4];
;             if (DIR == 0) { cum[0] = av[0]; hl[0] = bv[0];
; #pragma unroll
;                 for (int reg = 1; reg < 4; ++reg) { cum[reg] = cum[reg - 1] * av[reg]; hl[reg] = av[reg] * hl[reg - 1] + bv[reg]; } }
;             else { cum[3] = av[3]; hl[3] = bv[3];
; #pragma unroll
;     ...
;             const float A4 = DIR ? cum[0] : cum[3], H4 = DIR ? hl[0] : hl[3];
;             float Aq[4], Hq[4];
; #pragma unroll
;             for (int q = 0; q < 4; ++q) { Aq[q] = __shfl(A4, fr + 16 * q); Hq[q] = __shfl(H4, fr + 16 * q); }
;             float hin;
;             if (DIR == 0) { const float s0 = C[nt], s1 = Aq[0] * s0 + Hq[0], s2 = Aq[1] * s1 + Hq[1], s3 = Aq[2] * s2 + Hq[2]; C[nt] = Aq[3] * s3 + Hq[3]; hin = fq == 0 ? s0 : (fq == 1 ? s1 : (fq == 2 ? s2 : s3)); }
;             else { const float s3 = C[nt], s2 = Aq[3] * s3 + Hq[3], s1 = Aq[2] * s2 + Hq[2], s0 = Aq[1] * s1 + Hq[1]; C[nt] = Aq[0] * s0 + Hq[0]; hin = fq == 3 ? s3 : (fq == 2 ? s2 : (fq == 1 ? s1 : s0)); }
.LBB0_677:
	s_or_b64 exec, exec, s[4:5]
	ds_read_u16 v38, v52 offset:42240
	ds_read_u16 v45, v52 offset:42768
	ds_read_u16 v47, v52 offset:43296
	ds_read_u16 v65, v52 offset:43824
	ds_read_u16 v80, v58 offset:35376
	s_waitcnt lgkmcnt(4)
	v_lshlrev_b32_e32 v38, 16, v38
	v_mul_f32_e32 v66, 0x3d372713, v38
	v_mul_f32_e32 v66, v66, v38
	v_fma_f32 v66, v66, v38, v38
	v_mul_f32_e32 v66, 0x3f4c422a, v66
	v_add_f32_e32 v66, v66, v66
	v_mul_f32_e32 v66, 0x3fb8aa3b, v66
	v_exp_f32_e32 v66, v66
	v_fmac_f32_e32 v173, v174, v172
	v_fmac_f32_e32 v34, v39, v42
	v_mul_f32_e32 v38, 0.5, v38
	v_add_f32_e32 v66, 1.0, v66
	v_rcp_f32_e32 v66, v66
	v_add_f32_e32 v34, v173, v34
	v_fmac_f32_e32 v177, v178, v172
	v_fmac_f32_e32 v35, v40, v42
	v_fma_f32 v39, v66, -2.0, 2.0
	v_mul_f32_e32 v38, v38, v39
	v_mul_f32_e32 v34, v34, v38
	s_waitcnt lgkmcnt(3)
	v_lshlrev_b32_e32 v38, 16, v45
	v_mul_f32_e32 v39, 0x3d372713, v38
	v_mul_f32_e32 v39, v39, v38
	v_fma_f32 v39, v39, v38, v38
	v_mul_f32_e32 v39, 0x3f4c422a, v39
	v_add_f32_e32 v39, v39, v39
	v_mul_f32_e32 v39, 0x3fb8aa3b, v39
	v_exp_f32_e32 v39, v39
	v_bfe_u32 v45, v34, 16, 1
	v_add3_u32 v34, v34, v45, s27
	ds_write_b16_d16_hi v52, v34 offset:42240
	v_add_f32_e32 v34, 1.0, v39
	v_rcp_f32_e32 v34, v34
	v_mul_f32_e32 v38, 0.5, v38
	v_add_f32_e32 v35, v177, v35
	v_fmac_f32_e32 v176, v179, v172
	v_fma_f32 v34, v34, -2.0, 2.0
	v_mul_f32_e32 v34, v38, v34
	v_mul_f32_e32 v34, v35, v34
	s_waitcnt lgkmcnt(3)
	v_lshlrev_b32_e32 v35, 16, v47
	v_mul_f32_e32 v38, 0x3d372713, v35
	v_mul_f32_e32 v38, v38, v35
	v_fma_f32 v38, v38, v35, v35
	v_mul_f32_e32 v38, 0x3f4c422a, v38
	v_add_f32_e32 v38, v38, v38
	v_mul_f32_e32 v38, 0x3fb8aa3b, v38
	v_exp_f32_e32 v38, v38
	v_bfe_u32 v39, v34, 16, 1
	v_add3_u32 v34, v34, v39, s27
	ds_write_b16_d16_hi v52, v34 offset:42768
	v_add_f32_e32 v34, 1.0, v38
	v_rcp_f32_e32 v34, v34
	v_fmac_f32_e32 v36, v63, v42
	v_mul_f32_e32 v35, 0.5, v35
	v_add_f32_e32 v36, v176, v36
	v_fma_f32 v34, v34, -2.0, 2.0
	v_mul_f32_e32 v34, v35, v34
	s_waitcnt lgkmcnt(3)
	v_lshlrev_b32_e32 v35, 16, v65
	v_mul_f32_e32 v34, v36, v34
	v_mul_f32_e32 v36, 0x3d372713, v35
	v_mul_f32_e32 v36, v36, v35
	v_fma_f32 v36, v36, v35, v35
	v_mul_f32_e32 v36, 0x3f4c422a, v36
	v_add_f32_e32 v36, v36, v36
	v_mul_f32_e32 v36, 0x3fb8aa3b, v36
	v_exp_f32_e32 v36, v36
	v_bfe_u32 v38, v34, 16, 1
	v_add3_u32 v34, v34, v38, s27
	ds_write_b16_d16_hi v52, v34 offset:43296
	v_add_f32_e32 v34, 1.0, v36
	v_rcp_f32_e32 v34, v34
	v_fmac_f32_e32 v175, v180, v172
	v_fmac_f32_e32 v41, v37, v42
	v_mul_f32_e32 v35, 0.5, v35
	v_fma_f32 v34, v34, -2.0, 2.0
	v_add_f32_e32 v36, v175, v41
	v_mul_f32_e32 v34, v35, v34
	v_mul_f32_e32 v34, v36, v34
	v_bfe_u32 v35, v34, 16, 1
	v_add3_u32 v34, v34, v35, s27
	ds_write_b16_d16_hi v52, v34 offset:43824
	ds_read_b128 v[38:41], v62 offset:33792
	ds_read_b128 v[34:37], v62 offset:33856
	s_waitcnt lgkmcnt(1)
	v_mfma_f32_16x16x32_bf16 v[66:69], v[38:41], v[22:25], 0
	ds_read_u16 v45, v58 offset:33792
	ds_read_u16 v47, v58 offset:34320
	ds_read_u16 v63, v58 offset:34848
	v_fmac_f32_e32 v44, v64, v49
	v_cmp_gt_i32_e64 s[0:1], 3, v51
	s_waitcnt lgkmcnt(3)
	v_mfma_f32_16x16x32_bf16 v[66:69], v[34:37], v[18:21], v[66:69]
	s_waitcnt lgkmcnt(2)
	v_lshlrev_b32_e32 v45, 16, v45
	s_waitcnt lgkmcnt(0)
	v_lshlrev_b32_e32 v63, 16, v63
	v_mfma_f32_16x16x32_bf16 v[70:73], v[38:41], v[30:33], 0
	v_mfma_f32_16x16x32_bf16 v[70:73], v[34:37], v[26:29], v[70:73]
	s_nop 1
	v_fma_f32 v42, v66, s98, v153
	v_fma_f32 v66, v67, s98, v153
	s_nop 0
	v_exp_f32_e32 v66, v66
	s_nop 0
	v_exp_f32_e32 v42, v42
	v_fma_f32 v67, v71, s98, v152
	v_add_f32_e32 v66, 1.0, v66
	v_rcp_f32_e32 v66, v66
	v_add_f32_e32 v42, 1.0, v42
	v_rcp_f32_e32 v42, v42
	v_fma_f32 v65, v70, s98, v152
	v_mul_f32_e32 v66, v60, v66
	s_nop 0
	v_exp_f32_e32 v71, v66
	v_fma_f32 v66, v68, s98, v153
	s_nop 0
	v_exp_f32_e32 v66, v66
	v_mul_f32_e32 v42, v60, v42
	s_nop 0
	s_nop 0
	v_add_f32_e32 v66, 1.0, v66
	v_rcp_f32_e32 v66, v66
	v_exp_f32_e32 v65, v65
	v_exp_f32_e32 v70, v42
	v_fma_f32 v68, v72, s98, v152
	v_lshlrev_b32_e32 v72, 16, v47
	v_mul_f32_e32 v47, v60, v66
	s_nop 0
	v_add_f32_e32 v42, 1.0, v65
	v_fma_f32 v65, -v70, v70, 1.0
	v_exp_f32_e32 v66, v47
	v_fma_f32 v47, v69, s98, v153
	v_max_f32_e32 v65, 0, v65
	s_nop 0
	s_nop 0
	v_rcp_f32_e32 v42, v42
	v_sqrt_f32_e32 v65, v65
	v_exp_f32_e32 v67, v67
	v_exp_f32_e32 v47, v47
	s_nop 0
	v_mul_f32_e32 v65, v42, v65
	v_add_f32_e32 v42, 1.0, v67
	v_fma_f32 v67, -v71, v71, 1.0
	v_add_f32_e32 v47, 1.0, v47
	v_max_f32_e32 v67, 0, v67
	v_rcp_f32_e32 v47, v47
	v_rcp_f32_e32 v42, v42
	v_sqrt_f32_e32 v67, v67
	v_exp_f32_e32 v68, v68
	v_mul_f32_e32 v47, v60, v47
	s_nop 0
	v_mul_f32_e32 v81, v42, v67
	v_add_f32_e32 v42, 1.0, v68
	v_fma_f32 v68, v73, s98, v152
	s_nop 0
	v_exp_f32_e32 v47, v47
	v_exp_f32_e32 v68, v68
	v_fma_f32 v67, -v66, v66, 1.0
	v_max_f32_e32 v67, 0, v67
	v_fma_f32 v69, -v47, v47, 1.0
	v_add_f32_e32 v68, 1.0, v68
	v_max_f32_e32 v69, 0, v69
	v_rcp_f32_e32 v42, v42
	v_sqrt_f32_e32 v67, v67
	v_rcp_f32_e32 v68, v68
	v_sqrt_f32_e32 v69, v69
	v_mul_f32_e32 v73, v42, v67
	v_lshlrev_b32_e32 v42, 16, v80
	v_mul_f32_e32 v67, v68, v69
	v_mul_f32_e32 v42, v67, v42
	v_mul_f32_e32 v67, v66, v47
	v_mul_f32_e32 v66, v66, v42
	v_fmac_f32_e32 v66, v73, v63
	v_mul_f32_e32 v68, v71, v66
	v_mul_f32_e32 v69, v71, v67
	v_fmac_f32_e32 v68, v81, v72
	v_mul_f32_e32 v71, v70, v69
	v_mul_f32_e32 v70, v70, v68
	v_fmac_f32_e32 v70, v65, v45
	ds_bpermute_b32 v170, v54, v71
	ds_bpermute_b32 v72, v54, v70
	ds_bpermute_b32 v169, v55, v71
	ds_bpermute_b32 v73, v55, v70
	ds_bpermute_b32 v168, v56, v71
	ds_bpermute_b32 v65, v56, v70
	ds_bpermute_b32 v63, v61, v71
	ds_bpermute_b32 v45, v61, v70
	s_waitcnt lgkmcnt(6)
	v_fmac_f32_e32 v72, v44, v170
	s_waitcnt lgkmcnt(4)
	v_fmac_f32_e32 v73, v72, v169
	s_waitcnt lgkmcnt(2)
	v_fmac_f32_e32 v65, v73, v168
	s_and_saveexec_b64 s[4:5], s[0:1]
	s_cbranch_execz .LBB0_683
	v_cmp_ne_u32_e64 s[0:1], 2, v51
	s_and_saveexec_b64 s[34:35], s[0:1]
	s_xor_b64 s[0:1], exec, s[34:35]
	v_cndmask_b32_e32 v44, v65, v73, vcc
	s_andn2_saveexec_b64 s[0:1], s[0:1]
	v_mov_b32_e32 v44, v72
	s_or_b64 exec, exec, s[0:1]
; template <int DIR, int MODE>
; __device__ __forceinline__ void lru_pass(const Args& a, const LAS bf16_t* cxb, LAS bf16_t* gyb, const LAS float* carry, const bf16x8 (&Bw)[2][2][2], const float (&prm)[2][3], int l, int tt, float (&hf)[8][2][4]) {
;     ...
;     for (int mi = 0; mi < 8; ++mi) {
;         const int m = DIR ? 7 - mi : mi;
;         bf16x8 Af[2];
; #pragma unroll
;         for (int ks = 0; ks < 2; ++ks) Af[ks] = *(const LAS bf16x8*)(cxb + (m * 16 + fr) * CXS + 64 * h + 32 * ks + 8 * fq);
; #pragma unroll
;         for (int nt = 0; nt < 2; ++nt) {
;             f32x4 pr = (f32x4){0.f, 0.f, 0.f, 0.f}, pi = (f32x4){0.f, 0.f, 0.f, 0.f};
; #pragma unroll
;             for (int ks = 0; ks < 2; ++ks) { pr = __builtin_amdgcn_mfma_f32_16x16x32_bf16(Af[ks], Bw[0][nt][ks], pr, 0, 0, 0); pi = __builtin_amdgcn_mfma_f32_16x16x32_bf16(Af[ks], Bw[1][nt][ks], pi, 0, 0, 0); }
;             float av[4], bv[4];
; #pragma unroll
;             for (int reg = 0; reg < 4; ++reg) {
;                 const int tok = m * 16 + 4 * fq + reg;
;                 const float x = bf2f(cxb[tok * CXS + cc[nt]]);
;                 const float r = fsig(pr[reg] + ba[nt]), ig = fsig(pi[reg] + bxv[nt]);
;                 const float aa = __expf(k8[nt] * r);
;                 av[reg] = aa; bv[reg] = __builtin_amdgcn_sqrtf(fmaxf(1.0f - aa * aa, 0.f)) * ig * x;
;             }
;             float cum[4], hl[4];
;             if (DIR == 0) { cum[0] = av[0]; hl[0] = bv[0];
; #pragma unroll
;                 for (int reg = 1; reg < 4; ++reg) { cum[reg] = cum[reg - 1] * av[reg]; hl[reg] = av[reg] * hl[reg - 1] + bv[reg]; } }
;             else { cum[3] = av[3]; hl[3] = bv[3];
; #pragma unroll
;     ...
;             const float A4 = DIR ? cum[0] : cum[3], H4 = DIR ? hl[0] : hl[3];
;             float Aq[4], Hq[4];
; #pragma unroll
;             for (int q = 0; q < 4; ++q) { Aq[q] = __shfl(A4, fr + 16 * q); Hq[q] = __shfl(H4, fr + 16 * q); }
;             float hin;
;             if (DIR == 0) { const float s0 = C[nt], s1 = Aq[0] * s0 + Hq[0], s2 = Aq[1] * s1 + Hq[1], s3 = Aq[2] * s2 + Hq[2]; C[nt] = Aq[3] * s3 + Hq[3]; hin = fq == 0 ? s0 : (fq == 1 ? s1 : (fq == 2 ? s2 : s3)); }
;             else { const float s3 = C[nt], s2 = Aq[3] * s3 + Hq[3], s1 = Aq[2] * s2 + Hq[2], s0 = Aq[1] * s1 + Hq[1]; C[nt] = Aq[0] * s0 + Hq[0]; hin = fq == 3 ? s3 : (fq == 2 ? s2 : (fq == 1 ? s1 : s0)); }
.LBB0_683:
	s_or_b64 exec, exec, s[4:5]
	ds_read_u16 v49, v59 offset:33792
	v_fmac_f32_e32 v163, v164, v159
	v_fmac_f32_e32 v70, v71, v44
	v_fmac_f32_e32 v68, v69, v44
	v_fmac_f32_e32 v66, v67, v44
	v_fmac_f32_e32 v42, v47, v44
	ds_read_u16 v44, v59 offset:35376
	s_waitcnt lgkmcnt(1)
	v_lshlrev_b32_e32 v49, 16, v49
	v_add_f32_e32 v64, v163, v70
	v_mul_f32_e32 v70, 0x3d372713, v49
	v_mul_f32_e32 v70, v70, v49
	v_fma_f32 v70, v70, v49, v49
	v_mul_f32_e32 v70, 0x3f4c422a, v70
	v_add_f32_e32 v70, v70, v70
	v_mul_f32_e32 v70, 0x3fb8aa3b, v70
	v_exp_f32_e32 v70, v70
	v_mul_f32_e32 v49, 0.5, v49
	v_fmac_f32_e32 v162, v165, v159
	v_fmac_f32_e32 v161, v166, v159
	v_add_f32_e32 v70, 1.0, v70
	v_rcp_f32_e32 v70, v70
	s_waitcnt lgkmcnt(0)
	v_lshlrev_b32_e32 v44, 16, v44
	v_mul_f32_e32 v47, 0x3d372713, v44
	v_mul_f32_e32 v47, v47, v44
	v_fma_f32 v70, v70, -2.0, 2.0
	v_mul_f32_e32 v49, v49, v70
	v_mul_f32_e32 v49, v64, v49
	v_bfe_u32 v64, v49, 16, 1
	v_add3_u32 v49, v49, v64, s27
	ds_write_b16_d16_hi v59, v49 offset:33792
	ds_read_u16 v49, v59 offset:34320
	v_add_f32_e32 v64, v162, v68
	v_fma_f32 v47, v47, v44, v44
	v_mul_f32_e32 v47, 0x3f4c422a, v47
	v_add_f32_e32 v47, v47, v47
	s_waitcnt lgkmcnt(0)
	v_lshlrev_b32_e32 v49, 16, v49
	v_mul_f32_e32 v68, 0x3d372713, v49
	v_mul_f32_e32 v68, v68, v49
	v_fma_f32 v68, v68, v49, v49
	v_mul_f32_e32 v68, 0x3f4c422a, v68
	v_add_f32_e32 v68, v68, v68
	v_mul_f32_e32 v68, 0x3fb8aa3b, v68
	v_exp_f32_e32 v68, v68
	v_mul_f32_e32 v49, 0.5, v49
	v_mfma_f32_16x16x32_bf16 v[70:73], v[38:41], v[14:17], 0
	v_mul_f32_e32 v47, 0x3fb8aa3b, v47
	v_add_f32_e32 v68, 1.0, v68
	v_rcp_f32_e32 v68, v68
	v_exp_f32_e32 v47, v47
	v_fmac_f32_e32 v160, v167, v159
	v_mul_f32_e32 v44, 0.5, v44
	v_fma_f32 v68, v68, -2.0, 2.0
	v_mul_f32_e32 v49, v49, v68
	v_mul_f32_e32 v49, v64, v49
	v_bfe_u32 v64, v49, 16, 1
	v_add3_u32 v49, v49, v64, s27
	ds_write_b16_d16_hi v59, v49 offset:34320
	ds_read_u16 v49, v59 offset:34848
	v_add_f32_e32 v64, v161, v66
	v_add_f32_e32 v47, 1.0, v47
	v_rcp_f32_e32 v47, v47
	v_add_f32_e32 v42, v160, v42
	s_waitcnt lgkmcnt(0)
	v_lshlrev_b32_e32 v49, 16, v49
	v_mul_f32_e32 v66, 0x3d372713, v49
	v_mul_f32_e32 v66, v66, v49
	v_fma_f32 v66, v66, v49, v49
	v_mul_f32_e32 v66, 0x3f4c422a, v66
	v_add_f32_e32 v66, v66, v66
	v_mul_f32_e32 v66, 0x3fb8aa3b, v66
	v_exp_f32_e32 v66, v66
	v_mul_f32_e32 v49, 0.5, v49
	v_fma_f32 v47, v47, -2.0, 2.0
	v_mul_f32_e32 v44, v44, v47
	v_add_f32_e32 v66, 1.0, v66
	v_rcp_f32_e32 v66, v66
	v_mul_f32_e32 v42, v42, v44
	v_bfe_u32 v44, v42, 16, 1
	v_add3_u32 v42, v42, v44, s27
	v_fma_f32 v66, v66, -2.0, 2.0
	v_mul_f32_e32 v49, v49, v66
	v_mfma_f32_16x16x32_bf16 v[66:69], v[38:41], v[6:9], 0
	v_mul_f32_e32 v49, v64, v49
	v_bfe_u32 v64, v49, 16, 1
	v_add3_u32 v49, v49, v64, s27
	v_mfma_f32_16x16x32_bf16 v[38:41], v[34:37], v[2:5], v[66:69]
	ds_write_b16_d16_hi v59, v49 offset:34848
	ds_write_b16_d16_hi v59, v42 offset:35376
	ds_read_u16 v42, v58 offset:33824
	v_mfma_f32_16x16x32_bf16 v[34:37], v[34:37], v[10:13], v[70:73]
	v_fmac_f32_e32 v43, v48, v46
	s_nop 2
	v_fma_f32 v38, v38, s98, v151
	v_fma_f32 v39, v39, s98, v151
	v_fma_f32 v40, v40, s98, v151
	s_nop 0
	s_nop 0
	s_nop 0
	v_exp_f32_e32 v38, v38
	v_exp_f32_e32 v39, v39
	v_exp_f32_e32 v40, v40
	v_fma_f32 v34, v34, s98, v150
	v_fma_f32 v35, v35, s98, v150
	v_fma_f32 v36, v36, s98, v150
	s_nop 0
	s_nop 0
	s_nop 0
	v_fma_f32 v41, v41, s98, v151
	v_add_f32_e32 v38, 1.0, v38
	v_exp_f32_e32 v34, v34
	v_add_f32_e32 v39, 1.0, v39
	v_exp_f32_e32 v35, v35
	v_add_f32_e32 v40, 1.0, v40
	v_exp_f32_e32 v36, v36
	s_nop 0
	v_rcp_f32_e32 v38, v38
	v_rcp_f32_e32 v39, v39
	v_rcp_f32_e32 v40, v40
	v_exp_f32_e32 v41, v41
	v_fma_f32 v37, v37, s98, v150
	v_add_f32_e32 v34, 1.0, v34
	v_add_f32_e32 v35, 1.0, v35
	v_add_f32_e32 v36, 1.0, v36
	s_nop 0
	v_rcp_f32_e32 v44, v34
	v_mul_f32_e32 v34, v57, v38
	v_rcp_f32_e32 v47, v35
	v_mul_f32_e32 v35, v57, v39
	v_rcp_f32_e32 v49, v36
	v_mul_f32_e32 v36, v57, v40
	v_add_f32_e32 v41, 1.0, v41
	v_exp_f32_e32 v37, v37
	s_nop 0
	s_nop 0
	s_nop 0
	v_rcp_f32_e32 v41, v41
	v_exp_f32_e32 v34, v34
	v_exp_f32_e32 v35, v35
	v_exp_f32_e32 v36, v36
	v_add_f32_e32 v37, 1.0, v37
	v_rcp_f32_e32 v64, v37
	v_mul_f32_e32 v37, v57, v41
	v_fma_f32 v38, -v34, v34, 1.0
	v_fma_f32 v39, -v35, v35, 1.0
	v_fma_f32 v40, -v36, v36, 1.0
	s_nop 0
	v_max_f32_e32 v38, 0, v38
	v_max_f32_e32 v39, 0, v39
	v_max_f32_e32 v40, 0, v40
	v_exp_f32_e32 v37, v37
	v_sqrt_f32_e32 v38, v38
	v_sqrt_f32_e32 v39, v39
	v_sqrt_f32_e32 v40, v40
	v_fma_f32 v41, -v37, v37, 1.0
	v_mul_f32_e32 v38, v44, v38
	ds_read_u16 v44, v58 offset:34352
	v_mul_f32_e32 v39, v47, v39
	ds_read_u16 v47, v58 offset:34880
	v_mul_f32_e32 v40, v49, v40
	ds_read_u16 v49, v58 offset:35408
	v_max_f32_e32 v41, 0, v41
	v_sqrt_f32_e32 v41, v41
	s_waitcnt lgkmcnt(1)
	v_lshlrev_b32_e32 v47, 16, v47
	v_lshlrev_b32_e32 v44, 16, v44
	s_waitcnt lgkmcnt(0)
	v_lshlrev_b32_e32 v49, 16, v49
	v_mul_f32_e32 v41, v64, v41
	v_mul_f32_e32 v41, v41, v49
	v_mul_f32_e32 v64, v36, v37
	v_mul_f32_e32 v36, v36, v41
	v_fmac_f32_e32 v36, v40, v47
	v_mul_f32_e32 v40, v35, v64
	v_mul_f32_e32 v35, v35, v36
	v_fmac_f32_e32 v35, v39, v44
	v_lshlrev_b32_e32 v42, 16, v42
	v_mul_f32_e32 v39, v34, v40
	v_mul_f32_e32 v34, v34, v35
	v_fmac_f32_e32 v34, v38, v42
	ds_bpermute_b32 v68, v54, v39
	ds_bpermute_b32 v38, v54, v34
	ds_bpermute_b32 v67, v55, v39
	ds_bpermute_b32 v44, v55, v34
	ds_bpermute_b32 v66, v56, v39
	ds_bpermute_b32 v49, v56, v34
	ds_bpermute_b32 v47, v61, v39
	ds_bpermute_b32 v42, v61, v34
	s_waitcnt lgkmcnt(6)
	v_fmac_f32_e32 v38, v43, v68
	s_waitcnt lgkmcnt(4)
	v_fmac_f32_e32 v44, v38, v67
	s_waitcnt lgkmcnt(2)
	v_fmac_f32_e32 v49, v44, v66
	v_cmp_gt_i32_e64 s[0:1], 3, v51
	s_and_saveexec_b64 s[4:5], s[0:1]
	s_cbranch_execz .LBB0_689
	v_cmp_ne_u32_e64 s[0:1], 2, v51
	s_and_saveexec_b64 s[34:35], s[0:1]
	s_xor_b64 s[0:1], exec, s[34:35]
	v_cndmask_b32_e32 v43, v49, v44, vcc
	s_andn2_saveexec_b64 s[0:1], s[0:1]
	v_mov_b32_e32 v43, v38
	s_or_b64 exec, exec, s[0:1]
; template <int DIR, int MODE>
; __device__ __forceinline__ void lru_pass(const Args& a, const LAS bf16_t* cxb, LAS bf16_t* gyb, const LAS float* carry, const bf16x8 (&Bw)[2][2][2], const float (&prm)[2][3], int l, int tt, float (&hf)[8][2][4]) {
;     ...
;     for (int mi = 0; mi < 8; ++mi) {
;         const int m = DIR ? 7 - mi : mi;
;         bf16x8 Af[2];
; #pragma unroll
;         for (int ks = 0; ks < 2; ++ks) Af[ks] = *(const LAS bf16x8*)(cxb + (m * 16 + fr) * CXS + 64 * h + 32 * ks + 8 * fq);
; #pragma unroll
;         for (int nt = 0; nt < 2; ++nt) {
;             f32x4 pr = (f32x4){0.f, 0.f, 0.f, 0.f}, pi = (f32x4){0.f, 0.f, 0.f, 0.f};
; #pragma unroll
;             for (int ks = 0; ks < 2; ++ks) { pr = __builtin_amdgcn_mfma_f32_16x16x32_bf16(Af[ks], Bw[0][nt][ks], pr, 0, 0, 0); pi = __builtin_amdgcn_mfma_f32_16x16x32_bf16(Af[ks], Bw[1][nt][ks], pi, 0, 0, 0); }
;             float av[4], bv[4];
; #pragma unroll
;             for (int reg = 0; reg < 4; ++reg) {
;                 const int tok = m * 16 + 4 * fq + reg;
;                 const float x = bf2f(cxb[tok * CXS + cc[nt]]);
;                 const float r = fsig(pr[reg] + ba[nt]), ig = fsig(pi[reg] + bxv[nt]);
;                 const float aa = __expf(k8[nt] * r);
;                 av[reg] = aa; bv[reg] = __builtin_amdgcn_sqrtf(fmaxf(1.0f - aa * aa, 0.f)) * ig * x;
;             }
;             float cum[4], hl[4];
;             if (DIR == 0) { cum[0] = av[0]; hl[0] = bv[0];
; #pragma unroll
;                 for (int reg = 1; reg < 4; ++reg) { cum[reg] = cum[reg - 1] * av[reg]; hl[reg] = av[reg] * hl[reg - 1] + bv[reg]; } }
;             else { cum[3] = av[3]; hl[3] = bv[3];
; #pragma unroll
;     ...
;             const float A4 = DIR ? cum[0] : cum[3], H4 = DIR ? hl[0] : hl[3];
;             float Aq[4], Hq[4];
; #pragma unroll
;             for (int q = 0; q < 4; ++q) { Aq[q] = __shfl(A4, fr + 16 * q); Hq[q] = __shfl(H4, fr + 16 * q); }
;             float hin;
;             if (DIR == 0) { const float s0 = C[nt], s1 = Aq[0] * s0 + Hq[0], s2 = Aq[1] * s1 + Hq[1], s3 = Aq[2] * s2 + Hq[2]; C[nt] = Aq[3] * s3 + Hq[3]; hin = fq == 0 ? s0 : (fq == 1 ? s1 : (fq == 2 ? s2 : s3)); }
;             else { const float s3 = C[nt], s2 = Aq[3] * s3 + Hq[3], s1 = Aq[2] * s2 + Hq[2], s0 = Aq[1] * s1 + Hq[1]; C[nt] = Aq[0] * s0 + Hq[0]; hin = fq == 3 ? s3 : (fq == 2 ? s2 : (fq == 1 ? s1 : s0)); }
.LBB0_689:
	s_or_b64 exec, exec, s[4:5]
	ds_read_u16 v38, v52 offset:33792
	ds_read_u16 v44, v52 offset:34320
	ds_read_u16 v46, v52 offset:34848
	ds_read_u16 v48, v52 offset:35376
	ds_read_u16 v80, v58 offset:26928
	s_waitcnt lgkmcnt(4)
	v_lshlrev_b32_e32 v38, 16, v38
	v_mul_f32_e32 v66, 0x3d372713, v38
	v_mul_f32_e32 v66, v66, v38
	v_fma_f32 v66, v66, v38, v38
	v_mul_f32_e32 v66, 0x3f4c422a, v66
	v_add_f32_e32 v66, v66, v66
	v_mul_f32_e32 v66, 0x3fb8aa3b, v66
	v_exp_f32_e32 v66, v66
	v_fmac_f32_e32 v147, v148, v146
	v_fmac_f32_e32 v34, v39, v43
	v_mul_f32_e32 v38, 0.5, v38
	v_add_f32_e32 v66, 1.0, v66
	v_rcp_f32_e32 v66, v66
	v_add_f32_e32 v34, v147, v34
	v_fmac_f32_e32 v155, v156, v146
	v_fmac_f32_e32 v35, v40, v43
	v_fma_f32 v39, v66, -2.0, 2.0
	v_mul_f32_e32 v38, v38, v39
	v_mul_f32_e32 v34, v34, v38
	s_waitcnt lgkmcnt(3)
	v_lshlrev_b32_e32 v38, 16, v44
	v_mul_f32_e32 v39, 0x3d372713, v38
	v_mul_f32_e32 v39, v39, v38
	v_fma_f32 v39, v39, v38, v38
	v_mul_f32_e32 v39, 0x3f4c422a, v39
	v_add_f32_e32 v39, v39, v39
	v_mul_f32_e32 v39, 0x3fb8aa3b, v39
	v_exp_f32_e32 v39, v39
	v_bfe_u32 v44, v34, 16, 1
	v_add3_u32 v34, v34, v44, s27
	ds_write_b16_d16_hi v52, v34 offset:33792
	v_add_f32_e32 v34, 1.0, v39
	v_rcp_f32_e32 v34, v34
	v_mul_f32_e32 v38, 0.5, v38
	v_add_f32_e32 v35, v155, v35
	v_fmac_f32_e32 v154, v157, v146
	v_fma_f32 v34, v34, -2.0, 2.0
	v_mul_f32_e32 v34, v38, v34
	v_mul_f32_e32 v34, v35, v34
	s_waitcnt lgkmcnt(3)
	v_lshlrev_b32_e32 v35, 16, v46
	v_mul_f32_e32 v38, 0x3d372713, v35
	v_mul_f32_e32 v38, v38, v35
	v_fma_f32 v38, v38, v35, v35
	v_mul_f32_e32 v38, 0x3f4c422a, v38
	v_add_f32_e32 v38, v38, v38
	v_mul_f32_e32 v38, 0x3fb8aa3b, v38
	v_exp_f32_e32 v38, v38
	v_bfe_u32 v39, v34, 16, 1
	v_add3_u32 v34, v34, v39, s27
	ds_write_b16_d16_hi v52, v34 offset:34320
	v_add_f32_e32 v34, 1.0, v38
	v_rcp_f32_e32 v34, v34
	v_fmac_f32_e32 v36, v64, v43
	v_mul_f32_e32 v35, 0.5, v35
	v_add_f32_e32 v36, v154, v36
	v_fma_f32 v34, v34, -2.0, 2.0
	v_mul_f32_e32 v34, v35, v34
	s_waitcnt lgkmcnt(3)
	v_lshlrev_b32_e32 v35, 16, v48
	v_mul_f32_e32 v34, v36, v34
	v_mul_f32_e32 v36, 0x3d372713, v35
	v_mul_f32_e32 v36, v36, v35
	v_fma_f32 v36, v36, v35, v35
	v_mul_f32_e32 v36, 0x3f4c422a, v36
	v_add_f32_e32 v36, v36, v36
	v_mul_f32_e32 v36, 0x3fb8aa3b, v36
	v_exp_f32_e32 v36, v36
	v_bfe_u32 v38, v34, 16, 1
	v_add3_u32 v34, v34, v38, s27
	ds_write_b16_d16_hi v52, v34 offset:34848
	v_add_f32_e32 v34, 1.0, v36
	v_rcp_f32_e32 v34, v34
	v_fmac_f32_e32 v149, v158, v146
	v_fmac_f32_e32 v41, v37, v43
	v_mul_f32_e32 v35, 0.5, v35
	v_fma_f32 v34, v34, -2.0, 2.0
	v_add_f32_e32 v36, v149, v41
	v_mul_f32_e32 v34, v35, v34
	v_mul_f32_e32 v34, v36, v34
	v_bfe_u32 v35, v34, 16, 1
	v_add3_u32 v34, v34, v35, s27
	ds_write_b16_d16_hi v52, v34 offset:35376
	ds_read_b128 v[38:41], v62 offset:25344
	ds_read_b128 v[34:37], v62 offset:25408
	s_waitcnt lgkmcnt(1)
	v_mfma_f32_16x16x32_bf16 v[66:69], v[38:41], v[22:25], 0
	ds_read_u16 v44, v58 offset:25344
	ds_read_u16 v46, v58 offset:25872
	ds_read_u16 v48, v58 offset:26400
	v_fmac_f32_e32 v45, v65, v63
	v_cmp_gt_i32_e64 s[0:1], 3, v51
	s_waitcnt lgkmcnt(3)
	v_mfma_f32_16x16x32_bf16 v[66:69], v[34:37], v[18:21], v[66:69]
	s_waitcnt lgkmcnt(2)
	v_lshlrev_b32_e32 v44, 16, v44
	s_waitcnt lgkmcnt(0)
	v_lshlrev_b32_e32 v48, 16, v48
	v_mfma_f32_16x16x32_bf16 v[70:73], v[38:41], v[30:33], 0
	v_mfma_f32_16x16x32_bf16 v[70:73], v[34:37], v[26:29], v[70:73]
	s_nop 1
	v_fma_f32 v43, v66, s98, v153
	s_nop 0
	v_exp_f32_e32 v43, v43
	v_fma_f32 v67, v67, s98, v153
	s_nop 0
	s_nop 0
	v_fma_f32 v64, v70, s98, v152
	v_add_f32_e32 v43, 1.0, v43
	v_rcp_f32_e32 v43, v43
	s_nop 0
	v_exp_f32_e32 v64, v64
	v_exp_f32_e32 v67, v67
	v_mul_f32_e32 v43, v60, v43
	s_nop 0
	v_exp_f32_e32 v66, v43
	v_add_f32_e32 v43, 1.0, v64
	v_add_f32_e32 v67, 1.0, v67
	v_rcp_f32_e32 v43, v43
	v_fma_f32 v64, -v66, v66, 1.0
	v_max_f32_e32 v64, 0, v64
	v_sqrt_f32_e32 v64, v64
	v_fma_f32 v70, v71, s98, v152
	v_rcp_f32_e32 v67, v67
	s_nop 0
	v_exp_f32_e32 v70, v70
	v_mul_f32_e32 v81, v43, v64
	v_mul_f32_e32 v64, v60, v67
	s_nop 0
	v_add_f32_e32 v43, 1.0, v70
	v_exp_f32_e32 v70, v64
	v_fma_f32 v64, v68, s98, v153
	s_nop 0
	v_exp_f32_e32 v64, v64
	v_lshlrev_b32_e32 v71, 16, v46
	v_fma_f32 v67, -v70, v70, 1.0
	v_fma_f32 v68, v72, s98, v152
	v_add_f32_e32 v64, 1.0, v64
	v_rcp_f32_e32 v64, v64
	v_max_f32_e32 v67, 0, v67
	s_nop 0
	v_rcp_f32_e32 v43, v43
	v_mul_f32_e32 v46, v60, v64
	s_nop 0
	v_exp_f32_e32 v64, v46
	v_fma_f32 v46, v69, s98, v153
	s_nop 0
	v_exp_f32_e32 v46, v46
	v_sqrt_f32_e32 v67, v67
	v_exp_f32_e32 v68, v68
	v_add_f32_e32 v46, 1.0, v46
	v_rcp_f32_e32 v46, v46
	v_mul_f32_e32 v72, v43, v67
	v_add_f32_e32 v43, 1.0, v68
	v_fma_f32 v68, v73, s98, v152
	v_mul_f32_e32 v46, v60, v46
	s_nop 0
	s_nop 0
	v_exp_f32_e32 v46, v46
	v_exp_f32_e32 v68, v68
	v_fma_f32 v67, -v64, v64, 1.0
	v_max_f32_e32 v67, 0, v67
	v_fma_f32 v69, -v46, v46, 1.0
	v_add_f32_e32 v68, 1.0, v68
	v_max_f32_e32 v69, 0, v69
	v_rcp_f32_e32 v43, v43
	v_sqrt_f32_e32 v67, v67
	v_rcp_f32_e32 v68, v68
	v_sqrt_f32_e32 v69, v69
	v_mul_f32_e32 v73, v43, v67
	v_lshlrev_b32_e32 v43, 16, v80
	v_mul_f32_e32 v67, v68, v69
	v_mul_f32_e32 v43, v67, v43
	v_mul_f32_e32 v67, v64, v46
	v_mul_f32_e32 v64, v64, v43
	v_fmac_f32_e32 v64, v73, v48
	v_mul_f32_e32 v68, v70, v64
	v_fmac_f32_e32 v68, v72, v71
	v_mul_f32_e32 v69, v70, v67
	v_mul_f32_e32 v70, v66, v68
	v_mul_f32_e32 v71, v66, v69
	v_fmac_f32_e32 v70, v81, v44
	ds_bpermute_b32 v148, v54, v71
	ds_bpermute_b32 v72, v54, v70
	ds_bpermute_b32 v147, v55, v71
	ds_bpermute_b32 v73, v55, v70
	ds_bpermute_b32 v146, v56, v71
	ds_bpermute_b32 v66, v56, v70
	ds_bpermute_b32 v48, v61, v71
	ds_bpermute_b32 v44, v61, v70
	s_waitcnt lgkmcnt(6)
	v_fmac_f32_e32 v72, v45, v148
	s_waitcnt lgkmcnt(4)
	v_fmac_f32_e32 v73, v72, v147
	s_waitcnt lgkmcnt(2)
	v_fmac_f32_e32 v66, v73, v146
	s_and_saveexec_b64 s[4:5], s[0:1]
	s_cbranch_execz .LBB0_695
	v_cmp_ne_u32_e64 s[0:1], 2, v51
	s_and_saveexec_b64 s[34:35], s[0:1]
	s_xor_b64 s[0:1], exec, s[34:35]
	v_cndmask_b32_e32 v45, v66, v73, vcc
	s_andn2_saveexec_b64 s[0:1], s[0:1]
	v_mov_b32_e32 v45, v72
	s_or_b64 exec, exec, s[0:1]
; template <int DIR, int MODE>
; __device__ __forceinline__ void lru_pass(const Args& a, const LAS bf16_t* cxb, LAS bf16_t* gyb, const LAS float* carry, const bf16x8 (&Bw)[2][2][2], const float (&prm)[2][3], int l, int tt, float (&hf)[8][2][4]) {
;     ...
;     for (int mi = 0; mi < 8; ++mi) {
;         const int m = DIR ? 7 - mi : mi;
;         bf16x8 Af[2];
; #pragma unroll
;         for (int ks = 0; ks < 2; ++ks) Af[ks] = *(const LAS bf16x8*)(cxb + (m * 16 + fr) * CXS + 64 * h + 32 * ks + 8 * fq);
; #pragma unroll
;         for (int nt = 0; nt < 2; ++nt) {
;             f32x4 pr = (f32x4){0.f, 0.f, 0.f, 0.f}, pi = (f32x4){0.f, 0.f, 0.f, 0.f};
; #pragma unroll
;             for (int ks = 0; ks < 2; ++ks) { pr = __builtin_amdgcn_mfma_f32_16x16x32_bf16(Af[ks], Bw[0][nt][ks], pr, 0, 0, 0); pi = __builtin_amdgcn_mfma_f32_16x16x32_bf16(Af[ks], Bw[1][nt][ks], pi, 0, 0, 0); }
;             float av[4], bv[4];
; #pragma unroll
;             for (int reg = 0; reg < 4; ++reg) {
;                 const int tok = m * 16 + 4 * fq + reg;
;                 const float x = bf2f(cxb[tok * CXS + cc[nt]]);
;                 const float r = fsig(pr[reg] + ba[nt]), ig = fsig(pi[reg] + bxv[nt]);
;                 const float aa = __expf(k8[nt] * r);
;                 av[reg] = aa; bv[reg] = __builtin_amdgcn_sqrtf(fmaxf(1.0f - aa * aa, 0.f)) * ig * x;
;             }
;             float cum[4], hl[4];
;             if (DIR == 0) { cum[0] = av[0]; hl[0] = bv[0];
; #pragma unroll
;                 for (int reg = 1; reg < 4; ++reg) { cum[reg] = cum[reg - 1] * av[reg]; hl[reg] = av[reg] * hl[reg - 1] + bv[reg]; } }
;             else { cum[3] = av[3]; hl[3] = bv[3];
; #pragma unroll
;     ...
;             const float A4 = DIR ? cum[0] : cum[3], H4 = DIR ? hl[0] : hl[3];
;             float Aq[4], Hq[4];
; #pragma unroll
;             for (int q = 0; q < 4; ++q) { Aq[q] = __shfl(A4, fr + 16 * q); Hq[q] = __shfl(H4, fr + 16 * q); }
;             float hin;
;             if (DIR == 0) { const float s0 = C[nt], s1 = Aq[0] * s0 + Hq[0], s2 = Aq[1] * s1 + Hq[1], s3 = Aq[2] * s2 + Hq[2]; C[nt] = Aq[3] * s3 + Hq[3]; hin = fq == 0 ? s0 : (fq == 1 ? s1 : (fq == 2 ? s2 : s3)); }
;             else { const float s3 = C[nt], s2 = Aq[3] * s3 + Hq[3], s1 = Aq[2] * s2 + Hq[2], s0 = Aq[1] * s1 + Hq[1]; C[nt] = Aq[0] * s0 + Hq[0]; hin = fq == 3 ? s3 : (fq == 2 ? s2 : (fq == 1 ? s1 : s0)); }
.LBB0_695:
	s_or_b64 exec, exec, s[4:5]
	ds_read_u16 v63, v59 offset:25344
	v_fmac_f32_e32 v141, v142, v137
	v_fmac_f32_e32 v70, v71, v45
	v_fmac_f32_e32 v68, v69, v45
	v_fmac_f32_e32 v64, v67, v45
	v_fmac_f32_e32 v43, v46, v45
	ds_read_u16 v45, v59 offset:26928
	s_waitcnt lgkmcnt(1)
	v_lshlrev_b32_e32 v63, 16, v63
	v_add_f32_e32 v65, v141, v70
	v_mul_f32_e32 v70, 0x3d372713, v63
	v_mul_f32_e32 v70, v70, v63
	v_fma_f32 v70, v70, v63, v63
	v_mul_f32_e32 v70, 0x3f4c422a, v70
	v_add_f32_e32 v70, v70, v70
	v_mul_f32_e32 v70, 0x3fb8aa3b, v70
	v_exp_f32_e32 v70, v70
	v_mul_f32_e32 v63, 0.5, v63
	v_fmac_f32_e32 v140, v143, v137
	s_waitcnt lgkmcnt(0)
	v_lshlrev_b32_e32 v45, 16, v45
	v_add_f32_e32 v70, 1.0, v70
	v_rcp_f32_e32 v70, v70
	v_mul_f32_e32 v46, 0x3d372713, v45
	v_mul_f32_e32 v46, v46, v45
	v_fma_f32 v46, v46, v45, v45
	v_fma_f32 v70, v70, -2.0, 2.0
	v_mul_f32_e32 v63, v63, v70
	v_mul_f32_e32 v63, v65, v63
	v_bfe_u32 v65, v63, 16, 1
	v_add3_u32 v63, v63, v65, s27
	ds_write_b16_d16_hi v59, v63 offset:25344
	ds_read_u16 v63, v59 offset:25872
	v_add_f32_e32 v65, v140, v68
	v_mul_f32_e32 v46, 0x3f4c422a, v46
	v_add_f32_e32 v46, v46, v46
	v_mfma_f32_16x16x32_bf16 v[80:83], v[38:41], v[14:17], 0
	s_waitcnt lgkmcnt(0)
	v_lshlrev_b32_e32 v63, 16, v63
	v_mul_f32_e32 v68, 0x3d372713, v63
	v_mul_f32_e32 v68, v68, v63
	v_fma_f32 v68, v68, v63, v63
	v_mul_f32_e32 v68, 0x3f4c422a, v68
	v_add_f32_e32 v68, v68, v68
	v_mul_f32_e32 v68, 0x3fb8aa3b, v68
	v_exp_f32_e32 v68, v68
	v_mul_f32_e32 v63, 0.5, v63
	v_mul_f32_e32 v46, 0x3fb8aa3b, v46
	v_exp_f32_e32 v46, v46
	v_add_f32_e32 v68, 1.0, v68
	v_rcp_f32_e32 v68, v68
	v_fmac_f32_e32 v139, v144, v137
	v_add_f32_e32 v46, 1.0, v46
	v_rcp_f32_e32 v46, v46
	v_fma_f32 v68, v68, -2.0, 2.0
	v_mul_f32_e32 v63, v63, v68
	v_mul_f32_e32 v63, v65, v63
	v_bfe_u32 v65, v63, 16, 1
	v_add3_u32 v63, v63, v65, s27
	ds_write_b16_d16_hi v59, v63 offset:25872
	ds_read_u16 v63, v59 offset:26400
	v_mfma_f32_16x16x32_bf16 v[68:71], v[38:41], v[6:9], 0
	v_fmac_f32_e32 v138, v145, v137
	v_add_f32_e32 v64, v139, v64
	v_mul_f32_e32 v45, 0.5, v45
	s_waitcnt lgkmcnt(0)
	v_lshlrev_b32_e32 v63, 16, v63
	v_mul_f32_e32 v65, 0x3d372713, v63
	v_mul_f32_e32 v65, v65, v63
	v_fma_f32 v65, v65, v63, v63
	v_mul_f32_e32 v65, 0x3f4c422a, v65
	v_add_f32_e32 v65, v65, v65
	v_mul_f32_e32 v65, 0x3fb8aa3b, v65
	v_mfma_f32_16x16x32_bf16 v[38:41], v[34:37], v[2:5], v[68:71]
	v_exp_f32_e32 v65, v65
	v_mul_f32_e32 v63, 0.5, v63
	v_fma_f32 v46, v46, -2.0, 2.0
	v_mfma_f32_16x16x32_bf16 v[34:37], v[34:37], v[10:13], v[80:83]
	v_add_f32_e32 v65, 1.0, v65
	s_nop 2
	v_fma_f32 v38, v38, s98, v151
	v_fma_f32 v39, v39, s98, v151
	v_fma_f32 v40, v40, s98, v151
	s_nop 0
	s_nop 0
	s_nop 0
	v_rcp_f32_e32 v65, v65
	v_exp_f32_e32 v38, v38
	v_exp_f32_e32 v39, v39
	v_exp_f32_e32 v40, v40
	v_fma_f32 v34, v34, s98, v150
	v_fma_f32 v35, v35, s98, v150
	v_fma_f32 v36, v36, s98, v150
	s_nop 0
	s_nop 0
	s_nop 0
	v_fma_f32 v41, v41, s98, v151
	v_fma_f32 v65, v65, -2.0, 2.0
	v_add_f32_e32 v38, 1.0, v38
	v_exp_f32_e32 v34, v34
	v_add_f32_e32 v39, 1.0, v39
	v_exp_f32_e32 v35, v35
	v_add_f32_e32 v40, 1.0, v40
	v_exp_f32_e32 v36, v36
	s_nop 0
	v_mul_f32_e32 v63, v63, v65
	v_rcp_f32_e32 v38, v38
	v_rcp_f32_e32 v39, v39
	v_rcp_f32_e32 v40, v40
	v_exp_f32_e32 v41, v41
	v_mul_f32_e32 v63, v64, v63
	v_add_f32_e32 v43, v138, v43
	v_mul_f32_e32 v45, v45, v46
	v_bfe_u32 v64, v63, 16, 1
	v_mul_f32_e32 v43, v43, v45
	v_fma_f32 v37, v37, s98, v150
	v_add3_u32 v63, v63, v64, s27
	v_bfe_u32 v45, v43, 16, 1
	v_add_f32_e32 v34, 1.0, v34
	v_add_f32_e32 v35, 1.0, v35
	v_add_f32_e32 v36, 1.0, v36
	s_nop 0
	ds_write_b16_d16_hi v59, v63 offset:26400
	v_add3_u32 v43, v43, v45, s27
	v_rcp_f32_e32 v45, v34
	v_mul_f32_e32 v34, v57, v38
	v_rcp_f32_e32 v46, v35
	v_mul_f32_e32 v35, v57, v39
	v_rcp_f32_e32 v63, v36
	v_mul_f32_e32 v36, v57, v40
	v_add_f32_e32 v41, 1.0, v41
	v_exp_f32_e32 v37, v37
	s_nop 0
	s_nop 0
	s_nop 0
	v_rcp_f32_e32 v41, v41
	v_exp_f32_e32 v34, v34
	v_exp_f32_e32 v35, v35
	v_exp_f32_e32 v36, v36
	v_add_f32_e32 v37, 1.0, v37
	v_rcp_f32_e32 v64, v37
	v_mul_f32_e32 v37, v57, v41
	v_fma_f32 v38, -v34, v34, 1.0
	v_fma_f32 v39, -v35, v35, 1.0
	v_fma_f32 v40, -v36, v36, 1.0
	s_nop 0
	v_max_f32_e32 v38, 0, v38
	v_max_f32_e32 v39, 0, v39
	v_max_f32_e32 v40, 0, v40
	v_exp_f32_e32 v37, v37
	v_sqrt_f32_e32 v38, v38
	v_sqrt_f32_e32 v39, v39
	v_sqrt_f32_e32 v40, v40
	v_fma_f32 v41, -v37, v37, 1.0
	ds_write_b16_d16_hi v59, v43 offset:26928
	ds_read_u16 v43, v58 offset:25376
	v_mul_f32_e32 v38, v45, v38
	ds_read_u16 v45, v58 offset:25904
	v_mul_f32_e32 v39, v46, v39
	ds_read_u16 v46, v58 offset:26432
	v_mul_f32_e32 v40, v63, v40
	ds_read_u16 v63, v58 offset:26960
	v_max_f32_e32 v41, 0, v41
	v_sqrt_f32_e32 v41, v41
	s_waitcnt lgkmcnt(1)
	v_lshlrev_b32_e32 v46, 16, v46
	v_lshlrev_b32_e32 v45, 16, v45
	s_waitcnt lgkmcnt(0)
	v_lshlrev_b32_e32 v63, 16, v63
	v_mul_f32_e32 v41, v64, v41
	v_mul_f32_e32 v41, v41, v63
	v_mul_f32_e32 v63, v36, v37
	v_mul_f32_e32 v36, v36, v41
	v_fmac_f32_e32 v36, v40, v46
	v_mul_f32_e32 v40, v35, v63
	v_mul_f32_e32 v35, v35, v36
	v_fmac_f32_e32 v35, v39, v45
	v_lshlrev_b32_e32 v43, 16, v43
	v_mul_f32_e32 v39, v34, v40
	v_mul_f32_e32 v34, v34, v35
	v_fmac_f32_e32 v34, v38, v43
	ds_bpermute_b32 v68, v54, v39
	ds_bpermute_b32 v38, v54, v34
	ds_bpermute_b32 v67, v55, v39
	ds_bpermute_b32 v64, v55, v34
	ds_bpermute_b32 v65, v56, v39
	ds_bpermute_b32 v46, v56, v34
	ds_bpermute_b32 v45, v61, v39
	ds_bpermute_b32 v43, v61, v34
	v_fmac_f32_e32 v42, v49, v47
	s_waitcnt lgkmcnt(6)
	v_fmac_f32_e32 v38, v42, v68
	s_waitcnt lgkmcnt(4)
	v_fmac_f32_e32 v64, v38, v67
	s_waitcnt lgkmcnt(2)
	v_fmac_f32_e32 v46, v64, v65
	v_cmp_gt_i32_e64 s[0:1], 3, v51
	s_and_saveexec_b64 s[4:5], s[0:1]
	s_cbranch_execz .LBB0_701
	v_cmp_ne_u32_e64 s[0:1], 2, v51
	s_and_saveexec_b64 s[34:35], s[0:1]
	s_xor_b64 s[0:1], exec, s[34:35]
	v_cndmask_b32_e32 v42, v46, v64, vcc
	s_andn2_saveexec_b64 s[0:1], s[0:1]
	v_mov_b32_e32 v42, v38
	s_or_b64 exec, exec, s[0:1]
; template <int DIR, int MODE>
; __device__ __forceinline__ void lru_pass(const Args& a, const LAS bf16_t* cxb, LAS bf16_t* gyb, const LAS float* carry, const bf16x8 (&Bw)[2][2][2], const float (&prm)[2][3], int l, int tt, float (&hf)[8][2][4]) {
;     ...
;     for (int mi = 0; mi < 8; ++mi) {
;         const int m = DIR ? 7 - mi : mi;
;         bf16x8 Af[2];
; #pragma unroll
;         for (int ks = 0; ks < 2; ++ks) Af[ks] = *(const LAS bf16x8*)(cxb + (m * 16 + fr) * CXS + 64 * h + 32 * ks + 8 * fq);
; #pragma unroll
;         for (int nt = 0; nt < 2; ++nt) {
;             f32x4 pr = (f32x4){0.f, 0.f, 0.f, 0.f}, pi = (f32x4){0.f, 0.f, 0.f, 0.f};
; #pragma unroll
;             for (int ks = 0; ks < 2; ++ks) { pr = __builtin_amdgcn_mfma_f32_16x16x32_bf16(Af[ks], Bw[0][nt][ks], pr, 0, 0, 0); pi = __builtin_amdgcn_mfma_f32_16x16x32_bf16(Af[ks], Bw[1][nt][ks], pi, 0, 0, 0); }
;             float av[4], bv[4];
; #pragma unroll
;             for (int reg = 0; reg < 4; ++reg) {
;                 const int tok = m * 16 + 4 * fq + reg;
;                 const float x = bf2f(cxb[tok * CXS + cc[nt]]);
;                 const float r = fsig(pr[reg] + ba[nt]), ig = fsig(pi[reg] + bxv[nt]);
;                 const float aa = __expf(k8[nt] * r);
;                 av[reg] = aa; bv[reg] = __builtin_amdgcn_sqrtf(fmaxf(1.0f - aa * aa, 0.f)) * ig * x;
;             }
;             float cum[4], hl[4];
;             if (DIR == 0) { cum[0] = av[0]; hl[0] = bv[0];
; #pragma unroll
;                 for (int reg = 1; reg < 4; ++reg) { cum[reg] = cum[reg - 1] * av[reg]; hl[reg] = av[reg] * hl[reg - 1] + bv[reg]; } }
;             else { cum[3] = av[3]; hl[3] = bv[3];
; #pragma unroll
;     ...
;             const float A4 = DIR ? cum[0] : cum[3], H4 = DIR ? hl[0] : hl[3];
;             float Aq[4], Hq[4];
; #pragma unroll
;             for (int q = 0; q < 4; ++q) { Aq[q] = __shfl(A4, fr + 16 * q); Hq[q] = __shfl(H4, fr + 16 * q); }
;             float hin;
;             if (DIR == 0) { const float s0 = C[nt], s1 = Aq[0] * s0 + Hq[0], s2 = Aq[1] * s1 + Hq[1], s3 = Aq[2] * s2 + Hq[2]; C[nt] = Aq[3] * s3 + Hq[3]; hin = fq == 0 ? s0 : (fq == 1 ? s1 : (fq == 2 ? s2 : s3)); }
;             else { const float s3 = C[nt], s2 = Aq[3] * s3 + Hq[3], s1 = Aq[2] * s2 + Hq[2], s0 = Aq[1] * s1 + Hq[1]; C[nt] = Aq[0] * s0 + Hq[0]; hin = fq == 3 ? s3 : (fq == 2 ? s2 : (fq == 1 ? s1 : s0)); }
.LBB0_701:
	s_or_b64 exec, exec, s[4:5]
	ds_read_u16 v38, v52 offset:25344
	ds_read_u16 v47, v52 offset:25872
	ds_read_u16 v49, v52 offset:26400
	ds_read_u16 v64, v52 offset:26928
	ds_read_u16 v65, v58 offset:18480
	s_waitcnt lgkmcnt(4)
	v_lshlrev_b32_e32 v38, 16, v38
	v_mul_f32_e32 v67, 0x3d372713, v38
	v_mul_f32_e32 v67, v67, v38
	v_fma_f32 v67, v67, v38, v38
	v_mul_f32_e32 v67, 0x3f4c422a, v67
	v_add_f32_e32 v67, v67, v67
	v_mul_f32_e32 v67, 0x3fb8aa3b, v67
	v_exp_f32_e32 v67, v67
	v_fmac_f32_e32 v129, v130, v128
	v_fmac_f32_e32 v34, v39, v42
	v_mul_f32_e32 v38, 0.5, v38
	v_add_f32_e32 v67, 1.0, v67
	v_rcp_f32_e32 v67, v67
	v_add_f32_e32 v34, v129, v34
	v_fmac_f32_e32 v133, v134, v128
	v_fmac_f32_e32 v35, v40, v42
	v_fma_f32 v39, v67, -2.0, 2.0
	v_mul_f32_e32 v38, v38, v39
	v_mul_f32_e32 v34, v34, v38
	s_waitcnt lgkmcnt(3)
	v_lshlrev_b32_e32 v38, 16, v47
	v_mul_f32_e32 v39, 0x3d372713, v38
	v_mul_f32_e32 v39, v39, v38
	v_fma_f32 v39, v39, v38, v38
	v_mul_f32_e32 v39, 0x3f4c422a, v39
	v_add_f32_e32 v39, v39, v39
	v_mul_f32_e32 v39, 0x3fb8aa3b, v39
	v_exp_f32_e32 v39, v39
	v_bfe_u32 v47, v34, 16, 1
	v_add3_u32 v34, v34, v47, s27
	ds_write_b16_d16_hi v52, v34 offset:25344
	v_add_f32_e32 v34, 1.0, v39
	v_rcp_f32_e32 v34, v34
	v_mul_f32_e32 v38, 0.5, v38
	v_add_f32_e32 v35, v133, v35
	v_fmac_f32_e32 v132, v135, v128
	v_fma_f32 v34, v34, -2.0, 2.0
	v_mul_f32_e32 v34, v38, v34
	v_mul_f32_e32 v34, v35, v34
	s_waitcnt lgkmcnt(3)
	v_lshlrev_b32_e32 v35, 16, v49
	v_mul_f32_e32 v38, 0x3d372713, v35
	v_mul_f32_e32 v38, v38, v35
	v_fma_f32 v38, v38, v35, v35
	v_mul_f32_e32 v38, 0x3f4c422a, v38
	v_add_f32_e32 v38, v38, v38
	v_mul_f32_e32 v38, 0x3fb8aa3b, v38
	v_exp_f32_e32 v38, v38
	v_bfe_u32 v39, v34, 16, 1
	v_add3_u32 v34, v34, v39, s27
	ds_write_b16_d16_hi v52, v34 offset:25872
	v_add_f32_e32 v34, 1.0, v38
	v_rcp_f32_e32 v34, v34
	v_fmac_f32_e32 v36, v63, v42
	v_mul_f32_e32 v35, 0.5, v35
	v_add_f32_e32 v36, v132, v36
	v_fma_f32 v34, v34, -2.0, 2.0
	v_mul_f32_e32 v34, v35, v34
	s_waitcnt lgkmcnt(3)
	v_lshlrev_b32_e32 v35, 16, v64
	v_mul_f32_e32 v34, v36, v34
	v_mul_f32_e32 v36, 0x3d372713, v35
	v_mul_f32_e32 v36, v36, v35
	v_fma_f32 v36, v36, v35, v35
	v_mul_f32_e32 v36, 0x3f4c422a, v36
	v_add_f32_e32 v36, v36, v36
	v_mul_f32_e32 v36, 0x3fb8aa3b, v36
	v_exp_f32_e32 v36, v36
	v_bfe_u32 v38, v34, 16, 1
	v_add3_u32 v34, v34, v38, s27
	ds_write_b16_d16_hi v52, v34 offset:26400
	v_add_f32_e32 v34, 1.0, v36
	v_rcp_f32_e32 v34, v34
	v_fmac_f32_e32 v131, v136, v128
	v_fmac_f32_e32 v41, v37, v42
	v_mul_f32_e32 v35, 0.5, v35
	v_fma_f32 v34, v34, -2.0, 2.0
	v_add_f32_e32 v36, v131, v41
	v_mul_f32_e32 v34, v35, v34
	v_mul_f32_e32 v34, v36, v34
	v_bfe_u32 v35, v34, 16, 1
	v_add3_u32 v34, v34, v35, s27
	ds_write_b16_d16_hi v52, v34 offset:26928
	ds_read_b128 v[38:41], v62 offset:16896
	ds_read_b128 v[34:37], v62 offset:16960
	s_waitcnt lgkmcnt(1)
	v_mfma_f32_16x16x32_bf16 v[68:71], v[38:41], v[22:25], 0
	ds_read_u16 v47, v58 offset:16896
	ds_read_u16 v49, v58 offset:17424
	ds_read_u16 v63, v58 offset:17952
	v_fmac_f32_e32 v44, v66, v48
	v_cmp_gt_i32_e64 s[0:1], 3, v51
	s_waitcnt lgkmcnt(3)
	v_mfma_f32_16x16x32_bf16 v[68:71], v[34:37], v[18:21], v[68:71]
	s_waitcnt lgkmcnt(2)
	v_lshlrev_b32_e32 v72, 16, v47
	s_waitcnt lgkmcnt(1)
	v_lshlrev_b32_e32 v73, 16, v49
	v_mfma_f32_16x16x32_bf16 v[80:83], v[38:41], v[30:33], 0
	v_mfma_f32_16x16x32_bf16 v[80:83], v[34:37], v[26:29], v[80:83]
	s_nop 1
	v_fma_f32 v42, v68, s98, v153
	s_nop 0
	v_exp_f32_e32 v42, v42
	v_fma_f32 v67, v69, s98, v153
	s_nop 0
	s_nop 0
	v_fma_f32 v64, v80, s98, v152
	v_add_f32_e32 v42, 1.0, v42
	v_rcp_f32_e32 v42, v42
	s_nop 0
	v_exp_f32_e32 v67, v67
	v_exp_f32_e32 v64, v64
	v_mul_f32_e32 v42, v60, v42
	s_nop 0
	v_exp_f32_e32 v42, v42
	v_add_f32_e32 v67, 1.0, v67
	v_add_f32_e32 v47, 1.0, v64
	v_fma_f32 v68, v81, s98, v152
	v_fma_f32 v64, -v42, v42, 1.0
	v_rcp_f32_e32 v67, v67
	v_max_f32_e32 v64, 0, v64
	s_nop 0
	v_rcp_f32_e32 v47, v47
	v_sqrt_f32_e32 v64, v64
	v_exp_f32_e32 v68, v68
	v_mul_f32_e32 v67, v60, v67
	s_nop 0
	v_mul_f32_e32 v64, v47, v64
	v_add_f32_e32 v47, 1.0, v68
	v_exp_f32_e32 v68, v67
	v_fma_f32 v67, v70, s98, v153
	s_nop 0
	v_exp_f32_e32 v67, v67
	v_fma_f32 v69, -v68, v68, 1.0
	v_max_f32_e32 v69, 0, v69
	v_rcp_f32_e32 v47, v47
	v_add_f32_e32 v67, 1.0, v67
	v_rcp_f32_e32 v67, v67
	v_sqrt_f32_e32 v69, v69
	v_fma_f32 v70, v82, s98, v152
	s_nop 0
	v_mul_f32_e32 v49, v60, v67
	s_nop 0
	v_mul_f32_e32 v80, v47, v69
	v_exp_f32_e32 v69, v49
	v_fma_f32 v49, v71, s98, v153
	s_nop 0
	v_exp_f32_e32 v49, v49
	v_exp_f32_e32 v70, v70
	v_fma_f32 v67, -v69, v69, 1.0
	v_max_f32_e32 v67, 0, v67
	v_add_f32_e32 v49, 1.0, v49
	v_rcp_f32_e32 v49, v49
	v_add_f32_e32 v47, 1.0, v70
	v_fma_f32 v70, v83, s98, v152
	s_nop 0
	v_mul_f32_e32 v49, v60, v49
	s_nop 0
	v_exp_f32_e32 v49, v49
	v_exp_f32_e32 v70, v70
	v_rcp_f32_e32 v47, v47
	v_sqrt_f32_e32 v67, v67
	v_fma_f32 v71, -v49, v49, 1.0
	v_add_f32_e32 v70, 1.0, v70
	v_max_f32_e32 v71, 0, v71
	v_rcp_f32_e32 v70, v70
	v_sqrt_f32_e32 v71, v71
	s_waitcnt lgkmcnt(0)
	v_lshlrev_b32_e32 v81, 16, v63
	v_mul_f32_e32 v82, v47, v67
	v_lshlrev_b32_e32 v47, 16, v65
	v_mul_f32_e32 v63, v70, v71
	v_mul_f32_e32 v47, v63, v47
	v_mul_f32_e32 v63, v69, v47
	v_mul_f32_e32 v67, v69, v49
	v_fmac_f32_e32 v63, v82, v81
	v_mul_f32_e32 v69, v68, v67
	v_mul_f32_e32 v68, v68, v63
	v_fmac_f32_e32 v68, v80, v73
	v_mul_f32_e32 v70, v42, v68
	v_mul_f32_e32 v71, v42, v69
	v_fmac_f32_e32 v70, v64, v72
	ds_bpermute_b32 v130, v54, v71
	ds_bpermute_b32 v72, v54, v70
	ds_bpermute_b32 v129, v55, v71
	ds_bpermute_b32 v73, v55, v70
	ds_bpermute_b32 v128, v56, v71
	ds_bpermute_b32 v65, v56, v70
	ds_bpermute_b32 v64, v61, v71
	ds_bpermute_b32 v42, v61, v70
	s_waitcnt lgkmcnt(6)
	v_fmac_f32_e32 v72, v44, v130
	s_waitcnt lgkmcnt(4)
	v_fmac_f32_e32 v73, v72, v129
	s_waitcnt lgkmcnt(2)
	v_fmac_f32_e32 v65, v73, v128
	s_and_saveexec_b64 s[4:5], s[0:1]
	s_cbranch_execz .LBB0_707
	v_cmp_ne_u32_e64 s[0:1], 2, v51
	s_and_saveexec_b64 s[34:35], s[0:1]
	s_xor_b64 s[0:1], exec, s[34:35]
	v_cndmask_b32_e32 v44, v65, v73, vcc
	s_andn2_saveexec_b64 s[0:1], s[0:1]
	v_mov_b32_e32 v44, v72
	s_or_b64 exec, exec, s[0:1]
; template <int DIR, int MODE>
; __device__ __forceinline__ void lru_pass(const Args& a, const LAS bf16_t* cxb, LAS bf16_t* gyb, const LAS float* carry, const bf16x8 (&Bw)[2][2][2], const float (&prm)[2][3], int l, int tt, float (&hf)[8][2][4]) {
;     ...
;     for (int mi = 0; mi < 8; ++mi) {
;         const int m = DIR ? 7 - mi : mi;
;         bf16x8 Af[2];
; #pragma unroll
;         for (int ks = 0; ks < 2; ++ks) Af[ks] = *(const LAS bf16x8*)(cxb + (m * 16 + fr) * CXS + 64 * h + 32 * ks + 8 * fq);
; #pragma unroll
;         for (int nt = 0; nt < 2; ++nt) {
;             f32x4 pr = (f32x4){0.f, 0.f, 0.f, 0.f}, pi = (f32x4){0.f, 0.f, 0.f, 0.f};
; #pragma unroll
;             for (int ks = 0; ks < 2; ++ks) { pr = __builtin_amdgcn_mfma_f32_16x16x32_bf16(Af[ks], Bw[0][nt][ks], pr, 0, 0, 0); pi = __builtin_amdgcn_mfma_f32_16x16x32_bf16(Af[ks], Bw[1][nt][ks], pi, 0, 0, 0); }
;             float av[4], bv[4];
; #pragma unroll
;             for (int reg = 0; reg < 4; ++reg) {
;                 const int tok = m * 16 + 4 * fq + reg;
;                 const float x = bf2f(cxb[tok * CXS + cc[nt]]);
;                 const float r = fsig(pr[reg] + ba[nt]), ig = fsig(pi[reg] + bxv[nt]);
;                 const float aa = __expf(k8[nt] * r);
;                 av[reg] = aa; bv[reg] = __builtin_amdgcn_sqrtf(fmaxf(1.0f - aa * aa, 0.f)) * ig * x;
;             }
;             float cum[4], hl[4];
;             if (DIR == 0) { cum[0] = av[0]; hl[0] = bv[0];
; #pragma unroll
;                 for (int reg = 1; reg < 4; ++reg) { cum[reg] = cum[reg - 1] * av[reg]; hl[reg] = av[reg] * hl[reg - 1] + bv[reg]; } }
;             else { cum[3] = av[3]; hl[3] = bv[3];
; #pragma unroll
;     ...
;             const float A4 = DIR ? cum[0] : cum[3], H4 = DIR ? hl[0] : hl[3];
;             float Aq[4], Hq[4];
; #pragma unroll
;             for (int q = 0; q < 4; ++q) { Aq[q] = __shfl(A4, fr + 16 * q); Hq[q] = __shfl(H4, fr + 16 * q); }
;             float hin;
;             if (DIR == 0) { const float s0 = C[nt], s1 = Aq[0] * s0 + Hq[0], s2 = Aq[1] * s1 + Hq[1], s3 = Aq[2] * s2 + Hq[2]; C[nt] = Aq[3] * s3 + Hq[3]; hin = fq == 0 ? s0 : (fq == 1 ? s1 : (fq == 2 ? s2 : s3)); }
;             else { const float s3 = C[nt], s2 = Aq[3] * s3 + Hq[3], s1 = Aq[2] * s2 + Hq[2], s0 = Aq[1] * s1 + Hq[1]; C[nt] = Aq[0] * s0 + Hq[0]; hin = fq == 3 ? s3 : (fq == 2 ? s2 : (fq == 1 ? s1 : s0)); }
.LBB0_707:
	s_or_b64 exec, exec, s[4:5]
	ds_read_u16 v48, v59 offset:16896
	v_fmac_f32_e32 v123, v124, v119
	v_fmac_f32_e32 v70, v71, v44
	v_fmac_f32_e32 v68, v69, v44
	v_fmac_f32_e32 v63, v67, v44
	v_fmac_f32_e32 v47, v49, v44
	ds_read_u16 v44, v59 offset:18480
	s_waitcnt lgkmcnt(1)
	v_lshlrev_b32_e32 v48, 16, v48
	v_add_f32_e32 v66, v123, v70
	v_mul_f32_e32 v70, 0x3d372713, v48
	v_mul_f32_e32 v70, v70, v48
	v_fma_f32 v70, v70, v48, v48
	v_mul_f32_e32 v70, 0x3f4c422a, v70
	v_add_f32_e32 v70, v70, v70
	v_mul_f32_e32 v70, 0x3fb8aa3b, v70
	v_exp_f32_e32 v70, v70
	v_mul_f32_e32 v48, 0.5, v48
	v_fmac_f32_e32 v122, v125, v119
	v_fmac_f32_e32 v121, v126, v119
	v_add_f32_e32 v70, 1.0, v70
	v_rcp_f32_e32 v70, v70
	v_add_f32_e32 v63, v121, v63
	s_waitcnt lgkmcnt(0)
	v_lshlrev_b32_e32 v44, 16, v44
	v_fmac_f32_e32 v120, v127, v119
	v_fma_f32 v70, v70, -2.0, 2.0
	v_mul_f32_e32 v48, v48, v70
	v_mul_f32_e32 v48, v66, v48
	v_bfe_u32 v66, v48, 16, 1
	v_add3_u32 v48, v48, v66, s27
	ds_write_b16_d16_hi v59, v48 offset:16896
	ds_read_u16 v48, v59 offset:17424
	v_add_f32_e32 v66, v122, v68
	v_mfma_f32_16x16x32_bf16 v[70:73], v[38:41], v[14:17], 0
	v_add_f32_e32 v47, v120, v47
	v_fmac_f32_e32 v43, v46, v45
	s_waitcnt lgkmcnt(0)
	v_lshlrev_b32_e32 v48, 16, v48
	v_mul_f32_e32 v68, 0x3d372713, v48
	v_mul_f32_e32 v68, v68, v48
	v_fma_f32 v68, v68, v48, v48
	v_mul_f32_e32 v68, 0x3f4c422a, v68
	v_add_f32_e32 v68, v68, v68
	v_mul_f32_e32 v68, 0x3fb8aa3b, v68
	v_exp_f32_e32 v68, v68
	v_mul_f32_e32 v48, 0.5, v48
	v_cmp_gt_i32_e64 s[0:1], 3, v51
	v_add_f32_e32 v68, 1.0, v68
	v_rcp_f32_e32 v68, v68
	s_nop 0
	v_fma_f32 v68, v68, -2.0, 2.0
	v_mul_f32_e32 v48, v48, v68
	v_mul_f32_e32 v48, v66, v48
	v_bfe_u32 v66, v48, 16, 1
	v_add3_u32 v48, v48, v66, s27
	ds_write_b16_d16_hi v59, v48 offset:17424
	ds_read_u16 v48, v59 offset:17952
	s_waitcnt lgkmcnt(0)
	v_lshlrev_b32_e32 v48, 16, v48
	v_mul_f32_e32 v66, 0x3d372713, v48
	v_mul_f32_e32 v66, v66, v48
	v_fma_f32 v66, v66, v48, v48
	v_mul_f32_e32 v66, 0x3f4c422a, v66
	v_add_f32_e32 v66, v66, v66
	v_mul_f32_e32 v66, 0x3fb8aa3b, v66
	v_exp_f32_e32 v66, v66
	v_mul_f32_e32 v48, 0.5, v48
	v_add_f32_e32 v66, 1.0, v66
	v_rcp_f32_e32 v66, v66
	s_nop 0
	v_fma_f32 v66, v66, -2.0, 2.0
	v_mul_f32_e32 v48, v48, v66
	v_mul_f32_e32 v48, v63, v48
	v_bfe_u32 v63, v48, 16, 1
	v_add3_u32 v48, v48, v63, s27
	ds_write_b16_d16_hi v59, v48 offset:17952
	v_mul_f32_e32 v48, 0x3d372713, v44
	v_mfma_f32_16x16x32_bf16 v[66:69], v[38:41], v[6:9], 0
	v_mul_f32_e32 v48, v48, v44
	v_fma_f32 v48, v48, v44, v44
	v_mul_f32_e32 v48, 0x3f4c422a, v48
	v_add_f32_e32 v48, v48, v48
	v_mfma_f32_16x16x32_bf16 v[38:41], v[34:37], v[2:5], v[66:69]
	v_mul_f32_e32 v48, 0x3fb8aa3b, v48
	v_exp_f32_e32 v48, v48
	v_mul_f32_e32 v44, 0.5, v44
	v_mfma_f32_16x16x32_bf16 v[34:37], v[34:37], v[10:13], v[70:73]
	v_add_f32_e32 v48, 1.0, v48
	s_nop 2
	v_fma_f32 v38, v38, s98, v151
	v_fma_f32 v39, v39, s98, v151
	v_fma_f32 v40, v40, s98, v151
	s_nop 0
	s_nop 0
	s_nop 0
	v_exp_f32_e32 v38, v38
	v_exp_f32_e32 v39, v39
	v_exp_f32_e32 v40, v40
	v_rcp_f32_e32 v48, v48
	v_fma_f32 v34, v34, s98, v150
	v_fma_f32 v35, v35, s98, v150
	v_fma_f32 v36, v36, s98, v150
	s_nop 0
	s_nop 0
	s_nop 0
	v_fma_f32 v41, v41, s98, v151
	v_add_f32_e32 v38, 1.0, v38
	v_exp_f32_e32 v34, v34
	v_add_f32_e32 v39, 1.0, v39
	v_exp_f32_e32 v35, v35
	v_add_f32_e32 v40, 1.0, v40
	v_exp_f32_e32 v36, v36
	s_nop 0
	v_fma_f32 v48, v48, -2.0, 2.0
	v_rcp_f32_e32 v38, v38
	v_rcp_f32_e32 v39, v39
	v_rcp_f32_e32 v40, v40
	v_exp_f32_e32 v41, v41
	v_mul_f32_e32 v44, v44, v48
	v_mul_f32_e32 v44, v47, v44
	v_fma_f32 v37, v37, s98, v150
	v_bfe_u32 v47, v44, 16, 1
	v_add_f32_e32 v34, 1.0, v34
	v_add_f32_e32 v35, 1.0, v35
	v_add_f32_e32 v36, 1.0, v36
	s_nop 0
	v_add3_u32 v44, v44, v47, s27
	v_rcp_f32_e32 v47, v34
	v_mul_f32_e32 v34, v57, v38
	v_rcp_f32_e32 v48, v35
	v_mul_f32_e32 v35, v57, v39
	v_rcp_f32_e32 v49, v36
	v_mul_f32_e32 v36, v57, v40
	v_add_f32_e32 v41, 1.0, v41
	v_exp_f32_e32 v37, v37
	s_nop 0
	s_nop 0
	s_nop 0
	v_rcp_f32_e32 v41, v41
	v_exp_f32_e32 v34, v34
	v_exp_f32_e32 v35, v35
	v_exp_f32_e32 v36, v36
	v_add_f32_e32 v37, 1.0, v37
	v_rcp_f32_e32 v63, v37
	v_mul_f32_e32 v37, v57, v41
	v_fma_f32 v38, -v34, v34, 1.0
	v_fma_f32 v39, -v35, v35, 1.0
	v_fma_f32 v40, -v36, v36, 1.0
	s_nop 0
	v_max_f32_e32 v38, 0, v38
	v_max_f32_e32 v39, 0, v39
	v_max_f32_e32 v40, 0, v40
	v_exp_f32_e32 v37, v37
	v_sqrt_f32_e32 v38, v38
	v_sqrt_f32_e32 v39, v39
	v_sqrt_f32_e32 v40, v40
	v_fma_f32 v41, -v37, v37, 1.0
	ds_write_b16_d16_hi v59, v44 offset:18480
	ds_read_u16 v44, v58 offset:16928
	v_mul_f32_e32 v38, v47, v38
	ds_read_u16 v47, v58 offset:17456
	v_mul_f32_e32 v39, v48, v39
	ds_read_u16 v48, v58 offset:17984
	v_mul_f32_e32 v40, v49, v40
	ds_read_u16 v49, v58 offset:18512
	v_max_f32_e32 v41, 0, v41
	v_sqrt_f32_e32 v41, v41
	s_waitcnt lgkmcnt(1)
	v_lshlrev_b32_e32 v48, 16, v48
	v_mul_f32_e32 v66, v36, v37
	s_waitcnt lgkmcnt(0)
	v_lshlrev_b32_e32 v49, 16, v49
	v_mul_f32_e32 v41, v63, v41
	v_mul_f32_e32 v41, v41, v49
	v_mul_f32_e32 v36, v36, v41
	v_fmac_f32_e32 v36, v40, v48
	v_lshlrev_b32_e32 v47, 16, v47
	v_mul_f32_e32 v40, v35, v66
	v_mul_f32_e32 v35, v35, v36
	v_fmac_f32_e32 v35, v39, v47
	v_lshlrev_b32_e32 v44, 16, v44
	v_mul_f32_e32 v39, v34, v40
	v_mul_f32_e32 v34, v34, v35
	v_fmac_f32_e32 v34, v38, v44
	ds_bpermute_b32 v68, v54, v39
	ds_bpermute_b32 v38, v54, v34
	ds_bpermute_b32 v67, v55, v39
	ds_bpermute_b32 v44, v55, v34
	ds_bpermute_b32 v47, v56, v39
	ds_bpermute_b32 v63, v56, v34
	ds_bpermute_b32 v49, v61, v39
	ds_bpermute_b32 v48, v61, v34
	s_waitcnt lgkmcnt(6)
	v_fmac_f32_e32 v38, v43, v68
	s_waitcnt lgkmcnt(4)
	v_fmac_f32_e32 v44, v38, v67
	s_waitcnt lgkmcnt(2)
	v_fmac_f32_e32 v63, v44, v47
	s_and_saveexec_b64 s[4:5], s[0:1]
	s_cbranch_execz .LBB0_713
	v_cmp_ne_u32_e64 s[0:1], 2, v51
	s_and_saveexec_b64 s[34:35], s[0:1]
	s_xor_b64 s[0:1], exec, s[34:35]
	v_cndmask_b32_e32 v43, v63, v44, vcc
	s_andn2_saveexec_b64 s[0:1], s[0:1]
	v_mov_b32_e32 v43, v38
	s_or_b64 exec, exec, s[0:1]
; template <int DIR, int MODE>
; __device__ __forceinline__ void lru_pass(const Args& a, const LAS bf16_t* cxb, LAS bf16_t* gyb, const LAS float* carry, const bf16x8 (&Bw)[2][2][2], const float (&prm)[2][3], int l, int tt, float (&hf)[8][2][4]) {
;     ...
;     for (int mi = 0; mi < 8; ++mi) {
;         const int m = DIR ? 7 - mi : mi;
;         bf16x8 Af[2];
; #pragma unroll
;         for (int ks = 0; ks < 2; ++ks) Af[ks] = *(const LAS bf16x8*)(cxb + (m * 16 + fr) * CXS + 64 * h + 32 * ks + 8 * fq);
; #pragma unroll
;         for (int nt = 0; nt < 2; ++nt) {
;             f32x4 pr = (f32x4){0.f, 0.f, 0.f, 0.f}, pi = (f32x4){0.f, 0.f, 0.f, 0.f};
; #pragma unroll
;             for (int ks = 0; ks < 2; ++ks) { pr = __builtin_amdgcn_mfma_f32_16x16x32_bf16(Af[ks], Bw[0][nt][ks], pr, 0, 0, 0); pi = __builtin_amdgcn_mfma_f32_16x16x32_bf16(Af[ks], Bw[1][nt][ks], pi, 0, 0, 0); }
;             float av[4], bv[4];
; #pragma unroll
;             for (int reg = 0; reg < 4; ++reg) {
;                 const int tok = m * 16 + 4 * fq + reg;
;                 const float x = bf2f(cxb[tok * CXS + cc[nt]]);
;                 const float r = fsig(pr[reg] + ba[nt]), ig = fsig(pi[reg] + bxv[nt]);
;                 const float aa = __expf(k8[nt] * r);
;                 av[reg] = aa; bv[reg] = __builtin_amdgcn_sqrtf(fmaxf(1.0f - aa * aa, 0.f)) * ig * x;
;             }
;             float cum[4], hl[4];
;             if (DIR == 0) { cum[0] = av[0]; hl[0] = bv[0];
; #pragma unroll
;                 for (int reg = 1; reg < 4; ++reg) { cum[reg] = cum[reg - 1] * av[reg]; hl[reg] = av[reg] * hl[reg - 1] + bv[reg]; } }
;             else { cum[3] = av[3]; hl[3] = bv[3];
; #pragma unroll
;     ...
;             const float A4 = DIR ? cum[0] : cum[3], H4 = DIR ? hl[0] : hl[3];
;             float Aq[4], Hq[4];
; #pragma unroll
;             for (int q = 0; q < 4; ++q) { Aq[q] = __shfl(A4, fr + 16 * q); Hq[q] = __shfl(H4, fr + 16 * q); }
;             float hin;
;             if (DIR == 0) { const float s0 = C[nt], s1 = Aq[0] * s0 + Hq[0], s2 = Aq[1] * s1 + Hq[1], s3 = Aq[2] * s2 + Hq[2]; C[nt] = Aq[3] * s3 + Hq[3]; hin = fq == 0 ? s0 : (fq == 1 ? s1 : (fq == 2 ? s2 : s3)); }
;             else { const float s3 = C[nt], s2 = Aq[3] * s3 + Hq[3], s1 = Aq[2] * s2 + Hq[2], s0 = Aq[1] * s1 + Hq[1]; C[nt] = Aq[0] * s0 + Hq[0]; hin = fq == 3 ? s3 : (fq == 2 ? s2 : (fq == 1 ? s1 : s0)); }
.LBB0_713:
	s_or_b64 exec, exec, s[4:5]
	ds_read_u16 v38, v52 offset:16896
	ds_read_u16 v44, v52 offset:17424
	ds_read_u16 v45, v52 offset:17952
	ds_read_u16 v46, v52 offset:18480
	ds_read_u16 v70, v58 offset:10032
	s_waitcnt lgkmcnt(4)
	v_lshlrev_b32_e32 v38, 16, v38
	v_mul_f32_e32 v47, 0x3d372713, v38
	v_mul_f32_e32 v47, v47, v38
	v_fma_f32 v47, v47, v38, v38
	v_mul_f32_e32 v47, 0x3f4c422a, v47
	v_add_f32_e32 v47, v47, v47
	v_mul_f32_e32 v47, 0x3fb8aa3b, v47
	v_exp_f32_e32 v47, v47
	v_fmac_f32_e32 v111, v112, v110
	v_fmac_f32_e32 v34, v39, v43
	v_mul_f32_e32 v38, 0.5, v38
	v_add_f32_e32 v47, 1.0, v47
	v_rcp_f32_e32 v47, v47
	v_add_f32_e32 v34, v111, v34
	v_fmac_f32_e32 v115, v116, v110
	v_fmac_f32_e32 v35, v40, v43
	v_fma_f32 v39, v47, -2.0, 2.0
	v_mul_f32_e32 v38, v38, v39
	v_mul_f32_e32 v34, v34, v38
	s_waitcnt lgkmcnt(3)
	v_lshlrev_b32_e32 v38, 16, v44
	v_mul_f32_e32 v39, 0x3d372713, v38
	v_mul_f32_e32 v39, v39, v38
	v_fma_f32 v39, v39, v38, v38
	v_mul_f32_e32 v39, 0x3f4c422a, v39
	v_add_f32_e32 v39, v39, v39
	v_mul_f32_e32 v39, 0x3fb8aa3b, v39
	v_exp_f32_e32 v39, v39
	v_bfe_u32 v44, v34, 16, 1
	v_add3_u32 v34, v34, v44, s27
	ds_write_b16_d16_hi v52, v34 offset:16896
	v_add_f32_e32 v34, 1.0, v39
	v_rcp_f32_e32 v34, v34
	v_mul_f32_e32 v38, 0.5, v38
	v_add_f32_e32 v35, v115, v35
	v_fmac_f32_e32 v114, v117, v110
	v_fma_f32 v34, v34, -2.0, 2.0
	v_mul_f32_e32 v34, v38, v34
	v_mul_f32_e32 v34, v35, v34
	s_waitcnt lgkmcnt(3)
	v_lshlrev_b32_e32 v35, 16, v45
	v_mul_f32_e32 v38, 0x3d372713, v35
	v_mul_f32_e32 v38, v38, v35
	v_fma_f32 v38, v38, v35, v35
	v_mul_f32_e32 v38, 0x3f4c422a, v38
	v_add_f32_e32 v38, v38, v38
	v_mul_f32_e32 v38, 0x3fb8aa3b, v38
	v_exp_f32_e32 v38, v38
	v_bfe_u32 v39, v34, 16, 1
	v_add3_u32 v34, v34, v39, s27
	ds_write_b16_d16_hi v52, v34 offset:17424
	v_add_f32_e32 v34, 1.0, v38
	v_rcp_f32_e32 v34, v34
	v_fmac_f32_e32 v36, v66, v43
	v_mul_f32_e32 v35, 0.5, v35
	v_add_f32_e32 v36, v114, v36
	v_fma_f32 v34, v34, -2.0, 2.0
	v_mul_f32_e32 v34, v35, v34
	s_waitcnt lgkmcnt(3)
	v_lshlrev_b32_e32 v35, 16, v46
	v_mul_f32_e32 v34, v36, v34
	v_mul_f32_e32 v36, 0x3d372713, v35
	v_mul_f32_e32 v36, v36, v35
	v_fma_f32 v36, v36, v35, v35
	v_mul_f32_e32 v36, 0x3f4c422a, v36
	v_add_f32_e32 v36, v36, v36
	v_mul_f32_e32 v36, 0x3fb8aa3b, v36
	v_exp_f32_e32 v36, v36
	v_bfe_u32 v38, v34, 16, 1
	v_add3_u32 v34, v34, v38, s27
	ds_write_b16_d16_hi v52, v34 offset:17952
	v_add_f32_e32 v34, 1.0, v36
	v_rcp_f32_e32 v34, v34
	v_fmac_f32_e32 v113, v118, v110
	v_fmac_f32_e32 v41, v37, v43
	v_mul_f32_e32 v35, 0.5, v35
	v_fma_f32 v34, v34, -2.0, 2.0
	v_add_f32_e32 v36, v113, v41
	v_mul_f32_e32 v34, v35, v34
	v_mul_f32_e32 v34, v36, v34
	v_bfe_u32 v35, v34, 16, 1
	v_add3_u32 v34, v34, v35, s27
	ds_write_b16_d16_hi v52, v34 offset:18480
	ds_read_b128 v[38:41], v62 offset:8448
	ds_read_b128 v[34:37], v62 offset:8512
	s_waitcnt lgkmcnt(1)
	v_mfma_f32_16x16x32_bf16 v[44:47], v[38:41], v[22:25], 0
	v_fmac_f32_e32 v42, v65, v64
	v_cmp_gt_i32_e64 s[0:1], 3, v51
	s_waitcnt lgkmcnt(0)
	v_mfma_f32_16x16x32_bf16 v[44:47], v[34:37], v[18:21], v[44:47]
	v_mfma_f32_16x16x32_bf16 v[66:69], v[38:41], v[30:33], 0
	v_mfma_f32_16x16x32_bf16 v[66:69], v[34:37], v[26:29], v[66:69]
	s_nop 5
	v_fma_f32 v43, v44, s98, v153
	s_nop 0
	v_exp_f32_e32 v43, v43
	v_fma_f32 v45, v45, s98, v153
	s_nop 0
	v_exp_f32_e32 v45, v45
	v_add_f32_e32 v43, 1.0, v43
	v_rcp_f32_e32 v43, v43
	v_fma_f32 v66, v66, s98, v152
	v_add_f32_e32 v45, 1.0, v45
	v_rcp_f32_e32 v45, v45
	v_mul_f32_e32 v43, v60, v43
	s_nop 0
	s_nop 0
	v_exp_f32_e32 v66, v66
	v_exp_f32_e32 v43, v43
	ds_read_u16 v44, v58 offset:8448
	ds_read_u16 v71, v58 offset:8976
	ds_read_u16 v72, v58 offset:9504
	v_mul_f32_e32 v45, v60, v45
	s_nop 0
	v_exp_f32_e32 v81, v45
	v_fma_f32 v45, v46, s98, v153
	s_waitcnt lgkmcnt(2)
	v_lshlrev_b32_e32 v73, 16, v44
	v_add_f32_e32 v44, 1.0, v66
	v_fma_f32 v66, -v43, v43, 1.0
	s_nop 0
	v_max_f32_e32 v66, 0, v66
	v_fma_f32 v67, v67, s98, v152
	v_exp_f32_e32 v45, v45
	v_rcp_f32_e32 v44, v44
	v_sqrt_f32_e32 v66, v66
	s_nop 0
	v_exp_f32_e32 v67, v67
	v_add_f32_e32 v45, 1.0, v45
	v_mul_f32_e32 v80, v44, v66
	v_fma_f32 v46, -v81, v81, 1.0
	v_fma_f32 v66, v68, s98, v152
	v_rcp_f32_e32 v45, v45
	v_add_f32_e32 v44, 1.0, v67
	v_max_f32_e32 v46, 0, v46
	s_nop 0
	v_rcp_f32_e32 v44, v44
	v_sqrt_f32_e32 v46, v46
	v_exp_f32_e32 v66, v66
	v_mul_f32_e32 v45, v60, v45
	s_nop 0
	v_mul_f32_e32 v46, v44, v46
	v_add_f32_e32 v44, 1.0, v66
	v_exp_f32_e32 v66, v45
	v_fma_f32 v45, v47, s98, v153
	s_nop 0
	v_exp_f32_e32 v45, v45
	v_fma_f32 v67, v69, s98, v152
	s_nop 0
	v_exp_f32_e32 v67, v67
	v_add_f32_e32 v45, 1.0, v45
	v_rcp_f32_e32 v45, v45
	v_fma_f32 v47, -v66, v66, 1.0
	v_max_f32_e32 v47, 0, v47
	v_add_f32_e32 v67, 1.0, v67
	v_mul_f32_e32 v45, v60, v45
	s_nop 0
	v_exp_f32_e32 v45, v45
	v_rcp_f32_e32 v44, v44
	v_sqrt_f32_e32 v47, v47
	v_rcp_f32_e32 v67, v67
	v_fma_f32 v68, -v45, v45, 1.0
	v_max_f32_e32 v68, 0, v68
	v_sqrt_f32_e32 v68, v68
	v_mul_f32_e32 v47, v44, v47
	v_lshlrev_b32_e32 v44, 16, v70
	s_waitcnt lgkmcnt(0)
	v_lshlrev_b32_e32 v69, 16, v72
	v_mul_f32_e32 v67, v67, v68
	v_mul_f32_e32 v44, v67, v44
	v_mul_f32_e32 v67, v66, v45
	v_mul_f32_e32 v66, v66, v44
	v_fmac_f32_e32 v66, v47, v69
	v_lshlrev_b32_e32 v71, 16, v71
	v_mul_f32_e32 v68, v81, v66
	v_fmac_f32_e32 v68, v46, v71
	v_mul_f32_e32 v69, v81, v67
	v_mul_f32_e32 v70, v43, v68
	v_mul_f32_e32 v71, v43, v69
	v_fmac_f32_e32 v70, v80, v73
	ds_bpermute_b32 v112, v54, v71
	ds_bpermute_b32 v72, v54, v70
	ds_bpermute_b32 v111, v55, v71
	ds_bpermute_b32 v73, v55, v70
	ds_bpermute_b32 v110, v56, v71
	ds_bpermute_b32 v47, v56, v70
	ds_bpermute_b32 v46, v61, v71
	ds_bpermute_b32 v43, v61, v70
	s_waitcnt lgkmcnt(6)
	v_fmac_f32_e32 v72, v42, v112
	s_waitcnt lgkmcnt(4)
	v_fmac_f32_e32 v73, v72, v111
	s_waitcnt lgkmcnt(2)
	v_fmac_f32_e32 v47, v73, v110
	s_and_saveexec_b64 s[4:5], s[0:1]
	s_cbranch_execz .LBB0_719
	v_cmp_ne_u32_e64 s[0:1], 2, v51
	s_and_saveexec_b64 s[34:35], s[0:1]
	s_xor_b64 s[0:1], exec, s[34:35]
	v_cndmask_b32_e32 v42, v47, v73, vcc
	s_andn2_saveexec_b64 s[0:1], s[0:1]
	v_mov_b32_e32 v42, v72
	s_or_b64 exec, exec, s[0:1]
; template <int DIR, int MODE>
; __device__ __forceinline__ void lru_pass(const Args& a, const LAS bf16_t* cxb, LAS bf16_t* gyb, const LAS float* carry, const bf16x8 (&Bw)[2][2][2], const float (&prm)[2][3], int l, int tt, float (&hf)[8][2][4]) {
;     ...
;     for (int mi = 0; mi < 8; ++mi) {
;         const int m = DIR ? 7 - mi : mi;
;         bf16x8 Af[2];
; #pragma unroll
;         for (int ks = 0; ks < 2; ++ks) Af[ks] = *(const LAS bf16x8*)(cxb + (m * 16 + fr) * CXS + 64 * h + 32 * ks + 8 * fq);
; #pragma unroll
;         for (int nt = 0; nt < 2; ++nt) {
;             f32x4 pr = (f32x4){0.f, 0.f, 0.f, 0.f}, pi = (f32x4){0.f, 0.f, 0.f, 0.f};
; #pragma unroll
;             for (int ks = 0; ks < 2; ++ks) { pr = __builtin_amdgcn_mfma_f32_16x16x32_bf16(Af[ks], Bw[0][nt][ks], pr, 0, 0, 0); pi = __builtin_amdgcn_mfma_f32_16x16x32_bf16(Af[ks], Bw[1][nt][ks], pi, 0, 0, 0); }
;             float av[4], bv[4];
; #pragma unroll
;             for (int reg = 0; reg < 4; ++reg) {
;                 const int tok = m * 16 + 4 * fq + reg;
;                 const float x = bf2f(cxb[tok * CXS + cc[nt]]);
;                 const float r = fsig(pr[reg] + ba[nt]), ig = fsig(pi[reg] + bxv[nt]);
;                 const float aa = __expf(k8[nt] * r);
;                 av[reg] = aa; bv[reg] = __builtin_amdgcn_sqrtf(fmaxf(1.0f - aa * aa, 0.f)) * ig * x;
;             }
;             float cum[4], hl[4];
;             if (DIR == 0) { cum[0] = av[0]; hl[0] = bv[0];
; #pragma unroll
;                 for (int reg = 1; reg < 4; ++reg) { cum[reg] = cum[reg - 1] * av[reg]; hl[reg] = av[reg] * hl[reg - 1] + bv[reg]; } }
;             else { cum[3] = av[3]; hl[3] = bv[3];
; #pragma unroll
;     ...
;             const float A4 = DIR ? cum[0] : cum[3], H4 = DIR ? hl[0] : hl[3];
;             float Aq[4], Hq[4];
; #pragma unroll
;             for (int q = 0; q < 4; ++q) { Aq[q] = __shfl(A4, fr + 16 * q); Hq[q] = __shfl(H4, fr + 16 * q); }
;             float hin;
;             if (DIR == 0) { const float s0 = C[nt], s1 = Aq[0] * s0 + Hq[0], s2 = Aq[1] * s1 + Hq[1], s3 = Aq[2] * s2 + Hq[2]; C[nt] = Aq[3] * s3 + Hq[3]; hin = fq == 0 ? s0 : (fq == 1 ? s1 : (fq == 2 ? s2 : s3)); }
;             else { const float s3 = C[nt], s2 = Aq[3] * s3 + Hq[3], s1 = Aq[2] * s2 + Hq[2], s0 = Aq[1] * s1 + Hq[1]; C[nt] = Aq[0] * s0 + Hq[0]; hin = fq == 3 ? s3 : (fq == 2 ? s2 : (fq == 1 ? s1 : s0)); }
.LBB0_719:
	s_or_b64 exec, exec, s[4:5]
	ds_read_u16 v64, v59 offset:8448
	v_fmac_f32_e32 v105, v106, v101
	v_fmac_f32_e32 v70, v71, v42
	v_fmac_f32_e32 v68, v69, v42
	v_fmac_f32_e32 v66, v67, v42
	v_fmac_f32_e32 v44, v45, v42
	ds_read_u16 v42, v59 offset:10032
	s_waitcnt lgkmcnt(1)
	v_lshlrev_b32_e32 v64, 16, v64
	v_add_f32_e32 v65, v105, v70
	v_mul_f32_e32 v70, 0x3d372713, v64
	v_mul_f32_e32 v70, v70, v64
	v_fma_f32 v70, v70, v64, v64
	v_mul_f32_e32 v70, 0x3f4c422a, v70
	v_add_f32_e32 v70, v70, v70
	v_mul_f32_e32 v70, 0x3fb8aa3b, v70
	v_exp_f32_e32 v70, v70
	v_mul_f32_e32 v64, 0.5, v64
	v_fmac_f32_e32 v104, v107, v101
	v_fmac_f32_e32 v103, v108, v101
	v_add_f32_e32 v70, 1.0, v70
	v_rcp_f32_e32 v70, v70
	s_waitcnt lgkmcnt(0)
	v_lshlrev_b32_e32 v42, 16, v42
	v_mul_f32_e32 v45, 0x3d372713, v42
	v_mul_f32_e32 v45, v45, v42
	v_fma_f32 v70, v70, -2.0, 2.0
	v_mul_f32_e32 v64, v64, v70
	v_mul_f32_e32 v64, v65, v64
	v_bfe_u32 v65, v64, 16, 1
	v_add3_u32 v64, v64, v65, s27
	ds_write_b16_d16_hi v59, v64 offset:8448
	ds_read_u16 v64, v59 offset:8976
	v_add_f32_e32 v65, v104, v68
	v_fma_f32 v45, v45, v42, v42
	v_mul_f32_e32 v45, 0x3f4c422a, v45
	v_add_f32_e32 v45, v45, v45
	s_waitcnt lgkmcnt(0)
	v_lshlrev_b32_e32 v64, 16, v64
	v_mul_f32_e32 v68, 0x3d372713, v64
	v_mul_f32_e32 v68, v68, v64
	v_fma_f32 v68, v68, v64, v64
	v_mul_f32_e32 v68, 0x3f4c422a, v68
	v_add_f32_e32 v68, v68, v68
	v_mul_f32_e32 v68, 0x3fb8aa3b, v68
	v_exp_f32_e32 v68, v68
	v_mul_f32_e32 v64, 0.5, v64
	v_mul_f32_e32 v45, 0x3fb8aa3b, v45
	v_exp_f32_e32 v45, v45
	v_add_f32_e32 v68, 1.0, v68
	v_rcp_f32_e32 v68, v68
	v_fmac_f32_e32 v102, v109, v101
	v_add_f32_e32 v45, 1.0, v45
	v_rcp_f32_e32 v45, v45
	v_fma_f32 v68, v68, -2.0, 2.0
	v_mul_f32_e32 v64, v64, v68
	v_mul_f32_e32 v64, v65, v64
	v_bfe_u32 v65, v64, 16, 1
	v_add3_u32 v64, v64, v65, s27
	ds_write_b16_d16_hi v59, v64 offset:8976
	ds_read_u16 v64, v59 offset:9504
	v_add_f32_e32 v65, v103, v66
	v_mfma_f32_16x16x32_bf16 v[68:71], v[38:41], v[14:17], 0
	v_mul_f32_e32 v42, 0.5, v42
	v_fma_f32 v45, v45, -2.0, 2.0
	s_waitcnt lgkmcnt(0)
	v_lshlrev_b32_e32 v64, 16, v64
	v_mul_f32_e32 v66, 0x3d372713, v64
	v_mul_f32_e32 v66, v66, v64
	v_fma_f32 v66, v66, v64, v64
	v_mul_f32_e32 v66, 0x3f4c422a, v66
	v_add_f32_e32 v66, v66, v66
	v_mul_f32_e32 v66, 0x3fb8aa3b, v66
	v_exp_f32_e32 v66, v66
	v_mul_f32_e32 v64, 0.5, v64
	v_add_f32_e32 v44, v102, v44
	v_mul_f32_e32 v42, v42, v45
	v_add_f32_e32 v66, 1.0, v66
	v_rcp_f32_e32 v66, v66
	v_mul_f32_e32 v42, v44, v42
	v_bfe_u32 v44, v42, 16, 1
	v_add3_u32 v42, v42, v44, s27
	v_fma_f32 v66, v66, -2.0, 2.0
	v_mul_f32_e32 v64, v64, v66
	v_mul_f32_e32 v64, v65, v64
	v_bfe_u32 v65, v64, 16, 1
	v_add3_u32 v64, v64, v65, s27
	ds_write_b16_d16_hi v59, v64 offset:9504
	v_mfma_f32_16x16x32_bf16 v[64:67], v[38:41], v[6:9], 0
	ds_write_b16_d16_hi v59, v42 offset:10032
	ds_read_u16 v42, v58 offset:8480
	v_fmac_f32_e32 v48, v63, v49
	v_mfma_f32_16x16x32_bf16 v[38:41], v[34:37], v[2:5], v[64:67]
	v_cmp_gt_i32_e64 s[0:1], 3, v51
	v_mfma_f32_16x16x32_bf16 v[34:37], v[34:37], v[10:13], v[68:71]
	s_nop 5
	v_fma_f32 v38, v38, s98, v151
	v_fma_f32 v39, v39, s98, v151
	v_fma_f32 v40, v40, s98, v151
	s_nop 0
	s_nop 0
	s_nop 0
	v_exp_f32_e32 v38, v38
	v_exp_f32_e32 v39, v39
	v_exp_f32_e32 v40, v40
	v_fma_f32 v34, v34, s98, v150
	v_fma_f32 v35, v35, s98, v150
	v_fma_f32 v36, v36, s98, v150
	s_nop 0
	s_nop 0
	s_nop 0
	v_fma_f32 v41, v41, s98, v151
	v_add_f32_e32 v38, 1.0, v38
	v_exp_f32_e32 v34, v34
	v_add_f32_e32 v39, 1.0, v39
	v_exp_f32_e32 v35, v35
	v_add_f32_e32 v40, 1.0, v40
	v_exp_f32_e32 v36, v36
	s_nop 0
	v_rcp_f32_e32 v38, v38
	v_rcp_f32_e32 v39, v39
	v_rcp_f32_e32 v40, v40
	v_exp_f32_e32 v41, v41
	v_add_f32_e32 v34, 1.0, v34
	v_add_f32_e32 v35, 1.0, v35
	v_add_f32_e32 v36, 1.0, v36
	v_rcp_f32_e32 v44, v34
	v_mul_f32_e32 v34, v57, v38
	v_rcp_f32_e32 v45, v35
	v_mul_f32_e32 v35, v57, v39
	v_rcp_f32_e32 v64, v36
	v_mul_f32_e32 v36, v57, v40
	v_add_f32_e32 v41, 1.0, v41
	s_nop 0
	s_nop 0
	s_nop 0
	v_rcp_f32_e32 v41, v41
	v_exp_f32_e32 v34, v34
	v_exp_f32_e32 v35, v35
	v_exp_f32_e32 v36, v36
	v_mul_f32_e32 v41, v57, v41
	v_fma_f32 v38, -v34, v34, 1.0
	v_fma_f32 v39, -v35, v35, 1.0
	v_fma_f32 v40, -v36, v36, 1.0
	v_fma_f32 v37, v37, s98, v150
	s_nop 0
	v_max_f32_e32 v38, 0, v38
	v_max_f32_e32 v39, 0, v39
	v_max_f32_e32 v40, 0, v40
	s_nop 0
	v_exp_f32_e32 v41, v41
	v_sqrt_f32_e32 v38, v38
	v_sqrt_f32_e32 v39, v39
	v_sqrt_f32_e32 v40, v40
	v_exp_f32_e32 v37, v37
	v_fma_f32 v65, -v41, v41, 1.0
	v_mul_f32_e32 v38, v44, v38
	ds_read_u16 v44, v58 offset:9008
	v_mul_f32_e32 v39, v45, v39
	ds_read_u16 v45, v58 offset:9536
	v_mul_f32_e32 v40, v64, v40
	ds_read_u16 v64, v58 offset:10064
	v_add_f32_e32 v37, 1.0, v37
	v_max_f32_e32 v65, 0, v65
	v_rcp_f32_e32 v37, v37
	v_sqrt_f32_e32 v65, v65
	s_waitcnt lgkmcnt(0)
	v_lshlrev_b32_e32 v64, 16, v64
	v_lshlrev_b32_e32 v45, 16, v45
	v_lshlrev_b32_e32 v44, 16, v44
	v_mul_f32_e32 v37, v37, v65
	v_mul_f32_e32 v37, v37, v64
	v_mul_f32_e32 v64, v36, v41
	v_mul_f32_e32 v36, v36, v37
	v_fmac_f32_e32 v36, v40, v45
	v_mul_f32_e32 v40, v35, v64
	v_mul_f32_e32 v35, v35, v36
	v_fmac_f32_e32 v35, v39, v44
	v_lshlrev_b32_e32 v42, 16, v42
	v_mul_f32_e32 v39, v34, v40
	v_mul_f32_e32 v34, v34, v35
	v_fmac_f32_e32 v34, v38, v42
	ds_bpermute_b32 v67, v54, v39
	ds_bpermute_b32 v38, v54, v34
	ds_bpermute_b32 v44, v61, v39
	ds_bpermute_b32 v42, v61, v34
	ds_bpermute_b32 v66, v55, v39
	ds_bpermute_b32 v61, v55, v34
	ds_bpermute_b32 v65, v56, v39
	ds_bpermute_b32 v45, v56, v34
	s_waitcnt lgkmcnt(6)
	v_fmac_f32_e32 v38, v48, v67
	s_waitcnt lgkmcnt(2)
	v_fmac_f32_e32 v61, v38, v66
	s_waitcnt lgkmcnt(0)
	v_fmac_f32_e32 v45, v61, v65
	s_and_saveexec_b64 s[4:5], s[0:1]
	s_cbranch_execz .LBB0_725
	v_cmp_ne_u32_e64 s[0:1], 2, v51
	s_and_saveexec_b64 s[34:35], s[0:1]
	s_xor_b64 s[0:1], exec, s[34:35]
	v_cndmask_b32_e32 v48, v45, v61, vcc
	s_andn2_saveexec_b64 s[0:1], s[0:1]
	v_mov_b32_e32 v48, v38
	s_or_b64 exec, exec, s[0:1]
; template <int DIR, int MODE>
; __device__ __forceinline__ void lru_pass(const Args& a, const LAS bf16_t* cxb, LAS bf16_t* gyb, const LAS float* carry, const bf16x8 (&Bw)[2][2][2], const float (&prm)[2][3], int l, int tt, float (&hf)[8][2][4]) {
;     ...
;     for (int mi = 0; mi < 8; ++mi) {
;         const int m = DIR ? 7 - mi : mi;
;         bf16x8 Af[2];
; #pragma unroll
;         for (int ks = 0; ks < 2; ++ks) Af[ks] = *(const LAS bf16x8*)(cxb + (m * 16 + fr) * CXS + 64 * h + 32 * ks + 8 * fq);
; #pragma unroll
;         for (int nt = 0; nt < 2; ++nt) {
;             f32x4 pr = (f32x4){0.f, 0.f, 0.f, 0.f}, pi = (f32x4){0.f, 0.f, 0.f, 0.f};
; #pragma unroll
;             for (int ks = 0; ks < 2; ++ks) { pr = __builtin_amdgcn_mfma_f32_16x16x32_bf16(Af[ks], Bw[0][nt][ks], pr, 0, 0, 0); pi = __builtin_amdgcn_mfma_f32_16x16x32_bf16(Af[ks], Bw[1][nt][ks], pi, 0, 0, 0); }
;             float av[4], bv[4];
; #pragma unroll
;             for (int reg = 0; reg < 4; ++reg) {
;                 const int tok = m * 16 + 4 * fq + reg;
;                 const float x = bf2f(cxb[tok * CXS + cc[nt]]);
;                 const float r = fsig(pr[reg] + ba[nt]), ig = fsig(pi[reg] + bxv[nt]);
;                 const float aa = __expf(k8[nt] * r);
;                 av[reg] = aa; bv[reg] = __builtin_amdgcn_sqrtf(fmaxf(1.0f - aa * aa, 0.f)) * ig * x;
;             }
;             float cum[4], hl[4];
;             if (DIR == 0) { cum[0] = av[0]; hl[0] = bv[0];
; #pragma unroll
;                 for (int reg = 1; reg < 4; ++reg) { cum[reg] = cum[reg - 1] * av[reg]; hl[reg] = av[reg] * hl[reg - 1] + bv[reg]; } }
;             else { cum[3] = av[3]; hl[3] = bv[3];
; #pragma unroll
;     ...
;             const float A4 = DIR ? cum[0] : cum[3], H4 = DIR ? hl[0] : hl[3];
;             float Aq[4], Hq[4];
; #pragma unroll
;             for (int q = 0; q < 4; ++q) { Aq[q] = __shfl(A4, fr + 16 * q); Hq[q] = __shfl(H4, fr + 16 * q); }
;             float hin;
;             if (DIR == 0) { const float s0 = C[nt], s1 = Aq[0] * s0 + Hq[0], s2 = Aq[1] * s1 + Hq[1], s3 = Aq[2] * s2 + Hq[2]; C[nt] = Aq[3] * s3 + Hq[3]; hin = fq == 0 ? s0 : (fq == 1 ? s1 : (fq == 2 ? s2 : s3)); }
;             else { const float s3 = C[nt], s2 = Aq[3] * s3 + Hq[3], s1 = Aq[2] * s2 + Hq[2], s0 = Aq[1] * s1 + Hq[1]; C[nt] = Aq[0] * s0 + Hq[0]; hin = fq == 3 ? s3 : (fq == 2 ? s2 : (fq == 1 ? s1 : s0)); }
.LBB0_725:
	s_or_b64 exec, exec, s[4:5]
	ds_read_u16 v38, v52 offset:8448
	v_fmac_f32_e32 v34, v39, v48
	v_fmac_f32_e32 v93, v94, v92
	v_add_f32_e32 v34, v93, v34
	v_fmac_f32_e32 v97, v98, v92
	s_waitcnt lgkmcnt(0)
	v_lshlrev_b32_e32 v38, 16, v38
	v_mul_f32_e32 v39, 0x3d372713, v38
	v_mul_f32_e32 v39, v39, v38
	v_fma_f32 v39, v39, v38, v38
	v_mul_f32_e32 v39, 0x3f4c422a, v39
	v_add_f32_e32 v39, v39, v39
	v_mul_f32_e32 v39, 0x3fb8aa3b, v39
	v_exp_f32_e32 v39, v39
	v_mul_f32_e32 v38, 0.5, v38
	v_fmac_f32_e32 v35, v40, v48
	v_add_f32_e32 v35, v97, v35
	v_add_f32_e32 v39, 1.0, v39
	v_rcp_f32_e32 v39, v39
	v_fmac_f32_e32 v96, v99, v92
	v_fmac_f32_e32 v36, v64, v48
	v_fmac_f32_e32 v95, v100, v92
	v_fma_f32 v39, v39, -2.0, 2.0
	v_mul_f32_e32 v38, v38, v39
	v_mul_f32_e32 v34, v34, v38
	v_bfe_u32 v38, v34, 16, 1
	v_add3_u32 v34, v34, v38, s27
	ds_write_b16_d16_hi v52, v34 offset:8448
	ds_read_u16 v34, v52 offset:8976
	v_fmac_f32_e32 v37, v41, v48
	v_fmac_f32_e32 v43, v47, v46
	v_cmp_gt_i32_e64 s[0:1], 3, v51
	s_waitcnt lgkmcnt(0)
	v_lshlrev_b32_e32 v34, 16, v34
	v_mul_f32_e32 v38, 0x3d372713, v34
	v_mul_f32_e32 v38, v38, v34
	v_fma_f32 v38, v38, v34, v34
	v_mul_f32_e32 v38, 0x3f4c422a, v38
	v_add_f32_e32 v38, v38, v38
	v_mul_f32_e32 v38, 0x3fb8aa3b, v38
	v_exp_f32_e32 v38, v38
	v_mul_f32_e32 v34, 0.5, v34
	v_add_f32_e32 v38, 1.0, v38
	v_rcp_f32_e32 v38, v38
	s_nop 0
	v_fma_f32 v38, v38, -2.0, 2.0
	v_mul_f32_e32 v34, v34, v38
	v_mul_f32_e32 v34, v35, v34
	v_bfe_u32 v35, v34, 16, 1
	v_add3_u32 v34, v34, v35, s27
	ds_write_b16_d16_hi v52, v34 offset:8976
	ds_read_u16 v34, v52 offset:9504
	v_add_f32_e32 v35, v96, v36
	s_waitcnt lgkmcnt(0)
	v_lshlrev_b32_e32 v34, 16, v34
	v_mul_f32_e32 v36, 0x3d372713, v34
	v_mul_f32_e32 v36, v36, v34
	v_fma_f32 v36, v36, v34, v34
	v_mul_f32_e32 v36, 0x3f4c422a, v36
	v_add_f32_e32 v36, v36, v36
	v_mul_f32_e32 v36, 0x3fb8aa3b, v36
	v_exp_f32_e32 v36, v36
	v_mul_f32_e32 v34, 0.5, v34
	v_add_f32_e32 v36, 1.0, v36
	v_rcp_f32_e32 v36, v36
	s_nop 0
	v_fma_f32 v36, v36, -2.0, 2.0
	v_mul_f32_e32 v34, v34, v36
	v_mul_f32_e32 v34, v35, v34
	v_bfe_u32 v35, v34, 16, 1
	v_add3_u32 v34, v34, v35, s27
	ds_write_b16_d16_hi v52, v34 offset:9504
	ds_read_u16 v34, v52 offset:10032
	v_add_f32_e32 v35, v95, v37
	s_waitcnt lgkmcnt(0)
	v_lshlrev_b32_e32 v34, 16, v34
	v_mul_f32_e32 v36, 0x3d372713, v34
	v_mul_f32_e32 v36, v36, v34
	v_fma_f32 v36, v36, v34, v34
	v_mul_f32_e32 v36, 0x3f4c422a, v36
	v_add_f32_e32 v36, v36, v36
	v_mul_f32_e32 v36, 0x3fb8aa3b, v36
	v_exp_f32_e32 v36, v36
	v_mul_f32_e32 v34, 0.5, v34
	v_add_f32_e32 v36, 1.0, v36
	v_rcp_f32_e32 v36, v36
	s_nop 0
	v_fma_f32 v36, v36, -2.0, 2.0
	v_mul_f32_e32 v34, v34, v36
	v_mul_f32_e32 v34, v35, v34
	v_bfe_u32 v35, v34, 16, 1
	v_add3_u32 v34, v34, v35, s27
	ds_write_b16_d16_hi v52, v34 offset:10032
	ds_read_b128 v[38:41], v62
	ds_read_b128 v[34:37], v62 offset:64
	s_waitcnt lgkmcnt(1)
	v_mfma_f32_16x16x32_bf16 v[22:25], v[38:41], v[22:25], 0
	v_mfma_f32_16x16x32_bf16 v[30:33], v[38:41], v[30:33], 0
	s_waitcnt lgkmcnt(0)
	v_mfma_f32_16x16x32_bf16 v[22:25], v[34:37], v[18:21], v[22:25]
	v_mfma_f32_16x16x32_bf16 v[18:21], v[34:37], v[26:29], v[30:33]
	ds_read_u16 v26, v58
	s_nop 5
	v_fma_f32 v22, v22, s98, v153
	v_fma_f32 v23, v23, s98, v153
	v_fma_f32 v24, v24, s98, v153
	s_nop 0
	s_nop 0
	s_nop 0
	v_exp_f32_e32 v22, v22
	v_exp_f32_e32 v23, v23
	v_exp_f32_e32 v24, v24
	v_fma_f32 v18, v18, s98, v152
	v_fma_f32 v19, v19, s98, v152
	v_fma_f32 v20, v20, s98, v152
	s_nop 0
	s_nop 0
	s_nop 0
	v_fma_f32 v25, v25, s98, v153
	v_add_f32_e32 v22, 1.0, v22
	v_exp_f32_e32 v18, v18
	v_add_f32_e32 v23, 1.0, v23
	v_exp_f32_e32 v19, v19
	v_add_f32_e32 v24, 1.0, v24
	v_exp_f32_e32 v20, v20
	s_nop 0
	v_rcp_f32_e32 v22, v22
	v_rcp_f32_e32 v23, v23
	v_rcp_f32_e32 v24, v24
	v_exp_f32_e32 v25, v25
	v_add_f32_e32 v18, 1.0, v18
	v_add_f32_e32 v19, 1.0, v19
	v_add_f32_e32 v20, 1.0, v20
	v_rcp_f32_e32 v27, v18
	v_mul_f32_e32 v18, v60, v22
	v_rcp_f32_e32 v28, v19
	v_mul_f32_e32 v19, v60, v23
	v_rcp_f32_e32 v29, v20
	v_mul_f32_e32 v20, v60, v24
	v_add_f32_e32 v25, 1.0, v25
	s_nop 0
	s_nop 0
	s_nop 0
	v_rcp_f32_e32 v25, v25
	v_exp_f32_e32 v18, v18
	v_exp_f32_e32 v19, v19
	v_exp_f32_e32 v20, v20
	v_mul_f32_e32 v25, v60, v25
	v_fma_f32 v22, -v18, v18, 1.0
	v_fma_f32 v23, -v19, v19, 1.0
	v_fma_f32 v24, -v20, v20, 1.0
	v_fma_f32 v21, v21, s98, v152
	s_nop 0
	v_max_f32_e32 v22, 0, v22
	v_max_f32_e32 v23, 0, v23
	v_max_f32_e32 v24, 0, v24
	s_nop 0
	v_exp_f32_e32 v25, v25
	v_sqrt_f32_e32 v22, v22
	v_sqrt_f32_e32 v23, v23
	v_sqrt_f32_e32 v24, v24
	v_exp_f32_e32 v21, v21
	v_fma_f32 v30, -v25, v25, 1.0
	v_mul_f32_e32 v22, v27, v22
	ds_read_u16 v27, v58 offset:528
	v_mul_f32_e32 v23, v28, v23
	ds_read_u16 v28, v58 offset:1056
	v_mul_f32_e32 v24, v29, v24
	ds_read_u16 v29, v58 offset:1584
	v_add_f32_e32 v21, 1.0, v21
	v_max_f32_e32 v30, 0, v30
	v_rcp_f32_e32 v21, v21
	v_sqrt_f32_e32 v30, v30
	s_waitcnt lgkmcnt(0)
	v_lshlrev_b32_e32 v29, 16, v29
	v_lshlrev_b32_e32 v28, 16, v28
	v_lshlrev_b32_e32 v27, 16, v27
	v_mul_f32_e32 v21, v21, v30
	v_mul_f32_e32 v21, v21, v29
	v_mul_f32_e32 v29, v20, v25
	v_mul_f32_e32 v20, v20, v21
	v_fmac_f32_e32 v20, v24, v28
	v_mul_f32_e32 v24, v19, v29
	v_mul_f32_e32 v19, v19, v20
	v_fmac_f32_e32 v19, v23, v27
	v_lshlrev_b32_e32 v26, 16, v26
	v_mul_f32_e32 v23, v18, v24
	v_mul_f32_e32 v18, v18, v19
	v_fmac_f32_e32 v18, v22, v26
	ds_bpermute_b32 v26, v56, v23
	ds_bpermute_b32 v27, v56, v18
	ds_bpermute_b32 v30, v55, v23
	ds_bpermute_b32 v28, v55, v18
	ds_bpermute_b32 v31, v54, v23
	ds_bpermute_b32 v22, v54, v18
	s_and_saveexec_b64 s[4:5], s[0:1]
	s_cbranch_execz .LBB0_731
	s_waitcnt lgkmcnt(0)
	v_fmac_f32_e32 v22, v43, v31
	v_cmp_ne_u32_e64 s[0:1], 2, v51
	s_and_saveexec_b64 s[34:35], s[0:1]
	s_xor_b64 s[0:1], exec, s[34:35]
	v_fmac_f32_e32 v28, v22, v30
	v_fmac_f32_e32 v27, v28, v26
	v_cndmask_b32_e32 v43, v27, v28, vcc
	s_andn2_saveexec_b64 s[0:1], s[0:1]
	v_mov_b32_e32 v43, v22
	s_or_b64 exec, exec, s[0:1]
; template <int DIR, int MODE>
; __device__ __forceinline__ void lru_pass(const Args& a, const LAS bf16_t* cxb, LAS bf16_t* gyb, const LAS float* carry, const bf16x8 (&Bw)[2][2][2], const float (&prm)[2][3], int l, int tt, float (&hf)[8][2][4]) {
;     ...
;     for (int mi = 0; mi < 8; ++mi) {
;         const int m = DIR ? 7 - mi : mi;
;         bf16x8 Af[2];
; #pragma unroll
;         for (int ks = 0; ks < 2; ++ks) Af[ks] = *(const LAS bf16x8*)(cxb + (m * 16 + fr) * CXS + 64 * h + 32 * ks + 8 * fq);
; #pragma unroll
;         for (int nt = 0; nt < 2; ++nt) {
;             f32x4 pr = (f32x4){0.f, 0.f, 0.f, 0.f}, pi = (f32x4){0.f, 0.f, 0.f, 0.f};
; #pragma unroll
;             for (int ks = 0; ks < 2; ++ks) { pr = __builtin_amdgcn_mfma_f32_16x16x32_bf16(Af[ks], Bw[0][nt][ks], pr, 0, 0, 0); pi = __builtin_amdgcn_mfma_f32_16x16x32_bf16(Af[ks], Bw[1][nt][ks], pi, 0, 0, 0); }
;             float av[4], bv[4];
; #pragma unroll
;             for (int reg = 0; reg < 4; ++reg) {
;                 const int tok = m * 16 + 4 * fq + reg;
;                 const float x = bf2f(cxb[tok * CXS + cc[nt]]);
;                 const float r = fsig(pr[reg] + ba[nt]), ig = fsig(pi[reg] + bxv[nt]);
;                 const float aa = __expf(k8[nt] * r);
;                 av[reg] = aa; bv[reg] = __builtin_amdgcn_sqrtf(fmaxf(1.0f - aa * aa, 0.f)) * ig * x;
;             }
;             float cum[4], hl[4];
;             if (DIR == 0) { cum[0] = av[0]; hl[0] = bv[0];
; #pragma unroll
;                 for (int reg = 1; reg < 4; ++reg) { cum[reg] = cum[reg - 1] * av[reg]; hl[reg] = av[reg] * hl[reg - 1] + bv[reg]; } }
;             else { cum[3] = av[3]; hl[3] = bv[3];
; #pragma unroll
;     ...
;             const float A4 = DIR ? cum[0] : cum[3], H4 = DIR ? hl[0] : hl[3];
;             float Aq[4], Hq[4];
; #pragma unroll
;             for (int q = 0; q < 4; ++q) { Aq[q] = __shfl(A4, fr + 16 * q); Hq[q] = __shfl(H4, fr + 16 * q); }
;             float hin;
;             if (DIR == 0) { const float s0 = C[nt], s1 = Aq[0] * s0 + Hq[0], s2 = Aq[1] * s1 + Hq[1], s3 = Aq[2] * s2 + Hq[2]; C[nt] = Aq[3] * s3 + Hq[3]; hin = fq == 0 ? s0 : (fq == 1 ? s1 : (fq == 2 ? s2 : s3)); }
;             else { const float s3 = C[nt], s2 = Aq[3] * s3 + Hq[3], s1 = Aq[2] * s2 + Hq[2], s0 = Aq[1] * s1 + Hq[1]; C[nt] = Aq[0] * s0 + Hq[0]; hin = fq == 3 ? s3 : (fq == 2 ? s2 : (fq == 1 ? s1 : s0)); }
.LBB0_731:
	s_or_b64 exec, exec, s[4:5]
	v_mfma_f32_16x16x32_bf16 v[6:9], v[38:41], v[6:9], 0
	s_waitcnt lgkmcnt(0)
	ds_read_u16 v22, v59
	v_fmac_f32_e32 v18, v23, v43
	v_fmac_f32_e32 v88, v87, v74
	v_mfma_f32_16x16x32_bf16 v[14:17], v[38:41], v[14:17], 0
	v_add_f32_e32 v18, v88, v18
	v_fmac_f32_e32 v86, v89, v74
	v_fmac_f32_e32 v19, v24, v43
	v_mfma_f32_16x16x32_bf16 v[6:9], v[34:37], v[2:5], v[6:9]
	v_add_f32_e32 v19, v86, v19
	v_fmac_f32_e32 v85, v90, v74
	v_fmac_f32_e32 v20, v29, v43
	v_mfma_f32_16x16x32_bf16 v[2:5], v[34:37], v[10:13], v[14:17]
	ds_read_u16 v10, v58 offset:32
	s_nop 2
	v_fma_f32 v6, v6, s98, v151
	v_fma_f32 v7, v7, s98, v151
	v_fma_f32 v8, v8, s98, v151
	s_nop 0
	s_nop 0
	s_nop 0
	v_exp_f32_e32 v6, v6
	v_exp_f32_e32 v7, v7
	v_exp_f32_e32 v8, v8
	v_fma_f32 v2, v2, s98, v150
	v_fma_f32 v3, v3, s98, v150
	s_nop 0
	s_nop 0
	v_add_f32_e32 v6, 1.0, v6
	v_exp_f32_e32 v2, v2
	v_add_f32_e32 v7, 1.0, v7
	v_exp_f32_e32 v3, v3
	v_add_f32_e32 v8, 1.0, v8
	v_rcp_f32_e32 v6, v6
	v_rcp_f32_e32 v7, v7
	v_rcp_f32_e32 v8, v8
	v_add_f32_e32 v2, 1.0, v2
	v_add_f32_e32 v3, 1.0, v3
	v_rcp_f32_e32 v11, v2
	v_mul_f32_e32 v2, v57, v6
	v_rcp_f32_e32 v12, v3
	v_mul_f32_e32 v3, v57, v7
	v_mul_f32_e32 v8, v57, v8
	s_nop 0
	s_nop 0
	v_fma_f32 v4, v4, s98, v150
	s_nop 0
	v_exp_f32_e32 v2, v2
	v_exp_f32_e32 v3, v3
	s_nop 0
	v_exp_f32_e32 v8, v8
	v_exp_f32_e32 v4, v4
	v_fma_f32 v6, -v2, v2, 1.0
	v_fma_f32 v7, -v3, v3, 1.0
	v_fma_f32 v13, -v8, v8, 1.0
	v_max_f32_e32 v6, 0, v6
	v_max_f32_e32 v7, 0, v7
	v_add_f32_e32 v4, 1.0, v4
	v_max_f32_e32 v13, 0, v13
	v_sqrt_f32_e32 v6, v6
	v_sqrt_f32_e32 v7, v7
	v_rcp_f32_e32 v4, v4
	v_sqrt_f32_e32 v13, v13
	v_mul_f32_e32 v6, v11, v6
	ds_read_u16 v11, v58 offset:560
	v_mul_f32_e32 v7, v12, v7
	ds_read_u16 v12, v58 offset:1088
	v_mul_f32_e32 v13, v4, v13
	ds_read_u16 v4, v58 offset:1616
	s_waitcnt lgkmcnt(4)
	v_lshlrev_b32_e32 v22, 16, v22
	v_mul_f32_e32 v23, 0x3d372713, v22
	v_mul_f32_e32 v23, v23, v22
	v_fma_f32 v23, v23, v22, v22
	v_mul_f32_e32 v23, 0x3f4c422a, v23
	v_add_f32_e32 v23, v23, v23
	v_mul_f32_e32 v23, 0x3fb8aa3b, v23
	v_exp_f32_e32 v23, v23
	v_mul_f32_e32 v22, 0.5, v22
	v_fma_f32 v9, v9, s98, v151
	s_nop 0
	v_add_f32_e32 v23, 1.0, v23
	v_rcp_f32_e32 v23, v23
	v_exp_f32_e32 v9, v9
	v_fma_f32 v5, v5, s98, v150
	s_nop 0
	v_fma_f32 v23, v23, -2.0, 2.0
	v_mul_f32_e32 v22, v22, v23
	v_mul_f32_e32 v18, v18, v22
	v_bfe_u32 v22, v18, 16, 1
	v_add3_u32 v18, v18, v22, s27
	ds_write_b16_d16_hi v59, v18
	ds_read_u16 v18, v59 offset:528
	v_add_f32_e32 v9, 1.0, v9
	v_exp_f32_e32 v5, v5
	v_rcp_f32_e32 v9, v9
	s_waitcnt lgkmcnt(2)
	v_lshlrev_b32_e32 v4, 16, v4
	s_waitcnt lgkmcnt(0)
	v_lshlrev_b32_e32 v18, 16, v18
	v_mul_f32_e32 v22, 0x3d372713, v18
	v_mul_f32_e32 v22, v22, v18
	v_fma_f32 v22, v22, v18, v18
	v_mul_f32_e32 v22, 0x3f4c422a, v22
	v_add_f32_e32 v22, v22, v22
	v_mul_f32_e32 v22, 0x3fb8aa3b, v22
	v_exp_f32_e32 v22, v22
	v_mul_f32_e32 v18, 0.5, v18
	v_add_f32_e32 v5, 1.0, v5
	v_rcp_f32_e32 v14, v5
	v_add_f32_e32 v22, 1.0, v22
	v_rcp_f32_e32 v22, v22
	v_mul_f32_e32 v5, v57, v9
	s_nop 0
	v_exp_f32_e32 v5, v5
	v_fma_f32 v22, v22, -2.0, 2.0
	v_mul_f32_e32 v18, v18, v22
	v_mul_f32_e32 v18, v19, v18
	v_bfe_u32 v19, v18, 16, 1
	v_add3_u32 v18, v18, v19, s27
	ds_write_b16_d16_hi v59, v18 offset:528
	ds_read_u16 v18, v59 offset:1056
	v_add_f32_e32 v19, v85, v20
	v_fma_f32 v9, -v5, v5, 1.0
	v_max_f32_e32 v9, 0, v9
	v_sqrt_f32_e32 v9, v9
	s_waitcnt lgkmcnt(0)
	v_lshlrev_b32_e32 v18, 16, v18
	v_mul_f32_e32 v20, 0x3d372713, v18
	v_mul_f32_e32 v20, v20, v18
	v_fma_f32 v20, v20, v18, v18
	v_mul_f32_e32 v20, 0x3f4c422a, v20
	v_add_f32_e32 v20, v20, v20
	v_mul_f32_e32 v20, 0x3fb8aa3b, v20
	v_exp_f32_e32 v20, v20
	v_mul_f32_e32 v18, 0.5, v18
	v_mul_f32_e32 v9, v14, v9
	v_mul_f32_e32 v4, v9, v4
	v_add_f32_e32 v20, 1.0, v20
	v_rcp_f32_e32 v20, v20
	v_lshlrev_b32_e32 v12, 16, v12
	v_mul_f32_e32 v9, v8, v5
	v_mul_f32_e32 v8, v8, v4
	v_fma_f32 v20, v20, -2.0, 2.0
	v_mul_f32_e32 v18, v18, v20
	v_mul_f32_e32 v18, v19, v18
	v_bfe_u32 v19, v18, 16, 1
	v_add3_u32 v18, v18, v19, s27
	ds_write_b16_d16_hi v59, v18 offset:1056
	ds_read_u16 v18, v59 offset:1584
	v_fmac_f32_e32 v8, v13, v12
	v_lshlrev_b32_e32 v11, 16, v11
	v_mul_f32_e32 v12, v3, v9
	v_mul_f32_e32 v3, v3, v8
	s_waitcnt lgkmcnt(0)
	v_lshlrev_b32_e32 v18, 16, v18
	v_mul_f32_e32 v20, 0x3d372713, v18
	v_mul_f32_e32 v20, v20, v18
	v_fma_f32 v20, v20, v18, v18
	v_mul_f32_e32 v20, 0x3f4c422a, v20
	v_add_f32_e32 v20, v20, v20
	v_mul_f32_e32 v20, 0x3fb8aa3b, v20
	v_exp_f32_e32 v20, v20
	v_fmac_f32_e32 v3, v7, v11
	v_lshlrev_b32_e32 v10, 16, v10
	v_mul_f32_e32 v7, v2, v12
	v_add_f32_e32 v20, 1.0, v20
	v_rcp_f32_e32 v20, v20
	v_mul_f32_e32 v2, v2, v3
	v_fmac_f32_e32 v2, v6, v10
	v_fmac_f32_e32 v84, v91, v74
	v_fmac_f32_e32 v21, v25, v43
	v_mul_f32_e32 v18, 0.5, v18
	v_fma_f32 v20, v20, -2.0, 2.0
	ds_bpermute_b32 v10, v56, v7
	ds_bpermute_b32 v11, v56, v2
	ds_bpermute_b32 v14, v55, v7
	ds_bpermute_b32 v13, v55, v2
	ds_bpermute_b32 v15, v54, v7
	ds_bpermute_b32 v6, v54, v2
	v_add_f32_e32 v19, v84, v21
	v_mul_f32_e32 v18, v18, v20
	v_mul_f32_e32 v18, v19, v18
	v_bfe_u32 v19, v18, 16, 1
	v_add3_u32 v18, v18, v19, s27
	v_fmac_f32_e32 v42, v45, v44
	v_cmp_gt_i32_e64 s[0:1], 3, v51
	ds_write_b16_d16_hi v59, v18 offset:1584
	s_and_saveexec_b64 s[4:5], s[0:1]
	s_cbranch_execz .LBB0_737
	s_waitcnt lgkmcnt(1)
	v_fmac_f32_e32 v6, v42, v15
	v_cmp_ne_u32_e64 s[0:1], 2, v51
	s_and_saveexec_b64 s[34:35], s[0:1]
	s_xor_b64 s[0:1], exec, s[34:35]
	v_fmac_f32_e32 v13, v6, v14
	v_fmac_f32_e32 v11, v13, v10
	v_cndmask_b32_e32 v42, v11, v13, vcc
	s_andn2_saveexec_b64 s[0:1], s[0:1]
	v_mov_b32_e32 v42, v6
	s_or_b64 exec, exec, s[0:1]

; #define LAS __attribute__((address_space(3)))
; __device__ __forceinline__ u32x4 pack8(const float (&f)[8]) { u32x4 o; o.x = pk2(f[0], f[1]); o.y = pk2(f[2], f[3]); o.z = pk2(f[4], f[5]); o.w = pk2(f[6], f[7]); return o; }
; __device__ __forceinline__ void lru_conv_tile(const Args& a, LAS bf16_t* cxb, int l, const Tile& T) {
;     ...
;     for (int i = 0; i < 11; ++i) {
;         const int tg = T.t0 + grp * 8 + i - 2;
;         u32x4 rv = raw[i]; if (!(tg >= 0 && tg < T.seqlen)) rv = (u32x4){0u, 0u, 0u, 0u};
; #pragma unroll
;         for (int e = 0; e < 8; ++e) { win[0][e] = win[1][e]; win[1][e] = win[2][e]; win[2][e] = win[3][e]; }
;         unpack8(rv, win[3]);
;         if (i >= 3) {
;             float o[8];
; #pragma unroll
;             for (int e = 0; e < 8; ++e) o[e] = bias[e] + w[0][e] * win[0][e] + w[1][e] * win[1][e] + w[2][e] * win[2][e] + w[3][e] * win[3][e];
;             *(LAS u32x4*)(cxb + (grp * 8 + i - 3) * CXS + c0) = pack8(o);
;         }
;     }
.LBB0_771:
	s_or_b64 exec, exec, s[4:5]
	s_waitcnt vmcnt(0)
	v_lshlrev_b32_e32 v166, 16, v146
	v_and_b32_e32 v168, 0xffff0000, v146
	v_add_u32_e32 v146, 1, v162
	v_cmp_lt_i32_e32 vcc, 1, v146
	v_add_u32_e32 v146, -1, v162
	v_cmp_gt_u32_e64 s[0:1], s34, v146
	s_and_b64 vcc, vcc, s[0:1]
	v_cndmask_b32_e32 v182, 0, v144, vcc
	v_add_u32_e32 v144, 2, v162
	v_cndmask_b32_e32 v180, 0, v145, vcc
	v_cndmask_b32_e32 v143, 0, v143, vcc
	v_cndmask_b32_e32 v142, 0, v142, vcc
	v_cmp_lt_i32_e32 vcc, 1, v144
	v_cmp_ge_i32_e64 s[0:1], s34, v144
	s_and_b64 vcc, vcc, s[0:1]
	v_or_b32_e32 v190, 3, v164
	v_cndmask_b32_e32 v186, 0, v136, vcc
	v_add_u32_e32 v136, s35, v190
	v_cndmask_b32_e32 v184, 0, v137, vcc
	v_cndmask_b32_e32 v135, 0, v135, vcc
	v_cndmask_b32_e32 v134, 0, v134, vcc
	v_cmp_lt_i32_e32 vcc, 1, v136
	v_add_u32_e32 v136, -2, v136
	v_cmp_gt_u32_e64 s[0:1], s34, v136
	s_and_b64 vcc, vcc, s[0:1]
	v_cndmask_b32_e32 v136, 0, v139, vcc
	v_cndmask_b32_e32 v137, 0, v138, vcc
	v_lshlrev_b32_e32 v167, 16, v147
	v_and_b32_e32 v169, 0xffff0000, v147
	v_lshlrev_b32_e32 v177, 16, v135
	v_lshlrev_b32_e32 v176, 16, v134
	v_and_b32_e32 v179, 0xffff0000, v135
	v_and_b32_e32 v178, 0xffff0000, v134
	v_lshlrev_b32_e32 v147, 16, v136
	v_lshlrev_b32_e32 v146, 16, v137
	v_and_b32_e32 v145, 0xffff0000, v136
	v_and_b32_e32 v144, 0xffff0000, v137
	v_mov_b32_e32 v134, v86
	v_mov_b32_e32 v135, v88
	v_mov_b32_e32 v136, v102
	v_mov_b32_e32 v137, v104
	v_mov_b32_e32 v88, v87
	v_mov_b32_e32 v104, v103
	v_cndmask_b32_e32 v188, 0, v141, vcc
	v_cndmask_b32_e32 v191, 0, v140, vcc
	v_lshlrev_b32_e32 v173, 16, v143
	v_lshlrev_b32_e32 v172, 16, v142
	v_and_b32_e32 v175, 0xffff0000, v143
	v_and_b32_e32 v174, 0xffff0000, v142
	v_pk_fma_f32 v[140:141], v[134:135], v[166:167], v[136:137]
	v_mov_b32_e32 v138, v90
	v_mov_b32_e32 v139, v92
	v_pk_fma_f32 v[86:87], v[88:89], v[168:169], v[104:105]
	v_mov_b32_e32 v92, v91
	v_pk_fma_f32 v[142:143], v[138:139], v[172:173], v[140:141]
	v_mov_b32_e32 v140, v94
	v_mov_b32_e32 v141, v96
	v_pk_fma_f32 v[86:87], v[92:93], v[174:175], v[86:87]
	v_mov_b32_e32 v96, v95
	v_pk_fma_f32 v[164:165], v[140:141], v[176:177], v[142:143]
	v_mov_b32_e32 v143, v100
	v_pk_fma_f32 v[86:87], v[96:97], v[178:179], v[86:87]
	v_mov_b32_e32 v100, v99
	v_lshlrev_b32_e32 v170, 16, v148
	v_lshlrev_b32_e32 v171, 16, v149
	v_pk_fma_f32 v[166:167], v[100:101], v[144:145], v[86:87]
	v_mov_b32_e32 v86, v66
	v_mov_b32_e32 v87, v68
	v_mov_b32_e32 v90, v82
	v_mov_b32_e32 v91, v84
	v_and_b32_e32 v148, 0xffff0000, v148
	v_and_b32_e32 v149, 0xffff0000, v149
	v_mov_b32_e32 v142, v98
	v_lshlrev_b32_e32 v169, 16, v180
	v_lshlrev_b32_e32 v168, 16, v182
	v_pk_fma_f32 v[98:99], v[86:87], v[170:171], v[90:91]
	v_mov_b32_e32 v94, v70
	v_mov_b32_e32 v95, v72
	v_mov_b32_e32 v68, v67
	v_mov_b32_e32 v84, v83
	v_and_b32_e32 v181, 0xffff0000, v180
	v_and_b32_e32 v180, 0xffff0000, v182
	v_lshlrev_b32_e32 v183, 16, v184
	v_lshlrev_b32_e32 v182, 16, v186
	v_pk_fma_f32 v[102:103], v[94:95], v[168:169], v[98:99]
	v_mov_b32_e32 v98, v74
	v_mov_b32_e32 v99, v76
	v_pk_fma_f32 v[66:67], v[68:69], v[148:149], v[84:85]
	v_mov_b32_e32 v72, v71
	v_and_b32_e32 v185, 0xffff0000, v184
	v_and_b32_e32 v184, 0xffff0000, v186
	v_lshlrev_b32_e32 v187, 16, v188
	v_lshlrev_b32_e32 v186, 16, v191
	v_pk_fma_f32 v[170:171], v[98:99], v[182:183], v[102:103]
	v_mov_b32_e32 v102, v78
	v_mov_b32_e32 v103, v80
	v_pk_fma_f32 v[66:67], v[72:73], v[180:181], v[66:67]
	v_mov_b32_e32 v76, v75
	v_and_b32_e32 v189, 0xffff0000, v188
	v_and_b32_e32 v188, 0xffff0000, v191
	v_pk_fma_f32 v[170:171], v[102:103], v[186:187], v[170:171]
	v_pk_fma_f32 v[66:67], v[76:77], v[184:185], v[66:67]
	v_mov_b32_e32 v80, v79
	v_pk_fma_f32 v[66:67], v[80:81], v[188:189], v[66:67]
	v_bfe_u32 v78, v170, 16, 1
	v_pk_fma_f32 v[164:165], v[142:143], v[146:147], v[164:165]
	v_bfe_u32 v70, v67, 16, 1
	v_bfe_u32 v71, v66, 16, 1
	v_add3_u32 v78, v170, v78, s27
	v_bfe_u32 v75, v166, 16, 1
	v_add3_u32 v66, v66, v71, s27
	v_add3_u32 v67, v67, v70, s27
	v_bfe_u32 v70, v164, 16, 1
	v_bfe_u32 v71, v165, 16, 1
	v_bfe_u32 v79, v171, 16, 1
	v_lshrrev_b32_e32 v78, 16, v78
	v_bfe_u32 v74, v167, 16, 1
	v_add3_u32 v75, v166, v75, s27
	v_add3_u32 v79, v171, v79, s27
	v_add3_u32 v71, v165, v71, s27
	v_add3_u32 v70, v164, v70, s27
	v_and_or_b32 v166, v66, s6, v78
	v_mul_lo_u32 v66, v190, s55
	v_add3_u32 v74, v167, v74, s27
	v_lshrrev_b32_e32 v70, 16, v70
	v_lshrrev_b32_e32 v71, 16, v71
	v_lshrrev_b32_e32 v79, 16, v79
	v_add3_u32 v170, 0, v66, v206
	v_and_or_b32 v167, v67, s6, v79
	v_and_or_b32 v165, v74, s6, v71
	v_and_or_b32 v164, v75, s6, v70
	v_add_u32_e32 v66, 0xfffff9d0, v170
	ds_write_b128 v66, v[164:167]
	v_add_u32_e32 v66, 4, v162
	v_cmp_lt_i32_e32 vcc, 1, v66
	v_cmp_ge_i32_e64 s[0:1], s34, v66
	s_and_b64 vcc, vcc, s[0:1]
	v_cndmask_b32_e32 v133, 0, v133, vcc
	v_cndmask_b32_e32 v132, 0, v132, vcc
	v_cndmask_b32_e32 v70, 0, v131, vcc
	v_cndmask_b32_e32 v74, 0, v130, vcc
	v_pk_fma_f32 v[78:79], v[88:89], v[174:175], v[104:105]
	v_lshlrev_b32_e32 v83, 16, v133
	v_lshlrev_b32_e32 v82, 16, v132
	v_and_b32_e32 v149, 0xffff0000, v133
	v_and_b32_e32 v148, 0xffff0000, v132
	v_pk_fma_f32 v[132:133], v[68:69], v[180:181], v[84:85]
	v_lshlrev_b32_e32 v67, 16, v70
	v_lshlrev_b32_e32 v66, 16, v74
	v_and_b32_e32 v71, 0xffff0000, v70
	v_and_b32_e32 v70, 0xffff0000, v74
	v_pk_fma_f32 v[74:75], v[134:135], v[172:173], v[136:137]
	v_pk_fma_f32 v[78:79], v[92:93], v[178:179], v[78:79]
	v_pk_fma_f32 v[130:131], v[86:87], v[168:169], v[90:91]
	v_pk_fma_f32 v[132:133], v[72:73], v[184:185], v[132:133]
	v_pk_fma_f32 v[74:75], v[138:139], v[176:177], v[74:75]
	v_pk_fma_f32 v[78:79], v[96:97], v[144:145], v[78:79]
; #define LAS __attribute__((address_space(3)))
; __device__ __forceinline__ u32x4 pack8(const float (&f)[8]) { u32x4 o; o.x = pk2(f[0], f[1]); o.y = pk2(f[2], f[3]); o.z = pk2(f[4], f[5]); o.w = pk2(f[6], f[7]); return o; }
; __device__ __forceinline__ void lru_conv_tile(const Args& a, LAS bf16_t* cxb, int l, const Tile& T) {
;     ...
;     for (int i = 0; i < 11; ++i) {
;         const int tg = T.t0 + grp * 8 + i - 2;
;         u32x4 rv = raw[i]; if (!(tg >= 0 && tg < T.seqlen)) rv = (u32x4){0u, 0u, 0u, 0u};
; #pragma unroll
;         for (int e = 0; e < 8; ++e) { win[0][e] = win[1][e]; win[1][e] = win[2][e]; win[2][e] = win[3][e]; }
;         unpack8(rv, win[3]);
;         if (i >= 3) {
;             float o[8];
; #pragma unroll
;             for (int e = 0; e < 8; ++e) o[e] = bias[e] + w[0][e] * win[0][e] + w[1][e] * win[1][e] + w[2][e] * win[2][e] + w[3][e] * win[3][e];
;             *(LAS u32x4*)(cxb + (grp * 8 + i - 3) * CXS + c0) = pack8(o);
;         }
;     }
	v_pk_fma_f32 v[130:131], v[94:95], v[182:183], v[130:131]
	v_pk_fma_f32 v[132:133], v[76:77], v[188:189], v[132:133]
	v_pk_fma_f32 v[74:75], v[140:141], v[146:147], v[74:75]
	v_pk_fma_f32 v[78:79], v[100:101], v[70:71], v[78:79]
	v_pk_fma_f32 v[130:131], v[98:99], v[186:187], v[130:131]
	v_pk_fma_f32 v[132:133], v[80:81], v[148:149], v[132:133]
	v_pk_fma_f32 v[74:75], v[142:143], v[66:67], v[74:75]
	v_pk_fma_f32 v[130:131], v[102:103], v[82:83], v[130:131]
	v_bfe_u32 v164, v133, 16, 1
	v_bfe_u32 v165, v132, 16, 1
	v_bfe_u32 v166, v79, 16, 1
	v_bfe_u32 v167, v78, 16, 1
	v_add3_u32 v78, v78, v167, s27
	v_add3_u32 v79, v79, v166, s27
	v_add3_u32 v132, v132, v165, s27
	v_add3_u32 v133, v133, v164, s27
	v_bfe_u32 v164, v74, 16, 1
	v_bfe_u32 v165, v75, 16, 1
	v_bfe_u32 v166, v130, 16, 1
	v_bfe_u32 v167, v131, 16, 1
	v_add3_u32 v131, v131, v167, s27
	v_add3_u32 v130, v130, v166, s27
	v_add3_u32 v75, v75, v165, s27
	v_add3_u32 v74, v74, v164, s27
	v_lshrrev_b32_e32 v74, 16, v74
	v_lshrrev_b32_e32 v75, 16, v75
	v_lshrrev_b32_e32 v130, 16, v130
	v_lshrrev_b32_e32 v131, 16, v131
	v_and_or_b32 v133, v133, s6, v131
	v_and_or_b32 v132, v132, s6, v130
	v_and_or_b32 v131, v79, s6, v75
	v_and_or_b32 v130, v78, s6, v74
	v_add_u32_e32 v74, 0xfffffbe0, v170
	ds_write_b128 v74, v[130:133]
	v_add_u32_e32 v74, 5, v162
	v_cmp_lt_i32_e32 vcc, 1, v74
	v_add_u32_e32 v74, 3, v162
	v_cmp_gt_u32_e64 s[0:1], s34, v74
	s_and_b64 vcc, vcc, s[0:1]
	v_cndmask_b32_e32 v132, 0, v129, vcc
	v_cndmask_b32_e32 v164, 0, v128, vcc
	v_cndmask_b32_e32 v78, 0, v127, vcc
	v_cndmask_b32_e32 v126, 0, v126, vcc
	v_pk_fma_f32 v[128:129], v[88:89], v[178:179], v[104:105]
	v_pk_fma_f32 v[166:167], v[68:69], v[184:185], v[84:85]
	v_lshlrev_b32_e32 v75, 16, v78
	v_lshlrev_b32_e32 v74, 16, v126
	v_and_b32_e32 v79, 0xffff0000, v78
	v_and_b32_e32 v78, 0xffff0000, v126
	v_pk_fma_f32 v[126:127], v[134:135], v[176:177], v[136:137]
	v_pk_fma_f32 v[128:129], v[92:93], v[144:145], v[128:129]
	v_lshlrev_b32_e32 v131, 16, v132
	v_lshlrev_b32_e32 v130, 16, v164
	v_and_b32_e32 v133, 0xffff0000, v132
	v_and_b32_e32 v132, 0xffff0000, v164
	v_pk_fma_f32 v[164:165], v[86:87], v[182:183], v[90:91]
	v_pk_fma_f32 v[166:167], v[72:73], v[188:189], v[166:167]
	v_pk_fma_f32 v[126:127], v[138:139], v[146:147], v[126:127]
	v_pk_fma_f32 v[128:129], v[96:97], v[70:71], v[128:129]
	v_pk_fma_f32 v[164:165], v[94:95], v[186:187], v[164:165]
	v_pk_fma_f32 v[166:167], v[76:77], v[148:149], v[166:167]
	v_pk_fma_f32 v[126:127], v[140:141], v[66:67], v[126:127]
	v_pk_fma_f32 v[128:129], v[100:101], v[78:79], v[128:129]
	v_pk_fma_f32 v[164:165], v[98:99], v[82:83], v[164:165]
	v_pk_fma_f32 v[166:167], v[80:81], v[132:133], v[166:167]
	v_pk_fma_f32 v[126:127], v[142:143], v[74:75], v[126:127]
	v_pk_fma_f32 v[164:165], v[102:103], v[130:131], v[164:165]
	v_bfe_u32 v168, v167, 16, 1
	v_bfe_u32 v169, v166, 16, 1
	v_bfe_u32 v171, v129, 16, 1
	v_bfe_u32 v172, v128, 16, 1
	v_add3_u32 v172, v128, v172, s27
	v_add3_u32 v171, v129, v171, s27
	v_add3_u32 v128, v166, v169, s27
	v_add3_u32 v129, v167, v168, s27
	v_bfe_u32 v166, v126, 16, 1
	v_bfe_u32 v167, v127, 16, 1
	v_bfe_u32 v168, v164, 16, 1
	v_bfe_u32 v169, v165, 16, 1
	v_add3_u32 v165, v165, v169, s27
	v_add3_u32 v164, v164, v168, s27
	v_add3_u32 v127, v127, v167, s27
	v_add3_u32 v126, v126, v166, s27
	v_lshrrev_b32_e32 v126, 16, v126
	v_lshrrev_b32_e32 v127, 16, v127
	v_lshrrev_b32_e32 v164, 16, v164
	v_lshrrev_b32_e32 v165, 16, v165
	v_and_or_b32 v129, v129, s6, v165
	v_and_or_b32 v128, v128, s6, v164
	v_and_or_b32 v127, v171, s6, v127
	v_and_or_b32 v126, v172, s6, v126
	v_add_u32_e32 v164, 0xfffffdf0, v170
	ds_write_b128 v164, v[126:129]
	v_add_u32_e32 v126, 6, v162
	v_cmp_lt_i32_e32 vcc, 1, v126
	v_cmp_ge_i32_e64 s[0:1], s34, v126
	s_and_b64 vcc, vcc, s[0:1]
	v_cndmask_b32_e32 v164, 0, v125, vcc
	v_cndmask_b32_e32 v165, 0, v124, vcc
	v_cndmask_b32_e32 v123, 0, v123, vcc
	v_cndmask_b32_e32 v122, 0, v122, vcc
	v_pk_fma_f32 v[124:125], v[88:89], v[144:145], v[104:105]
	v_pk_fma_f32 v[166:167], v[68:69], v[188:189], v[84:85]
	v_lshlrev_b32_e32 v127, 16, v123
	v_lshlrev_b32_e32 v126, 16, v122
	v_and_b32_e32 v129, 0xffff0000, v123
	v_and_b32_e32 v128, 0xffff0000, v122
	v_pk_fma_f32 v[122:123], v[134:135], v[146:147], v[136:137]
	v_pk_fma_f32 v[124:125], v[92:93], v[70:71], v[124:125]
	v_lshlrev_b32_e32 v145, 16, v164
	v_lshlrev_b32_e32 v144, 16, v165
	v_and_b32_e32 v147, 0xffff0000, v164
	v_and_b32_e32 v146, 0xffff0000, v165
	v_pk_fma_f32 v[164:165], v[86:87], v[186:187], v[90:91]
	v_pk_fma_f32 v[166:167], v[72:73], v[148:149], v[166:167]
	v_pk_fma_f32 v[122:123], v[138:139], v[66:67], v[122:123]
	v_pk_fma_f32 v[124:125], v[96:97], v[78:79], v[124:125]
	v_pk_fma_f32 v[164:165], v[94:95], v[82:83], v[164:165]
	v_pk_fma_f32 v[166:167], v[76:77], v[132:133], v[166:167]
	v_pk_fma_f32 v[122:123], v[140:141], v[74:75], v[122:123]
	v_pk_fma_f32 v[124:125], v[100:101], v[128:129], v[124:125]
	v_pk_fma_f32 v[164:165], v[98:99], v[130:131], v[164:165]
	v_pk_fma_f32 v[166:167], v[80:81], v[146:147], v[166:167]
	v_pk_fma_f32 v[122:123], v[142:143], v[126:127], v[122:123]
	v_pk_fma_f32 v[164:165], v[102:103], v[144:145], v[164:165]
	v_bfe_u32 v168, v167, 16, 1
	v_bfe_u32 v169, v166, 16, 1
	v_bfe_u32 v171, v125, 16, 1
	v_bfe_u32 v172, v124, 16, 1
	v_add3_u32 v172, v124, v172, s27
	v_add3_u32 v171, v125, v171, s27
	v_add3_u32 v124, v166, v169, s27
	v_add3_u32 v125, v167, v168, s27
	v_bfe_u32 v166, v122, 16, 1
	v_bfe_u32 v167, v123, 16, 1
	v_bfe_u32 v168, v164, 16, 1
	v_bfe_u32 v169, v165, 16, 1
	v_add3_u32 v165, v165, v169, s27
	v_add3_u32 v164, v164, v168, s27
	v_add3_u32 v123, v123, v167, s27
; #define LAS __attribute__((address_space(3)))
; __device__ __forceinline__ u32x4 pack8(const float (&f)[8]) { u32x4 o; o.x = pk2(f[0], f[1]); o.y = pk2(f[2], f[3]); o.z = pk2(f[4], f[5]); o.w = pk2(f[6], f[7]); return o; }
; __device__ __forceinline__ void lru_conv_tile(const Args& a, LAS bf16_t* cxb, int l, const Tile& T) {
;     ...
;     for (int i = 0; i < 11; ++i) {
;         const int tg = T.t0 + grp * 8 + i - 2;
;         u32x4 rv = raw[i]; if (!(tg >= 0 && tg < T.seqlen)) rv = (u32x4){0u, 0u, 0u, 0u};
; #pragma unroll
;         for (int e = 0; e < 8; ++e) { win[0][e] = win[1][e]; win[1][e] = win[2][e]; win[2][e] = win[3][e]; }
;         unpack8(rv, win[3]);
;         if (i >= 3) {
;             float o[8];
; #pragma unroll
;             for (int e = 0; e < 8; ++e) o[e] = bias[e] + w[0][e] * win[0][e] + w[1][e] * win[1][e] + w[2][e] * win[2][e] + w[3][e] * win[3][e];
;             *(LAS u32x4*)(cxb + (grp * 8 + i - 3) * CXS + c0) = pack8(o);
;         }
;     }
	v_add3_u32 v122, v122, v166, s27
	v_lshrrev_b32_e32 v122, 16, v122
	v_lshrrev_b32_e32 v123, 16, v123
	v_lshrrev_b32_e32 v164, 16, v164
	v_lshrrev_b32_e32 v165, 16, v165
	v_and_or_b32 v125, v125, s6, v165
	v_and_or_b32 v124, v124, s6, v164
	v_and_or_b32 v123, v171, s6, v123
	v_and_or_b32 v122, v172, s6, v122
	v_or_b32_e32 v163, 7, v163
	ds_write_b128 v170, v[122:125]
	v_add_u32_e32 v122, s35, v163
	v_cmp_lt_i32_e32 vcc, 1, v122
	v_add_u32_e32 v122, -2, v122
	v_cmp_gt_u32_e64 s[0:1], s34, v122
	s_and_b64 vcc, vcc, s[0:1]
	v_cndmask_b32_e32 v119, 0, v119, vcc
	v_cndmask_b32_e32 v118, 0, v118, vcc
	v_lshlrev_b32_e32 v123, 16, v119
	v_lshlrev_b32_e32 v122, 16, v118
	v_and_b32_e32 v125, 0xffff0000, v119
	v_and_b32_e32 v124, 0xffff0000, v118
	v_pk_fma_f32 v[70:71], v[88:89], v[70:71], v[104:105]
	v_pk_fma_f32 v[118:119], v[68:69], v[148:149], v[84:85]
	v_cndmask_b32_e32 v121, 0, v121, vcc
	v_cndmask_b32_e32 v120, 0, v120, vcc
	v_pk_fma_f32 v[66:67], v[134:135], v[66:67], v[136:137]
	v_pk_fma_f32 v[70:71], v[92:93], v[78:79], v[70:71]
	v_pk_fma_f32 v[82:83], v[86:87], v[82:83], v[90:91]
	v_pk_fma_f32 v[118:119], v[72:73], v[132:133], v[118:119]
	v_pk_fma_f32 v[66:67], v[138:139], v[74:75], v[66:67]
	v_pk_fma_f32 v[70:71], v[96:97], v[128:129], v[70:71]
	v_and_b32_e32 v167, 0xffff0000, v121
	v_and_b32_e32 v166, 0xffff0000, v120
	v_pk_fma_f32 v[82:83], v[94:95], v[130:131], v[82:83]
	v_pk_fma_f32 v[118:119], v[76:77], v[146:147], v[118:119]
	v_pk_fma_f32 v[66:67], v[140:141], v[126:127], v[66:67]
	v_pk_fma_f32 v[70:71], v[100:101], v[124:125], v[70:71]
	v_lshlrev_b32_e32 v165, 16, v121
	v_lshlrev_b32_e32 v164, 16, v120
	v_pk_fma_f32 v[82:83], v[98:99], v[144:145], v[82:83]
	v_pk_fma_f32 v[118:119], v[80:81], v[166:167], v[118:119]
	v_pk_fma_f32 v[66:67], v[142:143], v[122:123], v[66:67]
	v_pk_fma_f32 v[82:83], v[102:103], v[164:165], v[82:83]
	v_bfe_u32 v120, v119, 16, 1
	v_bfe_u32 v148, v71, 16, 1
	v_add3_u32 v71, v71, v148, s27
	v_add3_u32 v119, v119, v120, s27
	v_bfe_u32 v120, v66, 16, 1
	v_bfe_u32 v148, v82, 16, 1
	v_bfe_u32 v121, v118, 16, 1
	v_bfe_u32 v149, v70, 16, 1
	v_add3_u32 v82, v82, v148, s27
	v_add3_u32 v66, v66, v120, s27
	v_add3_u32 v70, v70, v149, s27
	v_add3_u32 v118, v118, v121, s27
	v_bfe_u32 v121, v67, 16, 1
	v_bfe_u32 v149, v83, 16, 1
	v_lshrrev_b32_e32 v66, 16, v66
	v_lshrrev_b32_e32 v82, 16, v82
	v_add3_u32 v83, v83, v149, s27
	v_add3_u32 v67, v67, v121, s27
	v_and_or_b32 v120, v118, s6, v82
	v_and_or_b32 v118, v70, s6, v66
	v_mul_lo_u32 v66, v163, s55
	v_lshrrev_b32_e32 v67, 16, v67
	v_lshrrev_b32_e32 v83, 16, v83
	v_add_u32_e32 v66, 0, v66
	s_movk_i32 s0, 0xf9d0
	v_and_or_b32 v121, v119, s6, v83
	v_and_or_b32 v119, v71, s6, v67
	v_add3_u32 v66, v66, v206, s0
	ds_write_b128 v66, v[118:121]
	v_add_u32_e32 v66, 8, v162
	v_cmp_lt_i32_e32 vcc, 1, v66
	v_cmp_ge_i32_e64 s[0:1], s34, v66
	s_and_b64 vcc, vcc, s[0:1]
	v_cndmask_b32_e32 v117, 0, v117, vcc
	v_cndmask_b32_e32 v116, 0, v116, vcc
	v_cndmask_b32_e32 v70, 0, v115, vcc
	v_cndmask_b32_e32 v82, 0, v114, vcc
	v_lshlrev_b32_e32 v67, 16, v70
	v_lshlrev_b32_e32 v66, 16, v82
	v_and_b32_e32 v71, 0xffff0000, v70
	v_and_b32_e32 v70, 0xffff0000, v82
	v_pk_fma_f32 v[78:79], v[88:89], v[78:79], v[104:105]
	v_lshlrev_b32_e32 v83, 16, v117
	v_lshlrev_b32_e32 v82, 16, v116
	v_and_b32_e32 v119, 0xffff0000, v117
	v_and_b32_e32 v118, 0xffff0000, v116
	v_pk_fma_f32 v[116:117], v[68:69], v[132:133], v[84:85]
	v_pk_fma_f32 v[74:75], v[134:135], v[74:75], v[136:137]
	v_pk_fma_f32 v[78:79], v[92:93], v[128:129], v[78:79]
	v_pk_fma_f32 v[114:115], v[86:87], v[130:131], v[90:91]
	v_pk_fma_f32 v[116:117], v[72:73], v[146:147], v[116:117]
	v_pk_fma_f32 v[74:75], v[138:139], v[126:127], v[74:75]
	v_pk_fma_f32 v[78:79], v[96:97], v[124:125], v[78:79]
	v_pk_fma_f32 v[114:115], v[94:95], v[144:145], v[114:115]
	v_pk_fma_f32 v[116:117], v[76:77], v[166:167], v[116:117]
	v_pk_fma_f32 v[74:75], v[140:141], v[122:123], v[74:75]
	v_pk_fma_f32 v[78:79], v[100:101], v[70:71], v[78:79]
	v_pk_fma_f32 v[114:115], v[98:99], v[164:165], v[114:115]
	v_pk_fma_f32 v[116:117], v[80:81], v[118:119], v[116:117]
	v_pk_fma_f32 v[74:75], v[142:143], v[66:67], v[74:75]
	v_pk_fma_f32 v[114:115], v[102:103], v[82:83], v[114:115]
	v_bfe_u32 v120, v117, 16, 1
	v_bfe_u32 v130, v79, 16, 1
	v_add3_u32 v79, v79, v130, s27
	v_add3_u32 v117, v117, v120, s27
	v_bfe_u32 v120, v74, 16, 1
	v_bfe_u32 v130, v114, 16, 1
	v_bfe_u32 v121, v116, 16, 1
	v_bfe_u32 v131, v78, 16, 1
	v_add3_u32 v114, v114, v130, s27
	v_add3_u32 v74, v74, v120, s27
	v_add3_u32 v78, v78, v131, s27
	v_add3_u32 v116, v116, v121, s27
	v_lshrrev_b32_e32 v74, 16, v74
	v_lshrrev_b32_e32 v114, 16, v114
	v_and_or_b32 v116, v116, s6, v114
	v_and_or_b32 v114, v78, s6, v74
	v_add_u32_e32 v74, 9, v162
	v_bfe_u32 v121, v75, 16, 1
	v_bfe_u32 v131, v115, 16, 1
	v_cmp_lt_i32_e32 vcc, 1, v74
	v_add_u32_e32 v74, 7, v162
	v_add3_u32 v115, v115, v131, s27
	v_add3_u32 v75, v75, v121, s27
	v_cmp_gt_u32_e64 s[0:1], s34, v74
	v_lshrrev_b32_e32 v75, 16, v75
	v_lshrrev_b32_e32 v115, 16, v115
	s_and_b64 vcc, vcc, s[0:1]
	v_and_or_b32 v117, v117, s6, v115
	v_and_or_b32 v115, v79, s6, v75
	v_cndmask_b32_e32 v78, 0, v111, vcc
	v_cndmask_b32_e32 v110, 0, v110, vcc
	ds_write_b128 v170, v[114:117] offset:1056
	v_cndmask_b32_e32 v116, 0, v113, vcc
	v_cndmask_b32_e32 v120, 0, v112, vcc
	v_lshlrev_b32_e32 v75, 16, v78
	v_lshlrev_b32_e32 v74, 16, v110
	v_and_b32_e32 v79, 0xffff0000, v78
	v_and_b32_e32 v78, 0xffff0000, v110
	v_pk_fma_f32 v[110:111], v[134:135], v[126:127], v[136:137]
	v_pk_fma_f32 v[112:113], v[88:89], v[128:129], v[104:105]
	v_pk_fma_f32 v[126:127], v[68:69], v[146:147], v[84:85]
; #define LAS __attribute__((address_space(3)))
; __device__ __forceinline__ u32x4 pack8(const float (&f)[8]) { u32x4 o; o.x = pk2(f[0], f[1]); o.y = pk2(f[2], f[3]); o.z = pk2(f[4], f[5]); o.w = pk2(f[6], f[7]); return o; }
; __device__ __forceinline__ void lru_conv_tile(const Args& a, LAS bf16_t* cxb, int l, const Tile& T) {
;     ...
;     for (int i = 0; i < 11; ++i) {
;         const int tg = T.t0 + grp * 8 + i - 2;
;         u32x4 rv = raw[i]; if (!(tg >= 0 && tg < T.seqlen)) rv = (u32x4){0u, 0u, 0u, 0u};
; #pragma unroll
;         for (int e = 0; e < 8; ++e) { win[0][e] = win[1][e]; win[1][e] = win[2][e]; win[2][e] = win[3][e]; }
;         unpack8(rv, win[3]);
;         if (i >= 3) {
;             float o[8];
; #pragma unroll
;             for (int e = 0; e < 8; ++e) o[e] = bias[e] + w[0][e] * win[0][e] + w[1][e] * win[1][e] + w[2][e] * win[2][e] + w[3][e] * win[3][e];
;             *(LAS u32x4*)(cxb + (grp * 8 + i - 3) * CXS + c0) = pack8(o);
;         }
;     }
; template <int MODE>
; __device__ __forceinline__ void lru_unit(const Args& a, LAS unsigned char* lds, int l, int tt) {
;     ...
;     for (int nt = 0; nt < 2; ++nt) { prm0[nt][2] = -8.0f * log1pf(__expf(-prm0[nt][2])); prm1[nt][2] = -8.0f * log1pf(__expf(-prm1[nt][2])); }
	v_pk_fma_f32 v[112:113], v[92:93], v[124:125], v[112:113]
	v_lshlrev_b32_e32 v115, 16, v116
	v_lshlrev_b32_e32 v114, 16, v120
	v_and_b32_e32 v117, 0xffff0000, v116
	v_and_b32_e32 v116, 0xffff0000, v120
	v_pk_fma_f32 v[120:121], v[86:87], v[144:145], v[90:91]
	v_pk_fma_f32 v[126:127], v[72:73], v[166:167], v[126:127]
	v_pk_fma_f32 v[110:111], v[138:139], v[122:123], v[110:111]
	v_pk_fma_f32 v[112:113], v[96:97], v[70:71], v[112:113]
	v_pk_fma_f32 v[120:121], v[94:95], v[164:165], v[120:121]
	v_pk_fma_f32 v[126:127], v[76:77], v[118:119], v[126:127]
	v_pk_fma_f32 v[110:111], v[140:141], v[66:67], v[110:111]
	v_pk_fma_f32 v[112:113], v[100:101], v[78:79], v[112:113]
	v_pk_fma_f32 v[120:121], v[98:99], v[82:83], v[120:121]
	v_pk_fma_f32 v[126:127], v[80:81], v[116:117], v[126:127]
	v_pk_fma_f32 v[110:111], v[142:143], v[74:75], v[110:111]
	v_pk_fma_f32 v[120:121], v[102:103], v[114:115], v[120:121]
	v_bfe_u32 v128, v127, 16, 1
	v_bfe_u32 v129, v126, 16, 1
	v_bfe_u32 v130, v113, 16, 1
	v_bfe_u32 v131, v112, 16, 1
	v_add3_u32 v131, v112, v131, s27
	v_add3_u32 v130, v113, v130, s27
	v_add3_u32 v112, v126, v129, s27
	v_add3_u32 v113, v127, v128, s27
	v_bfe_u32 v126, v110, 16, 1
	v_bfe_u32 v127, v111, 16, 1
	v_bfe_u32 v128, v120, 16, 1
	v_bfe_u32 v129, v121, 16, 1
	v_add3_u32 v121, v121, v129, s27
	v_add3_u32 v120, v120, v128, s27
	v_add3_u32 v111, v111, v127, s27
	v_add3_u32 v110, v110, v126, s27
	v_lshrrev_b32_e32 v110, 16, v110
	v_lshrrev_b32_e32 v111, 16, v111
	v_lshrrev_b32_e32 v120, 16, v120
	v_lshrrev_b32_e32 v121, 16, v121
	v_and_or_b32 v113, v113, s6, v121
	v_and_or_b32 v112, v112, s6, v120
	v_and_or_b32 v111, v130, s6, v111
	v_and_or_b32 v110, v131, s6, v110
	ds_write_b128 v170, v[110:113] offset:1584
	v_add_u32_e32 v110, 10, v162
	v_cmp_lt_i32_e32 vcc, 1, v110
	v_cmp_ge_i32_e64 s[0:1], s34, v110
	s_and_b64 vcc, vcc, s[0:1]
	v_cndmask_b32_e32 v113, 0, v108, vcc
	v_cndmask_b32_e32 v108, 0, v107, vcc
	v_cndmask_b32_e32 v110, 0, v106, vcc
	v_cndmask_b32_e32 v112, 0, v109, vcc
	v_and_b32_e32 v107, 0xffff0000, v108
	v_and_b32_e32 v106, 0xffff0000, v110
	v_lshlrev_b32_e32 v109, 16, v108
	v_lshlrev_b32_e32 v108, 16, v110
	v_pk_fma_f32 v[110:111], v[134:135], v[122:123], v[136:137]
	v_pk_fma_f32 v[86:87], v[86:87], v[164:165], v[90:91]
	v_pk_fma_f32 v[66:67], v[138:139], v[66:67], v[110:111]
	v_pk_fma_f32 v[68:69], v[68:69], v[166:167], v[84:85]
	v_pk_fma_f32 v[66:67], v[140:141], v[74:75], v[66:67]
	v_pk_fma_f32 v[74:75], v[88:89], v[124:125], v[104:105]
	v_pk_fma_f32 v[82:83], v[94:95], v[82:83], v[86:87]
	v_pk_fma_f32 v[70:71], v[92:93], v[70:71], v[74:75]
	v_pk_fma_f32 v[68:69], v[72:73], v[118:119], v[68:69]
	v_pk_fma_f32 v[70:71], v[96:97], v[78:79], v[70:71]
	v_and_b32_e32 v75, 0xffff0000, v112
	v_pk_fma_f32 v[70:71], v[100:101], v[106:107], v[70:71]
	v_and_b32_e32 v74, 0xffff0000, v113
	v_lshlrev_b32_e32 v79, 16, v112
	v_lshlrev_b32_e32 v78, 16, v113
	v_pk_fma_f32 v[82:83], v[98:99], v[114:115], v[82:83]
	v_pk_fma_f32 v[68:69], v[76:77], v[116:117], v[68:69]
	v_pk_fma_f32 v[78:79], v[102:103], v[78:79], v[82:83]
	v_pk_fma_f32 v[68:69], v[80:81], v[74:75], v[68:69]
	v_bfe_u32 v74, v71, 16, 1
	v_pk_fma_f32 v[66:67], v[142:143], v[108:109], v[66:67]
	v_bfe_u32 v72, v69, 16, 1
	v_add3_u32 v71, v71, v74, s27
	v_bfe_u32 v74, v78, 16, 1
	v_bfe_u32 v73, v68, 16, 1
	v_add3_u32 v69, v69, v72, s27
	v_bfe_u32 v72, v66, 16, 1
	v_add3_u32 v74, v78, v74, s27
	v_add3_u32 v68, v68, v73, s27
	v_add3_u32 v66, v66, v72, s27
	v_lshrrev_b32_e32 v72, 16, v74
	v_bfe_u32 v75, v70, 16, 1
	v_and_or_b32 v68, v68, s6, v72
	v_mul_f32_e32 v72, 0xbfb8aa3b, v161
	v_add3_u32 v70, v70, v75, s27
	v_bfe_u32 v73, v67, 16, 1
	v_bfe_u32 v75, v79, 16, 1
	v_exp_f32_e32 v72, v72
	v_add3_u32 v75, v79, v75, s27
	v_add3_u32 v67, v67, v73, s27
	v_lshrrev_b32_e32 v66, 16, v66
	v_lshrrev_b32_e32 v67, 16, v67
	v_lshrrev_b32_e32 v73, 16, v75
	v_and_or_b32 v69, v69, s6, v73
	v_and_or_b32 v67, v71, s6, v67
	v_and_or_b32 v66, v70, s6, v66
	ds_write_b128 v170, v[66:69] offset:2112
	v_add_f32_e32 v68, 1.0, v72
	v_add_f32_e32 v66, -1.0, v68
	v_sub_f32_e32 v67, v66, v68
	v_add_f32_e32 v67, 1.0, v67
	v_sub_f32_e32 v66, v72, v66
	v_add_f32_e32 v69, v66, v67
	v_frexp_mant_f32_e32 v70, v68
	v_cvt_f64_f32_e32 v[66:67], v68
	s_mov_b32 s28, 0x3f2aaaab
	v_frexp_exp_i32_f64_e32 v66, v[66:67]
	v_cmp_gt_f32_e32 vcc, s28, v70
	s_mov_b32 s4, 0x3f317218
	v_mov_b32_e32 v79, 0x3ecc95a3
	v_subbrev_co_u32_e32 v66, vcc, 0, v66, vcc
	v_sub_u32_e32 v67, 0, v66
	v_ldexp_f32 v68, v68, v67
	v_ldexp_f32 v67, v69, v67
	v_add_f32_e32 v69, -1.0, v68
	v_add_f32_e32 v73, 1.0, v68
	v_add_f32_e32 v70, 1.0, v69
	v_add_f32_e32 v74, -1.0, v73
	v_sub_f32_e32 v70, v68, v70
	v_sub_f32_e32 v68, v68, v74
	v_add_f32_e32 v70, v67, v70
	v_add_f32_e32 v67, v67, v68
	v_add_f32_e32 v68, v73, v67
	v_rcp_f32_e32 v74, v68
	v_add_f32_e32 v71, v69, v70
	v_sub_f32_e32 v69, v71, v69
	v_sub_f32_e32 v69, v70, v69
	v_sub_f32_e32 v70, v68, v73
	v_sub_f32_e32 v67, v67, v70
	v_mul_f32_e32 v70, v71, v74
	v_mul_f32_e32 v73, v68, v70
	v_fma_f32 v75, v70, v68, -v73
	v_fmac_f32_e32 v75, v70, v67
	v_add_f32_e32 v76, v73, v75
	v_sub_f32_e32 v77, v71, v76
	v_sub_f32_e32 v71, v71, v77
	v_sub_f32_e32 v73, v76, v73
	v_sub_f32_e32 v71, v71, v76
	v_add_f32_e32 v69, v69, v71
	v_sub_f32_e32 v71, v73, v75
	v_add_f32_e32 v69, v71, v69
	v_add_f32_e32 v71, v77, v69
	v_mul_f32_e32 v73, v74, v71
	v_mul_f32_e32 v75, v68, v73
	v_fma_f32 v68, v73, v68, -v75
	v_fmac_f32_e32 v68, v73, v67
	v_sub_f32_e32 v67, v77, v71
	v_add_f32_e32 v67, v69, v67
	v_add_f32_e32 v69, v75, v68
	v_sub_f32_e32 v76, v71, v69
	v_sub_f32_e32 v71, v71, v76
	v_sub_f32_e32 v75, v69, v75
; #define LAS __attribute__((address_space(3)))
; __device__ __forceinline__ int opaque_tid() { int t = threadIdx.x; asm volatile("" : "+v"(t)); return t; }
; template <int DIR, int MODE>
; __device__ __forceinline__ void lru_pass(const Args& a, const LAS bf16_t* cxb, LAS bf16_t* gyb, const LAS float* carry, const bf16x8 (&Bw)[2][2][2], const float (&prm)[2][3], int l, int tt, float (&hf)[8][2][4]) {
;     const int tid = opaque_tid(), lane = tid & 63, w = __builtin_amdgcn_readfirstlane(tid >> 6), h = w & 3, nh = w >> 2, fr = lane & 15, fq = lane >> 4;
;     float* SUM = (float*)(a.ws + WS_SUM);
;     float ba[2], bxv[2], k8[2], C[2], At[2]; int cc[2];
; #pragma unroll
;     for (int nt = 0; nt < 2; ++nt) {
;         const int c = 64 * h + 32 * nh + 16 * nt + fr; cc[nt] = c;
;         ba[nt] = prm[nt][0]; bxv[nt] = prm[nt][1]; k8[nt] = prm[nt][2];
;         C[nt] = MODE == 1 ? carry[DIR * 256 + c] : 0.f; At[nt] = 1.f;
;     }
; #pragma unroll
;     for (int mi = 0; mi < 8; ++mi) {
;         const int m = DIR ? 7 - mi : mi;
;         bf16x8 Af[2];
; #pragma unroll
;         for (int ks = 0; ks < 2; ++ks) Af[ks] = *(const LAS bf16x8*)(cxb + (m * 16 + fr) * CXS + 64 * h + 32 * ks + 8 * fq);
; template <int MODE>
; __device__ __forceinline__ void lru_unit(const Args& a, LAS unsigned char* lds, int l, int tt) {
;     ...
;     for (int nt = 0; nt < 2; ++nt) { prm0[nt][2] = -8.0f * log1pf(__expf(-prm0[nt][2])); prm1[nt][2] = -8.0f * log1pf(__expf(-prm1[nt][2])); }
;     __syncthreads();
	v_sub_f32_e32 v69, v71, v69
	v_add_f32_e32 v67, v67, v69
	v_sub_f32_e32 v68, v75, v68
	v_cvt_f32_i32_e32 v66, v66
	v_add_f32_e32 v67, v68, v67
	v_add_f32_e32 v68, v70, v73
	v_add_f32_e32 v67, v76, v67
	v_sub_f32_e32 v69, v68, v70
	v_mul_f32_e32 v67, v74, v67
	v_sub_f32_e32 v69, v73, v69
	v_add_f32_e32 v67, v69, v67
	v_mul_f32_e32 v73, 0x3f317218, v66
	v_add_f32_e32 v69, v68, v67
	v_fma_f32 v74, v66, s4, -v73
	v_mul_f32_e32 v70, v69, v69
	v_fmac_f32_e32 v74, 0xb102e308, v66
	v_sub_f32_e32 v66, v69, v68
	v_fmamk_f32 v71, v70, 0x3e9b6dac, v79
	v_sub_f32_e32 v66, v67, v66
	v_add_f32_e32 v67, v73, v74
	v_fmaak_f32 v71, v70, v71, 0x3f2aaada
	v_sub_f32_e32 v68, v67, v73
	v_ldexp_f32 v73, v69, 1
	v_mul_f32_e32 v69, v69, v70
	v_mul_f32_e32 v69, v69, v71
	v_add_f32_e32 v70, v73, v69
	v_sub_f32_e32 v71, v70, v73
	v_ldexp_f32 v66, v66, 1
	v_sub_f32_e32 v69, v69, v71
	v_add_f32_e32 v66, v66, v69
	v_add_f32_e32 v69, v70, v66
	v_sub_f32_e32 v70, v69, v70
	v_sub_f32_e32 v66, v66, v70
	v_add_f32_e32 v70, v67, v69
	v_sub_f32_e32 v71, v70, v67
	v_sub_f32_e32 v73, v70, v71
	v_sub_f32_e32 v68, v74, v68
	v_sub_f32_e32 v67, v67, v73
	v_sub_f32_e32 v69, v69, v71
	v_add_f32_e32 v67, v69, v67
	v_add_f32_e32 v69, v68, v66
	v_sub_f32_e32 v71, v69, v68
	v_sub_f32_e32 v73, v69, v71
	v_sub_f32_e32 v68, v68, v73
	v_sub_f32_e32 v66, v66, v71
	v_add_f32_e32 v67, v69, v67
	v_add_f32_e32 v66, v66, v68
	v_add_f32_e32 v68, v70, v67
	v_sub_f32_e32 v69, v68, v70
	v_sub_f32_e32 v67, v67, v69
	v_add_f32_e32 v66, v66, v67
	s_mov_b32 s5, 0x7f800000
	v_add_f32_e32 v66, v68, v66
	v_cmp_neq_f32_e32 vcc, s5, v72
	v_mov_b32_e32 v80, 0x7f800000
	v_mov_b32_e32 v81, 0x7fc00000
	v_cndmask_b32_e32 v66, v80, v66, vcc
	v_cmp_ngt_f32_e32 vcc, -1.0, v72
	v_mov_b32_e32 v82, 0xff800000
	s_mov_b32 s29, 0x33800000
	v_cndmask_b32_e32 v66, v81, v66, vcc
	v_cmp_neq_f32_e32 vcc, -1.0, v72
	v_mul_f32_e32 v67, 0xbfb8aa3b, v160
	v_exp_f32_e32 v116, v67
	v_cndmask_b32_e32 v66, v82, v66, vcc
	v_cmp_lt_f32_e64 vcc, |v72|, s29
	s_waitcnt lgkmcnt(0)
	v_add_f32_e32 v118, 1.0, v116
	v_cndmask_b32_e32 v66, v66, v72, vcc
	v_mul_f32_e32 v75, 0xc138aa3b, v66
	v_mul_f32_e32 v66, 0xbfb8aa3b, v159
	v_exp_f32_e32 v70, v66
	v_frexp_mant_f32_e32 v66, v118
	v_cmp_gt_f32_e32 vcc, s28, v66
	s_barrier
	s_mov_b32 s98, 0xbfb8aa3b
	v_mul_f32_e32 v154, 0xbfb8aa3b, v154
	v_mul_f32_e32 v155, 0xbfb8aa3b, v155
	v_mul_f32_e32 v156, 0xbfb8aa3b, v156
	v_mul_f32_e32 v157, 0xbfb8aa3b, v157
	v_mul_f32_e32 v150, 0xbfb8aa3b, v150
	v_mul_f32_e32 v151, 0xbfb8aa3b, v151
	v_mul_f32_e32 v152, 0xbfb8aa3b, v152
	v_mul_f32_e32 v153, 0xbfb8aa3b, v153
	v_add_f32_e32 v68, 1.0, v70
	v_add_f32_e32 v66, -1.0, v68
	v_sub_f32_e32 v67, v66, v68
	v_add_f32_e32 v67, 1.0, v67
	v_sub_f32_e32 v66, v70, v66
	v_add_f32_e32 v69, v66, v67
	v_frexp_mant_f32_e32 v71, v68
	v_cvt_f64_f32_e32 v[66:67], v68
	v_frexp_exp_i32_f64_e32 v66, v[66:67]
	v_cmp_gt_f32_e64 s[0:1], s28, v71
	v_and_b32_e32 v85, 64, v227
	s_nop 0
	v_subbrev_co_u32_e64 v66, s[0:1], 0, v66, s[0:1]
	v_sub_u32_e32 v67, 0, v66
	v_ldexp_f32 v68, v68, v67
	v_ldexp_f32 v67, v69, v67
	v_add_f32_e32 v69, -1.0, v68
	v_add_f32_e32 v73, 1.0, v68
	v_add_f32_e32 v71, 1.0, v69
	v_add_f32_e32 v74, -1.0, v73
	v_sub_f32_e32 v71, v68, v71
	v_sub_f32_e32 v68, v68, v74
	v_add_f32_e32 v71, v67, v71
	v_add_f32_e32 v67, v67, v68
	v_add_f32_e32 v68, v73, v67
	v_rcp_f32_e32 v74, v68
	v_add_f32_e32 v72, v69, v71
	v_sub_f32_e32 v69, v72, v69
	v_sub_f32_e32 v69, v71, v69
	v_sub_f32_e32 v71, v68, v73
	v_sub_f32_e32 v67, v67, v71
	v_mul_f32_e32 v71, v72, v74
	v_mul_f32_e32 v73, v68, v71
	v_fma_f32 v76, v71, v68, -v73
	v_fmac_f32_e32 v76, v71, v67
	v_add_f32_e32 v77, v73, v76
	v_sub_f32_e32 v78, v72, v77
	v_sub_f32_e32 v72, v72, v78
	v_sub_f32_e32 v73, v77, v73
	v_sub_f32_e32 v72, v72, v77
	v_add_f32_e32 v69, v69, v72
	v_sub_f32_e32 v72, v73, v76
	v_add_f32_e32 v69, v72, v69
	v_add_f32_e32 v72, v78, v69
	v_mul_f32_e32 v73, v74, v72
	v_mul_f32_e32 v76, v68, v73
	v_fma_f32 v68, v73, v68, -v76
	v_fmac_f32_e32 v68, v73, v67
	v_sub_f32_e32 v67, v78, v72
	v_add_f32_e32 v67, v69, v67
	v_add_f32_e32 v69, v76, v68
	v_sub_f32_e32 v77, v72, v69
	v_sub_f32_e32 v72, v72, v77
	v_sub_f32_e32 v76, v69, v76
	v_sub_f32_e32 v69, v72, v69
	v_add_f32_e32 v67, v67, v69
	v_sub_f32_e32 v68, v76, v68
	v_cvt_f32_i32_e32 v66, v66
	v_add_f32_e32 v67, v68, v67
	v_add_f32_e32 v68, v71, v73
	v_add_f32_e32 v67, v77, v67
	v_sub_f32_e32 v69, v68, v71
	v_mul_f32_e32 v67, v74, v67
	v_sub_f32_e32 v69, v73, v69
	v_add_f32_e32 v67, v69, v67
	v_mul_f32_e32 v73, 0x3f317218, v66
	v_add_f32_e32 v69, v68, v67
	v_fma_f32 v74, v66, s4, -v73
	v_mul_f32_e32 v71, v69, v69
	v_fmac_f32_e32 v74, 0xb102e308, v66
	v_sub_f32_e32 v66, v69, v68
	v_fmamk_f32 v72, v71, 0x3e9b6dac, v79
	v_sub_f32_e32 v66, v67, v66
	v_add_f32_e32 v67, v73, v74
	v_fmaak_f32 v72, v71, v72, 0x3f2aaada
	v_sub_f32_e32 v68, v67, v73
	v_ldexp_f32 v73, v69, 1
	v_mul_f32_e32 v69, v69, v71
	v_mul_f32_e32 v69, v69, v72
	v_add_f32_e32 v71, v73, v69
	v_sub_f32_e32 v72, v71, v73
	v_ldexp_f32 v66, v66, 1
	v_sub_f32_e32 v69, v69, v72
	v_add_f32_e32 v66, v66, v69
	v_add_f32_e32 v69, v71, v66
	v_sub_f32_e32 v71, v69, v71
	v_sub_f32_e32 v66, v66, v71
	v_add_f32_e32 v71, v67, v69
	v_sub_f32_e32 v72, v71, v67
	v_sub_f32_e32 v73, v71, v72
	v_sub_f32_e32 v68, v74, v68
	v_sub_f32_e32 v67, v67, v73
	v_sub_f32_e32 v69, v69, v72
	v_add_f32_e32 v67, v69, v67
	v_add_f32_e32 v69, v68, v66
	v_sub_f32_e32 v72, v69, v68
	v_sub_f32_e32 v73, v69, v72
	v_sub_f32_e32 v68, v68, v73
	v_sub_f32_e32 v66, v66, v72
	v_add_f32_e32 v67, v69, v67
	v_add_f32_e32 v66, v66, v68
	v_add_f32_e32 v68, v71, v67
	v_sub_f32_e32 v69, v68, v71
	v_sub_f32_e32 v67, v67, v69
	v_add_f32_e32 v66, v66, v67
	v_add_f32_e32 v66, v68, v66
	v_cmp_neq_f32_e64 s[0:1], s5, v70
	s_nop 1
	v_cndmask_b32_e64 v66, v80, v66, s[0:1]
	v_cmp_ngt_f32_e64 s[0:1], -1.0, v70
	s_nop 1
	v_cndmask_b32_e64 v71, v81, v66, s[0:1]
	v_mov_b32_e32 v66, v0
	s_nop 0
	v_readfirstlane_b32 s4, v66
	s_bfe_u32 s5, s4, 0x20006
	v_and_b32_e32 v84, 15, v66
	v_bfe_u32 v100, v66, 4, 2
	s_lshl_b32 s0, s5, 7
	s_add_i32 s0, s0, 0
	v_lshlrev_b32_e32 v66, 4, v100
	v_mul_u32_u24_e32 v67, 0x210, v84
	v_add3_u32 v127, s0, v66, v67
	ds_read_b128 v[66:69], v127
	v_cmp_neq_f32_e64 s[0:1], -1.0, v70
	v_cmp_eq_u32_e64 s[36:37], 0, v100
	s_nop 0
	v_cndmask_b32_e64 v71, v82, v71, s[0:1]
	v_cmp_lt_f32_e64 s[0:1], |v70|, s29
	s_nop 1
	v_cndmask_b32_e64 v70, v71, v70, s[0:1]
	v_mul_f32_e32 v104, 0xc138aa3b, v70
	v_mul_f32_e32 v70, 0xbfb8aa3b, v158
	v_exp_f32_e32 v117, v70
	ds_read_b128 v[70:73], v127 offset:64
	s_waitcnt lgkmcnt(1)
; template <int DIR, int MODE>
; __device__ __forceinline__ void lru_pass(const Args& a, const LAS bf16_t* cxb, LAS bf16_t* gyb, const LAS float* carry, const bf16x8 (&Bw)[2][2][2], const float (&prm)[2][3], int l, int tt, float (&hf)[8][2][4]) {
;     ...
;     for (int mi = 0; mi < 8; ++mi) {
;         const int m = DIR ? 7 - mi : mi;
;         bf16x8 Af[2];
; #pragma unroll
;         for (int ks = 0; ks < 2; ++ks) Af[ks] = *(const LAS bf16x8*)(cxb + (m * 16 + fr) * CXS + 64 * h + 32 * ks + 8 * fq);
; #pragma unroll
;         for (int nt = 0; nt < 2; ++nt) {
;             f32x4 pr = (f32x4){0.f, 0.f, 0.f, 0.f}, pi = (f32x4){0.f, 0.f, 0.f, 0.f};
; #pragma unroll
;             for (int ks = 0; ks < 2; ++ks) { pr = __builtin_amdgcn_mfma_f32_16x16x32_bf16(Af[ks], Bw[0][nt][ks], pr, 0, 0, 0); pi = __builtin_amdgcn_mfma_f32_16x16x32_bf16(Af[ks], Bw[1][nt][ks], pi, 0, 0, 0); }
;             float av[4], bv[4];
; #pragma unroll
;             for (int reg = 0; reg < 4; ++reg) {
;                 const int tok = m * 16 + 4 * fq + reg;
;                 const float x = bf2f(cxb[tok * CXS + cc[nt]]);
;                 const float r = fsig(pr[reg] + ba[nt]), ig = fsig(pi[reg] + bxv[nt]);
;                 const float aa = __expf(k8[nt] * r);
;                 av[reg] = aa; bv[reg] = __builtin_amdgcn_sqrtf(fmaxf(1.0f - aa * aa, 0.f)) * ig * x;
;             }
;             float cum[4], hl[4];
;             if (DIR == 0) { cum[0] = av[0]; hl[0] = bv[0];
; #pragma unroll
;                 for (int reg = 1; reg < 4; ++reg) { cum[reg] = cum[reg - 1] * av[reg]; hl[reg] = av[reg] * hl[reg - 1] + bv[reg]; } }
;             else { cum[3] = av[3]; hl[3] = bv[3];
; #pragma unroll
;     ...
;             const float A4 = DIR ? cum[0] : cum[3], H4 = DIR ? hl[0] : hl[3];
;             float Aq[4], Hq[4];
; #pragma unroll
;             for (int q = 0; q < 4; ++q) { Aq[q] = __shfl(A4, fr + 16 * q); Hq[q] = __shfl(H4, fr + 16 * q); }
;             float hin;
;             if (DIR == 0) { const float s0 = C[nt], s1 = Aq[0] * s0 + Hq[0], s2 = Aq[1] * s1 + Hq[1], s3 = Aq[2] * s2 + Hq[2]; C[nt] = Aq[3] * s3 + Hq[3]; hin = fq == 0 ? s0 : (fq == 1 ? s1 : (fq == 2 ? s2 : s3)); }
;             else { const float s3 = C[nt], s2 = Aq[3] * s3 + Hq[3], s1 = Aq[2] * s2 + Hq[2], s0 = Aq[1] * s1 + Hq[1]; C[nt] = Aq[0] * s0 + Hq[0]; hin = fq == 3 ? s3 : (fq == 2 ? s2 : (fq == 1 ? s1 : s0)); }
	v_mfma_f32_16x16x32_bf16 v[76:79], v[66:69], v[54:57], 0
	s_ashr_i32 s1, s4, 3
	s_lshl_b32 s0, s5, 6
	s_andn2_b32 s1, s1, 31
	s_waitcnt lgkmcnt(0)
	v_mfma_f32_16x16x32_bf16 v[76:79], v[70:73], v[50:53], v[76:79]
	s_add_i32 s0, s0, s1
	v_or_b32_e32 v74, s0, v84
	v_or_b32_e32 v84, v85, v84
	s_nop 4
	v_fma_f32 v76, v76, s98, v157
	s_nop 0
	v_exp_f32_e32 v76, v76
	v_mfma_f32_16x16x32_bf16 v[80:83], v[66:69], v[62:65], 0
	v_fma_f32 v77, v77, s98, v157
	s_nop 0
	v_add_f32_e32 v76, 1.0, v76
	v_rcp_f32_e32 v76, v76
	v_mfma_f32_16x16x32_bf16 v[80:83], v[70:73], v[58:61], v[80:83]
	v_exp_f32_e32 v77, v77
	v_fma_f32 v78, v78, s98, v157
	v_mul_f32_e32 v76, v75, v76
	s_nop 0
	v_add_f32_e32 v77, 1.0, v77
	s_nop 2
	v_fma_f32 v80, v80, s98, v156
	s_nop 0
	v_exp_f32_e32 v76, v76
	v_rcp_f32_e32 v77, v77
	s_nop 0
	v_fma_f32 v79, v79, s98, v157
	v_exp_f32_e32 v80, v80
	v_exp_f32_e32 v78, v78
	s_nop 0
	v_exp_f32_e32 v79, v79
	v_lshlrev_b32_e32 v102, 2, v84
	v_lshlrev_b32_e32 v84, 1, v74
	v_mul_u32_u24_e32 v85, 0x840, v100
	v_add3_u32 v106, 0, v84, v85
	v_fma_f32 v84, -v76, v76, 1.0
	v_mul_f32_e32 v77, v75, v77
	v_add_f32_e32 v80, 1.0, v80
	v_max_f32_e32 v84, 0, v84
	v_fma_f32 v81, v81, s98, v156
	s_nop 0
	v_add_f32_e32 v78, 1.0, v78
	v_rcp_f32_e32 v80, v80
	v_sqrt_f32_e32 v84, v84
	s_nop 0
	v_exp_f32_e32 v77, v77
	v_rcp_f32_e32 v78, v78
	v_add_f32_e32 v79, 1.0, v79
	v_exp_f32_e32 v81, v81
	v_rcp_f32_e32 v79, v79
	v_mul_f32_e32 v80, v80, v84
	v_fma_f32 v84, -v77, v77, 1.0
	v_mul_f32_e32 v78, v75, v78
	v_add_f32_e32 v81, 1.0, v81
	v_max_f32_e32 v84, 0, v84
	v_fma_f32 v82, v82, s98, v156
	s_nop 0
	v_mul_f32_e32 v79, v75, v79
	v_rcp_f32_e32 v81, v81
	v_sqrt_f32_e32 v84, v84
	s_nop 0
	v_exp_f32_e32 v78, v78
	v_fma_f32 v83, v83, s98, v156
	s_nop 0
	v_exp_f32_e32 v82, v82
	s_nop 0
	v_exp_f32_e32 v79, v79
	v_exp_f32_e32 v83, v83
	ds_read_u16 v85, v106
	ds_read_u16 v86, v106 offset:32
	ds_read_u16 v87, v106 offset:528
	ds_read_u16 v88, v106 offset:1056
	ds_read_u16 v89, v106 offset:1584
	ds_read_u16 v90, v106 offset:1616
	ds_read_u16 v91, v106 offset:1088
	ds_read_u16 v92, v106 offset:560
	s_waitcnt lgkmcnt(7)
	v_lshlrev_b32_e32 v85, 16, v85
	v_mul_f32_e32 v81, v81, v84
	v_fma_f32 v84, -v78, v78, 1.0
	v_mul_f32_e32 v80, v80, v85
	s_waitcnt lgkmcnt(5)
	v_lshlrev_b32_e32 v85, 16, v87
	v_add_f32_e32 v82, 1.0, v82
	v_max_f32_e32 v84, 0, v84
	v_fma_f32 v87, -v79, v79, 1.0
	v_rcp_f32_e32 v82, v82
	v_sqrt_f32_e32 v84, v84
	v_add_f32_e32 v83, 1.0, v83
	v_max_f32_e32 v87, 0, v87
	v_rcp_f32_e32 v83, v83
	v_sqrt_f32_e32 v87, v87
	v_mul_f32_e32 v76, v77, v76
	v_mul_f32_e32 v77, v77, v80
	v_fmac_f32_e32 v77, v81, v85
	s_waitcnt lgkmcnt(4)
	v_lshlrev_b32_e32 v88, 16, v88
	v_mul_f32_e32 v82, v82, v84
	v_mul_f32_e32 v77, v78, v77
	v_mul_f32_e32 v87, v83, v87
	v_fmac_f32_e32 v77, v82, v88
	v_mfma_f32_16x16x32_bf16 v[80:83], v[66:69], v[38:41], 0
	s_waitcnt lgkmcnt(3)
	v_lshlrev_b32_e32 v84, 16, v89
	v_mul_f32_e32 v77, v79, v77
	v_fmac_f32_e32 v77, v87, v84
	v_mfma_f32_16x16x32_bf16 v[82:85], v[70:73], v[34:37], v[80:83]
	v_mul_f32_e32 v76, v78, v76
	v_mul_f32_e32 v88, v79, v76
	ds_bpermute_b32 v119, v102, v77
	v_mfma_f32_16x16x32_bf16 v[66:69], v[66:69], v[46:49], 0
	ds_bpermute_b32 v120, v102, v77 offset:64
	s_nop 2
	v_fma_f32 v79, v82, s98, v155
	s_nop 0
	v_exp_f32_e32 v79, v79
	v_mfma_f32_16x16x32_bf16 v[66:69], v[70:73], v[42:45], v[66:69]
	v_lshlrev_b32_e32 v72, 16, v86
	ds_bpermute_b32 v121, v102, v77 offset:128
	v_add_f32_e32 v70, 1.0, v79
	v_rcp_f32_e32 v70, v70
	ds_bpermute_b32 v122, v102, v77 offset:192
	s_nop 2
	v_fma_f32 v66, v66, s98, v154
	s_nop 0
	v_mul_f32_e32 v70, v104, v70
	s_nop 0
	v_exp_f32_e32 v70, v70
	v_exp_f32_e32 v66, v66
	v_fma_f32 v67, v67, s98, v154
	s_nop 0
	v_fma_f32 v71, -v70, v70, 1.0
	v_add_f32_e32 v66, 1.0, v66
	v_max_f32_e32 v71, 0, v71
	v_rcp_f32_e32 v66, v66
	v_sqrt_f32_e32 v71, v71
	v_exp_f32_e32 v67, v67
	v_fma_f32 v68, v68, s98, v154
	v_fma_f32 v69, v69, s98, v154
	v_mul_f32_e32 v66, v66, v71
	v_mul_f32_e32 v66, v66, v72
	v_fma_f32 v72, v84, s98, v155
	s_nop 0
	v_exp_f32_e32 v72, v72
	v_fma_f32 v71, v83, s98, v155
	s_nop 0
	v_exp_f32_e32 v71, v71
	v_add_f32_e32 v72, 1.0, v72
	v_rcp_f32_e32 v72, v72
	v_add_f32_e32 v67, 1.0, v67
	v_add_f32_e32 v71, 1.0, v71
	v_rcp_f32_e32 v71, v71
	v_mul_f32_e32 v72, v104, v72
	s_nop 0
	v_exp_f32_e32 v79, v72
	v_fma_f32 v72, v85, s98, v155
	s_nop 0
	v_exp_f32_e32 v72, v72
	v_mul_f32_e32 v71, v104, v71
	s_nop 0
	v_exp_f32_e32 v71, v71
	v_add_f32_e32 v72, 1.0, v72
	v_rcp_f32_e32 v72, v72
	v_rcp_f32_e32 v67, v67
	v_fma_f32 v73, -v71, v71, 1.0
	v_max_f32_e32 v73, 0, v73
	v_sqrt_f32_e32 v73, v73
	v_mul_f32_e32 v72, v104, v72
	s_nop 0
	s_nop 0
	s_nop 0
	v_exp_f32_e32 v81, v72
	v_exp_f32_e32 v68, v68
	v_exp_f32_e32 v69, v69
	v_mul_f32_e32 v67, v67, v73
	v_fma_f32 v73, -v79, v79, 1.0
	v_max_f32_e32 v73, 0, v73
	v_sqrt_f32_e32 v72, v73
	v_fma_f32 v73, -v81, v81, 1.0
	v_add_f32_e32 v68, 1.0, v68
	v_add_f32_e32 v69, 1.0, v69
	v_max_f32_e32 v73, 0, v73
	v_rcp_f32_e32 v68, v68
	v_rcp_f32_e32 v69, v69
	v_sqrt_f32_e32 v73, v73
	s_waitcnt lgkmcnt(4)
	v_lshlrev_b32_e32 v77, 16, v92
	v_mul_f32_e32 v66, v71, v66
	v_mul_f32_e32 v68, v68, v72
	v_mul_f32_e32 v69, v69, v73
	v_mul_f32_e32 v85, v71, v70
	ds_read_b128 v[70:73], v127 offset:8448
	v_fmac_f32_e32 v66, v67, v77
	v_lshlrev_b32_e32 v83, 16, v91
	v_mul_f32_e32 v66, v79, v66
	v_fmac_f32_e32 v66, v68, v83
	v_lshlrev_b32_e32 v84, 16, v90
	v_mul_f32_e32 v67, v79, v85
	v_mul_f32_e32 v79, v81, v66
	v_mul_f32_e32 v77, v81, v67
	v_fmac_f32_e32 v79, v69, v84
	ds_read_b128 v[66:69], v127 offset:8512
	s_waitcnt lgkmcnt(1)
; template <int DIR, int MODE>
; __device__ __forceinline__ void lru_pass(const Args& a, const LAS bf16_t* cxb, LAS bf16_t* gyb, const LAS float* carry, const bf16x8 (&Bw)[2][2][2], const float (&prm)[2][3], int l, int tt, float (&hf)[8][2][4]) {
;     ...
;     for (int mi = 0; mi < 8; ++mi) {
;         const int m = DIR ? 7 - mi : mi;
;         bf16x8 Af[2];
; #pragma unroll
;         for (int ks = 0; ks < 2; ++ks) Af[ks] = *(const LAS bf16x8*)(cxb + (m * 16 + fr) * CXS + 64 * h + 32 * ks + 8 * fq);
; #pragma unroll
;         for (int nt = 0; nt < 2; ++nt) {
;             f32x4 pr = (f32x4){0.f, 0.f, 0.f, 0.f}, pi = (f32x4){0.f, 0.f, 0.f, 0.f};
; #pragma unroll
;             for (int ks = 0; ks < 2; ++ks) { pr = __builtin_amdgcn_mfma_f32_16x16x32_bf16(Af[ks], Bw[0][nt][ks], pr, 0, 0, 0); pi = __builtin_amdgcn_mfma_f32_16x16x32_bf16(Af[ks], Bw[1][nt][ks], pi, 0, 0, 0); }
;             float av[4], bv[4];
; #pragma unroll
;             for (int reg = 0; reg < 4; ++reg) {
;                 const int tok = m * 16 + 4 * fq + reg;
;                 const float x = bf2f(cxb[tok * CXS + cc[nt]]);
;                 const float r = fsig(pr[reg] + ba[nt]), ig = fsig(pi[reg] + bxv[nt]);
;                 const float aa = __expf(k8[nt] * r);
;                 av[reg] = aa; bv[reg] = __builtin_amdgcn_sqrtf(fmaxf(1.0f - aa * aa, 0.f)) * ig * x;
;             }
;             float cum[4], hl[4];
;             if (DIR == 0) { cum[0] = av[0]; hl[0] = bv[0];
; #pragma unroll
;                 for (int reg = 1; reg < 4; ++reg) { cum[reg] = cum[reg - 1] * av[reg]; hl[reg] = av[reg] * hl[reg - 1] + bv[reg]; } }
;             else { cum[3] = av[3]; hl[3] = bv[3];
; #pragma unroll
;     ...
;             const float A4 = DIR ? cum[0] : cum[3], H4 = DIR ? hl[0] : hl[3];
;             float Aq[4], Hq[4];
; #pragma unroll
;             for (int q = 0; q < 4; ++q) { Aq[q] = __shfl(A4, fr + 16 * q); Hq[q] = __shfl(H4, fr + 16 * q); }
;             float hin;
;             if (DIR == 0) { const float s0 = C[nt], s1 = Aq[0] * s0 + Hq[0], s2 = Aq[1] * s1 + Hq[1], s3 = Aq[2] * s2 + Hq[2]; C[nt] = Aq[3] * s3 + Hq[3]; hin = fq == 0 ? s0 : (fq == 1 ? s1 : (fq == 2 ? s2 : s3)); }
;             else { const float s3 = C[nt], s2 = Aq[3] * s3 + Hq[3], s1 = Aq[2] * s2 + Hq[2], s0 = Aq[1] * s1 + Hq[1]; C[nt] = Aq[0] * s0 + Hq[0]; hin = fq == 3 ? s3 : (fq == 2 ? s2 : (fq == 1 ? s1 : s0)); }
	v_mfma_f32_16x16x32_bf16 v[90:93], v[70:73], v[54:57], 0
	ds_bpermute_b32 v76, v102, v88
	ds_bpermute_b32 v78, v102, v88 offset:64
	ds_bpermute_b32 v80, v102, v88 offset:128
	s_waitcnt lgkmcnt(3)
	v_mfma_f32_16x16x32_bf16 v[90:93], v[66:69], v[50:53], v[90:93]
	ds_bpermute_b32 v82, v102, v88 offset:192
	ds_bpermute_b32 v86, v102, v77
	ds_bpermute_b32 v84, v102, v77 offset:64
	s_nop 4
	v_fma_f32 v81, v90, s98, v157
	s_nop 0
	v_exp_f32_e32 v81, v81
	v_mfma_f32_16x16x32_bf16 v[94:97], v[70:73], v[62:65], 0
	ds_bpermute_b32 v88, v102, v77 offset:128
	ds_bpermute_b32 v90, v102, v77 offset:192
	v_add_f32_e32 v77, 1.0, v81
	v_mfma_f32_16x16x32_bf16 v[94:97], v[66:69], v[58:61], v[94:97]
	v_rcp_f32_e32 v77, v77
	ds_bpermute_b32 v123, v102, v79
	ds_bpermute_b32 v124, v102, v79 offset:64
	ds_bpermute_b32 v125, v102, v79 offset:128
	v_mul_f32_e32 v77, v75, v77
	s_nop 2
	v_fma_f32 v81, v94, s98, v156
	s_nop 0
	s_nop 0
	v_exp_f32_e32 v81, v81
	v_exp_f32_e32 v77, v77
	ds_bpermute_b32 v126, v102, v79 offset:192
	ds_read_u16 v83, v106 offset:8448
	ds_read_u16 v85, v106 offset:8976
	ds_read_u16 v87, v106 offset:9504
	ds_read_u16 v89, v106 offset:10032
	ds_read_u16 v98, v106 offset:10064
	ds_read_u16 v99, v106 offset:9536
	ds_read_u16 v101, v106 offset:9008
	ds_read_u16 v103, v106 offset:8480
	v_add_f32_e32 v79, 1.0, v81
	v_fma_f32 v81, -v77, v77, 1.0
	v_max_f32_e32 v81, 0, v81
	v_rcp_f32_e32 v79, v79
	v_sqrt_f32_e32 v81, v81
	s_waitcnt lgkmcnt(7)
	v_lshlrev_b32_e32 v83, 16, v83
	v_fma_f32 v93, v93, s98, v157
	s_nop 0
	v_mul_f32_e32 v79, v79, v81
	v_fma_f32 v81, v91, s98, v157
	v_fma_f32 v91, v95, s98, v156
	s_nop 0
	s_nop 0
	v_exp_f32_e32 v81, v81
	v_exp_f32_e32 v91, v91
	v_mul_f32_e32 v79, v79, v83
	v_exp_f32_e32 v93, v93
	v_add_f32_e32 v81, 1.0, v81
	v_add_f32_e32 v83, 1.0, v91
	v_fma_f32 v91, v92, s98, v157
	v_rcp_f32_e32 v81, v81
	s_nop 0
	v_exp_f32_e32 v91, v91
	v_add_f32_e32 v93, 1.0, v93
	v_mul_f32_e32 v81, v75, v81
	s_nop 0
	v_add_f32_e32 v91, 1.0, v91
	v_exp_f32_e32 v81, v81
	v_rcp_f32_e32 v91, v91
	v_rcp_f32_e32 v93, v93
	v_fma_f32 v94, v96, s98, v156
	v_fma_f32 v92, -v81, v81, 1.0
	v_mul_f32_e32 v91, v75, v91
	v_max_f32_e32 v92, 0, v92
	s_nop 0
	s_nop 0
	v_rcp_f32_e32 v83, v83
	v_sqrt_f32_e32 v92, v92
	v_exp_f32_e32 v94, v94
	v_exp_f32_e32 v91, v91
	v_fma_f32 v95, v97, s98, v156
	v_mul_f32_e32 v93, v75, v93
	s_nop 0
	s_nop 0
	v_exp_f32_e32 v95, v95
	v_exp_f32_e32 v96, v93
	v_mul_f32_e32 v83, v83, v92
	v_add_f32_e32 v92, 1.0, v94
	v_fma_f32 v94, -v91, v91, 1.0
	v_max_f32_e32 v94, 0, v94
	v_sqrt_f32_e32 v93, v94
	v_add_f32_e32 v94, 1.0, v95
	v_fma_f32 v95, -v96, v96, 1.0
	v_rcp_f32_e32 v92, v92
	v_max_f32_e32 v95, 0, v95
	v_rcp_f32_e32 v94, v94
	v_sqrt_f32_e32 v95, v95
	s_waitcnt lgkmcnt(6)
	v_lshlrev_b32_e32 v85, 16, v85
	v_mul_f32_e32 v79, v81, v79
	v_fmac_f32_e32 v79, v83, v85
	s_waitcnt lgkmcnt(5)
	v_lshlrev_b32_e32 v87, 16, v87
	v_mul_f32_e32 v92, v92, v93
	v_mul_f32_e32 v79, v91, v79
	v_mul_f32_e32 v97, v94, v95
	v_fmac_f32_e32 v79, v92, v87
	v_mfma_f32_16x16x32_bf16 v[92:95], v[70:73], v[38:41], 0
	v_mul_f32_e32 v77, v81, v77
	s_waitcnt lgkmcnt(4)
	v_lshlrev_b32_e32 v89, 16, v89
	v_mul_f32_e32 v85, v96, v79
	v_mfma_f32_16x16x32_bf16 v[92:95], v[66:69], v[34:37], v[92:95]
	v_fmac_f32_e32 v85, v97, v89
	ds_bpermute_b32 v128, v102, v85
	ds_bpermute_b32 v129, v102, v85 offset:64
	v_mfma_f32_16x16x32_bf16 v[70:73], v[70:73], v[46:49], 0
	ds_bpermute_b32 v130, v102, v85 offset:128
	s_nop 2
	v_fma_f32 v81, v92, s98, v155
	s_nop 0
	v_exp_f32_e32 v87, v81
	v_mfma_f32_16x16x32_bf16 v[66:69], v[66:69], v[42:45], v[70:73]
	ds_bpermute_b32 v131, v102, v85 offset:192
	s_waitcnt lgkmcnt(5)
	v_lshlrev_b32_e32 v85, 16, v101
	v_mul_f32_e32 v77, v91, v77
	v_add_f32_e32 v70, 1.0, v87
	v_rcp_f32_e32 v70, v70
	s_nop 1
	v_fma_f32 v66, v66, s98, v154
	s_nop 0
	v_exp_f32_e32 v66, v66
	v_mul_f32_e32 v70, v104, v70
	s_nop 0
	v_exp_f32_e32 v70, v70
	v_add_f32_e32 v66, 1.0, v66
	v_rcp_f32_e32 v66, v66
	s_waitcnt lgkmcnt(4)
	v_lshlrev_b32_e32 v72, 16, v103
	v_fma_f32 v71, -v70, v70, 1.0
	v_max_f32_e32 v71, 0, v71
	v_sqrt_f32_e32 v71, v71
	v_fma_f32 v67, v67, s98, v154
	s_nop 0
	v_exp_f32_e32 v67, v67
	v_mul_f32_e32 v66, v66, v71
	v_mul_f32_e32 v66, v66, v72
	v_fma_f32 v72, v94, s98, v155
	s_nop 0
	v_exp_f32_e32 v72, v72
	v_fma_f32 v71, v93, s98, v155
	s_nop 0
	v_exp_f32_e32 v71, v71
	v_add_f32_e32 v72, 1.0, v72
	v_rcp_f32_e32 v72, v72
	v_add_f32_e32 v67, 1.0, v67
	v_add_f32_e32 v71, 1.0, v71
	v_rcp_f32_e32 v71, v71
	v_mul_f32_e32 v72, v104, v72
	s_nop 0
	v_exp_f32_e32 v87, v72
	v_fma_f32 v72, v95, s98, v155
	s_nop 0
	v_exp_f32_e32 v72, v72
	v_mul_f32_e32 v71, v104, v71
	s_nop 0
	v_exp_f32_e32 v71, v71
	v_add_f32_e32 v72, 1.0, v72
	v_rcp_f32_e32 v72, v72
	v_rcp_f32_e32 v67, v67
	v_fma_f32 v73, -v71, v71, 1.0
	v_max_f32_e32 v73, 0, v73
	v_sqrt_f32_e32 v73, v73
	v_mul_f32_e32 v72, v104, v72
	v_fma_f32 v68, v68, s98, v154
	v_fma_f32 v69, v69, s98, v154
	s_nop 0
	s_nop 0
	s_nop 0
	v_exp_f32_e32 v89, v72
	v_exp_f32_e32 v68, v68
	v_exp_f32_e32 v69, v69
	v_mul_f32_e32 v67, v67, v73
	v_fma_f32 v73, -v87, v87, 1.0
	v_max_f32_e32 v73, 0, v73
	v_sqrt_f32_e32 v72, v73
	v_fma_f32 v73, -v89, v89, 1.0
	v_add_f32_e32 v68, 1.0, v68
	v_add_f32_e32 v69, 1.0, v69
	v_max_f32_e32 v73, 0, v73
	v_rcp_f32_e32 v68, v68
	v_rcp_f32_e32 v69, v69
	v_sqrt_f32_e32 v73, v73
	v_mul_f32_e32 v66, v71, v66
	v_mul_f32_e32 v68, v68, v72
	v_mul_f32_e32 v93, v71, v70
	v_mul_f32_e32 v69, v69, v73
	ds_read_b128 v[70:73], v127 offset:16896
	v_fmac_f32_e32 v66, v67, v85
	v_lshlrev_b32_e32 v91, 16, v99
	v_mul_f32_e32 v66, v87, v66
	v_fmac_f32_e32 v66, v68, v91
	v_lshlrev_b32_e32 v92, 16, v98
	v_mul_f32_e32 v67, v87, v93
	v_mul_f32_e32 v101, v89, v66
	v_mul_f32_e32 v91, v89, v67
	v_fmac_f32_e32 v101, v69, v92
	ds_read_b128 v[66:69], v127 offset:16960
	s_waitcnt lgkmcnt(1)
; template <int DIR, int MODE>
; __device__ __forceinline__ void lru_pass(const Args& a, const LAS bf16_t* cxb, LAS bf16_t* gyb, const LAS float* carry, const bf16x8 (&Bw)[2][2][2], const float (&prm)[2][3], int l, int tt, float (&hf)[8][2][4]) {
;     ...
;     for (int mi = 0; mi < 8; ++mi) {
;         const int m = DIR ? 7 - mi : mi;
;         bf16x8 Af[2];
; #pragma unroll
;         for (int ks = 0; ks < 2; ++ks) Af[ks] = *(const LAS bf16x8*)(cxb + (m * 16 + fr) * CXS + 64 * h + 32 * ks + 8 * fq);
; #pragma unroll
;         for (int nt = 0; nt < 2; ++nt) {
;             f32x4 pr = (f32x4){0.f, 0.f, 0.f, 0.f}, pi = (f32x4){0.f, 0.f, 0.f, 0.f};
; #pragma unroll
;             for (int ks = 0; ks < 2; ++ks) { pr = __builtin_amdgcn_mfma_f32_16x16x32_bf16(Af[ks], Bw[0][nt][ks], pr, 0, 0, 0); pi = __builtin_amdgcn_mfma_f32_16x16x32_bf16(Af[ks], Bw[1][nt][ks], pi, 0, 0, 0); }
;             float av[4], bv[4];
; #pragma unroll
;             for (int reg = 0; reg < 4; ++reg) {
;                 const int tok = m * 16 + 4 * fq + reg;
;                 const float x = bf2f(cxb[tok * CXS + cc[nt]]);
;                 const float r = fsig(pr[reg] + ba[nt]), ig = fsig(pi[reg] + bxv[nt]);
;                 const float aa = __expf(k8[nt] * r);
;                 av[reg] = aa; bv[reg] = __builtin_amdgcn_sqrtf(fmaxf(1.0f - aa * aa, 0.f)) * ig * x;
;             }
;             float cum[4], hl[4];
;             if (DIR == 0) { cum[0] = av[0]; hl[0] = bv[0];
; #pragma unroll
;                 for (int reg = 1; reg < 4; ++reg) { cum[reg] = cum[reg - 1] * av[reg]; hl[reg] = av[reg] * hl[reg - 1] + bv[reg]; } }
;             else { cum[3] = av[3]; hl[3] = bv[3];
; #pragma unroll
;     ...
;             const float A4 = DIR ? cum[0] : cum[3], H4 = DIR ? hl[0] : hl[3];
;             float Aq[4], Hq[4];
; #pragma unroll
;             for (int q = 0; q < 4; ++q) { Aq[q] = __shfl(A4, fr + 16 * q); Hq[q] = __shfl(H4, fr + 16 * q); }
;             float hin;
;             if (DIR == 0) { const float s0 = C[nt], s1 = Aq[0] * s0 + Hq[0], s2 = Aq[1] * s1 + Hq[1], s3 = Aq[2] * s2 + Hq[2]; C[nt] = Aq[3] * s3 + Hq[3]; hin = fq == 0 ? s0 : (fq == 1 ? s1 : (fq == 2 ? s2 : s3)); }
;             else { const float s3 = C[nt], s2 = Aq[3] * s3 + Hq[3], s1 = Aq[2] * s2 + Hq[2], s0 = Aq[1] * s1 + Hq[1]; C[nt] = Aq[0] * s0 + Hq[0]; hin = fq == 3 ? s3 : (fq == 2 ? s2 : (fq == 1 ? s1 : s0)); }
	v_mfma_f32_16x16x32_bf16 v[92:95], v[70:73], v[54:57], 0
	v_mul_f32_e32 v83, v96, v77
	ds_bpermute_b32 v132, v102, v101
	ds_bpermute_b32 v133, v102, v101 offset:64
	s_waitcnt lgkmcnt(2)
	v_mfma_f32_16x16x32_bf16 v[92:95], v[66:69], v[50:53], v[92:95]
	ds_bpermute_b32 v134, v102, v101 offset:128
	ds_bpermute_b32 v135, v102, v101 offset:192
	ds_read_u16 v103, v106 offset:16896
	ds_read_u16 v105, v106 offset:17424
	ds_read_u16 v107, v106 offset:17952
	ds_read_u16 v108, v106 offset:18480
	ds_read_u16 v109, v106 offset:18512
	ds_read_u16 v110, v106 offset:17984
	ds_read_u16 v111, v106 offset:17456
	ds_read_u16 v112, v106 offset:16928
	v_fma_f32 v92, v92, s98, v157
	s_nop 0
	v_exp_f32_e32 v92, v92
	v_mfma_f32_16x16x32_bf16 v[96:99], v[70:73], v[62:65], 0
	v_fma_f32 v93, v93, s98, v157
	s_nop 0
	v_add_f32_e32 v92, 1.0, v92
	v_rcp_f32_e32 v92, v92
	v_mfma_f32_16x16x32_bf16 v[96:99], v[66:69], v[58:61], v[96:99]
	v_exp_f32_e32 v93, v93
	v_fma_f32 v94, v94, s98, v157
	v_mul_f32_e32 v92, v75, v92
	s_nop 0
	v_add_f32_e32 v93, 1.0, v93
	s_nop 2
	v_fma_f32 v96, v96, s98, v156
	s_nop 0
	v_exp_f32_e32 v92, v92
	v_rcp_f32_e32 v93, v93
	s_nop 0
	v_fma_f32 v95, v95, s98, v157
	v_exp_f32_e32 v96, v96
	v_exp_f32_e32 v94, v94
	s_nop 0
	v_exp_f32_e32 v95, v95
	v_fma_f32 v101, -v92, v92, 1.0
	v_mul_f32_e32 v93, v75, v93
	v_add_f32_e32 v96, 1.0, v96
	v_max_f32_e32 v101, 0, v101
	v_fma_f32 v97, v97, s98, v156
	s_nop 0
	v_add_f32_e32 v94, 1.0, v94
	v_rcp_f32_e32 v96, v96
	v_sqrt_f32_e32 v101, v101
	s_nop 0
	v_exp_f32_e32 v93, v93
	v_rcp_f32_e32 v94, v94
	v_add_f32_e32 v95, 1.0, v95
	v_exp_f32_e32 v97, v97
	v_rcp_f32_e32 v95, v95
	v_mul_f32_e32 v96, v96, v101
	v_fma_f32 v101, -v93, v93, 1.0
	v_mul_f32_e32 v94, v75, v94
	v_add_f32_e32 v97, 1.0, v97
	v_max_f32_e32 v101, 0, v101
	v_fma_f32 v98, v98, s98, v156
	s_nop 0
	v_mul_f32_e32 v95, v75, v95
	v_rcp_f32_e32 v97, v97
	v_sqrt_f32_e32 v101, v101
	s_nop 0
	v_exp_f32_e32 v94, v94
	v_fma_f32 v99, v99, s98, v156
	s_nop 0
	v_exp_f32_e32 v98, v98
	s_nop 0
	v_exp_f32_e32 v95, v95
	v_exp_f32_e32 v99, v99
	s_waitcnt lgkmcnt(7)
	v_lshlrev_b32_e32 v103, 16, v103
	v_mul_f32_e32 v97, v97, v101
	v_fma_f32 v101, -v94, v94, 1.0
	v_mul_f32_e32 v96, v96, v103
	s_waitcnt lgkmcnt(6)
	v_lshlrev_b32_e32 v103, 16, v105
	v_add_f32_e32 v98, 1.0, v98
	v_max_f32_e32 v101, 0, v101
	v_fma_f32 v105, -v95, v95, 1.0
	v_rcp_f32_e32 v98, v98
	v_sqrt_f32_e32 v101, v101
	v_add_f32_e32 v99, 1.0, v99
	v_max_f32_e32 v105, 0, v105
	v_rcp_f32_e32 v99, v99
	v_sqrt_f32_e32 v105, v105
	v_mul_f32_e32 v92, v93, v92
	v_mul_f32_e32 v93, v93, v96
	v_fmac_f32_e32 v93, v97, v103
	s_waitcnt lgkmcnt(5)
	v_lshlrev_b32_e32 v107, 16, v107
	v_mul_f32_e32 v98, v98, v101
	v_mul_f32_e32 v93, v94, v93
	v_mul_f32_e32 v105, v99, v105
	v_fmac_f32_e32 v93, v98, v107
	v_mfma_f32_16x16x32_bf16 v[96:99], v[70:73], v[38:41], 0
	v_mul_f32_e32 v107, v95, v93
	v_mul_f32_e32 v92, v94, v92
	v_mul_f32_e32 v103, v95, v92
	v_mfma_f32_16x16x32_bf16 v[96:99], v[66:69], v[34:37], v[96:99]
	ds_bpermute_b32 v92, v102, v103
	ds_bpermute_b32 v94, v102, v103 offset:64
	s_waitcnt lgkmcnt(6)
	v_lshlrev_b32_e32 v101, 16, v108
	v_mfma_f32_16x16x32_bf16 v[70:73], v[70:73], v[46:49], 0
	v_fmac_f32_e32 v107, v105, v101
	s_nop 1
	v_fma_f32 v93, v96, s98, v155
	s_nop 0
	v_exp_f32_e32 v95, v93
	v_mfma_f32_16x16x32_bf16 v[66:69], v[66:69], v[42:45], v[70:73]
	s_waitcnt lgkmcnt(3)
	v_lshlrev_b32_e32 v96, 16, v111
	ds_bpermute_b32 v93, v102, v103 offset:128
	v_lshlrev_b32_e32 v101, 16, v109
	v_add_f32_e32 v70, 1.0, v95
	v_rcp_f32_e32 v70, v70
	s_nop 1
	v_fma_f32 v66, v66, s98, v154
	s_nop 0
	v_exp_f32_e32 v66, v66
	v_mul_f32_e32 v70, v104, v70
	s_nop 0
	v_exp_f32_e32 v70, v70
	v_add_f32_e32 v66, 1.0, v66
	v_rcp_f32_e32 v66, v66
	s_waitcnt lgkmcnt(3)
	v_lshlrev_b32_e32 v72, 16, v112
	v_fma_f32 v71, -v70, v70, 1.0
	v_max_f32_e32 v71, 0, v71
	v_sqrt_f32_e32 v71, v71
	v_fma_f32 v67, v67, s98, v154
	s_nop 0
	v_exp_f32_e32 v67, v67
	v_mul_f32_e32 v66, v66, v71
	v_mul_f32_e32 v66, v66, v72
	v_fma_f32 v72, v98, s98, v155
	s_nop 0
	v_exp_f32_e32 v72, v72
	v_fma_f32 v71, v97, s98, v155
	s_nop 0
	v_exp_f32_e32 v71, v71
	v_add_f32_e32 v72, 1.0, v72
	v_rcp_f32_e32 v72, v72
	v_add_f32_e32 v67, 1.0, v67
	v_add_f32_e32 v71, 1.0, v71
	v_rcp_f32_e32 v71, v71
	v_mul_f32_e32 v72, v104, v72
	s_nop 0
	v_exp_f32_e32 v97, v72
	v_fma_f32 v72, v99, s98, v155
	s_nop 0
	v_exp_f32_e32 v72, v72
	v_mul_f32_e32 v71, v104, v71
	s_nop 0
	v_exp_f32_e32 v71, v71
	v_add_f32_e32 v72, 1.0, v72
	v_rcp_f32_e32 v72, v72
	v_rcp_f32_e32 v67, v67
	v_fma_f32 v73, -v71, v71, 1.0
	v_max_f32_e32 v73, 0, v73
	v_sqrt_f32_e32 v73, v73
	v_mul_f32_e32 v72, v104, v72
	v_fma_f32 v68, v68, s98, v154
	v_fma_f32 v69, v69, s98, v154
	s_nop 0
	s_nop 0
	s_nop 0
	v_exp_f32_e32 v98, v72
	v_exp_f32_e32 v68, v68
	v_exp_f32_e32 v69, v69
	v_mul_f32_e32 v67, v67, v73
	v_fma_f32 v73, -v97, v97, 1.0
	v_max_f32_e32 v73, 0, v73
	v_sqrt_f32_e32 v72, v73
	v_fma_f32 v73, -v98, v98, 1.0
	v_add_f32_e32 v68, 1.0, v68
	v_add_f32_e32 v69, 1.0, v69
	v_max_f32_e32 v73, 0, v73
	v_rcp_f32_e32 v68, v68
	v_rcp_f32_e32 v69, v69
	v_sqrt_f32_e32 v73, v73
	v_mul_f32_e32 v66, v71, v66
	ds_bpermute_b32 v95, v102, v103 offset:192
	v_mul_f32_e32 v68, v68, v72
	v_mul_f32_e32 v69, v69, v73
	v_mul_f32_e32 v103, v71, v70
	ds_read_b128 v[70:73], v127 offset:25344
	v_fmac_f32_e32 v66, v67, v96
	v_lshlrev_b32_e32 v99, 16, v110
	v_mul_f32_e32 v66, v97, v66
	v_fmac_f32_e32 v66, v68, v99
	v_mul_f32_e32 v67, v97, v103
	v_mul_f32_e32 v103, v98, v66
	v_mul_f32_e32 v97, v98, v67
	v_fmac_f32_e32 v103, v69, v101
	ds_read_b128 v[66:69], v127 offset:25408
	s_waitcnt lgkmcnt(1)
; template <int DIR, int MODE>
; __device__ __forceinline__ void lru_pass(const Args& a, const LAS bf16_t* cxb, LAS bf16_t* gyb, const LAS float* carry, const bf16x8 (&Bw)[2][2][2], const float (&prm)[2][3], int l, int tt, float (&hf)[8][2][4]) {
;     ...
;     for (int mi = 0; mi < 8; ++mi) {
;         const int m = DIR ? 7 - mi : mi;
;         bf16x8 Af[2];
; #pragma unroll
;         for (int ks = 0; ks < 2; ++ks) Af[ks] = *(const LAS bf16x8*)(cxb + (m * 16 + fr) * CXS + 64 * h + 32 * ks + 8 * fq);
; #pragma unroll
;         for (int nt = 0; nt < 2; ++nt) {
;             f32x4 pr = (f32x4){0.f, 0.f, 0.f, 0.f}, pi = (f32x4){0.f, 0.f, 0.f, 0.f};
; #pragma unroll
;             for (int ks = 0; ks < 2; ++ks) { pr = __builtin_amdgcn_mfma_f32_16x16x32_bf16(Af[ks], Bw[0][nt][ks], pr, 0, 0, 0); pi = __builtin_amdgcn_mfma_f32_16x16x32_bf16(Af[ks], Bw[1][nt][ks], pi, 0, 0, 0); }
;             float av[4], bv[4];
; #pragma unroll
;             for (int reg = 0; reg < 4; ++reg) {
;                 const int tok = m * 16 + 4 * fq + reg;
;                 const float x = bf2f(cxb[tok * CXS + cc[nt]]);
;                 const float r = fsig(pr[reg] + ba[nt]), ig = fsig(pi[reg] + bxv[nt]);
;                 const float aa = __expf(k8[nt] * r);
;                 av[reg] = aa; bv[reg] = __builtin_amdgcn_sqrtf(fmaxf(1.0f - aa * aa, 0.f)) * ig * x;
;             }
;             float cum[4], hl[4];
;             if (DIR == 0) { cum[0] = av[0]; hl[0] = bv[0];
; #pragma unroll
;                 for (int reg = 1; reg < 4; ++reg) { cum[reg] = cum[reg - 1] * av[reg]; hl[reg] = av[reg] * hl[reg - 1] + bv[reg]; } }
;             else { cum[3] = av[3]; hl[3] = bv[3];
; #pragma unroll
;     ...
;             const float A4 = DIR ? cum[0] : cum[3], H4 = DIR ? hl[0] : hl[3];
;             float Aq[4], Hq[4];
; #pragma unroll
;             for (int q = 0; q < 4; ++q) { Aq[q] = __shfl(A4, fr + 16 * q); Hq[q] = __shfl(H4, fr + 16 * q); }
;             float hin;
;             if (DIR == 0) { const float s0 = C[nt], s1 = Aq[0] * s0 + Hq[0], s2 = Aq[1] * s1 + Hq[1], s3 = Aq[2] * s2 + Hq[2]; C[nt] = Aq[3] * s3 + Hq[3]; hin = fq == 0 ? s0 : (fq == 1 ? s1 : (fq == 2 ? s2 : s3)); }
;             else { const float s3 = C[nt], s2 = Aq[3] * s3 + Hq[3], s1 = Aq[2] * s2 + Hq[2], s0 = Aq[1] * s1 + Hq[1]; C[nt] = Aq[0] * s0 + Hq[0]; hin = fq == 3 ? s3 : (fq == 2 ? s2 : (fq == 1 ? s1 : s0)); }
	v_mfma_f32_16x16x32_bf16 v[108:111], v[70:73], v[54:57], 0
	ds_bpermute_b32 v140, v102, v103
	ds_bpermute_b32 v141, v102, v103 offset:64
	ds_bpermute_b32 v142, v102, v103 offset:128
	s_waitcnt lgkmcnt(3)
	v_mfma_f32_16x16x32_bf16 v[108:111], v[66:69], v[50:53], v[108:111]
	ds_bpermute_b32 v143, v102, v103 offset:192
	ds_bpermute_b32 v136, v102, v107
	ds_bpermute_b32 v137, v102, v107 offset:64
	s_nop 4
	v_fma_f32 v101, v108, s98, v157
	s_nop 0
	v_exp_f32_e32 v101, v101
	v_mfma_f32_16x16x32_bf16 v[112:115], v[70:73], v[62:65], 0
	ds_bpermute_b32 v138, v102, v107 offset:128
	ds_bpermute_b32 v139, v102, v107 offset:192
	v_add_f32_e32 v101, 1.0, v101
	v_mfma_f32_16x16x32_bf16 v[112:115], v[66:69], v[58:61], v[112:115]
	v_rcp_f32_e32 v101, v101
	v_fma_f32 v111, v111, s98, v157
	s_nop 0
	v_exp_f32_e32 v111, v111
	v_mul_f32_e32 v101, v75, v101
	s_nop 2
	v_fma_f32 v105, v112, s98, v156
	s_nop 0
	s_nop 0
	v_exp_f32_e32 v105, v105
	v_exp_f32_e32 v101, v101
	ds_read_u16 v107, v106 offset:25344
	ds_read_u16 v108, v106 offset:25872
	ds_read_u16 v112, v106 offset:26400
	ds_read_u16 v144, v106 offset:26928
	ds_read_u16 v160, v106 offset:26960
	ds_read_u16 v161, v106 offset:26432
	ds_read_u16 v162, v106 offset:25904
	ds_read_u16 v163, v106 offset:25376
	s_waitcnt lgkmcnt(7)
	v_lshlrev_b32_e32 v107, 16, v107
	v_add_f32_e32 v103, 1.0, v105
	v_fma_f32 v105, -v101, v101, 1.0
	v_max_f32_e32 v105, 0, v105
	v_rcp_f32_e32 v103, v103
	v_sqrt_f32_e32 v105, v105
	v_add_f32_e32 v111, 1.0, v111
	v_rcp_f32_e32 v111, v111
	s_waitcnt lgkmcnt(6)
	v_lshlrev_b32_e32 v108, 16, v108
	v_mul_f32_e32 v103, v103, v105
	v_fma_f32 v105, v109, s98, v157
	v_fma_f32 v109, v113, s98, v156
	s_nop 0
	s_nop 0
	v_exp_f32_e32 v105, v105
	v_exp_f32_e32 v109, v109
	v_mul_f32_e32 v103, v103, v107
	v_fma_f32 v113, v114, s98, v156
	v_add_f32_e32 v105, 1.0, v105
	v_add_f32_e32 v107, 1.0, v109
	v_fma_f32 v109, v110, s98, v157
	v_rcp_f32_e32 v105, v105
	s_nop 0
	v_exp_f32_e32 v109, v109
	s_nop 0
	v_mul_f32_e32 v105, v75, v105
	s_nop 0
	v_add_f32_e32 v109, 1.0, v109
	v_exp_f32_e32 v105, v105
	v_rcp_f32_e32 v109, v109
	v_rcp_f32_e32 v107, v107
	v_exp_f32_e32 v113, v113
	v_fma_f32 v110, -v105, v105, 1.0
	v_mul_f32_e32 v109, v75, v109
	v_max_f32_e32 v110, 0, v110
	s_nop 0
	v_sqrt_f32_e32 v110, v110
	v_exp_f32_e32 v109, v109
	v_mul_f32_e32 v111, v75, v111
	s_nop 0
	v_mul_f32_e32 v107, v107, v110
	v_add_f32_e32 v110, 1.0, v113
	v_fma_f32 v113, -v109, v109, 1.0
	v_max_f32_e32 v113, 0, v113
	v_rcp_f32_e32 v110, v110
	v_fma_f32 v114, v115, s98, v156
	v_exp_f32_e32 v115, v111
	v_sqrt_f32_e32 v111, v113
	v_mul_f32_e32 v103, v105, v103
	v_fmac_f32_e32 v103, v107, v108
	s_waitcnt lgkmcnt(5)
	v_lshlrev_b32_e32 v112, 16, v112
	v_mul_f32_e32 v110, v110, v111
	v_mul_f32_e32 v101, v105, v101
	v_mul_f32_e32 v103, v109, v103
	v_mul_f32_e32 v101, v109, v101
	v_fmac_f32_e32 v103, v110, v112
	v_mfma_f32_16x16x32_bf16 v[108:111], v[70:73], v[38:41], 0
	s_nop 0
	v_exp_f32_e32 v114, v114
	s_waitcnt lgkmcnt(4)
	v_lshlrev_b32_e32 v144, 16, v144
	v_mfma_f32_16x16x32_bf16 v[108:111], v[66:69], v[34:37], v[108:111]
	v_mul_f32_e32 v103, v115, v103
	v_add_f32_e32 v113, 1.0, v114
	v_fma_f32 v114, -v115, v115, 1.0
	v_mfma_f32_16x16x32_bf16 v[70:73], v[70:73], v[46:49], 0
	v_max_f32_e32 v114, 0, v114
	s_nop 2
	v_fma_f32 v105, v108, s98, v155
	s_nop 0
	v_exp_f32_e32 v105, v105
	v_mfma_f32_16x16x32_bf16 v[66:69], v[66:69], v[42:45], v[70:73]
	v_rcp_f32_e32 v113, v113
	v_sqrt_f32_e32 v114, v114
	v_mul_f32_e32 v101, v115, v101
	v_add_f32_e32 v70, 1.0, v105
	v_rcp_f32_e32 v70, v70
	s_nop 2
	v_fma_f32 v66, v66, s98, v154
	s_nop 0
	v_exp_f32_e32 v66, v66
	v_mul_f32_e32 v70, v104, v70
	s_nop 0
	v_exp_f32_e32 v70, v70
	v_add_f32_e32 v66, 1.0, v66
	v_rcp_f32_e32 v66, v66
	s_waitcnt lgkmcnt(0)
	v_lshlrev_b32_e32 v72, 16, v163
	v_fma_f32 v71, -v70, v70, 1.0
	v_max_f32_e32 v71, 0, v71
	v_sqrt_f32_e32 v71, v71
	v_mul_f32_e32 v113, v113, v114
	v_fmac_f32_e32 v103, v113, v144
	ds_bpermute_b32 v145, v102, v103
	v_mul_f32_e32 v66, v66, v71
	v_mul_f32_e32 v66, v66, v72
	v_fma_f32 v72, v110, s98, v155
	s_nop 0
	v_exp_f32_e32 v72, v72
	v_fma_f32 v71, v109, s98, v155
	s_nop 0
	v_exp_f32_e32 v71, v71
	v_add_f32_e32 v72, 1.0, v72
	v_rcp_f32_e32 v72, v72
	ds_bpermute_b32 v146, v102, v103 offset:64
	v_add_f32_e32 v71, 1.0, v71
	v_rcp_f32_e32 v71, v71
	v_mul_f32_e32 v72, v104, v72
	s_nop 0
	ds_bpermute_b32 v149, v102, v103 offset:128
	ds_bpermute_b32 v158, v102, v103 offset:192
	v_exp_f32_e32 v103, v72
	v_fma_f32 v72, v111, s98, v155
	s_nop 0
	v_exp_f32_e32 v72, v72
	v_mul_f32_e32 v71, v104, v71
	v_fma_f32 v67, v67, s98, v154
	s_nop 0
	s_nop 0
	v_exp_f32_e32 v71, v71
	v_exp_f32_e32 v67, v67
	v_add_f32_e32 v72, 1.0, v72
	v_rcp_f32_e32 v72, v72
	v_fma_f32 v73, -v71, v71, 1.0
	v_add_f32_e32 v67, 1.0, v67
	v_max_f32_e32 v73, 0, v73
	v_rcp_f32_e32 v67, v67
	v_sqrt_f32_e32 v73, v73
	v_mul_f32_e32 v72, v104, v72
	v_fma_f32 v68, v68, s98, v154
	v_fma_f32 v69, v69, s98, v154
	s_nop 0
	s_nop 0
	s_nop 0
	v_exp_f32_e32 v105, v72
	v_exp_f32_e32 v68, v68
	v_exp_f32_e32 v69, v69
	v_mul_f32_e32 v67, v67, v73
	v_fma_f32 v73, -v103, v103, 1.0
	v_max_f32_e32 v73, 0, v73
	v_sqrt_f32_e32 v72, v73
	v_fma_f32 v73, -v105, v105, 1.0
	v_add_f32_e32 v68, 1.0, v68
	v_add_f32_e32 v69, 1.0, v69
	v_max_f32_e32 v73, 0, v73
	v_rcp_f32_e32 v68, v68
	v_rcp_f32_e32 v69, v69
	v_sqrt_f32_e32 v73, v73
	ds_bpermute_b32 v144, v102, v101
	ds_bpermute_b32 v147, v102, v101 offset:64
	ds_bpermute_b32 v148, v102, v101 offset:128
	ds_bpermute_b32 v159, v102, v101 offset:192
	v_lshlrev_b32_e32 v101, 16, v162
	v_mul_f32_e32 v66, v71, v66
	v_mul_f32_e32 v68, v68, v72
	v_mul_f32_e32 v69, v69, v73
	v_mul_f32_e32 v109, v71, v70
	ds_read_b128 v[70:73], v127 offset:33792
	v_fmac_f32_e32 v66, v67, v101
	v_lshlrev_b32_e32 v107, 16, v161
	v_mul_f32_e32 v66, v103, v66
	v_fmac_f32_e32 v66, v68, v107
	v_lshlrev_b32_e32 v108, 16, v160
	v_mul_f32_e32 v67, v103, v109
	v_mul_f32_e32 v103, v105, v66
	v_mul_f32_e32 v101, v105, v67
	v_fmac_f32_e32 v103, v69, v108
	ds_read_b128 v[66:69], v127 offset:33856
	s_waitcnt lgkmcnt(1)
; template <int DIR, int MODE>
; __device__ __forceinline__ void lru_pass(const Args& a, const LAS bf16_t* cxb, LAS bf16_t* gyb, const LAS float* carry, const bf16x8 (&Bw)[2][2][2], const float (&prm)[2][3], int l, int tt, float (&hf)[8][2][4]) {
;     ...
;     for (int mi = 0; mi < 8; ++mi) {
;         const int m = DIR ? 7 - mi : mi;
;         bf16x8 Af[2];
; #pragma unroll
;         for (int ks = 0; ks < 2; ++ks) Af[ks] = *(const LAS bf16x8*)(cxb + (m * 16 + fr) * CXS + 64 * h + 32 * ks + 8 * fq);
; #pragma unroll
;         for (int nt = 0; nt < 2; ++nt) {
;             f32x4 pr = (f32x4){0.f, 0.f, 0.f, 0.f}, pi = (f32x4){0.f, 0.f, 0.f, 0.f};
; #pragma unroll
;             for (int ks = 0; ks < 2; ++ks) { pr = __builtin_amdgcn_mfma_f32_16x16x32_bf16(Af[ks], Bw[0][nt][ks], pr, 0, 0, 0); pi = __builtin_amdgcn_mfma_f32_16x16x32_bf16(Af[ks], Bw[1][nt][ks], pi, 0, 0, 0); }
;             float av[4], bv[4];
; #pragma unroll
;             for (int reg = 0; reg < 4; ++reg) {
;                 const int tok = m * 16 + 4 * fq + reg;
;                 const float x = bf2f(cxb[tok * CXS + cc[nt]]);
;                 const float r = fsig(pr[reg] + ba[nt]), ig = fsig(pi[reg] + bxv[nt]);
;                 const float aa = __expf(k8[nt] * r);
;                 av[reg] = aa; bv[reg] = __builtin_amdgcn_sqrtf(fmaxf(1.0f - aa * aa, 0.f)) * ig * x;
;             }
;             float cum[4], hl[4];
;             if (DIR == 0) { cum[0] = av[0]; hl[0] = bv[0];
; #pragma unroll
;                 for (int reg = 1; reg < 4; ++reg) { cum[reg] = cum[reg - 1] * av[reg]; hl[reg] = av[reg] * hl[reg - 1] + bv[reg]; } }
;             else { cum[3] = av[3]; hl[3] = bv[3];
; #pragma unroll
;     ...
;             const float A4 = DIR ? cum[0] : cum[3], H4 = DIR ? hl[0] : hl[3];
;             float Aq[4], Hq[4];
; #pragma unroll
;             for (int q = 0; q < 4; ++q) { Aq[q] = __shfl(A4, fr + 16 * q); Hq[q] = __shfl(H4, fr + 16 * q); }
;             float hin;
;             if (DIR == 0) { const float s0 = C[nt], s1 = Aq[0] * s0 + Hq[0], s2 = Aq[1] * s1 + Hq[1], s3 = Aq[2] * s2 + Hq[2]; C[nt] = Aq[3] * s3 + Hq[3]; hin = fq == 0 ? s0 : (fq == 1 ? s1 : (fq == 2 ? s2 : s3)); }
;             else { const float s3 = C[nt], s2 = Aq[3] * s3 + Hq[3], s1 = Aq[2] * s2 + Hq[2], s0 = Aq[1] * s1 + Hq[1]; C[nt] = Aq[0] * s0 + Hq[0]; hin = fq == 3 ? s3 : (fq == 2 ? s2 : (fq == 1 ? s1 : s0)); }
	v_mfma_f32_16x16x32_bf16 v[108:111], v[70:73], v[54:57], 0
	ds_bpermute_b32 v161, v102, v101
	ds_bpermute_b32 v162, v102, v101 offset:64
	ds_bpermute_b32 v165, v102, v101 offset:128
	s_waitcnt lgkmcnt(3)
	v_mfma_f32_16x16x32_bf16 v[108:111], v[66:69], v[50:53], v[108:111]
	ds_bpermute_b32 v166, v102, v101 offset:192
	ds_bpermute_b32 v160, v102, v103
	ds_bpermute_b32 v163, v102, v103 offset:64
	s_nop 4
	v_fma_f32 v105, v108, s98, v157
	s_nop 0
	v_exp_f32_e32 v105, v105
	v_mfma_f32_16x16x32_bf16 v[112:115], v[70:73], v[62:65], 0
	ds_bpermute_b32 v164, v102, v103 offset:128
	ds_bpermute_b32 v167, v102, v103 offset:192
	v_add_f32_e32 v101, 1.0, v105
	v_mfma_f32_16x16x32_bf16 v[112:115], v[66:69], v[58:61], v[112:115]
	v_rcp_f32_e32 v101, v101
	v_fma_f32 v111, v111, s98, v157
	s_nop 0
	v_exp_f32_e32 v111, v111
	v_mul_f32_e32 v101, v75, v101
	s_nop 2
	v_fma_f32 v105, v112, s98, v156
	s_nop 0
	s_nop 0
	v_exp_f32_e32 v105, v105
	v_exp_f32_e32 v101, v101
	ds_read_u16 v107, v106 offset:33792
	ds_read_u16 v108, v106 offset:34320
	ds_read_u16 v112, v106 offset:34848
	ds_read_u16 v168, v106 offset:35376
	ds_read_u16 v174, v106 offset:35408
	ds_read_u16 v175, v106 offset:34880
	ds_read_u16 v176, v106 offset:34352
	ds_read_u16 v177, v106 offset:33824
	s_waitcnt lgkmcnt(7)
	v_lshlrev_b32_e32 v107, 16, v107
	v_add_f32_e32 v103, 1.0, v105
	v_fma_f32 v105, -v101, v101, 1.0
	v_max_f32_e32 v105, 0, v105
	v_rcp_f32_e32 v103, v103
	v_sqrt_f32_e32 v105, v105
	v_add_f32_e32 v111, 1.0, v111
	v_rcp_f32_e32 v111, v111
	s_waitcnt lgkmcnt(6)
	v_lshlrev_b32_e32 v108, 16, v108
	v_mul_f32_e32 v103, v103, v105
	v_fma_f32 v105, v109, s98, v157
	v_fma_f32 v109, v113, s98, v156
	s_nop 0
	s_nop 0
	v_exp_f32_e32 v105, v105
	v_exp_f32_e32 v109, v109
	v_mul_f32_e32 v103, v103, v107
	v_fma_f32 v113, v114, s98, v156
	v_add_f32_e32 v105, 1.0, v105
	v_add_f32_e32 v107, 1.0, v109
	v_fma_f32 v109, v110, s98, v157
	v_rcp_f32_e32 v105, v105
	s_nop 0
	v_exp_f32_e32 v109, v109
	s_nop 0
	v_mul_f32_e32 v105, v75, v105
	s_nop 0
	v_add_f32_e32 v109, 1.0, v109
	v_exp_f32_e32 v105, v105
	v_rcp_f32_e32 v109, v109
	v_rcp_f32_e32 v107, v107
	v_exp_f32_e32 v113, v113
	v_fma_f32 v110, -v105, v105, 1.0
	v_mul_f32_e32 v109, v75, v109
	v_max_f32_e32 v110, 0, v110
	s_nop 0
	v_sqrt_f32_e32 v110, v110
	v_exp_f32_e32 v109, v109
	v_mul_f32_e32 v111, v75, v111
	s_nop 0
	v_mul_f32_e32 v107, v107, v110
	v_add_f32_e32 v110, 1.0, v113
	v_fma_f32 v113, -v109, v109, 1.0
	v_max_f32_e32 v113, 0, v113
	v_rcp_f32_e32 v110, v110
	v_fma_f32 v114, v115, s98, v156
	v_exp_f32_e32 v115, v111
	v_sqrt_f32_e32 v111, v113
	v_mul_f32_e32 v103, v105, v103
	v_fmac_f32_e32 v103, v107, v108
	s_waitcnt lgkmcnt(5)
	v_lshlrev_b32_e32 v112, 16, v112
	v_mul_f32_e32 v110, v110, v111
	v_mul_f32_e32 v101, v105, v101
	v_mul_f32_e32 v103, v109, v103
	v_mul_f32_e32 v101, v109, v101
	v_fmac_f32_e32 v103, v110, v112
	v_mfma_f32_16x16x32_bf16 v[108:111], v[70:73], v[38:41], 0
	v_mul_f32_e32 v105, v115, v101
	v_mul_f32_e32 v107, v115, v103
	s_nop 0
	v_mfma_f32_16x16x32_bf16 v[108:111], v[66:69], v[34:37], v[108:111]
	v_exp_f32_e32 v114, v114
	s_waitcnt lgkmcnt(4)
	v_lshlrev_b32_e32 v168, 16, v168
	ds_bpermute_b32 v171, v102, v105 offset:64
	v_mfma_f32_16x16x32_bf16 v[70:73], v[70:73], v[46:49], 0
	v_add_f32_e32 v113, 1.0, v114
	s_nop 1
	v_fma_f32 v101, v108, s98, v155
	s_nop 0
	v_exp_f32_e32 v103, v101
	v_mfma_f32_16x16x32_bf16 v[66:69], v[66:69], v[42:45], v[70:73]
	v_fma_f32 v114, -v115, v115, 1.0
	v_max_f32_e32 v114, 0, v114
	v_rcp_f32_e32 v113, v113
	v_add_f32_e32 v70, 1.0, v103
	v_rcp_f32_e32 v70, v70
	s_nop 2
	v_fma_f32 v66, v66, s98, v154
	s_nop 0
	v_exp_f32_e32 v66, v66
	v_mul_f32_e32 v70, v104, v70
	s_nop 0
	v_exp_f32_e32 v70, v70
	v_add_f32_e32 v66, 1.0, v66
	v_rcp_f32_e32 v66, v66
	s_waitcnt lgkmcnt(1)
	v_lshlrev_b32_e32 v72, 16, v177
	v_fma_f32 v71, -v70, v70, 1.0
	v_max_f32_e32 v71, 0, v71
	v_sqrt_f32_e32 v71, v71
	v_sqrt_f32_e32 v114, v114
	v_fma_f32 v67, v67, s98, v154
	s_nop 0
	v_mul_f32_e32 v66, v66, v71
	v_mul_f32_e32 v66, v66, v72
	v_fma_f32 v72, v110, s98, v155
	s_nop 0
	v_exp_f32_e32 v72, v72
	v_fma_f32 v71, v109, s98, v155
	s_nop 0
	v_exp_f32_e32 v71, v71
	v_add_f32_e32 v72, 1.0, v72
	v_rcp_f32_e32 v72, v72
	v_mul_f32_e32 v113, v113, v114
	v_add_f32_e32 v71, 1.0, v71
	v_fmac_f32_e32 v107, v113, v168
	v_mul_f32_e32 v72, v104, v72
	v_rcp_f32_e32 v71, v71
	s_nop 0
	ds_bpermute_b32 v169, v102, v107
	ds_bpermute_b32 v170, v102, v107 offset:64
	ds_bpermute_b32 v172, v102, v107 offset:128
	ds_bpermute_b32 v173, v102, v107 offset:192
	v_exp_f32_e32 v107, v72
	v_fma_f32 v72, v111, s98, v155
	s_nop 0
	v_exp_f32_e32 v72, v72
	v_mul_f32_e32 v71, v104, v71
	s_nop 0
	v_exp_f32_e32 v71, v71
	v_exp_f32_e32 v67, v67
	v_add_f32_e32 v72, 1.0, v72
	v_rcp_f32_e32 v72, v72
	v_fma_f32 v73, -v71, v71, 1.0
	v_add_f32_e32 v67, 1.0, v67
	v_max_f32_e32 v73, 0, v73
	v_rcp_f32_e32 v67, v67
	v_sqrt_f32_e32 v73, v73
	v_mul_f32_e32 v72, v104, v72
	v_fma_f32 v68, v68, s98, v154
	v_fma_f32 v69, v69, s98, v154
	s_nop 0
	s_nop 0
	s_nop 0
	v_exp_f32_e32 v108, v72
	v_exp_f32_e32 v68, v68
	v_exp_f32_e32 v69, v69
	v_mul_f32_e32 v67, v67, v73
	v_fma_f32 v73, -v107, v107, 1.0
	v_max_f32_e32 v73, 0, v73
	v_sqrt_f32_e32 v72, v73
	v_fma_f32 v73, -v108, v108, 1.0
	v_add_f32_e32 v68, 1.0, v68
	v_add_f32_e32 v69, 1.0, v69
	v_max_f32_e32 v73, 0, v73
	v_rcp_f32_e32 v68, v68
	v_rcp_f32_e32 v69, v69
	v_sqrt_f32_e32 v73, v73
	ds_bpermute_b32 v168, v102, v105
	ds_bpermute_b32 v101, v102, v105 offset:128
	ds_bpermute_b32 v103, v102, v105 offset:192
	v_lshlrev_b32_e32 v105, 16, v176
	v_mul_f32_e32 v66, v71, v66
	v_mul_f32_e32 v68, v68, v72
	v_mul_f32_e32 v69, v69, v73
	v_mul_f32_e32 v111, v71, v70
	ds_read_b128 v[70:73], v127 offset:42240
	v_fmac_f32_e32 v66, v67, v105
	v_lshlrev_b32_e32 v109, 16, v175
	v_mul_f32_e32 v66, v107, v66
	v_fmac_f32_e32 v66, v68, v109
	v_lshlrev_b32_e32 v110, 16, v174
	v_mul_f32_e32 v67, v107, v111
	v_mul_f32_e32 v179, v108, v66
	v_mul_f32_e32 v107, v108, v67
	v_fmac_f32_e32 v179, v69, v110
	ds_read_b128 v[66:69], v127 offset:42304
	s_waitcnt lgkmcnt(1)
; template <int DIR, int MODE>
; __device__ __forceinline__ void lru_pass(const Args& a, const LAS bf16_t* cxb, LAS bf16_t* gyb, const LAS float* carry, const bf16x8 (&Bw)[2][2][2], const float (&prm)[2][3], int l, int tt, float (&hf)[8][2][4]) {
;     ...
;     for (int mi = 0; mi < 8; ++mi) {
;         const int m = DIR ? 7 - mi : mi;
;         bf16x8 Af[2];
; #pragma unroll
;         for (int ks = 0; ks < 2; ++ks) Af[ks] = *(const LAS bf16x8*)(cxb + (m * 16 + fr) * CXS + 64 * h + 32 * ks + 8 * fq);
; #pragma unroll
;         for (int nt = 0; nt < 2; ++nt) {
;             f32x4 pr = (f32x4){0.f, 0.f, 0.f, 0.f}, pi = (f32x4){0.f, 0.f, 0.f, 0.f};
; #pragma unroll
;             for (int ks = 0; ks < 2; ++ks) { pr = __builtin_amdgcn_mfma_f32_16x16x32_bf16(Af[ks], Bw[0][nt][ks], pr, 0, 0, 0); pi = __builtin_amdgcn_mfma_f32_16x16x32_bf16(Af[ks], Bw[1][nt][ks], pi, 0, 0, 0); }
;             float av[4], bv[4];
; #pragma unroll
;             for (int reg = 0; reg < 4; ++reg) {
;                 const int tok = m * 16 + 4 * fq + reg;
;                 const float x = bf2f(cxb[tok * CXS + cc[nt]]);
;                 const float r = fsig(pr[reg] + ba[nt]), ig = fsig(pi[reg] + bxv[nt]);
;                 const float aa = __expf(k8[nt] * r);
;                 av[reg] = aa; bv[reg] = __builtin_amdgcn_sqrtf(fmaxf(1.0f - aa * aa, 0.f)) * ig * x;
;             }
;             float cum[4], hl[4];
;             if (DIR == 0) { cum[0] = av[0]; hl[0] = bv[0];
; #pragma unroll
;                 for (int reg = 1; reg < 4; ++reg) { cum[reg] = cum[reg - 1] * av[reg]; hl[reg] = av[reg] * hl[reg - 1] + bv[reg]; } }
;             else { cum[3] = av[3]; hl[3] = bv[3];
; #pragma unroll
;     ...
;             const float A4 = DIR ? cum[0] : cum[3], H4 = DIR ? hl[0] : hl[3];
;             float Aq[4], Hq[4];
; #pragma unroll
;             for (int q = 0; q < 4; ++q) { Aq[q] = __shfl(A4, fr + 16 * q); Hq[q] = __shfl(H4, fr + 16 * q); }
;             float hin;
;             if (DIR == 0) { const float s0 = C[nt], s1 = Aq[0] * s0 + Hq[0], s2 = Aq[1] * s1 + Hq[1], s3 = Aq[2] * s2 + Hq[2]; C[nt] = Aq[3] * s3 + Hq[3]; hin = fq == 0 ? s0 : (fq == 1 ? s1 : (fq == 2 ? s2 : s3)); }
;             else { const float s3 = C[nt], s2 = Aq[3] * s3 + Hq[3], s1 = Aq[2] * s2 + Hq[2], s0 = Aq[1] * s1 + Hq[1]; C[nt] = Aq[0] * s0 + Hq[0]; hin = fq == 3 ? s3 : (fq == 2 ? s2 : (fq == 1 ? s1 : s0)); }
	v_mfma_f32_16x16x32_bf16 v[108:111], v[70:73], v[54:57], 0
	ds_read_u16 v181, v106 offset:42240
	ds_read_u16 v182, v106 offset:42768
	ds_read_u16 v183, v106 offset:43296
	ds_read_u16 v184, v106 offset:43824
	ds_read_u16 v185, v106 offset:43856
	ds_read_u16 v186, v106 offset:43328
	ds_read_u16 v187, v106 offset:42800
	ds_read_u16 v188, v106 offset:42272
	s_waitcnt lgkmcnt(7)
	v_lshlrev_b32_e32 v181, 16, v181
	s_waitcnt lgkmcnt(5)
	v_lshlrev_b32_e32 v183, 16, v183
	v_mfma_f32_16x16x32_bf16 v[108:111], v[66:69], v[50:53], v[108:111]
	ds_bpermute_b32 v77, v102, v83
	ds_bpermute_b32 v79, v102, v83 offset:64
	ds_bpermute_b32 v81, v102, v83 offset:128
	s_nop 4
	v_fma_f32 v108, v108, s98, v157
	s_nop 0
	v_exp_f32_e32 v108, v108
	v_mfma_f32_16x16x32_bf16 v[112:115], v[70:73], v[62:65], 0
	v_fma_f32 v109, v109, s98, v157
	s_nop 0
	v_add_f32_e32 v108, 1.0, v108
	v_rcp_f32_e32 v108, v108
	v_mfma_f32_16x16x32_bf16 v[112:115], v[66:69], v[58:61], v[112:115]
	v_exp_f32_e32 v109, v109
	v_fma_f32 v110, v110, s98, v157
	v_mul_f32_e32 v108, v75, v108
	s_nop 0
	v_add_f32_e32 v109, 1.0, v109
	s_nop 2
	v_fma_f32 v112, v112, s98, v156
	s_nop 0
	v_exp_f32_e32 v108, v108
	v_rcp_f32_e32 v109, v109
	s_nop 0
	v_fma_f32 v111, v111, s98, v157
	v_exp_f32_e32 v112, v112
	v_exp_f32_e32 v110, v110
	s_nop 0
	v_exp_f32_e32 v111, v111
	v_fma_f32 v180, -v108, v108, 1.0
	v_mul_f32_e32 v109, v75, v109
	v_add_f32_e32 v112, 1.0, v112
	v_max_f32_e32 v180, 0, v180
	v_fma_f32 v113, v113, s98, v156
	s_nop 0
	v_add_f32_e32 v110, 1.0, v110
	v_rcp_f32_e32 v112, v112
	v_sqrt_f32_e32 v180, v180
	s_nop 0
	v_exp_f32_e32 v109, v109
	v_rcp_f32_e32 v110, v110
	v_add_f32_e32 v111, 1.0, v111
	v_exp_f32_e32 v113, v113
	v_rcp_f32_e32 v111, v111
	v_mul_f32_e32 v112, v112, v180
	v_fma_f32 v180, -v109, v109, 1.0
	v_mul_f32_e32 v110, v75, v110
	v_add_f32_e32 v113, 1.0, v113
	v_max_f32_e32 v180, 0, v180
	v_fma_f32 v114, v114, s98, v156
	s_nop 0
	v_mul_f32_e32 v111, v75, v111
	v_rcp_f32_e32 v113, v113
	v_sqrt_f32_e32 v180, v180
	s_nop 0
	v_exp_f32_e32 v110, v110
	v_fma_f32 v115, v115, s98, v156
	s_nop 0
	v_exp_f32_e32 v114, v114
	s_nop 0
	v_exp_f32_e32 v111, v111
	v_exp_f32_e32 v115, v115
	v_mul_f32_e32 v113, v113, v180
	v_fma_f32 v180, -v110, v110, 1.0
	v_mul_f32_e32 v112, v112, v181
	v_lshlrev_b32_e32 v181, 16, v182
	v_add_f32_e32 v114, 1.0, v114
	v_max_f32_e32 v180, 0, v180
	v_fma_f32 v182, -v111, v111, 1.0
	v_rcp_f32_e32 v114, v114
	v_sqrt_f32_e32 v180, v180
	v_add_f32_e32 v115, 1.0, v115
	v_max_f32_e32 v182, 0, v182
	v_rcp_f32_e32 v115, v115
	v_sqrt_f32_e32 v182, v182
	v_mul_f32_e32 v108, v109, v108
	v_mul_f32_e32 v109, v109, v112
	v_fmac_f32_e32 v109, v113, v181
	v_mul_f32_e32 v114, v114, v180
	v_mul_f32_e32 v109, v110, v109
	v_mul_f32_e32 v182, v115, v182
	v_fmac_f32_e32 v109, v114, v183
	v_mfma_f32_16x16x32_bf16 v[112:115], v[70:73], v[38:41], 0
	s_waitcnt lgkmcnt(7)
	v_lshlrev_b32_e32 v180, 16, v184
	v_mul_f32_e32 v184, v111, v109
	v_mul_f32_e32 v108, v110, v108
	v_mfma_f32_16x16x32_bf16 v[112:115], v[66:69], v[34:37], v[112:115]
	v_mul_f32_e32 v183, v111, v108
	v_fmac_f32_e32 v184, v182, v180
	ds_bpermute_b32 v108, v102, v183
	v_mfma_f32_16x16x32_bf16 v[70:73], v[70:73], v[46:49], 0
	ds_bpermute_b32 v180, v102, v184
	s_nop 2
	v_fma_f32 v109, v112, s98, v155
	s_nop 0
	v_exp_f32_e32 v111, v109
	v_mfma_f32_16x16x32_bf16 v[66:69], v[66:69], v[42:45], v[70:73]
	s_waitcnt lgkmcnt(6)
	v_lshlrev_b32_e32 v112, 16, v187
	ds_bpermute_b32 v110, v102, v183 offset:64
	ds_bpermute_b32 v181, v102, v184 offset:64
	v_add_f32_e32 v70, 1.0, v111
	v_rcp_f32_e32 v70, v70
	s_nop 1
	v_fma_f32 v66, v66, s98, v154
	s_nop 0
	v_exp_f32_e32 v66, v66
	v_mul_f32_e32 v70, v104, v70
	s_nop 0
	v_exp_f32_e32 v70, v70
	v_add_f32_e32 v66, 1.0, v66
	v_rcp_f32_e32 v66, v66
	s_waitcnt lgkmcnt(7)
	v_lshlrev_b32_e32 v72, 16, v188
	v_fma_f32 v71, -v70, v70, 1.0
	v_max_f32_e32 v71, 0, v71
	v_sqrt_f32_e32 v71, v71
	v_fma_f32 v67, v67, s98, v154
	s_nop 0
	v_exp_f32_e32 v67, v67
	v_mul_f32_e32 v66, v66, v71
	v_mul_f32_e32 v66, v66, v72
	v_fma_f32 v72, v114, s98, v155
	s_nop 0
	v_exp_f32_e32 v72, v72
	v_fma_f32 v71, v113, s98, v155
	s_nop 0
	v_exp_f32_e32 v71, v71
	v_add_f32_e32 v72, 1.0, v72
	v_rcp_f32_e32 v72, v72
	v_add_f32_e32 v67, 1.0, v67
	v_add_f32_e32 v71, 1.0, v71
	v_rcp_f32_e32 v71, v71
	v_mul_f32_e32 v72, v104, v72
	s_nop 0
	v_exp_f32_e32 v113, v72
	v_fma_f32 v72, v115, s98, v155
	s_nop 0
	v_exp_f32_e32 v72, v72
	v_mul_f32_e32 v71, v104, v71
	s_nop 0
	v_exp_f32_e32 v71, v71
	v_add_f32_e32 v72, 1.0, v72
	v_rcp_f32_e32 v72, v72
	v_rcp_f32_e32 v67, v67
	v_fma_f32 v73, -v71, v71, 1.0
	v_max_f32_e32 v73, 0, v73
	v_sqrt_f32_e32 v73, v73
	v_mul_f32_e32 v72, v104, v72
	v_fma_f32 v68, v68, s98, v154
	v_fma_f32 v69, v69, s98, v154
	s_nop 0
	s_nop 0
	s_nop 0
	v_exp_f32_e32 v114, v72
	v_exp_f32_e32 v68, v68
	v_exp_f32_e32 v69, v69
	v_mul_f32_e32 v67, v67, v73
	v_fma_f32 v73, -v113, v113, 1.0
	v_max_f32_e32 v73, 0, v73
	v_sqrt_f32_e32 v72, v73
	v_fma_f32 v73, -v114, v114, 1.0
	v_add_f32_e32 v68, 1.0, v68
	v_add_f32_e32 v69, 1.0, v69
	v_max_f32_e32 v73, 0, v73
	v_rcp_f32_e32 v68, v68
	v_rcp_f32_e32 v69, v69
	v_sqrt_f32_e32 v73, v73
	v_mul_f32_e32 v66, v71, v66
	ds_bpermute_b32 v109, v102, v183 offset:128
	ds_bpermute_b32 v182, v102, v184 offset:128
	ds_bpermute_b32 v111, v102, v183 offset:192
	ds_bpermute_b32 v183, v102, v184 offset:192
	v_mul_f32_e32 v68, v68, v72
	v_lshlrev_b32_e32 v184, 16, v185
	v_mul_f32_e32 v69, v69, v73
	v_mul_f32_e32 v185, v71, v70
	ds_read_b128 v[70:73], v127 offset:50688
	v_fmac_f32_e32 v66, v67, v112
	v_lshlrev_b32_e32 v115, 16, v186
	v_mul_f32_e32 v66, v113, v66
	v_fmac_f32_e32 v66, v68, v115
	v_mul_f32_e32 v67, v113, v185
	v_mul_f32_e32 v187, v114, v66
	v_mul_f32_e32 v113, v114, v67
	v_fmac_f32_e32 v187, v69, v184
	ds_read_b128 v[66:69], v127 offset:50752
	s_waitcnt lgkmcnt(1)
; template <int DIR, int MODE>
; __device__ __forceinline__ void lru_pass(const Args& a, const LAS bf16_t* cxb, LAS bf16_t* gyb, const LAS float* carry, const bf16x8 (&Bw)[2][2][2], const float (&prm)[2][3], int l, int tt, float (&hf)[8][2][4]) {
;     ...
;     for (int mi = 0; mi < 8; ++mi) {
;         const int m = DIR ? 7 - mi : mi;
;         bf16x8 Af[2];
; #pragma unroll
;         for (int ks = 0; ks < 2; ++ks) Af[ks] = *(const LAS bf16x8*)(cxb + (m * 16 + fr) * CXS + 64 * h + 32 * ks + 8 * fq);
; #pragma unroll
;         for (int nt = 0; nt < 2; ++nt) {
;             f32x4 pr = (f32x4){0.f, 0.f, 0.f, 0.f}, pi = (f32x4){0.f, 0.f, 0.f, 0.f};
; #pragma unroll
;             for (int ks = 0; ks < 2; ++ks) { pr = __builtin_amdgcn_mfma_f32_16x16x32_bf16(Af[ks], Bw[0][nt][ks], pr, 0, 0, 0); pi = __builtin_amdgcn_mfma_f32_16x16x32_bf16(Af[ks], Bw[1][nt][ks], pi, 0, 0, 0); }
;             float av[4], bv[4];
; #pragma unroll
;             for (int reg = 0; reg < 4; ++reg) {
;                 const int tok = m * 16 + 4 * fq + reg;
;                 const float x = bf2f(cxb[tok * CXS + cc[nt]]);
;                 const float r = fsig(pr[reg] + ba[nt]), ig = fsig(pi[reg] + bxv[nt]);
;                 const float aa = __expf(k8[nt] * r);
;                 av[reg] = aa; bv[reg] = __builtin_amdgcn_sqrtf(fmaxf(1.0f - aa * aa, 0.f)) * ig * x;
;             }
;             float cum[4], hl[4];
;             if (DIR == 0) { cum[0] = av[0]; hl[0] = bv[0];
; #pragma unroll
;                 for (int reg = 1; reg < 4; ++reg) { cum[reg] = cum[reg - 1] * av[reg]; hl[reg] = av[reg] * hl[reg - 1] + bv[reg]; } }
;             else { cum[3] = av[3]; hl[3] = bv[3];
; #pragma unroll
;     ...
;             const float A4 = DIR ? cum[0] : cum[3], H4 = DIR ? hl[0] : hl[3];
;             float Aq[4], Hq[4];
; #pragma unroll
;             for (int q = 0; q < 4; ++q) { Aq[q] = __shfl(A4, fr + 16 * q); Hq[q] = __shfl(H4, fr + 16 * q); }
;             float hin;
;             if (DIR == 0) { const float s0 = C[nt], s1 = Aq[0] * s0 + Hq[0], s2 = Aq[1] * s1 + Hq[1], s3 = Aq[2] * s2 + Hq[2]; C[nt] = Aq[3] * s3 + Hq[3]; hin = fq == 0 ? s0 : (fq == 1 ? s1 : (fq == 2 ? s2 : s3)); }
;             else { const float s3 = C[nt], s2 = Aq[3] * s3 + Hq[3], s1 = Aq[2] * s2 + Hq[2], s0 = Aq[1] * s1 + Hq[1]; C[nt] = Aq[0] * s0 + Hq[0]; hin = fq == 3 ? s3 : (fq == 2 ? s2 : (fq == 1 ? s1 : s0)); }
	v_mfma_f32_16x16x32_bf16 v[188:191], v[70:73], v[54:57], 0
	ds_read_u16 v197, v106 offset:50688
	ds_read_u16 v198, v106 offset:51216
	ds_read_u16 v199, v106 offset:51744
	ds_read_u16 v200, v106 offset:52272
	ds_read_u16 v201, v106 offset:52304
	ds_read_u16 v202, v106 offset:51776
	ds_read_u16 v203, v106 offset:51248
	ds_read_u16 v204, v106 offset:50720
	s_waitcnt lgkmcnt(7)
	v_lshlrev_b32_e32 v197, 16, v197
	s_waitcnt lgkmcnt(5)
	v_lshlrev_b32_e32 v199, 16, v199
	v_mfma_f32_16x16x32_bf16 v[188:191], v[66:69], v[50:53], v[188:191]
	ds_bpermute_b32 v83, v102, v83 offset:192
	ds_bpermute_b32 v87, v102, v91
	ds_bpermute_b32 v85, v102, v91 offset:64
	s_nop 4
	v_fma_f32 v188, v188, s98, v157
	s_nop 0
	v_exp_f32_e32 v188, v188
	v_mfma_f32_16x16x32_bf16 v[192:195], v[70:73], v[62:65], 0
	v_fma_f32 v189, v189, s98, v157
	s_nop 0
	v_add_f32_e32 v188, 1.0, v188
	v_rcp_f32_e32 v188, v188
	v_mfma_f32_16x16x32_bf16 v[192:195], v[66:69], v[58:61], v[192:195]
	v_exp_f32_e32 v189, v189
	v_fma_f32 v190, v190, s98, v157
	v_mul_f32_e32 v188, v75, v188
	s_nop 0
	v_add_f32_e32 v189, 1.0, v189
	s_nop 2
	v_fma_f32 v192, v192, s98, v156
	s_nop 0
	v_exp_f32_e32 v188, v188
	v_rcp_f32_e32 v189, v189
	s_nop 0
	v_fma_f32 v191, v191, s98, v157
	v_exp_f32_e32 v192, v192
	v_exp_f32_e32 v190, v190
	s_nop 0
	v_exp_f32_e32 v191, v191
	v_fma_f32 v196, -v188, v188, 1.0
	v_mul_f32_e32 v189, v75, v189
	v_add_f32_e32 v192, 1.0, v192
	v_max_f32_e32 v196, 0, v196
	v_fma_f32 v193, v193, s98, v156
	s_nop 0
	v_add_f32_e32 v190, 1.0, v190
	v_rcp_f32_e32 v192, v192
	v_sqrt_f32_e32 v196, v196
	s_nop 0
	v_exp_f32_e32 v189, v189
	v_rcp_f32_e32 v190, v190
	v_add_f32_e32 v191, 1.0, v191
	v_exp_f32_e32 v193, v193
	v_rcp_f32_e32 v191, v191
	v_mul_f32_e32 v192, v192, v196
	v_fma_f32 v196, -v189, v189, 1.0
	v_mul_f32_e32 v190, v75, v190
	v_add_f32_e32 v193, 1.0, v193
	v_max_f32_e32 v196, 0, v196
	v_fma_f32 v194, v194, s98, v156
	s_nop 0
	v_mul_f32_e32 v191, v75, v191
	v_rcp_f32_e32 v193, v193
	v_sqrt_f32_e32 v196, v196
	s_nop 0
	v_exp_f32_e32 v190, v190
	v_fma_f32 v195, v195, s98, v156
	s_nop 0
	v_exp_f32_e32 v194, v194
	s_nop 0
	v_exp_f32_e32 v191, v191
	v_exp_f32_e32 v195, v195
	v_mul_f32_e32 v193, v193, v196
	v_fma_f32 v196, -v190, v190, 1.0
	v_mul_f32_e32 v192, v192, v197
	v_lshlrev_b32_e32 v197, 16, v198
	v_add_f32_e32 v194, 1.0, v194
	v_max_f32_e32 v196, 0, v196
	v_fma_f32 v198, -v191, v191, 1.0
	v_rcp_f32_e32 v194, v194
	v_sqrt_f32_e32 v196, v196
	v_add_f32_e32 v195, 1.0, v195
	v_max_f32_e32 v198, 0, v198
	v_rcp_f32_e32 v195, v195
	v_sqrt_f32_e32 v198, v198
	v_mul_f32_e32 v188, v189, v188
	v_mul_f32_e32 v189, v189, v192
	v_fmac_f32_e32 v189, v193, v197
	v_mul_f32_e32 v194, v194, v196
	v_mul_f32_e32 v189, v190, v189
	v_mul_f32_e32 v198, v195, v198
	v_fmac_f32_e32 v189, v194, v199
	v_mfma_f32_16x16x32_bf16 v[192:195], v[70:73], v[38:41], 0
	s_waitcnt lgkmcnt(7)
	v_lshlrev_b32_e32 v196, 16, v200
	v_mul_f32_e32 v205, v191, v189
	v_fmac_f32_e32 v205, v198, v196
	v_mfma_f32_16x16x32_bf16 v[196:199], v[66:69], v[34:37], v[192:195]
	v_mul_f32_e32 v188, v190, v188
	v_mul_f32_e32 v200, v191, v188
	ds_bpermute_b32 v188, v102, v200
	v_mfma_f32_16x16x32_bf16 v[70:73], v[70:73], v[46:49], 0
	ds_bpermute_b32 v191, v102, v200 offset:64
	s_nop 2
	v_fma_f32 v192, v196, s98, v155
	s_nop 0
	v_exp_f32_e32 v193, v192
	v_mfma_f32_16x16x32_bf16 v[66:69], v[66:69], v[42:45], v[70:73]
	s_waitcnt lgkmcnt(6)
	v_lshlrev_b32_e32 v196, 16, v203
	ds_bpermute_b32 v192, v102, v200 offset:128
	ds_bpermute_b32 v195, v102, v200 offset:192
	v_add_f32_e32 v70, 1.0, v193
	v_rcp_f32_e32 v70, v70
	s_nop 1
	v_fma_f32 v66, v66, s98, v154
	s_nop 0
	v_exp_f32_e32 v66, v66
	v_mul_f32_e32 v70, v104, v70
	s_nop 0
	v_exp_f32_e32 v70, v70
	v_add_f32_e32 v66, 1.0, v66
	v_rcp_f32_e32 v66, v66
	s_waitcnt lgkmcnt(7)
	v_lshlrev_b32_e32 v72, 16, v204
	v_fma_f32 v71, -v70, v70, 1.0
	v_max_f32_e32 v71, 0, v71
	v_sqrt_f32_e32 v71, v71
	v_fma_f32 v67, v67, s98, v154
	s_nop 0
	v_exp_f32_e32 v67, v67
	v_mul_f32_e32 v66, v66, v71
	v_mul_f32_e32 v66, v66, v72
	v_fma_f32 v72, v198, s98, v155
	s_nop 0
	v_exp_f32_e32 v72, v72
	v_fma_f32 v71, v197, s98, v155
	s_nop 0
	v_exp_f32_e32 v71, v71
	v_add_f32_e32 v72, 1.0, v72
	v_rcp_f32_e32 v72, v72
	v_add_f32_e32 v67, 1.0, v67
	v_add_f32_e32 v71, 1.0, v71
	v_rcp_f32_e32 v71, v71
	v_mul_f32_e32 v72, v104, v72
	s_nop 0
	v_exp_f32_e32 v197, v72
	v_fma_f32 v72, v199, s98, v155
	s_nop 0
	v_exp_f32_e32 v72, v72
	v_mul_f32_e32 v71, v104, v71
	s_nop 0
	v_exp_f32_e32 v71, v71
	v_add_f32_e32 v72, 1.0, v72
	v_rcp_f32_e32 v72, v72
	v_rcp_f32_e32 v67, v67
	v_fma_f32 v73, -v71, v71, 1.0
	v_max_f32_e32 v73, 0, v73
	v_sqrt_f32_e32 v73, v73
	v_mul_f32_e32 v72, v104, v72
	v_fma_f32 v68, v68, s98, v154
	v_fma_f32 v69, v69, s98, v154
	s_nop 0
	s_nop 0
	s_nop 0
	v_exp_f32_e32 v198, v72
	v_exp_f32_e32 v68, v68
	v_exp_f32_e32 v69, v69
	v_mul_f32_e32 v67, v67, v73
	v_fma_f32 v73, -v197, v197, 1.0
	v_max_f32_e32 v73, 0, v73
	v_sqrt_f32_e32 v72, v73
	v_fma_f32 v73, -v198, v198, 1.0
	v_add_f32_e32 v68, 1.0, v68
	v_add_f32_e32 v69, 1.0, v69
	v_max_f32_e32 v73, 0, v73
	v_rcp_f32_e32 v68, v68
	v_rcp_f32_e32 v69, v69
	v_sqrt_f32_e32 v73, v73
	v_mul_f32_e32 v66, v71, v66
	v_mul_f32_e32 v68, v68, v72
	v_lshlrev_b32_e32 v200, 16, v201
	v_mul_f32_e32 v69, v69, v73
	v_mul_f32_e32 v201, v71, v70
	ds_read_b128 v[70:73], v127 offset:59136
	v_fmac_f32_e32 v66, v67, v196
	v_lshlrev_b32_e32 v199, 16, v202
	v_mul_f32_e32 v66, v197, v66
	v_fmac_f32_e32 v66, v68, v199
	ds_bpermute_b32 v189, v102, v205
	ds_bpermute_b32 v190, v102, v205 offset:64
	ds_bpermute_b32 v193, v102, v205 offset:128
	ds_bpermute_b32 v194, v102, v205 offset:192
	v_mul_f32_e32 v67, v197, v201
	v_mul_f32_e32 v205, v198, v66
	v_mul_f32_e32 v204, v198, v67
	v_fmac_f32_e32 v205, v69, v200
	ds_read_b128 v[66:69], v127 offset:59200
	s_waitcnt lgkmcnt(5)
; template <int DIR, int MODE>
; __device__ __forceinline__ void lru_pass(const Args& a, const LAS bf16_t* cxb, LAS bf16_t* gyb, const LAS float* carry, const bf16x8 (&Bw)[2][2][2], const float (&prm)[2][3], int l, int tt, float (&hf)[8][2][4]) {
;     ...
;     for (int mi = 0; mi < 8; ++mi) {
;         const int m = DIR ? 7 - mi : mi;
;         bf16x8 Af[2];
; #pragma unroll
;         for (int ks = 0; ks < 2; ++ks) Af[ks] = *(const LAS bf16x8*)(cxb + (m * 16 + fr) * CXS + 64 * h + 32 * ks + 8 * fq);
; #pragma unroll
;         for (int nt = 0; nt < 2; ++nt) {
;             f32x4 pr = (f32x4){0.f, 0.f, 0.f, 0.f}, pi = (f32x4){0.f, 0.f, 0.f, 0.f};
; #pragma unroll
;             for (int ks = 0; ks < 2; ++ks) { pr = __builtin_amdgcn_mfma_f32_16x16x32_bf16(Af[ks], Bw[0][nt][ks], pr, 0, 0, 0); pi = __builtin_amdgcn_mfma_f32_16x16x32_bf16(Af[ks], Bw[1][nt][ks], pi, 0, 0, 0); }
;             float av[4], bv[4];
; #pragma unroll
;             for (int reg = 0; reg < 4; ++reg) {
;                 const int tok = m * 16 + 4 * fq + reg;
;                 const float x = bf2f(cxb[tok * CXS + cc[nt]]);
;                 const float r = fsig(pr[reg] + ba[nt]), ig = fsig(pi[reg] + bxv[nt]);
;                 const float aa = __expf(k8[nt] * r);
;                 av[reg] = aa; bv[reg] = __builtin_amdgcn_sqrtf(fmaxf(1.0f - aa * aa, 0.f)) * ig * x;
;             }
;             float cum[4], hl[4];
;             if (DIR == 0) { cum[0] = av[0]; hl[0] = bv[0];
; #pragma unroll
;                 for (int reg = 1; reg < 4; ++reg) { cum[reg] = cum[reg - 1] * av[reg]; hl[reg] = av[reg] * hl[reg - 1] + bv[reg]; } }
;             else { cum[3] = av[3]; hl[3] = bv[3];
; #pragma unroll
;     ...
;             const float A4 = DIR ? cum[0] : cum[3], H4 = DIR ? hl[0] : hl[3];
;             float Aq[4], Hq[4];
; #pragma unroll
;             for (int q = 0; q < 4; ++q) { Aq[q] = __shfl(A4, fr + 16 * q); Hq[q] = __shfl(H4, fr + 16 * q); }
;             float hin;
;             if (DIR == 0) { const float s0 = C[nt], s1 = Aq[0] * s0 + Hq[0], s2 = Aq[1] * s1 + Hq[1], s3 = Aq[2] * s2 + Hq[2]; C[nt] = Aq[3] * s3 + Hq[3]; hin = fq == 0 ? s0 : (fq == 1 ? s1 : (fq == 2 ? s2 : s3)); }
;             else { const float s3 = C[nt], s2 = Aq[3] * s3 + Hq[3], s1 = Aq[2] * s2 + Hq[2], s0 = Aq[1] * s1 + Hq[1]; C[nt] = Aq[0] * s0 + Hq[0]; hin = fq == 3 ? s3 : (fq == 2 ? s2 : (fq == 1 ? s1 : s0)); }
	v_mfma_f32_16x16x32_bf16 v[196:199], v[70:73], v[54:57], 0
	ds_bpermute_b32 v89, v102, v91 offset:128
	ds_bpermute_b32 v91, v102, v91 offset:192
	ds_bpermute_b32 v98, v102, v97
	s_waitcnt lgkmcnt(3)
	v_mfma_f32_16x16x32_bf16 v[196:199], v[66:69], v[50:53], v[196:199]
	ds_bpermute_b32 v96, v102, v97 offset:64
	ds_bpermute_b32 v99, v102, v97 offset:128
	ds_bpermute_b32 v97, v102, v97 offset:192
	s_nop 4
	v_fma_f32 v50, v196, s98, v157
	s_nop 0
	v_exp_f32_e32 v51, v50
	v_mfma_f32_16x16x32_bf16 v[200:203], v[70:73], v[62:65], 0
	ds_bpermute_b32 v175, v102, v107
	ds_bpermute_b32 v174, v102, v179
	v_add_f32_e32 v51, 1.0, v51
	v_rcp_f32_e32 v51, v51
	v_mfma_f32_16x16x32_bf16 v[58:61], v[66:69], v[58:61], v[200:203]
	ds_read_u16 v64, v106 offset:59136
	ds_read_u16 v65, v106 offset:59664
	ds_read_u16 v127, v106 offset:60192
	ds_read_u16 v196, v106 offset:60720
	ds_read_u16 v200, v106 offset:60752
	ds_read_u16 v201, v106 offset:60224
	ds_read_u16 v202, v106 offset:59696
	ds_read_u16 v106, v106 offset:59168
	s_waitcnt lgkmcnt(7)
	v_lshlrev_b32_e32 v64, 16, v64
	v_mul_f32_e32 v51, v75, v51
	v_fma_f32 v52, v58, s98, v156
	s_nop 0
	s_nop 0
	v_exp_f32_e32 v53, v51
	v_exp_f32_e32 v52, v52
	v_fma_f32 v59, v59, s98, v156
	s_nop 0
	v_fma_f32 v58, -v53, v53, 1.0
	v_add_f32_e32 v52, 1.0, v52
	v_max_f32_e32 v58, 0, v58
	v_rcp_f32_e32 v52, v52
	v_sqrt_f32_e32 v58, v58
	v_exp_f32_e32 v59, v59
	v_fma_f32 v60, v60, s98, v156
	s_nop 0
	v_mul_f32_e32 v52, v52, v58
	v_fma_f32 v58, v197, s98, v157
	s_nop 0
	v_exp_f32_e32 v58, v58
	v_mul_f32_e32 v52, v52, v64
	v_fma_f32 v64, v198, s98, v157
	s_nop 0
	v_add_f32_e32 v58, 1.0, v58
	v_rcp_f32_e32 v58, v58
	v_fma_f32 v157, v199, s98, v157
	v_exp_f32_e32 v64, v64
	s_nop 0
	v_exp_f32_e32 v157, v157
	v_mul_f32_e32 v58, v75, v58
	s_nop 0
	v_add_f32_e32 v64, 1.0, v64
	v_exp_f32_e32 v58, v58
	v_rcp_f32_e32 v64, v64
	v_add_f32_e32 v157, 1.0, v157
	v_rcp_f32_e32 v157, v157
	v_fma_f32 v197, -v58, v58, 1.0
	v_mul_f32_e32 v64, v75, v64
	v_add_f32_e32 v59, 1.0, v59
	v_max_f32_e32 v197, 0, v197
	s_nop 0
	v_mul_f32_e32 v75, v75, v157
	v_rcp_f32_e32 v59, v59
	v_sqrt_f32_e32 v197, v197
	v_exp_f32_e32 v64, v64
	v_fma_f32 v61, v61, s98, v156
	s_nop 0
	v_exp_f32_e32 v60, v60
	s_nop 0
	v_exp_f32_e32 v75, v75
	v_exp_f32_e32 v61, v61
	v_mul_f32_e32 v59, v59, v197
	v_fma_f32 v197, -v64, v64, 1.0
	v_add_f32_e32 v60, 1.0, v60
	v_max_f32_e32 v197, 0, v197
	v_fma_f32 v157, -v75, v75, 1.0
	v_rcp_f32_e32 v60, v60
	v_sqrt_f32_e32 v156, v197
	v_add_f32_e32 v61, 1.0, v61
	v_max_f32_e32 v157, 0, v157
	v_rcp_f32_e32 v61, v61
	v_sqrt_f32_e32 v157, v157
	s_waitcnt lgkmcnt(6)
	v_lshlrev_b32_e32 v65, 16, v65
	v_mul_f32_e32 v52, v58, v52
	v_fmac_f32_e32 v52, v59, v65
	s_waitcnt lgkmcnt(5)
	v_lshlrev_b32_e32 v127, 16, v127
	v_mul_f32_e32 v60, v60, v156
	v_mul_f32_e32 v52, v64, v52
	v_mul_f32_e32 v157, v61, v157
	v_mul_f32_e32 v53, v58, v53
	v_fmac_f32_e32 v52, v60, v127
	v_mfma_f32_16x16x32_bf16 v[58:61], v[70:73], v[38:41], 0
	s_waitcnt lgkmcnt(4)
	v_lshlrev_b32_e32 v156, 16, v196
	v_mul_f32_e32 v38, v75, v52
	v_fmac_f32_e32 v38, v157, v156
	v_mfma_f32_16x16x32_bf16 v[58:61], v[66:69], v[34:37], v[58:61]
	v_mul_f32_e32 v53, v64, v53
	v_mul_f32_e32 v53, v75, v53
	ds_bpermute_b32 v39, v102, v53
	v_mfma_f32_16x16x32_bf16 v[70:73], v[70:73], v[46:49], 0
	ds_bpermute_b32 v46, v102, v38
	s_nop 2
	v_fma_f32 v34, v58, s98, v155
	s_nop 0
	v_exp_f32_e32 v34, v34
	v_mfma_f32_16x16x32_bf16 v[40:43], v[66:69], v[42:45], v[70:73]
	ds_bpermute_b32 v47, v102, v38 offset:64
	ds_bpermute_b32 v49, v102, v38 offset:128
	v_add_f32_e32 v34, 1.0, v34
	v_rcp_f32_e32 v34, v34
	ds_bpermute_b32 v45, v102, v38 offset:192
	s_nop 2
	v_fma_f32 v36, v40, s98, v154
	s_nop 0
	v_mul_f32_e32 v34, v104, v34
	s_nop 0
	v_exp_f32_e32 v34, v34
	v_exp_f32_e32 v36, v36
	v_fma_f32 v41, v41, s98, v154
	s_nop 0
	v_fma_f32 v37, -v34, v34, 1.0
	v_add_f32_e32 v36, 1.0, v36
	v_max_f32_e32 v37, 0, v37
	v_rcp_f32_e32 v36, v36
	v_sqrt_f32_e32 v40, v37
	v_exp_f32_e32 v41, v41
	s_waitcnt lgkmcnt(5)
	v_lshlrev_b32_e32 v38, 16, v106
	v_fma_f32 v42, v42, s98, v154
	v_mul_f32_e32 v36, v36, v40
	v_fma_f32 v40, v59, s98, v155
	s_nop 0
	v_exp_f32_e32 v40, v40
	v_mul_f32_e32 v36, v36, v38
	v_add_f32_e32 v38, 1.0, v41
	v_rcp_f32_e32 v38, v38
	v_add_f32_e32 v40, 1.0, v40
	v_rcp_f32_e32 v40, v40
	v_fma_f32 v41, v60, s98, v155
	s_nop 0
	v_exp_f32_e32 v41, v41
	v_mul_f32_e32 v40, v104, v40
	s_nop 0
	v_exp_f32_e32 v40, v40
	v_add_f32_e32 v41, 1.0, v41
	v_rcp_f32_e32 v41, v41
	s_nop 0
	v_fma_f32 v44, -v40, v40, 1.0
	v_max_f32_e32 v44, 0, v44
	v_sqrt_f32_e32 v44, v44
	v_mul_f32_e32 v41, v104, v41
	s_nop 0
	v_exp_f32_e32 v41, v41
	v_mul_f32_e32 v38, v38, v44
	v_fma_f32 v44, v61, s98, v155
	s_nop 0
	v_exp_f32_e32 v44, v44
	v_exp_f32_e32 v42, v42
	v_fma_f32 v43, v43, s98, v154
	s_nop 0
	v_add_f32_e32 v44, 1.0, v44
	v_rcp_f32_e32 v44, v44
	v_exp_f32_e32 v43, v43
	ds_bpermute_b32 v48, v102, v53 offset:64
	ds_bpermute_b32 v35, v102, v53 offset:128
	v_mul_f32_e32 v44, v104, v44
	s_nop 0
	v_exp_f32_e32 v44, v44
	ds_bpermute_b32 v37, v102, v53 offset:192
	v_fma_f32 v53, -v41, v41, 1.0
	v_add_f32_e32 v42, 1.0, v42
	v_max_f32_e32 v53, 0, v53
	v_rcp_f32_e32 v42, v42
	v_sqrt_f32_e32 v53, v53
	v_fma_f32 v58, -v44, v44, 1.0
	v_add_f32_e32 v43, 1.0, v43
	v_max_f32_e32 v58, 0, v58
	v_lshlrev_b32_e32 v52, 16, v202
	v_rcp_f32_e32 v43, v43
	v_sqrt_f32_e32 v58, v58
	v_mul_f32_e32 v36, v40, v36
	v_fmac_f32_e32 v36, v38, v52
	v_lshlrev_b32_e32 v59, 16, v201
	v_mul_f32_e32 v42, v42, v53
	v_mul_f32_e32 v36, v41, v36
	v_mul_f32_e32 v34, v40, v34
	v_fmac_f32_e32 v36, v42, v59
	v_lshlrev_b32_e32 v53, 16, v200
	v_mul_f32_e32 v43, v43, v58
	v_mul_f32_e32 v34, v41, v34
; #define LAS __attribute__((address_space(3)))
; __device__ __forceinline__ unsigned f2bf(float f) { unsigned u = __builtin_bit_cast(unsigned, f); return (u + 0x7fffu + ((u >> 16) & 1u)) >> 16; }
; __device__ __forceinline__ float fgelu(float x) { const float u = 0.7978845608028654f * (x + 0.044715f * x * x * x); return 0.5f * x * (2.0f - 2.0f * frcp(__expf(2.0f * u) + 1.0f)); }
; template <int DIR, int MODE>
; __device__ __forceinline__ void lru_pass(const Args& a, const LAS bf16_t* cxb, LAS bf16_t* gyb, const LAS float* carry, const bf16x8 (&Bw)[2][2][2], const float (&prm)[2][3], int l, int tt, float (&hf)[8][2][4]) {
;     ...
;             for (int q = 0; q < 4; ++q) { Aq[q] = __shfl(A4, fr + 16 * q); Hq[q] = __shfl(H4, fr + 16 * q); }
;             float hin;
;             if (DIR == 0) { const float s0 = C[nt], s1 = Aq[0] * s0 + Hq[0], s2 = Aq[1] * s1 + Hq[1], s3 = Aq[2] * s2 + Hq[2]; C[nt] = Aq[3] * s3 + Hq[3]; hin = fq == 0 ? s0 : (fq == 1 ? s1 : (fq == 2 ? s2 : s3)); }
;             else { const float s3 = C[nt], s2 = Aq[3] * s3 + Hq[3], s1 = Aq[2] * s2 + Hq[2], s0 = Aq[1] * s1 + Hq[1]; C[nt] = Aq[0] * s0 + Hq[0]; hin = fq == 3 ? s3 : (fq == 2 ? s2 : (fq == 1 ? s1 : s0)); }
;             if (MODE == 0) At[nt] *= (Aq[0] * Aq[1]) * (Aq[2] * Aq[3]);
;             else {
; #pragma unroll
;                 for (int reg = 0; reg < 4; ++reg) {
;                     const float hv = hl[reg] + cum[reg] * hin;
;                     if (DIR == 0) hf[m][nt][reg] = hv;
;                     else { LAS bf16_t* gp = gyb + (m * 16 + 4 * fq + reg) * CXS + cc[nt];
;                         const float g = bf2f(*gp);
;                         *gp = (bf16_t)f2bf((hf[m][nt][reg] + hv) * fgelu(g)); }
;                 }
;             }
;         }
;     }
;     if (MODE == 0 && fq == 0) {
; #pragma unroll
;         for (int nt = 0; nt < 2; ++nt) { f32x2 sm; sm[0] = At[nt]; sm[1] = C[nt]; *(f32x2*)(SUM + ((size_t)(tt * 2 + DIR) * 256 + cc[nt]) * 2) = sm; }
;     }
	v_mul_f32_e32 v40, v44, v36
	v_mul_f32_e32 v38, v44, v34
	v_fmac_f32_e32 v40, v43, v53
	ds_bpermute_b32 v176, v102, v107 offset:64
	ds_bpermute_b32 v177, v102, v179 offset:64
	ds_bpermute_b32 v105, v102, v107 offset:128
	ds_bpermute_b32 v178, v102, v179 offset:128
	ds_bpermute_b32 v107, v102, v107 offset:192
	ds_bpermute_b32 v179, v102, v179 offset:192
	ds_bpermute_b32 v114, v102, v113
	ds_bpermute_b32 v184, v102, v187
	ds_bpermute_b32 v112, v102, v113 offset:64
	ds_bpermute_b32 v185, v102, v187 offset:64
	ds_bpermute_b32 v115, v102, v113 offset:128
	ds_bpermute_b32 v186, v102, v187 offset:128
	ds_bpermute_b32 v113, v102, v113 offset:192
	ds_bpermute_b32 v187, v102, v187 offset:192
	ds_bpermute_b32 v55, v102, v204
	ds_bpermute_b32 v54, v102, v205
	ds_bpermute_b32 v56, v102, v204 offset:64
	ds_bpermute_b32 v57, v102, v205 offset:64
	ds_bpermute_b32 v63, v102, v204 offset:128
	ds_bpermute_b32 v62, v102, v205 offset:128
	ds_bpermute_b32 v50, v102, v204 offset:192
	ds_bpermute_b32 v51, v102, v205 offset:192
	ds_bpermute_b32 v58, v102, v38
	ds_bpermute_b32 v34, v102, v40
	ds_bpermute_b32 v59, v102, v38 offset:64
	ds_bpermute_b32 v36, v102, v40 offset:64
	ds_bpermute_b32 v43, v102, v38 offset:128
	ds_bpermute_b32 v53, v102, v40 offset:128
	ds_bpermute_b32 v41, v102, v38 offset:192
	ds_bpermute_b32 v52, v102, v40 offset:192
	v_add_f32_e32 v44, 1.0, v117
	v_frexp_mant_f32_e32 v38, v44
	v_cmp_gt_f32_e64 s[0:1], s28, v38
	s_and_saveexec_b64 s[4:5], s[36:37]
	s_cbranch_execz .LBB0_773
	v_fmac_f32_e32 v123, 0, v86
	v_fmac_f32_e32 v124, v123, v84
	v_fmac_f32_e32 v125, v124, v88
	v_fmac_f32_e32 v126, v125, v90
	v_fmac_f32_e32 v132, v126, v87
	v_fmac_f32_e32 v133, v132, v85
	v_fmac_f32_e32 v134, v133, v89
	v_fmac_f32_e32 v135, v134, v91
	v_fmac_f32_e32 v140, v135, v98
	v_fmac_f32_e32 v119, 0, v76
	v_fmac_f32_e32 v141, v140, v96
	v_fmac_f32_e32 v120, v119, v78
	v_fmac_f32_e32 v142, v141, v99
	v_fmac_f32_e32 v121, v120, v80
	v_fmac_f32_e32 v143, v142, v97
	v_fmac_f32_e32 v122, v121, v82
	v_fmac_f32_e32 v160, v143, v161
	v_fmac_f32_e32 v128, v122, v77
	v_fmac_f32_e32 v163, v160, v162
	v_fmac_f32_e32 v129, v128, v79
	v_fmac_f32_e32 v164, v163, v165
	v_fmac_f32_e32 v130, v129, v81
	v_fmac_f32_e32 v167, v164, v166
	v_fmac_f32_e32 v131, v130, v83
	v_fmac_f32_e32 v174, v167, v175
	v_fmac_f32_e32 v136, v131, v92
	s_waitcnt lgkmcnt(14)
	v_fmac_f32_e32 v177, v174, v176
	v_fmac_f32_e32 v137, v136, v94
	v_fmac_f32_e32 v178, v177, v105
	v_fmac_f32_e32 v138, v137, v93
	v_fmac_f32_e32 v179, v178, v107
	v_fmac_f32_e32 v139, v138, v95
	v_fmac_f32_e32 v184, v179, v114
	v_fmac_f32_e32 v145, v139, v144
	v_fmac_f32_e32 v185, v184, v112
	v_fmac_f32_e32 v146, v145, v147
	v_fmac_f32_e32 v186, v185, v115
	v_fmac_f32_e32 v149, v146, v148
	v_fmac_f32_e32 v187, v186, v113
	v_fmac_f32_e32 v158, v149, v159
	v_fmac_f32_e32 v54, v187, v55
	v_fmac_f32_e32 v169, v158, v168
	s_waitcnt lgkmcnt(12)
	v_fmac_f32_e32 v57, v54, v56
	v_fmac_f32_e32 v170, v169, v171
	v_pk_mul_f32 v[66:67], v[86:87], v[84:85]
	v_pk_mul_f32 v[68:69], v[88:89], v[90:91]
	s_waitcnt lgkmcnt(10)
	v_fmac_f32_e32 v62, v57, v63
	v_fmac_f32_e32 v172, v170, v101
	v_pk_mul_f32 v[64:65], v[98:99], v[96:97]
	v_pk_mul_f32 v[66:67], v[66:67], v[68:69]
	s_waitcnt lgkmcnt(8)
	v_fmac_f32_e32 v51, v62, v50
	v_fmac_f32_e32 v173, v172, v103
	v_pk_mul_f32 v[66:67], v[66:67], v[66:67] op_sel:[0,1] op_sel_hi:[1,0]
	v_pk_mul_f32 v[64:65], v[64:65], v[64:65] op_sel:[0,1] op_sel_hi:[1,0]
	s_waitcnt lgkmcnt(6)
	v_fmac_f32_e32 v34, v51, v58
	v_fmac_f32_e32 v180, v173, v108
	v_mul_f32_e32 v42, v55, v56
	v_mul_f32_e32 v40, v63, v50
	v_mov_b32_e32 v67, v175
	v_mov_b32_e32 v65, v176
	s_waitcnt lgkmcnt(4)
	v_fmac_f32_e32 v36, v34, v59
	v_pk_mul_f32 v[50:51], v[76:77], v[78:79]
	v_pk_mul_f32 v[54:55], v[80:81], v[82:83]
	v_fmac_f32_e32 v181, v180, v110
	v_pk_mul_f32 v[64:65], v[66:67], v[64:65]
	s_waitcnt lgkmcnt(1)
	v_pk_mul_f32 v[66:67], v[42:43], v[40:41]
	v_fmac_f32_e32 v53, v36, v43
	v_pk_mul_f32 v[42:43], v[92:93], v[94:95]
	v_pk_mul_f32 v[50:51], v[50:51], v[54:55]
	v_fmac_f32_e32 v182, v181, v109
	v_pk_mul_f32 v[50:51], v[50:51], v[50:51] op_sel:[0,1] op_sel_hi:[1,0]
	v_pk_mul_f32 v[42:43], v[42:43], v[42:43] op_sel:[0,1] op_sel_hi:[1,0]
	v_fmac_f32_e32 v183, v182, v111
	v_mul_f32_e32 v100, v144, v147
	v_mul_f32_e32 v102, v148, v159
	v_mov_b32_e32 v51, v168
	v_mov_b32_e32 v43, v171
	v_fmac_f32_e32 v189, v183, v188
	v_pk_mul_f32 v[54:55], v[100:101], v[102:103]
	v_pk_mul_f32 v[42:43], v[50:51], v[42:43]
	v_fmac_f32_e32 v190, v189, v191
	v_mul_f32_e32 v104, v161, v162
	v_mul_f32_e32 v106, v165, v166
	s_waitcnt lgkmcnt(0)
	v_fmac_f32_e32 v52, v53, v41
	v_pk_mul_f32 v[40:41], v[108:109], v[110:111]
	v_pk_mul_f32 v[42:43], v[42:43], v[54:55]
	v_fmac_f32_e32 v193, v190, v192
	v_pk_mul_f32 v[68:69], v[104:105], v[106:107]
	v_pk_mul_f32 v[42:43], v[42:43], v[42:43] op_sel:[0,1] op_sel_hi:[1,0]
	v_pk_mul_f32 v[40:41], v[40:41], v[40:41] op_sel:[0,1] op_sel_hi:[1,0]
	v_fmac_f32_e32 v194, v193, v195
	s_lshl_b32 s34, s82, 1
	v_pk_mul_f32 v[60:61], v[114:115], v[112:113]
	v_pk_mul_f32 v[64:65], v[64:65], v[68:69]
	v_mul_f32_e32 v34, v188, v191
	v_mul_f32_e32 v36, v192, v195
	v_mov_b32_e32 v43, v39
	v_mov_b32_e32 v41, v48
	v_fmac_f32_e32 v46, v194, v39
	s_ashr_i32 s35, s34, 31
	v_pk_mul_f32 v[64:65], v[64:65], v[64:65] op_sel:[0,1] op_sel_hi:[1,0]
	v_pk_mul_f32 v[60:61], v[60:61], v[60:61] op_sel:[0,1] op_sel_hi:[1,0]
	v_pk_mul_f32 v[50:51], v[34:35], v[36:37]
	v_pk_mul_f32 v[40:41], v[42:43], v[40:41]
	v_fmac_f32_e32 v47, v46, v48
	s_lshl_b64 s[34:35], s[34:35], 11
	v_readlane_b32 s28, v253, 43
	v_mov_b32_e32 v65, v58
	v_mov_b32_e32 v61, v59
	v_pk_mul_f32 v[40:41], v[40:41], v[50:51]
	v_fmac_f32_e32 v49, v47, v35
	v_readlane_b32 s29, v253, 44
	s_add_u32 s34, s28, s34
	v_pk_mul_f32 v[60:61], v[64:65], v[60:61]
	v_fmac_f32_e32 v45, v49, v37
	s_addc_u32 s35, s29, s35
	v_pk_mul_f32 v[34:35], v[40:41], v[40:41] op_sel:[0,1] op_sel_hi:[1,0]
	v_ashrrev_i32_e32 v75, 31, v74
	v_or_b32_e32 v38, 16, v74
	v_pk_mul_f32 v[60:61], v[60:61], v[66:67]
	v_mov_b32_e32 v35, v45
	v_lshl_add_u64 v[36:37], v[74:75], 3, s[34:35]
	global_store_dwordx2 v[36:37], v[34:35], off
	v_pk_mul_f32 v[34:35], v[60:61], v[60:61] op_sel:[0,1] op_sel_hi:[1,0]
	v_ashrrev_i32_e32 v39, 31, v38
	v_mov_b32_e32 v35, v52
	v_lshl_add_u64 v[36:37], v[38:39], 3, s[34:35]
	global_store_dwordx2 v[36:37], v[34:35], off
; template <int MODE>
; __device__ __forceinline__ void lru_unit(const Args& a, LAS unsigned char* lds, int l, int tt) {
;     ...
;     for (int nt = 0; nt < 2; ++nt) { prm0[nt][2] = -8.0f * log1pf(__expf(-prm0[nt][2])); prm1[nt][2] = -8.0f * log1pf(__expf(-prm1[nt][2])); }
.LBB0_773:
	s_or_b64 exec, exec, s[4:5]
	s_waitcnt lgkmcnt(6)
	v_add_f32_e32 v34, -1.0, v118
	v_sub_f32_e32 v35, v34, v118
	v_add_f32_e32 v35, 1.0, v35
	v_sub_f32_e32 v34, v116, v34
	s_waitcnt lgkmcnt(4)
	v_add_f32_e32 v36, v34, v35
	v_cvt_f64_f32_e32 v[34:35], v118
	v_frexp_exp_i32_f64_e32 v34, v[34:35]
	v_subbrev_co_u32_e32 v34, vcc, 0, v34, vcc
	v_sub_u32_e32 v35, 0, v34
	v_ldexp_f32 v37, v118, v35
	v_ldexp_f32 v35, v36, v35
	v_add_f32_e32 v36, -1.0, v37
	v_add_f32_e32 v40, 1.0, v37
	v_add_f32_e32 v38, 1.0, v36
	s_waitcnt lgkmcnt(1)
	v_add_f32_e32 v41, -1.0, v40
	v_sub_f32_e32 v38, v37, v38
	v_sub_f32_e32 v37, v37, v41
	v_add_f32_e32 v38, v35, v38
	v_add_f32_e32 v35, v35, v37
	v_add_f32_e32 v37, v40, v35
	v_rcp_f32_e32 v41, v37
	v_add_f32_e32 v39, v36, v38
	v_sub_f32_e32 v36, v39, v36
	v_sub_f32_e32 v36, v38, v36
	v_sub_f32_e32 v38, v37, v40
	v_sub_f32_e32 v35, v35, v38
	v_mul_f32_e32 v38, v39, v41
	v_mul_f32_e32 v40, v37, v38
	v_fma_f32 v42, v38, v37, -v40
	v_fmac_f32_e32 v42, v38, v35
	v_add_f32_e32 v43, v40, v42
	v_sub_f32_e32 v45, v39, v43
	v_sub_f32_e32 v39, v39, v45
	v_sub_f32_e32 v40, v43, v40
	v_sub_f32_e32 v39, v39, v43
	v_add_f32_e32 v36, v36, v39
	v_sub_f32_e32 v39, v40, v42
	v_add_f32_e32 v36, v39, v36
	v_add_f32_e32 v39, v45, v36
	v_mul_f32_e32 v40, v41, v39
	v_mul_f32_e32 v42, v37, v40
	v_fma_f32 v37, v40, v37, -v42
	v_fmac_f32_e32 v37, v40, v35
	v_sub_f32_e32 v35, v45, v39
	v_add_f32_e32 v35, v36, v35
	v_add_f32_e32 v36, v42, v37
	v_sub_f32_e32 v43, v39, v36
	v_sub_f32_e32 v39, v39, v43
	v_sub_f32_e32 v42, v36, v42
	v_sub_f32_e32 v36, v39, v36
	v_add_f32_e32 v35, v35, v36
	v_sub_f32_e32 v36, v42, v37
	v_cvt_f32_i32_e32 v34, v34
	v_add_f32_e32 v35, v36, v35
	v_add_f32_e32 v36, v38, v40
	v_add_f32_e32 v35, v43, v35
	v_sub_f32_e32 v37, v36, v38
	v_mul_f32_e32 v35, v41, v35
	v_sub_f32_e32 v37, v40, v37
	v_add_f32_e32 v35, v37, v35
	v_mul_f32_e32 v40, 0x3f317218, v34
	s_mov_b32 s4, 0x3f317218
	v_add_f32_e32 v37, v36, v35
	v_fma_f32 v41, v34, s4, -v40
	v_fmac_f32_e32 v41, 0xb102e308, v34
	v_sub_f32_e32 v34, v37, v36
	v_sub_f32_e32 v34, v35, v34
	v_ldexp_f32 v42, v34, 1
	v_add_f32_e32 v34, -1.0, v44
	v_sub_f32_e32 v35, v34, v44
	v_add_f32_e32 v35, 1.0, v35
	v_sub_f32_e32 v34, v117, v34
	v_add_f32_e32 v45, v34, v35
	v_cvt_f64_f32_e32 v[34:35], v44
	v_frexp_exp_i32_f64_e32 v34, v[34:35]
	v_subbrev_co_u32_e64 v34, vcc, 0, v34, s[0:1]
	v_sub_u32_e32 v35, 0, v34
	v_ldexp_f32 v44, v44, v35
	v_ldexp_f32 v35, v45, v35
	v_add_f32_e32 v45, -1.0, v44
	v_add_f32_e32 v48, 1.0, v44
	v_add_f32_e32 v46, 1.0, v45
	v_add_f32_e32 v49, -1.0, v48
	v_sub_f32_e32 v46, v44, v46
	v_sub_f32_e32 v44, v44, v49
	v_add_f32_e32 v46, v35, v46
	v_add_f32_e32 v35, v35, v44
	v_add_f32_e32 v44, v48, v35
	v_rcp_f32_e32 v49, v44
	v_add_f32_e32 v47, v45, v46
	v_sub_f32_e32 v45, v47, v45
	v_sub_f32_e32 v45, v46, v45
	v_sub_f32_e32 v46, v44, v48
	v_sub_f32_e32 v35, v35, v46
	v_mul_f32_e32 v46, v47, v49
	v_mul_f32_e32 v48, v44, v46
	v_fma_f32 v50, v46, v44, -v48
	v_fmac_f32_e32 v50, v46, v35
	v_add_f32_e32 v51, v48, v50
	s_waitcnt lgkmcnt(0)
	v_sub_f32_e32 v52, v47, v51
	v_sub_f32_e32 v47, v47, v52
	v_sub_f32_e32 v48, v51, v48
	v_sub_f32_e32 v47, v47, v51
	v_add_f32_e32 v45, v45, v47
	v_sub_f32_e32 v47, v48, v50
	v_mul_f32_e32 v38, v37, v37
	v_mov_b32_e32 v53, 0x3ecc95a3
	v_add_f32_e32 v45, v47, v45
	v_fmamk_f32 v39, v38, 0x3e9b6dac, v53
	v_add_f32_e32 v47, v52, v45
	v_fmaak_f32 v39, v38, v39, 0x3f2aaada
	v_ldexp_f32 v36, v37, 1
	v_mul_f32_e32 v48, v49, v47
	v_mul_f32_e32 v37, v37, v38
	v_mul_f32_e32 v50, v44, v48
	v_mul_f32_e32 v37, v37, v39
	v_fma_f32 v44, v48, v44, -v50
	v_add_f32_e32 v38, v36, v37
	v_fmac_f32_e32 v44, v48, v35
	v_sub_f32_e32 v35, v52, v47
	v_sub_f32_e32 v36, v38, v36
	v_add_f32_e32 v35, v45, v35
	v_add_f32_e32 v45, v50, v44
	v_sub_f32_e32 v36, v37, v36
	v_sub_f32_e32 v51, v47, v45
	v_add_f32_e32 v36, v42, v36
	v_sub_f32_e32 v50, v45, v50
	v_sub_f32_e32 v47, v47, v51
	v_add_f32_e32 v37, v38, v36
	v_sub_f32_e32 v45, v47, v45
	v_sub_f32_e32 v44, v50, v44
	v_add_f32_e32 v50, v40, v41
	v_sub_f32_e32 v38, v37, v38
	v_add_f32_e32 v35, v35, v45
	v_sub_f32_e32 v36, v36, v38
	v_add_f32_e32 v38, v50, v37
	v_add_f32_e32 v35, v44, v35
	v_add_f32_e32 v44, v46, v48
	v_sub_f32_e32 v40, v50, v40
	v_sub_f32_e32 v39, v38, v50
	v_add_f32_e32 v35, v51, v35
	v_sub_f32_e32 v45, v44, v46
	v_cvt_f32_i32_e32 v34, v34
	v_sub_f32_e32 v40, v41, v40
	v_sub_f32_e32 v41, v38, v39
	v_mul_f32_e32 v35, v49, v35
	v_sub_f32_e32 v45, v48, v45
	v_sub_f32_e32 v41, v50, v41
	v_sub_f32_e32 v37, v37, v39
	v_add_f32_e32 v35, v45, v35
	v_add_f32_e32 v37, v37, v41
	v_add_f32_e32 v39, v40, v36
	v_add_f32_e32 v45, v44, v35
	v_sub_f32_e32 v41, v39, v40
	v_add_f32_e32 v37, v39, v37
	v_mul_f32_e32 v46, v45, v45
	v_mul_f32_e32 v48, 0x3f317218, v34
	v_sub_f32_e32 v42, v39, v41
	v_add_f32_e32 v39, v38, v37
	v_fmamk_f32 v47, v46, 0x3e9b6dac, v53
	v_fma_f32 v49, v34, s4, -v48
	v_sub_f32_e32 v40, v40, v42
	v_sub_f32_e32 v36, v36, v41
	v_sub_f32_e32 v38, v39, v38
	v_fmaak_f32 v47, v46, v47, 0x3f2aaada
	v_fmac_f32_e32 v49, 0xb102e308, v34
	v_sub_f32_e32 v34, v45, v44
	v_add_f32_e32 v36, v36, v40
	v_sub_f32_e32 v37, v37, v38
	v_mul_f32_e32 v38, v45, v46
	v_sub_f32_e32 v34, v35, v34
	v_ldexp_f32 v35, v45, 1
	v_add_f32_e32 v36, v36, v37
	s_mov_b32 s5, 0x7f800000
	v_mul_f32_e32 v38, v38, v47
	v_add_f32_e32 v36, v39, v36
	v_cmp_neq_f32_e32 vcc, s5, v116
	v_mov_b32_e32 v41, 0x7f800000
	v_add_f32_e32 v39, v35, v38
	v_cndmask_b32_e32 v36, v41, v36, vcc
	v_cmp_ngt_f32_e32 vcc, -1.0, v116
	v_mov_b32_e32 v42, 0x7fc00000
	v_sub_f32_e32 v35, v39, v35
	v_and_b32_e32 v43, 0x7fffffff, v116
	v_ldexp_f32 v34, v34, 1
; template <int DIR, int MODE>
; __device__ __forceinline__ void lru_pass(const Args& a, const LAS bf16_t* cxb, LAS bf16_t* gyb, const LAS float* carry, const bf16x8 (&Bw)[2][2][2], const float (&prm)[2][3], int l, int tt, float (&hf)[8][2][4]) {
;     ...
;     for (int mi = 0; mi < 8; ++mi) {
;         const int m = DIR ? 7 - mi : mi;
;         bf16x8 Af[2];
; #pragma unroll
;         for (int ks = 0; ks < 2; ++ks) Af[ks] = *(const LAS bf16x8*)(cxb + (m * 16 + fr) * CXS + 64 * h + 32 * ks + 8 * fq);
; #pragma unroll
;         for (int nt = 0; nt < 2; ++nt) {
;             f32x4 pr = (f32x4){0.f, 0.f, 0.f, 0.f}, pi = (f32x4){0.f, 0.f, 0.f, 0.f};
; #pragma unroll
;             for (int ks = 0; ks < 2; ++ks) { pr = __builtin_amdgcn_mfma_f32_16x16x32_bf16(Af[ks], Bw[0][nt][ks], pr, 0, 0, 0); pi = __builtin_amdgcn_mfma_f32_16x16x32_bf16(Af[ks], Bw[1][nt][ks], pi, 0, 0, 0); }
;             float av[4], bv[4];
; #pragma unroll
;             for (int reg = 0; reg < 4; ++reg) {
;                 const int tok = m * 16 + 4 * fq + reg;
;                 const float x = bf2f(cxb[tok * CXS + cc[nt]]);
;                 const float r = fsig(pr[reg] + ba[nt]), ig = fsig(pi[reg] + bxv[nt]);
;                 const float aa = __expf(k8[nt] * r);
;                 av[reg] = aa; bv[reg] = __builtin_amdgcn_sqrtf(fmaxf(1.0f - aa * aa, 0.f)) * ig * x;
;             }
;             float cum[4], hl[4];
;             if (DIR == 0) { cum[0] = av[0]; hl[0] = bv[0];
; #pragma unroll
;                 for (int reg = 1; reg < 4; ++reg) { cum[reg] = cum[reg - 1] * av[reg]; hl[reg] = av[reg] * hl[reg - 1] + bv[reg]; } }
;             else { cum[3] = av[3]; hl[3] = bv[3];
; #pragma unroll
;     ...
;             const float A4 = DIR ? cum[0] : cum[3], H4 = DIR ? hl[0] : hl[3];
;             float Aq[4], Hq[4];
; #pragma unroll
;             for (int q = 0; q < 4; ++q) { Aq[q] = __shfl(A4, fr + 16 * q); Hq[q] = __shfl(H4, fr + 16 * q); }
;             float hin;
;             if (DIR == 0) { const float s0 = C[nt], s1 = Aq[0] * s0 + Hq[0], s2 = Aq[1] * s1 + Hq[1], s3 = Aq[2] * s2 + Hq[2]; C[nt] = Aq[3] * s3 + Hq[3]; hin = fq == 0 ? s0 : (fq == 1 ? s1 : (fq == 2 ? s2 : s3)); }
;             else { const float s3 = C[nt], s2 = Aq[3] * s3 + Hq[3], s1 = Aq[2] * s2 + Hq[2], s0 = Aq[1] * s1 + Hq[1]; C[nt] = Aq[0] * s0 + Hq[0]; hin = fq == 3 ? s3 : (fq == 2 ? s2 : (fq == 1 ? s1 : s0)); }
	v_cndmask_b32_e32 v36, v42, v36, vcc
	v_cmp_neq_f32_e32 vcc, -1.0, v116
	v_mov_b32_e32 v50, 0xff800000
	s_mov_b32 s28, 0x33800000
	v_sub_f32_e32 v35, v38, v35
	v_cndmask_b32_e32 v36, v50, v36, vcc
	v_cmp_gt_f32_e32 vcc, s28, v43
	v_add_f32_e32 v34, v34, v35
	v_add_f32_e32 v35, v39, v34
	v_cndmask_b32_e32 v36, v36, v116, vcc
	v_mul_f32_e32 v74, 0xc138aa3b, v36
	v_add_f32_e32 v36, v48, v49
	v_sub_f32_e32 v38, v35, v39
	v_sub_f32_e32 v34, v34, v38
	v_add_f32_e32 v38, v36, v35
	v_sub_f32_e32 v39, v38, v36
	v_sub_f32_e32 v37, v36, v48
	v_sub_f32_e32 v40, v38, v39
	v_sub_f32_e32 v37, v49, v37
	v_sub_f32_e32 v36, v36, v40
	v_sub_f32_e32 v35, v35, v39
	v_add_f32_e32 v35, v35, v36
	v_add_f32_e32 v36, v37, v34
	v_sub_f32_e32 v39, v36, v37
	v_sub_f32_e32 v40, v36, v39
	v_add_f32_e32 v35, v36, v35
	v_sub_f32_e32 v37, v37, v40
	v_sub_f32_e32 v34, v34, v39
	v_add_f32_e32 v36, v38, v35
	v_add_f32_e32 v34, v34, v37
	v_sub_f32_e32 v37, v36, v38
	v_sub_f32_e32 v35, v35, v37
	v_add_f32_e32 v34, v34, v35
	v_add_f32_e32 v38, v36, v34
	v_mov_b32_e32 v34, v0
	v_cmp_neq_f32_e32 vcc, s5, v117
	v_readfirstlane_b32 s0, v34
	s_bfe_u32 s1, s0, 0x20006
	v_and_b32_e32 v52, 15, v34
	v_bfe_u32 v43, v34, 4, 2
	s_lshl_b32 s4, s1, 7
	s_add_i32 s4, s4, 0
	v_lshlrev_b32_e32 v34, 4, v43
	v_mul_u32_u24_e32 v35, 0x210, v52
	v_add3_u32 v89, s4, v34, v35
	ds_read_b128 v[34:37], v89 offset:59136
	v_cndmask_b32_e32 v38, v41, v38, vcc
	v_cmp_ngt_f32_e32 vcc, -1.0, v117
	v_and_b32_e32 v44, 0x7fffffff, v117
	s_ashr_i32 s0, s0, 3
	v_cndmask_b32_e32 v38, v42, v38, vcc
	v_cmp_neq_f32_e32 vcc, -1.0, v117
	s_lshl_b32 s1, s1, 6
	s_andn2_b32 s0, s0, 31
	v_cndmask_b32_e32 v42, v50, v38, vcc
	ds_read_b128 v[38:41], v89 offset:59200
	v_cmp_gt_f32_e32 vcc, s28, v44
	s_waitcnt lgkmcnt(1)
	v_mfma_f32_16x16x32_bf16 v[44:47], v[34:37], v[26:29], 0
	s_add_i32 s1, s1, s0
	v_cndmask_b32_e32 v42, v42, v117, vcc
	v_and_b32_e32 v53, 64, v227
	s_waitcnt lgkmcnt(0)
	v_mfma_f32_16x16x32_bf16 v[44:47], v[38:41], v[18:21], v[44:47]
	v_mul_f32_e32 v72, 0xc138aa3b, v42
	v_or_b32_e32 v42, s1, v52
	v_or_b32_e32 v52, v52, v53
	s_nop 4
	v_fma_f32 v44, v44, s98, v153
	v_fma_f32 v45, v45, s98, v153
	s_nop 0
	s_nop 0
	v_exp_f32_e32 v44, v44
	v_exp_f32_e32 v45, v45
	v_mfma_f32_16x16x32_bf16 v[48:51], v[34:37], v[30:33], 0
	v_fma_f32 v46, v46, s98, v153
	v_add_f32_e32 v44, 1.0, v44
	v_add_f32_e32 v45, 1.0, v45
	v_fma_f32 v47, v47, s98, v153
	v_rcp_f32_e32 v44, v44
	v_rcp_f32_e32 v45, v45
	s_nop 0
	s_nop 0
	v_mfma_f32_16x16x32_bf16 v[48:51], v[38:41], v[22:25], v[48:51]
	v_exp_f32_e32 v46, v46
	v_exp_f32_e32 v47, v47
	v_mul_f32_e32 v44, v74, v44
	v_mul_f32_e32 v45, v74, v45
	s_nop 0
	s_nop 2
	v_fma_f32 v48, v48, s98, v152
	v_fma_f32 v49, v49, s98, v152
	s_nop 0
	v_add_f32_e32 v46, 1.0, v46
	v_add_f32_e32 v47, 1.0, v47
	s_nop 0
	v_exp_f32_e32 v44, v44
	s_nop 0
	v_exp_f32_e32 v45, v45
	v_rcp_f32_e32 v46, v46
	v_rcp_f32_e32 v47, v47
	v_exp_f32_e32 v48, v48
	v_exp_f32_e32 v49, v49
	v_lshlrev_b32_e32 v68, 2, v52
	v_lshlrev_b32_e32 v52, 1, v42
	v_mul_u32_u24_e32 v53, 0x840, v43
	v_add3_u32 v70, 0, v52, v53
	v_fma_f32 v53, -v44, v44, 1.0
	v_fma_f32 v55, -v45, v45, 1.0
	v_mul_f32_e32 v46, v74, v46
	v_mul_f32_e32 v47, v74, v47
	ds_read_u16 v52, v70 offset:59136
	ds_read_u16 v54, v70 offset:59664
	v_add_f32_e32 v48, 1.0, v48
	v_max_f32_e32 v53, 0, v53
	v_add_f32_e32 v49, 1.0, v49
	v_max_f32_e32 v55, 0, v55
	v_fma_f32 v50, v50, s98, v152
	s_nop 0
	v_fma_f32 v51, v51, s98, v152
	s_nop 0
	v_rcp_f32_e32 v48, v48
	v_sqrt_f32_e32 v53, v53
	v_rcp_f32_e32 v49, v49
	v_sqrt_f32_e32 v55, v55
	s_nop 0
	v_exp_f32_e32 v46, v46
	s_nop 0
	v_exp_f32_e32 v47, v47
	v_exp_f32_e32 v50, v50
	v_exp_f32_e32 v51, v51
	v_mul_f32_e32 v48, v48, v53
	v_mul_f32_e32 v49, v49, v55
	ds_read_u16 v53, v70 offset:60192
	ds_read_u16 v55, v70 offset:60720
	s_waitcnt lgkmcnt(3)
	v_lshlrev_b32_e32 v56, 16, v52
	s_waitcnt lgkmcnt(2)
	v_lshlrev_b32_e32 v52, 16, v54
	v_fma_f32 v54, -v46, v46, 1.0
	v_fma_f32 v57, -v47, v47, 1.0
	v_add_f32_e32 v50, 1.0, v50
	v_max_f32_e32 v54, 0, v54
	v_add_f32_e32 v51, 1.0, v51
	v_max_f32_e32 v57, 0, v57
	v_rcp_f32_e32 v50, v50
	v_sqrt_f32_e32 v54, v54
	v_rcp_f32_e32 v51, v51
	v_sqrt_f32_e32 v57, v57
	s_waitcnt lgkmcnt(1)
	v_lshlrev_b32_e32 v53, 16, v53
	v_mul_f32_e32 v50, v50, v54
	s_waitcnt lgkmcnt(0)
	v_lshlrev_b32_e32 v54, 16, v55
	v_mul_f32_e32 v51, v51, v57
	v_mul_f32_e32 v51, v51, v54
	v_mul_f32_e32 v47, v46, v47
	v_mul_f32_e32 v46, v46, v51
	v_fmac_f32_e32 v46, v50, v53
	v_mul_f32_e32 v47, v45, v47
	v_mul_f32_e32 v45, v45, v46
	v_fmac_f32_e32 v45, v49, v52
	v_mfma_f32_16x16x32_bf16 v[50:53], v[34:37], v[6:9], 0
	v_mul_f32_e32 v47, v44, v47
	v_mul_f32_e32 v45, v44, v45
	v_fmac_f32_e32 v45, v48, v56
	v_mfma_f32_16x16x32_bf16 v[34:37], v[34:37], v[14:17], 0
	ds_bpermute_b32 v44, v68, v47
	ds_bpermute_b32 v46, v68, v47 offset:64
	ds_bpermute_b32 v48, v68, v47 offset:128
	v_mfma_f32_16x16x32_bf16 v[52:55], v[38:41], v[2:5], v[50:53]
	ds_bpermute_b32 v84, v68, v45
	ds_bpermute_b32 v85, v68, v45 offset:64
	ds_bpermute_b32 v86, v68, v45 offset:128
	v_mfma_f32_16x16x32_bf16 v[34:37], v[38:41], v[10:13], v[34:37]
	ds_bpermute_b32 v50, v68, v47 offset:192
	s_nop 2
	v_fma_f32 v38, v52, s98, v151
	s_nop 0
	v_exp_f32_e32 v38, v38
	v_fma_f32 v39, v53, s98, v151
	s_nop 0
	v_exp_f32_e32 v39, v39
	v_add_f32_e32 v38, 1.0, v38
	v_rcp_f32_e32 v38, v38
	v_fma_f32 v34, v34, s98, v150
	s_nop 0
	v_add_f32_e32 v39, 1.0, v39
	v_mul_f32_e32 v38, v72, v38
	s_nop 0
	v_exp_f32_e32 v38, v38
	v_exp_f32_e32 v34, v34
	v_rcp_f32_e32 v39, v39
	v_fma_f32 v35, v35, s98, v150
	v_fma_f32 v41, -v38, v38, 1.0
	v_add_f32_e32 v34, 1.0, v34
	v_max_f32_e32 v41, 0, v41
	v_mul_f32_e32 v39, v72, v39
	v_rcp_f32_e32 v34, v34
	v_sqrt_f32_e32 v41, v41
	s_nop 0
	s_nop 0
	v_exp_f32_e32 v39, v39
	v_exp_f32_e32 v35, v35
	v_mul_f32_e32 v47, v34, v41
	v_fma_f32 v34, v54, s98, v151
	ds_bpermute_b32 v87, v68, v45 offset:192
	v_fma_f32 v45, -v39, v39, 1.0
	s_nop 0
	v_add_f32_e32 v35, 1.0, v35
	v_max_f32_e32 v45, 0, v45
	v_exp_f32_e32 v34, v34
	v_rcp_f32_e32 v35, v35
	v_sqrt_f32_e32 v51, v45
	ds_read_u16 v40, v70 offset:59168
	ds_read_u16 v49, v70 offset:59696
	v_add_f32_e32 v34, 1.0, v34
	v_mul_f32_e32 v41, v35, v51
	v_fma_f32 v35, v36, s98, v150
	v_rcp_f32_e32 v36, v34
	ds_read_u16 v34, v70 offset:60224
	s_waitcnt lgkmcnt(2)
; template <int DIR, int MODE>
; __device__ __forceinline__ void lru_pass(const Args& a, const LAS bf16_t* cxb, LAS bf16_t* gyb, const LAS float* carry, const bf16x8 (&Bw)[2][2][2], const float (&prm)[2][3], int l, int tt, float (&hf)[8][2][4]) {
;     ...
;     for (int mi = 0; mi < 8; ++mi) {
;         const int m = DIR ? 7 - mi : mi;
;         bf16x8 Af[2];
; #pragma unroll
;         for (int ks = 0; ks < 2; ++ks) Af[ks] = *(const LAS bf16x8*)(cxb + (m * 16 + fr) * CXS + 64 * h + 32 * ks + 8 * fq);
; #pragma unroll
;         for (int nt = 0; nt < 2; ++nt) {
;             f32x4 pr = (f32x4){0.f, 0.f, 0.f, 0.f}, pi = (f32x4){0.f, 0.f, 0.f, 0.f};
; #pragma unroll
;             for (int ks = 0; ks < 2; ++ks) { pr = __builtin_amdgcn_mfma_f32_16x16x32_bf16(Af[ks], Bw[0][nt][ks], pr, 0, 0, 0); pi = __builtin_amdgcn_mfma_f32_16x16x32_bf16(Af[ks], Bw[1][nt][ks], pi, 0, 0, 0); }
;             float av[4], bv[4];
; #pragma unroll
;             for (int reg = 0; reg < 4; ++reg) {
;                 const int tok = m * 16 + 4 * fq + reg;
;                 const float x = bf2f(cxb[tok * CXS + cc[nt]]);
;                 const float r = fsig(pr[reg] + ba[nt]), ig = fsig(pi[reg] + bxv[nt]);
;                 const float aa = __expf(k8[nt] * r);
;                 av[reg] = aa; bv[reg] = __builtin_amdgcn_sqrtf(fmaxf(1.0f - aa * aa, 0.f)) * ig * x;
;             }
;             float cum[4], hl[4];
;             if (DIR == 0) { cum[0] = av[0]; hl[0] = bv[0];
; #pragma unroll
;                 for (int reg = 1; reg < 4; ++reg) { cum[reg] = cum[reg - 1] * av[reg]; hl[reg] = av[reg] * hl[reg - 1] + bv[reg]; } }
;             else { cum[3] = av[3]; hl[3] = bv[3];
; #pragma unroll
;     ...
;             const float A4 = DIR ? cum[0] : cum[3], H4 = DIR ? hl[0] : hl[3];
;             float Aq[4], Hq[4];
; #pragma unroll
;             for (int q = 0; q < 4; ++q) { Aq[q] = __shfl(A4, fr + 16 * q); Hq[q] = __shfl(H4, fr + 16 * q); }
;             float hin;
;             if (DIR == 0) { const float s0 = C[nt], s1 = Aq[0] * s0 + Hq[0], s2 = Aq[1] * s1 + Hq[1], s3 = Aq[2] * s2 + Hq[2]; C[nt] = Aq[3] * s3 + Hq[3]; hin = fq == 0 ? s0 : (fq == 1 ? s1 : (fq == 2 ? s2 : s3)); }
;             else { const float s3 = C[nt], s2 = Aq[3] * s3 + Hq[3], s1 = Aq[2] * s2 + Hq[2], s0 = Aq[1] * s1 + Hq[1]; C[nt] = Aq[0] * s0 + Hq[0]; hin = fq == 3 ? s3 : (fq == 2 ? s2 : (fq == 1 ? s1 : s0)); }
	v_lshlrev_b32_e32 v45, 16, v40
	s_waitcnt lgkmcnt(1)
	v_lshlrev_b32_e32 v40, 16, v49
	v_mul_f32_e32 v36, v72, v36
	s_nop 0
	v_exp_f32_e32 v49, v36
	v_fma_f32 v36, v55, s98, v151
	s_nop 0
	v_exp_f32_e32 v51, v36
	v_fma_f32 v37, v37, s98, v150
	s_nop 0
	s_nop 0
	v_add_f32_e32 v51, 1.0, v51
	v_rcp_f32_e32 v52, v51
	v_exp_f32_e32 v51, v37
	v_exp_f32_e32 v35, v35
	v_fma_f32 v36, -v49, v49, 1.0
	v_mul_f32_e32 v37, v72, v52
	s_nop 0
	v_exp_f32_e32 v37, v37
	v_add_f32_e32 v35, 1.0, v35
	v_max_f32_e32 v36, 0, v36
	ds_read_u16 v52, v70 offset:60752
	v_fma_f32 v53, -v37, v37, 1.0
	v_add_f32_e32 v51, 1.0, v51
	v_max_f32_e32 v53, 0, v53
	v_rcp_f32_e32 v35, v35
	v_sqrt_f32_e32 v36, v36
	v_rcp_f32_e32 v51, v51
	v_sqrt_f32_e32 v53, v53
	s_waitcnt lgkmcnt(1)
	v_lshlrev_b32_e32 v54, 16, v34
	v_mul_f32_e32 v55, v35, v36
	s_waitcnt lgkmcnt(0)
	v_lshlrev_b32_e32 v34, 16, v52
	v_mul_f32_e32 v35, v51, v53
	v_mul_f32_e32 v51, v35, v34
	v_mul_f32_e32 v52, v49, v37
	ds_read_b128 v[34:37], v89 offset:50688
	v_mul_f32_e32 v49, v49, v51
	v_fmac_f32_e32 v49, v55, v54
	v_mul_f32_e32 v51, v39, v52
	v_mul_f32_e32 v39, v39, v49
	v_fmac_f32_e32 v39, v41, v40
	v_mul_f32_e32 v49, v38, v51
	v_mul_f32_e32 v51, v38, v39
	ds_read_b128 v[38:41], v89 offset:50752
	s_waitcnt lgkmcnt(1)
	v_mfma_f32_16x16x32_bf16 v[58:61], v[34:37], v[26:29], 0
	v_fmac_f32_e32 v51, v47, v45
	ds_bpermute_b32 v88, v68, v51
	ds_bpermute_b32 v90, v68, v51 offset:64
	s_waitcnt lgkmcnt(2)
	v_mfma_f32_16x16x32_bf16 v[76:79], v[38:41], v[18:21], v[58:61]
	ds_bpermute_b32 v91, v68, v51 offset:128
	ds_bpermute_b32 v92, v68, v51 offset:192
	ds_read_u16 v57, v70 offset:51216
	s_nop 4
	v_fma_f32 v45, v76, s98, v153
	s_nop 0
	v_exp_f32_e32 v45, v45
	v_mfma_f32_16x16x32_bf16 v[62:65], v[34:37], v[30:33], 0
	v_fma_f32 v51, v77, s98, v153
	s_nop 0
	v_add_f32_e32 v45, 1.0, v45
	v_rcp_f32_e32 v45, v45
	v_mfma_f32_16x16x32_bf16 v[60:63], v[38:41], v[22:25], v[62:65]
	v_exp_f32_e32 v51, v51
	ds_bpermute_b32 v52, v68, v49
	v_mul_f32_e32 v45, v74, v45
	s_nop 0
	v_exp_f32_e32 v45, v45
	s_nop 2
	v_fma_f32 v47, v60, s98, v152
	s_nop 0
	v_exp_f32_e32 v47, v47
	v_fma_f32 v53, -v45, v45, 1.0
	v_max_f32_e32 v53, 0, v53
	v_add_f32_e32 v51, 1.0, v51
	v_add_f32_e32 v47, 1.0, v47
	v_rcp_f32_e32 v47, v47
	v_sqrt_f32_e32 v53, v53
	v_rcp_f32_e32 v51, v51
	v_fma_f32 v55, v61, s98, v152
	ds_read_u16 v60, v70 offset:51744
	ds_read_u16 v64, v70 offset:52272
	v_mul_f32_e32 v51, v74, v51
	v_mul_f32_e32 v47, v47, v53
	s_waitcnt lgkmcnt(3)
	v_lshlrev_b32_e32 v53, 16, v57
	v_fma_f32 v57, v78, s98, v153
	v_fma_f32 v61, v79, s98, v153
	s_nop 0
	s_nop 0
	s_nop 0
	s_nop 0
	v_exp_f32_e32 v51, v51
	v_exp_f32_e32 v57, v57
	v_exp_f32_e32 v61, v61
	v_exp_f32_e32 v55, v55
	v_fma_f32 v59, -v51, v51, 1.0
	v_add_f32_e32 v57, 1.0, v57
	v_add_f32_e32 v61, 1.0, v61
	v_add_f32_e32 v55, 1.0, v55
	v_max_f32_e32 v59, 0, v59
	v_rcp_f32_e32 v57, v57
	v_rcp_f32_e32 v61, v61
	v_rcp_f32_e32 v55, v55
	v_sqrt_f32_e32 v59, v59
	v_mul_f32_e32 v57, v74, v57
	v_mul_f32_e32 v61, v74, v61
	s_nop 0
	v_mul_f32_e32 v55, v55, v59
	v_fma_f32 v59, v62, s98, v152
	v_fma_f32 v63, v63, s98, v152
	s_nop 0
	s_nop 0
	v_exp_f32_e32 v57, v57
	s_nop 0
	v_exp_f32_e32 v61, v61
	v_exp_f32_e32 v59, v59
	v_exp_f32_e32 v63, v63
	v_fma_f32 v62, -v57, v57, 1.0
	v_fma_f32 v65, -v61, v61, 1.0
	v_add_f32_e32 v59, 1.0, v59
	v_max_f32_e32 v62, 0, v62
	v_add_f32_e32 v63, 1.0, v63
	v_max_f32_e32 v65, 0, v65
	v_rcp_f32_e32 v59, v59
	v_sqrt_f32_e32 v62, v62
	v_rcp_f32_e32 v63, v63
	v_sqrt_f32_e32 v65, v65
	s_waitcnt lgkmcnt(1)
	v_lshlrev_b32_e32 v60, 16, v60
	v_mul_f32_e32 v59, v59, v62
	s_waitcnt lgkmcnt(0)
	v_lshlrev_b32_e32 v62, 16, v64
	v_mul_f32_e32 v63, v63, v65
	v_mul_f32_e32 v62, v63, v62
	v_mul_f32_e32 v61, v57, v61
	v_mul_f32_e32 v57, v57, v62
	v_fmac_f32_e32 v57, v59, v60
	v_mul_f32_e32 v59, v51, v61
	v_mfma_f32_16x16x32_bf16 v[60:63], v[34:37], v[6:9], 0
	ds_bpermute_b32 v54, v68, v49 offset:64
	ds_bpermute_b32 v56, v68, v49 offset:128
	ds_bpermute_b32 v58, v68, v49 offset:192
	v_mfma_f32_16x16x32_bf16 v[34:37], v[34:37], v[14:17], 0
	ds_read_u16 v49, v70 offset:50688
	ds_read_u16 v73, v70 offset:42768
	v_mul_f32_e32 v51, v51, v57
	v_mfma_f32_16x16x32_bf16 v[60:63], v[38:41], v[2:5], v[60:63]
	v_fmac_f32_e32 v51, v55, v53
	v_mul_f32_e32 v55, v45, v51
	ds_read_u16 v57, v70 offset:51248
	v_mfma_f32_16x16x32_bf16 v[34:37], v[38:41], v[10:13], v[34:37]
	ds_read_u16 v40, v70 offset:50720
	ds_read_u16 v76, v70 offset:43824
	s_nop 1
	v_fma_f32 v38, v60, s98, v151
	s_nop 0
	v_exp_f32_e32 v38, v38
	v_fma_f32 v39, v61, s98, v151
	s_nop 0
	v_exp_f32_e32 v39, v39
	v_add_f32_e32 v38, 1.0, v38
	v_rcp_f32_e32 v38, v38
	v_fma_f32 v34, v34, s98, v150
	s_nop 0
	v_add_f32_e32 v39, 1.0, v39
	v_mul_f32_e32 v38, v72, v38
	s_nop 0
	v_exp_f32_e32 v38, v38
	v_exp_f32_e32 v34, v34
	v_rcp_f32_e32 v39, v39
	v_fma_f32 v35, v35, s98, v150
	v_fma_f32 v41, -v38, v38, 1.0
	v_add_f32_e32 v34, 1.0, v34
	v_max_f32_e32 v41, 0, v41
	v_mul_f32_e32 v39, v72, v39
	v_rcp_f32_e32 v34, v34
	v_sqrt_f32_e32 v41, v41
	s_nop 0
	s_nop 0
	v_exp_f32_e32 v39, v39
	s_waitcnt lgkmcnt(4)
	v_lshlrev_b32_e32 v49, 16, v49
	v_exp_f32_e32 v35, v35
	v_fmac_f32_e32 v55, v47, v49
	v_mul_f32_e32 v53, v45, v59
	ds_bpermute_b32 v93, v68, v55
	ds_bpermute_b32 v94, v68, v55 offset:64
	ds_bpermute_b32 v95, v68, v55 offset:128
	ds_bpermute_b32 v96, v68, v55 offset:192
	v_mul_f32_e32 v55, v34, v41
	v_fma_f32 v34, v62, s98, v151
	ds_bpermute_b32 v45, v68, v53
	ds_bpermute_b32 v47, v68, v53 offset:64
	ds_bpermute_b32 v49, v68, v53 offset:128
	ds_bpermute_b32 v51, v68, v53 offset:192
	v_fma_f32 v53, -v39, v39, 1.0
	s_nop 0
	v_add_f32_e32 v35, 1.0, v35
	v_max_f32_e32 v53, 0, v53
	v_exp_f32_e32 v34, v34
	v_rcp_f32_e32 v35, v35
	v_sqrt_f32_e32 v59, v53
	s_waitcnt lgkmcnt(9)
; template <int DIR, int MODE>
; __device__ __forceinline__ void lru_pass(const Args& a, const LAS bf16_t* cxb, LAS bf16_t* gyb, const LAS float* carry, const bf16x8 (&Bw)[2][2][2], const float (&prm)[2][3], int l, int tt, float (&hf)[8][2][4]) {
;     ...
;     for (int mi = 0; mi < 8; ++mi) {
;         const int m = DIR ? 7 - mi : mi;
;         bf16x8 Af[2];
; #pragma unroll
;         for (int ks = 0; ks < 2; ++ks) Af[ks] = *(const LAS bf16x8*)(cxb + (m * 16 + fr) * CXS + 64 * h + 32 * ks + 8 * fq);
; #pragma unroll
;         for (int nt = 0; nt < 2; ++nt) {
;             f32x4 pr = (f32x4){0.f, 0.f, 0.f, 0.f}, pi = (f32x4){0.f, 0.f, 0.f, 0.f};
; #pragma unroll
;             for (int ks = 0; ks < 2; ++ks) { pr = __builtin_amdgcn_mfma_f32_16x16x32_bf16(Af[ks], Bw[0][nt][ks], pr, 0, 0, 0); pi = __builtin_amdgcn_mfma_f32_16x16x32_bf16(Af[ks], Bw[1][nt][ks], pi, 0, 0, 0); }
;             float av[4], bv[4];
; #pragma unroll
;             for (int reg = 0; reg < 4; ++reg) {
;                 const int tok = m * 16 + 4 * fq + reg;
;                 const float x = bf2f(cxb[tok * CXS + cc[nt]]);
;                 const float r = fsig(pr[reg] + ba[nt]), ig = fsig(pi[reg] + bxv[nt]);
;                 const float aa = __expf(k8[nt] * r);
;                 av[reg] = aa; bv[reg] = __builtin_amdgcn_sqrtf(fmaxf(1.0f - aa * aa, 0.f)) * ig * x;
;             }
;             float cum[4], hl[4];
;             if (DIR == 0) { cum[0] = av[0]; hl[0] = bv[0];
; #pragma unroll
;                 for (int reg = 1; reg < 4; ++reg) { cum[reg] = cum[reg - 1] * av[reg]; hl[reg] = av[reg] * hl[reg - 1] + bv[reg]; } }
;             else { cum[3] = av[3]; hl[3] = bv[3];
; #pragma unroll
;     ...
;             const float A4 = DIR ? cum[0] : cum[3], H4 = DIR ? hl[0] : hl[3];
;             float Aq[4], Hq[4];
; #pragma unroll
;             for (int q = 0; q < 4; ++q) { Aq[q] = __shfl(A4, fr + 16 * q); Hq[q] = __shfl(H4, fr + 16 * q); }
;             float hin;
;             if (DIR == 0) { const float s0 = C[nt], s1 = Aq[0] * s0 + Hq[0], s2 = Aq[1] * s1 + Hq[1], s3 = Aq[2] * s2 + Hq[2]; C[nt] = Aq[3] * s3 + Hq[3]; hin = fq == 0 ? s0 : (fq == 1 ? s1 : (fq == 2 ? s2 : s3)); }
;             else { const float s3 = C[nt], s2 = Aq[3] * s3 + Hq[3], s1 = Aq[2] * s2 + Hq[2], s0 = Aq[1] * s1 + Hq[1]; C[nt] = Aq[0] * s0 + Hq[0]; hin = fq == 3 ? s3 : (fq == 2 ? s2 : (fq == 1 ? s1 : s0)); }
	v_lshlrev_b32_e32 v53, 16, v40
	v_add_f32_e32 v34, 1.0, v34
	v_lshlrev_b32_e32 v40, 16, v57
	v_mul_f32_e32 v41, v35, v59
	v_fma_f32 v35, v36, s98, v150
	v_rcp_f32_e32 v36, v34
	v_fma_f32 v37, v37, s98, v150
	s_nop 0
	s_nop 0
	v_mul_f32_e32 v36, v72, v36
	s_nop 0
	v_exp_f32_e32 v57, v36
	v_fma_f32 v36, v63, s98, v151
	s_nop 0
	v_exp_f32_e32 v59, v36
	v_exp_f32_e32 v35, v35
	v_fma_f32 v36, -v57, v57, 1.0
	ds_read_u16 v34, v70 offset:51776
	v_add_f32_e32 v59, 1.0, v59
	v_rcp_f32_e32 v60, v59
	v_exp_f32_e32 v59, v37
	v_add_f32_e32 v35, 1.0, v35
	v_max_f32_e32 v36, 0, v36
	v_mul_f32_e32 v37, v72, v60
	s_nop 0
	v_exp_f32_e32 v37, v37
	ds_read_u16 v60, v70 offset:52304
	v_add_f32_e32 v59, 1.0, v59
	v_rcp_f32_e32 v35, v35
	v_fma_f32 v61, -v37, v37, 1.0
	v_max_f32_e32 v61, 0, v61
	v_sqrt_f32_e32 v36, v36
	v_rcp_f32_e32 v59, v59
	v_sqrt_f32_e32 v61, v61
	s_waitcnt lgkmcnt(1)
	v_lshlrev_b32_e32 v62, 16, v34
	v_mul_f32_e32 v63, v35, v36
	s_waitcnt lgkmcnt(0)
	v_lshlrev_b32_e32 v34, 16, v60
	v_mul_f32_e32 v35, v59, v61
	v_mul_f32_e32 v59, v35, v34
	v_mul_f32_e32 v60, v57, v37
	ds_read_b128 v[34:37], v89 offset:42240
	v_mul_f32_e32 v57, v57, v59
	v_fmac_f32_e32 v57, v63, v62
	v_mul_f32_e32 v59, v39, v60
	v_mul_f32_e32 v39, v39, v57
	v_fmac_f32_e32 v39, v41, v40
	v_mul_f32_e32 v59, v38, v59
	v_mul_f32_e32 v69, v38, v39
	ds_read_b128 v[38:41], v89 offset:42304
	s_waitcnt lgkmcnt(1)
	v_mfma_f32_16x16x32_bf16 v[60:63], v[34:37], v[26:29], 0
	v_fmac_f32_e32 v69, v55, v53
	ds_bpermute_b32 v97, v68, v69
	ds_bpermute_b32 v98, v68, v69 offset:64
	s_waitcnt lgkmcnt(2)
	v_mfma_f32_16x16x32_bf16 v[60:63], v[38:41], v[18:21], v[60:63]
	ds_bpermute_b32 v99, v68, v69 offset:128
	ds_bpermute_b32 v100, v68, v69 offset:192
	ds_read_u16 v69, v70 offset:42240
	s_nop 4
	v_fma_f32 v61, v61, s98, v153
	s_nop 0
	v_exp_f32_e32 v61, v61
	v_fma_f32 v60, v60, s98, v153
	v_mfma_f32_16x16x32_bf16 v[64:67], v[34:37], v[30:33], 0
	s_nop 0
	v_exp_f32_e32 v60, v60
	v_add_f32_e32 v61, 1.0, v61
	v_fma_f32 v62, v62, s98, v153
	v_fma_f32 v63, v63, s98, v153
	v_rcp_f32_e32 v61, v61
	s_nop 0
	s_nop 0
	v_mfma_f32_16x16x32_bf16 v[64:67], v[38:41], v[22:25], v[64:67]
	v_exp_f32_e32 v62, v62
	v_exp_f32_e32 v63, v63
	v_add_f32_e32 v60, 1.0, v60
	v_rcp_f32_e32 v60, v60
	v_mul_f32_e32 v61, v74, v61
	s_nop 2
	v_fma_f32 v65, v65, s98, v152
	s_nop 0
	v_add_f32_e32 v62, 1.0, v62
	v_add_f32_e32 v63, 1.0, v63
	s_nop 0
	v_exp_f32_e32 v61, v61
	v_rcp_f32_e32 v62, v62
	v_rcp_f32_e32 v63, v63
	v_mul_f32_e32 v60, v74, v60
	v_exp_f32_e32 v65, v65
	v_fma_f32 v64, v64, s98, v152
	s_nop 0
	s_nop 0
	v_exp_f32_e32 v60, v60
	v_exp_f32_e32 v64, v64
	v_fma_f32 v75, -v61, v61, 1.0
	v_mul_f32_e32 v62, v74, v62
	v_mul_f32_e32 v63, v74, v63
	v_add_f32_e32 v65, 1.0, v65
	v_max_f32_e32 v75, 0, v75
	v_fma_f32 v66, v66, s98, v152
	s_nop 0
	v_fma_f32 v67, v67, s98, v152
	s_nop 0
	v_rcp_f32_e32 v65, v65
	v_sqrt_f32_e32 v75, v75
	s_nop 0
	v_exp_f32_e32 v62, v62
	s_nop 0
	v_exp_f32_e32 v63, v63
	v_fma_f32 v71, -v60, v60, 1.0
	v_exp_f32_e32 v66, v66
	v_exp_f32_e32 v67, v67
	v_add_f32_e32 v64, 1.0, v64
	v_max_f32_e32 v71, 0, v71
	v_rcp_f32_e32 v64, v64
	v_sqrt_f32_e32 v71, v71
	v_mul_f32_e32 v65, v65, v75
	v_fma_f32 v75, -v62, v62, 1.0
	v_fma_f32 v77, -v63, v63, 1.0
	v_add_f32_e32 v66, 1.0, v66
	v_max_f32_e32 v75, 0, v75
	v_add_f32_e32 v67, 1.0, v67
	v_max_f32_e32 v77, 0, v77
	v_rcp_f32_e32 v66, v66
	v_sqrt_f32_e32 v75, v75
	v_rcp_f32_e32 v67, v67
	v_sqrt_f32_e32 v77, v77
	v_mul_f32_e32 v71, v64, v71
	v_lshlrev_b32_e32 v64, 16, v73
	ds_read_u16 v73, v70 offset:43296
	v_mul_f32_e32 v66, v66, v75
	v_lshlrev_b32_e32 v75, 16, v76
	v_mul_f32_e32 v67, v67, v77
	v_mul_f32_e32 v67, v67, v75
	s_waitcnt lgkmcnt(0)
	v_lshlrev_b32_e32 v73, 16, v73
	v_mul_f32_e32 v63, v62, v63
	v_mul_f32_e32 v62, v62, v67
	v_fmac_f32_e32 v62, v66, v73
	v_mul_f32_e32 v63, v61, v63
	v_mul_f32_e32 v61, v61, v62
	v_fmac_f32_e32 v61, v65, v64
	v_mfma_f32_16x16x32_bf16 v[64:67], v[34:37], v[6:9], 0
	v_mul_f32_e32 v73, v60, v61
	ds_read_u16 v109, v70 offset:35376
	ds_read_u16 v141, v70 offset:18480
	v_mfma_f32_16x16x32_bf16 v[34:37], v[34:37], v[14:17], 0
	ds_read_u16 v159, v70 offset:8976
	ds_read_u16 v139, v70 offset:17424
	ds_read_u16 v125, v70 offset:26928
	v_mfma_f32_16x16x32_bf16 v[64:67], v[38:41], v[2:5], v[64:67]
	v_mul_f32_e32 v63, v60, v63
	ds_bpermute_b32 v53, v68, v59
	ds_bpermute_b32 v55, v68, v59 offset:64
	v_mfma_f32_16x16x32_bf16 v[34:37], v[38:41], v[10:13], v[34:37]
	ds_read_u16 v40, v70 offset:42272
	s_nop 2
	v_fma_f32 v38, v64, s98, v151
	s_nop 0
	v_exp_f32_e32 v38, v38
	v_fma_f32 v39, v65, s98, v151
	s_nop 0
	v_exp_f32_e32 v39, v39
	v_add_f32_e32 v38, 1.0, v38
	v_rcp_f32_e32 v38, v38
	v_fma_f32 v34, v34, s98, v150
	s_nop 0
	v_add_f32_e32 v39, 1.0, v39
	v_mul_f32_e32 v38, v72, v38
	s_nop 0
	v_exp_f32_e32 v38, v38
	v_exp_f32_e32 v34, v34
	v_rcp_f32_e32 v39, v39
	v_fma_f32 v35, v35, s98, v150
	v_fma_f32 v41, -v38, v38, 1.0
	v_add_f32_e32 v34, 1.0, v34
	v_max_f32_e32 v41, 0, v41
	v_mul_f32_e32 v39, v72, v39
	v_rcp_f32_e32 v34, v34
	v_sqrt_f32_e32 v41, v41
	s_nop 0
	s_nop 0
	v_exp_f32_e32 v39, v39
	v_exp_f32_e32 v35, v35
	v_mul_f32_e32 v65, v34, v41
	v_fma_f32 v34, v66, s98, v151
	v_fma_f32 v64, -v39, v39, 1.0
	s_nop 0
	v_lshlrev_b32_e32 v69, 16, v69
	v_add_f32_e32 v35, 1.0, v35
	v_max_f32_e32 v64, 0, v64
	v_exp_f32_e32 v34, v34
	v_fmac_f32_e32 v73, v71, v69
	v_rcp_f32_e32 v35, v35
	v_sqrt_f32_e32 v71, v64
	v_add_f32_e32 v34, 1.0, v34
	ds_read_u16 v69, v70 offset:42800
	s_waitcnt lgkmcnt(1)
	v_lshlrev_b32_e32 v64, 16, v40
	v_mul_f32_e32 v41, v35, v71
	v_fma_f32 v35, v36, s98, v150
	v_rcp_f32_e32 v36, v34
	ds_read_u16 v34, v70 offset:43328
	s_waitcnt lgkmcnt(1)
; template <int DIR, int MODE>
; __device__ __forceinline__ void lru_pass(const Args& a, const LAS bf16_t* cxb, LAS bf16_t* gyb, const LAS float* carry, const bf16x8 (&Bw)[2][2][2], const float (&prm)[2][3], int l, int tt, float (&hf)[8][2][4]) {
;     ...
;     for (int mi = 0; mi < 8; ++mi) {
;         const int m = DIR ? 7 - mi : mi;
;         bf16x8 Af[2];
; #pragma unroll
;         for (int ks = 0; ks < 2; ++ks) Af[ks] = *(const LAS bf16x8*)(cxb + (m * 16 + fr) * CXS + 64 * h + 32 * ks + 8 * fq);
; #pragma unroll
;         for (int nt = 0; nt < 2; ++nt) {
;             f32x4 pr = (f32x4){0.f, 0.f, 0.f, 0.f}, pi = (f32x4){0.f, 0.f, 0.f, 0.f};
; #pragma unroll
;             for (int ks = 0; ks < 2; ++ks) { pr = __builtin_amdgcn_mfma_f32_16x16x32_bf16(Af[ks], Bw[0][nt][ks], pr, 0, 0, 0); pi = __builtin_amdgcn_mfma_f32_16x16x32_bf16(Af[ks], Bw[1][nt][ks], pi, 0, 0, 0); }
;             float av[4], bv[4];
; #pragma unroll
;             for (int reg = 0; reg < 4; ++reg) {
;                 const int tok = m * 16 + 4 * fq + reg;
;                 const float x = bf2f(cxb[tok * CXS + cc[nt]]);
;                 const float r = fsig(pr[reg] + ba[nt]), ig = fsig(pi[reg] + bxv[nt]);
;                 const float aa = __expf(k8[nt] * r);
;                 av[reg] = aa; bv[reg] = __builtin_amdgcn_sqrtf(fmaxf(1.0f - aa * aa, 0.f)) * ig * x;
;             }
;             float cum[4], hl[4];
;             if (DIR == 0) { cum[0] = av[0]; hl[0] = bv[0];
; #pragma unroll
;                 for (int reg = 1; reg < 4; ++reg) { cum[reg] = cum[reg - 1] * av[reg]; hl[reg] = av[reg] * hl[reg - 1] + bv[reg]; } }
;             else { cum[3] = av[3]; hl[3] = bv[3];
; #pragma unroll
;     ...
;             const float A4 = DIR ? cum[0] : cum[3], H4 = DIR ? hl[0] : hl[3];
;             float Aq[4], Hq[4];
; #pragma unroll
;             for (int q = 0; q < 4; ++q) { Aq[q] = __shfl(A4, fr + 16 * q); Hq[q] = __shfl(H4, fr + 16 * q); }
;             float hin;
;             if (DIR == 0) { const float s0 = C[nt], s1 = Aq[0] * s0 + Hq[0], s2 = Aq[1] * s1 + Hq[1], s3 = Aq[2] * s2 + Hq[2]; C[nt] = Aq[3] * s3 + Hq[3]; hin = fq == 0 ? s0 : (fq == 1 ? s1 : (fq == 2 ? s2 : s3)); }
;             else { const float s3 = C[nt], s2 = Aq[3] * s3 + Hq[3], s1 = Aq[2] * s2 + Hq[2], s0 = Aq[1] * s1 + Hq[1]; C[nt] = Aq[0] * s0 + Hq[0]; hin = fq == 3 ? s3 : (fq == 2 ? s2 : (fq == 1 ? s1 : s0)); }
	v_lshlrev_b32_e32 v40, 16, v69
	v_fma_f32 v37, v37, s98, v150
	v_mul_f32_e32 v36, v72, v36
	s_nop 0
	v_exp_f32_e32 v66, v36
	v_fma_f32 v36, v67, s98, v151
	s_nop 0
	v_exp_f32_e32 v67, v36
	s_nop 0
	s_nop 0
	v_exp_f32_e32 v35, v35
	v_add_f32_e32 v67, 1.0, v67
	v_rcp_f32_e32 v69, v67
	v_exp_f32_e32 v67, v37
	v_fma_f32 v36, -v66, v66, 1.0
	v_add_f32_e32 v35, 1.0, v35
	v_mul_f32_e32 v37, v72, v69
	s_nop 0
	v_exp_f32_e32 v37, v37
	v_max_f32_e32 v36, 0, v36
	ds_read_u16 v69, v70 offset:43856
	v_add_f32_e32 v67, 1.0, v67
	v_fma_f32 v71, -v37, v37, 1.0
	v_max_f32_e32 v71, 0, v71
	v_rcp_f32_e32 v35, v35
	v_sqrt_f32_e32 v36, v36
	v_rcp_f32_e32 v67, v67
	v_sqrt_f32_e32 v71, v71
	ds_bpermute_b32 v101, v68, v73
	ds_bpermute_b32 v102, v68, v73 offset:64
	ds_bpermute_b32 v103, v68, v73 offset:128
	ds_bpermute_b32 v104, v68, v73 offset:192
	s_waitcnt lgkmcnt(5)
	v_lshlrev_b32_e32 v73, 16, v34
	v_mul_f32_e32 v75, v35, v36
	s_waitcnt lgkmcnt(4)
	v_lshlrev_b32_e32 v34, 16, v69
	v_mul_f32_e32 v35, v67, v71
	v_mul_f32_e32 v67, v35, v34
	v_mul_f32_e32 v69, v66, v37
	ds_read_b128 v[34:37], v89 offset:33792
	v_mul_f32_e32 v66, v66, v67
	v_fmac_f32_e32 v66, v75, v73
	v_mul_f32_e32 v67, v39, v69
	v_mul_f32_e32 v39, v39, v66
	v_fmac_f32_e32 v39, v41, v40
	v_mul_f32_e32 v67, v38, v67
	v_mul_f32_e32 v69, v38, v39
	ds_read_b128 v[38:41], v89 offset:33856
	s_waitcnt lgkmcnt(1)
	v_mfma_f32_16x16x32_bf16 v[76:79], v[34:37], v[26:29], 0
	v_fmac_f32_e32 v69, v65, v64
	ds_bpermute_b32 v105, v68, v69
	ds_bpermute_b32 v106, v68, v69 offset:64
	s_waitcnt lgkmcnt(2)
	v_mfma_f32_16x16x32_bf16 v[76:79], v[38:41], v[18:21], v[76:79]
	ds_bpermute_b32 v107, v68, v69 offset:128
	ds_bpermute_b32 v108, v68, v69 offset:192
	ds_read_u16 v73, v70 offset:33792
	s_nop 4
	v_fma_f32 v69, v76, s98, v153
	v_fma_f32 v75, v77, s98, v153
	s_nop 0
	s_nop 0
	v_exp_f32_e32 v69, v69
	v_exp_f32_e32 v75, v75
	v_mfma_f32_16x16x32_bf16 v[80:83], v[34:37], v[30:33], 0
	v_fma_f32 v78, v78, s98, v153
	v_add_f32_e32 v69, 1.0, v69
	v_add_f32_e32 v75, 1.0, v75
	v_rcp_f32_e32 v69, v69
	v_rcp_f32_e32 v75, v75
	v_mfma_f32_16x16x32_bf16 v[80:83], v[38:41], v[22:25], v[80:83]
	v_fma_f32 v79, v79, s98, v153
	v_mul_f32_e32 v69, v74, v69
	v_mul_f32_e32 v75, v74, v75
	s_nop 0
	s_nop 0
	s_nop 2
	v_fma_f32 v71, v80, s98, v152
	v_fma_f32 v77, v81, s98, v152
	s_nop 0
	s_nop 0
	s_nop 0
	v_exp_f32_e32 v69, v69
	s_nop 0
	v_exp_f32_e32 v75, v75
	v_exp_f32_e32 v78, v78
	v_exp_f32_e32 v79, v79
	v_exp_f32_e32 v71, v71
	v_exp_f32_e32 v77, v77
	v_fma_f32 v76, -v69, v69, 1.0
	v_fma_f32 v81, -v75, v75, 1.0
	v_add_f32_e32 v78, 1.0, v78
	v_add_f32_e32 v79, 1.0, v79
	v_add_f32_e32 v71, 1.0, v71
	v_max_f32_e32 v76, 0, v76
	ds_read_u16 v80, v70 offset:34320
	v_add_f32_e32 v77, 1.0, v77
	v_max_f32_e32 v81, 0, v81
	v_rcp_f32_e32 v78, v78
	v_rcp_f32_e32 v79, v79
	v_rcp_f32_e32 v71, v71
	v_sqrt_f32_e32 v76, v76
	v_rcp_f32_e32 v77, v77
	v_sqrt_f32_e32 v81, v81
	v_mul_f32_e32 v78, v74, v78
	v_mul_f32_e32 v79, v74, v79
	v_mul_f32_e32 v71, v71, v76
	v_mul_f32_e32 v77, v77, v81
	ds_read_u16 v81, v70 offset:34848
	s_waitcnt lgkmcnt(1)
	v_lshlrev_b32_e32 v76, 16, v80
	v_fma_f32 v80, v82, s98, v152
	s_nop 0
	v_fma_f32 v83, v83, s98, v152
	s_nop 0
	s_nop 0
	v_exp_f32_e32 v78, v78
	s_nop 0
	v_exp_f32_e32 v79, v79
	v_exp_f32_e32 v80, v80
	v_exp_f32_e32 v83, v83
	v_fma_f32 v82, -v78, v78, 1.0
	v_fma_f32 v110, -v79, v79, 1.0
	v_add_f32_e32 v80, 1.0, v80
	v_max_f32_e32 v82, 0, v82
	v_add_f32_e32 v83, 1.0, v83
	v_max_f32_e32 v110, 0, v110
	v_rcp_f32_e32 v80, v80
	v_sqrt_f32_e32 v82, v82
	v_rcp_f32_e32 v83, v83
	v_sqrt_f32_e32 v110, v110
	s_waitcnt lgkmcnt(0)
	v_lshlrev_b32_e32 v81, 16, v81
	v_mul_f32_e32 v80, v80, v82
	v_lshlrev_b32_e32 v82, 16, v109
	v_mul_f32_e32 v83, v83, v110
	v_mul_f32_e32 v82, v83, v82
	v_mul_f32_e32 v79, v78, v79
	v_mul_f32_e32 v78, v78, v82
	v_fmac_f32_e32 v78, v80, v81
	v_mul_f32_e32 v79, v75, v79
	v_mul_f32_e32 v75, v75, v78
	v_fmac_f32_e32 v75, v77, v76
	v_mul_f32_e32 v80, v69, v79
	v_mfma_f32_16x16x32_bf16 v[76:79], v[34:37], v[6:9], 0
	v_mul_f32_e32 v69, v69, v75
	ds_bpermute_b32 v110, v68, v80
	ds_bpermute_b32 v112, v68, v80 offset:64
	v_mfma_f32_16x16x32_bf16 v[34:37], v[34:37], v[14:17], 0
	ds_bpermute_b32 v113, v68, v80 offset:128
	ds_bpermute_b32 v116, v68, v80 offset:192
	ds_bpermute_b32 v57, v68, v59 offset:128
	v_mfma_f32_16x16x32_bf16 v[76:79], v[38:41], v[2:5], v[76:79]
	ds_bpermute_b32 v59, v68, v59 offset:192
	ds_bpermute_b32 v60, v68, v63
	ds_bpermute_b32 v62, v68, v63 offset:64
	v_mfma_f32_16x16x32_bf16 v[34:37], v[38:41], v[10:13], v[34:37]
	ds_read_u16 v40, v70 offset:33824
	s_nop 2
	v_fma_f32 v38, v76, s98, v151
	s_nop 0
	v_exp_f32_e32 v38, v38
	v_fma_f32 v39, v77, s98, v151
	s_nop 0
	v_exp_f32_e32 v39, v39
	v_add_f32_e32 v38, 1.0, v38
	v_rcp_f32_e32 v38, v38
	v_fma_f32 v34, v34, s98, v150
	s_nop 0
	v_add_f32_e32 v39, 1.0, v39
	v_mul_f32_e32 v38, v72, v38
	s_nop 0
	v_exp_f32_e32 v38, v38
	v_exp_f32_e32 v34, v34
	v_rcp_f32_e32 v39, v39
	v_fma_f32 v35, v35, s98, v150
	v_fma_f32 v41, -v38, v38, 1.0
	v_add_f32_e32 v34, 1.0, v34
	v_max_f32_e32 v41, 0, v41
	v_mul_f32_e32 v39, v72, v39
	v_rcp_f32_e32 v34, v34
	v_sqrt_f32_e32 v41, v41
	s_nop 0
	s_nop 0
	v_exp_f32_e32 v39, v39
	v_exp_f32_e32 v35, v35
	v_lshlrev_b32_e32 v73, 16, v73
	v_fmac_f32_e32 v69, v71, v73
	v_mul_f32_e32 v71, v34, v41
	v_fma_f32 v34, v78, s98, v151
	ds_bpermute_b32 v109, v68, v69
	ds_bpermute_b32 v111, v68, v69 offset:64
	ds_bpermute_b32 v114, v68, v69 offset:128
	ds_bpermute_b32 v115, v68, v69 offset:192
	v_fma_f32 v69, -v39, v39, 1.0
	s_nop 0
	v_add_f32_e32 v35, 1.0, v35
	v_max_f32_e32 v69, 0, v69
	v_exp_f32_e32 v34, v34
	v_rcp_f32_e32 v35, v35
	v_sqrt_f32_e32 v75, v69
	ds_read_u16 v73, v70 offset:34352
	v_add_f32_e32 v34, 1.0, v34
	s_waitcnt lgkmcnt(5)
; template <int DIR, int MODE>
; __device__ __forceinline__ void lru_pass(const Args& a, const LAS bf16_t* cxb, LAS bf16_t* gyb, const LAS float* carry, const bf16x8 (&Bw)[2][2][2], const float (&prm)[2][3], int l, int tt, float (&hf)[8][2][4]) {
;     ...
;     for (int mi = 0; mi < 8; ++mi) {
;         const int m = DIR ? 7 - mi : mi;
;         bf16x8 Af[2];
; #pragma unroll
;         for (int ks = 0; ks < 2; ++ks) Af[ks] = *(const LAS bf16x8*)(cxb + (m * 16 + fr) * CXS + 64 * h + 32 * ks + 8 * fq);
; #pragma unroll
;         for (int nt = 0; nt < 2; ++nt) {
;             f32x4 pr = (f32x4){0.f, 0.f, 0.f, 0.f}, pi = (f32x4){0.f, 0.f, 0.f, 0.f};
; #pragma unroll
;             for (int ks = 0; ks < 2; ++ks) { pr = __builtin_amdgcn_mfma_f32_16x16x32_bf16(Af[ks], Bw[0][nt][ks], pr, 0, 0, 0); pi = __builtin_amdgcn_mfma_f32_16x16x32_bf16(Af[ks], Bw[1][nt][ks], pi, 0, 0, 0); }
;             float av[4], bv[4];
; #pragma unroll
;             for (int reg = 0; reg < 4; ++reg) {
;                 const int tok = m * 16 + 4 * fq + reg;
;                 const float x = bf2f(cxb[tok * CXS + cc[nt]]);
;                 const float r = fsig(pr[reg] + ba[nt]), ig = fsig(pi[reg] + bxv[nt]);
;                 const float aa = __expf(k8[nt] * r);
;                 av[reg] = aa; bv[reg] = __builtin_amdgcn_sqrtf(fmaxf(1.0f - aa * aa, 0.f)) * ig * x;
;             }
;             float cum[4], hl[4];
;             if (DIR == 0) { cum[0] = av[0]; hl[0] = bv[0];
; #pragma unroll
;                 for (int reg = 1; reg < 4; ++reg) { cum[reg] = cum[reg - 1] * av[reg]; hl[reg] = av[reg] * hl[reg - 1] + bv[reg]; } }
;             else { cum[3] = av[3]; hl[3] = bv[3];
; #pragma unroll
;     ...
;             const float A4 = DIR ? cum[0] : cum[3], H4 = DIR ? hl[0] : hl[3];
;             float Aq[4], Hq[4];
; #pragma unroll
;             for (int q = 0; q < 4; ++q) { Aq[q] = __shfl(A4, fr + 16 * q); Hq[q] = __shfl(H4, fr + 16 * q); }
;             float hin;
;             if (DIR == 0) { const float s0 = C[nt], s1 = Aq[0] * s0 + Hq[0], s2 = Aq[1] * s1 + Hq[1], s3 = Aq[2] * s2 + Hq[2]; C[nt] = Aq[3] * s3 + Hq[3]; hin = fq == 0 ? s0 : (fq == 1 ? s1 : (fq == 2 ? s2 : s3)); }
;             else { const float s3 = C[nt], s2 = Aq[3] * s3 + Hq[3], s1 = Aq[2] * s2 + Hq[2], s0 = Aq[1] * s1 + Hq[1]; C[nt] = Aq[0] * s0 + Hq[0]; hin = fq == 3 ? s3 : (fq == 2 ? s2 : (fq == 1 ? s1 : s0)); }
	v_lshlrev_b32_e32 v69, 16, v40
	v_mul_f32_e32 v41, v35, v75
	v_fma_f32 v35, v36, s98, v150
	v_rcp_f32_e32 v36, v34
	ds_read_u16 v34, v70 offset:34880
	s_waitcnt lgkmcnt(1)
	v_lshlrev_b32_e32 v40, 16, v73
	v_fma_f32 v37, v37, s98, v150
	v_mul_f32_e32 v36, v72, v36
	s_nop 0
	v_exp_f32_e32 v73, v36
	v_fma_f32 v36, v79, s98, v151
	s_nop 0
	v_exp_f32_e32 v75, v36
	s_nop 0
	s_nop 0
	v_exp_f32_e32 v35, v35
	v_add_f32_e32 v75, 1.0, v75
	v_rcp_f32_e32 v76, v75
	v_exp_f32_e32 v75, v37
	v_fma_f32 v36, -v73, v73, 1.0
	v_add_f32_e32 v35, 1.0, v35
	v_mul_f32_e32 v37, v72, v76
	s_nop 0
	v_exp_f32_e32 v37, v37
	v_max_f32_e32 v36, 0, v36
	ds_read_u16 v76, v70 offset:35408
	v_add_f32_e32 v75, 1.0, v75
	v_fma_f32 v77, -v37, v37, 1.0
	v_max_f32_e32 v77, 0, v77
	v_rcp_f32_e32 v35, v35
	v_sqrt_f32_e32 v36, v36
	v_rcp_f32_e32 v75, v75
	v_sqrt_f32_e32 v77, v77
	s_waitcnt lgkmcnt(1)
	v_lshlrev_b32_e32 v78, 16, v34
	v_mul_f32_e32 v79, v35, v36
	s_waitcnt lgkmcnt(0)
	v_lshlrev_b32_e32 v34, 16, v76
	v_mul_f32_e32 v35, v75, v77
	v_mul_f32_e32 v75, v35, v34
	v_mul_f32_e32 v76, v73, v37
	ds_read_b128 v[34:37], v89 offset:25344
	v_mul_f32_e32 v73, v73, v75
	v_fmac_f32_e32 v73, v79, v78
	v_mul_f32_e32 v75, v39, v76
	v_mul_f32_e32 v39, v39, v73
	v_fmac_f32_e32 v39, v41, v40
	v_mul_f32_e32 v73, v38, v75
	v_mul_f32_e32 v75, v38, v39
	ds_read_b128 v[38:41], v89 offset:25408
	s_waitcnt lgkmcnt(1)
	v_mfma_f32_16x16x32_bf16 v[76:79], v[34:37], v[26:29], 0
	v_fmac_f32_e32 v75, v71, v69
	ds_bpermute_b32 v117, v68, v75
	ds_bpermute_b32 v119, v68, v75 offset:64
	s_waitcnt lgkmcnt(2)
	v_mfma_f32_16x16x32_bf16 v[76:79], v[38:41], v[18:21], v[76:79]
	ds_bpermute_b32 v122, v68, v75 offset:128
	ds_bpermute_b32 v123, v68, v75 offset:192
	ds_bpermute_b32 v118, v68, v73
	s_nop 4
	v_fma_f32 v69, v76, s98, v153
	v_fma_f32 v75, v77, s98, v153
	s_nop 0
	s_nop 0
	v_exp_f32_e32 v69, v69
	v_exp_f32_e32 v75, v75
	v_mfma_f32_16x16x32_bf16 v[80:83], v[34:37], v[30:33], 0
	v_fma_f32 v78, v78, s98, v153
	v_add_f32_e32 v69, 1.0, v69
	v_add_f32_e32 v75, 1.0, v75
	v_rcp_f32_e32 v69, v69
	v_rcp_f32_e32 v75, v75
	v_mfma_f32_16x16x32_bf16 v[80:83], v[38:41], v[22:25], v[80:83]
	v_fma_f32 v79, v79, s98, v153
	v_mul_f32_e32 v69, v74, v69
	v_mul_f32_e32 v75, v74, v75
	s_nop 0
	s_nop 0
	s_nop 2
	v_fma_f32 v71, v80, s98, v152
	v_fma_f32 v77, v81, s98, v152
	s_nop 0
	s_nop 0
	s_nop 0
	v_exp_f32_e32 v69, v69
	s_nop 0
	v_exp_f32_e32 v75, v75
	v_exp_f32_e32 v78, v78
	v_exp_f32_e32 v79, v79
	v_exp_f32_e32 v71, v71
	v_exp_f32_e32 v77, v77
	v_fma_f32 v76, -v69, v69, 1.0
	v_fma_f32 v81, -v75, v75, 1.0
	v_add_f32_e32 v78, 1.0, v78
	v_add_f32_e32 v79, 1.0, v79
	v_add_f32_e32 v71, 1.0, v71
	v_max_f32_e32 v76, 0, v76
	ds_read_u16 v80, v70 offset:25872
	v_add_f32_e32 v77, 1.0, v77
	v_max_f32_e32 v81, 0, v81
	v_rcp_f32_e32 v78, v78
	v_rcp_f32_e32 v79, v79
	v_rcp_f32_e32 v71, v71
	v_sqrt_f32_e32 v76, v76
	v_rcp_f32_e32 v77, v77
	v_sqrt_f32_e32 v81, v81
	v_mul_f32_e32 v78, v74, v78
	v_mul_f32_e32 v79, v74, v79
	v_mul_f32_e32 v71, v71, v76
	v_mul_f32_e32 v77, v77, v81
	ds_read_u16 v81, v70 offset:26400
	s_waitcnt lgkmcnt(1)
	v_lshlrev_b32_e32 v76, 16, v80
	v_fma_f32 v80, v82, s98, v152
	s_nop 0
	v_fma_f32 v83, v83, s98, v152
	s_nop 0
	s_nop 0
	v_exp_f32_e32 v78, v78
	s_nop 0
	v_exp_f32_e32 v79, v79
	v_exp_f32_e32 v80, v80
	v_exp_f32_e32 v83, v83
	v_fma_f32 v82, -v78, v78, 1.0
	v_fma_f32 v126, -v79, v79, 1.0
	v_add_f32_e32 v80, 1.0, v80
	v_max_f32_e32 v82, 0, v82
	v_add_f32_e32 v83, 1.0, v83
	v_max_f32_e32 v126, 0, v126
	v_rcp_f32_e32 v80, v80
	v_sqrt_f32_e32 v82, v82
	v_rcp_f32_e32 v83, v83
	v_sqrt_f32_e32 v126, v126
	s_waitcnt lgkmcnt(0)
	v_lshlrev_b32_e32 v81, 16, v81
	v_mul_f32_e32 v80, v80, v82
	v_lshlrev_b32_e32 v82, 16, v125
	v_mul_f32_e32 v83, v83, v126
	v_mul_f32_e32 v82, v83, v82
	v_mul_f32_e32 v79, v78, v79
	v_mul_f32_e32 v78, v78, v82
	v_fmac_f32_e32 v78, v80, v81
	v_mul_f32_e32 v79, v75, v79
	v_mul_f32_e32 v75, v75, v78
	v_fmac_f32_e32 v75, v77, v76
	v_mul_f32_e32 v80, v69, v79
	v_mfma_f32_16x16x32_bf16 v[76:79], v[34:37], v[6:9], 0
	ds_bpermute_b32 v120, v68, v73 offset:64
	ds_bpermute_b32 v121, v68, v73 offset:128
	ds_bpermute_b32 v124, v68, v73 offset:192
	v_mfma_f32_16x16x32_bf16 v[34:37], v[34:37], v[14:17], 0
	ds_read_u16 v73, v70 offset:25344
	v_mul_f32_e32 v75, v69, v75
	ds_bpermute_b32 v126, v68, v80
	v_mfma_f32_16x16x32_bf16 v[76:79], v[38:41], v[2:5], v[76:79]
	ds_bpermute_b32 v128, v68, v80 offset:64
	ds_bpermute_b32 v69, v68, v80 offset:128
	ds_bpermute_b32 v61, v68, v63 offset:128
	v_mfma_f32_16x16x32_bf16 v[34:37], v[38:41], v[10:13], v[34:37]
	ds_read_u16 v40, v70 offset:25376
	s_nop 2
	v_fma_f32 v38, v76, s98, v151
	s_nop 0
	v_exp_f32_e32 v38, v38
	v_fma_f32 v39, v77, s98, v151
	s_nop 0
	v_exp_f32_e32 v39, v39
	v_add_f32_e32 v38, 1.0, v38
	v_rcp_f32_e32 v38, v38
	v_fma_f32 v34, v34, s98, v150
	s_nop 0
	v_add_f32_e32 v39, 1.0, v39
	v_mul_f32_e32 v38, v72, v38
	s_nop 0
	v_exp_f32_e32 v38, v38
	v_exp_f32_e32 v34, v34
	v_rcp_f32_e32 v39, v39
	v_fma_f32 v35, v35, s98, v150
	v_fma_f32 v41, -v38, v38, 1.0
	v_add_f32_e32 v34, 1.0, v34
	v_max_f32_e32 v41, 0, v41
	v_mul_f32_e32 v39, v72, v39
	v_rcp_f32_e32 v34, v34
	v_sqrt_f32_e32 v41, v41
	s_nop 0
	s_nop 0
	v_exp_f32_e32 v39, v39
	v_exp_f32_e32 v35, v35
	ds_read_u16 v76, v70 offset:25904
	s_waitcnt lgkmcnt(6)
	v_lshlrev_b32_e32 v73, 16, v73
	v_fmac_f32_e32 v75, v71, v73
	ds_bpermute_b32 v125, v68, v75
	ds_bpermute_b32 v127, v68, v75 offset:64
	ds_bpermute_b32 v129, v68, v75 offset:128
	ds_bpermute_b32 v130, v68, v75 offset:192
	v_mul_f32_e32 v75, v34, v41
	v_fma_f32 v34, v78, s98, v151
	v_fma_f32 v73, -v39, v39, 1.0
	s_nop 0
	v_add_f32_e32 v35, 1.0, v35
	v_max_f32_e32 v73, 0, v73
	v_exp_f32_e32 v34, v34
	v_rcp_f32_e32 v35, v35
	v_sqrt_f32_e32 v77, v73
	s_waitcnt lgkmcnt(5)
; template <int DIR, int MODE>
; __device__ __forceinline__ void lru_pass(const Args& a, const LAS bf16_t* cxb, LAS bf16_t* gyb, const LAS float* carry, const bf16x8 (&Bw)[2][2][2], const float (&prm)[2][3], int l, int tt, float (&hf)[8][2][4]) {
;     ...
;     for (int mi = 0; mi < 8; ++mi) {
;         const int m = DIR ? 7 - mi : mi;
;         bf16x8 Af[2];
; #pragma unroll
;         for (int ks = 0; ks < 2; ++ks) Af[ks] = *(const LAS bf16x8*)(cxb + (m * 16 + fr) * CXS + 64 * h + 32 * ks + 8 * fq);
; #pragma unroll
;         for (int nt = 0; nt < 2; ++nt) {
;             f32x4 pr = (f32x4){0.f, 0.f, 0.f, 0.f}, pi = (f32x4){0.f, 0.f, 0.f, 0.f};
; #pragma unroll
;             for (int ks = 0; ks < 2; ++ks) { pr = __builtin_amdgcn_mfma_f32_16x16x32_bf16(Af[ks], Bw[0][nt][ks], pr, 0, 0, 0); pi = __builtin_amdgcn_mfma_f32_16x16x32_bf16(Af[ks], Bw[1][nt][ks], pi, 0, 0, 0); }
;             float av[4], bv[4];
; #pragma unroll
;             for (int reg = 0; reg < 4; ++reg) {
;                 const int tok = m * 16 + 4 * fq + reg;
;                 const float x = bf2f(cxb[tok * CXS + cc[nt]]);
;                 const float r = fsig(pr[reg] + ba[nt]), ig = fsig(pi[reg] + bxv[nt]);
;                 const float aa = __expf(k8[nt] * r);
;                 av[reg] = aa; bv[reg] = __builtin_amdgcn_sqrtf(fmaxf(1.0f - aa * aa, 0.f)) * ig * x;
;             }
;             float cum[4], hl[4];
;             if (DIR == 0) { cum[0] = av[0]; hl[0] = bv[0];
; #pragma unroll
;                 for (int reg = 1; reg < 4; ++reg) { cum[reg] = cum[reg - 1] * av[reg]; hl[reg] = av[reg] * hl[reg - 1] + bv[reg]; } }
;             else { cum[3] = av[3]; hl[3] = bv[3];
; #pragma unroll
;     ...
;             const float A4 = DIR ? cum[0] : cum[3], H4 = DIR ? hl[0] : hl[3];
;             float Aq[4], Hq[4];
; #pragma unroll
;             for (int q = 0; q < 4; ++q) { Aq[q] = __shfl(A4, fr + 16 * q); Hq[q] = __shfl(H4, fr + 16 * q); }
;             float hin;
;             if (DIR == 0) { const float s0 = C[nt], s1 = Aq[0] * s0 + Hq[0], s2 = Aq[1] * s1 + Hq[1], s3 = Aq[2] * s2 + Hq[2]; C[nt] = Aq[3] * s3 + Hq[3]; hin = fq == 0 ? s0 : (fq == 1 ? s1 : (fq == 2 ? s2 : s3)); }
;             else { const float s3 = C[nt], s2 = Aq[3] * s3 + Hq[3], s1 = Aq[2] * s2 + Hq[2], s0 = Aq[1] * s1 + Hq[1]; C[nt] = Aq[0] * s0 + Hq[0]; hin = fq == 3 ? s3 : (fq == 2 ? s2 : (fq == 1 ? s1 : s0)); }
	v_lshlrev_b32_e32 v73, 16, v40
	v_add_f32_e32 v34, 1.0, v34
	s_waitcnt lgkmcnt(4)
	v_lshlrev_b32_e32 v40, 16, v76
	v_mul_f32_e32 v41, v35, v77
	v_fma_f32 v35, v36, s98, v150
	v_rcp_f32_e32 v36, v34
	v_fma_f32 v37, v37, s98, v150
	s_nop 0
	s_nop 0
	v_mul_f32_e32 v36, v72, v36
	s_nop 0
	v_exp_f32_e32 v76, v36
	v_fma_f32 v36, v79, s98, v151
	s_nop 0
	v_exp_f32_e32 v77, v36
	v_exp_f32_e32 v35, v35
	v_fma_f32 v36, -v76, v76, 1.0
	ds_read_u16 v34, v70 offset:26432
	v_add_f32_e32 v77, 1.0, v77
	v_rcp_f32_e32 v78, v77
	v_exp_f32_e32 v77, v37
	v_add_f32_e32 v35, 1.0, v35
	v_max_f32_e32 v36, 0, v36
	v_mul_f32_e32 v37, v72, v78
	s_nop 0
	v_exp_f32_e32 v37, v37
	ds_read_u16 v78, v70 offset:26960
	v_add_f32_e32 v77, 1.0, v77
	v_rcp_f32_e32 v35, v35
	v_fma_f32 v79, -v37, v37, 1.0
	v_max_f32_e32 v79, 0, v79
	v_sqrt_f32_e32 v36, v36
	v_rcp_f32_e32 v77, v77
	v_sqrt_f32_e32 v79, v79
	ds_bpermute_b32 v71, v68, v80 offset:192
	s_waitcnt lgkmcnt(2)
	v_lshlrev_b32_e32 v80, 16, v34
	v_mul_f32_e32 v81, v35, v36
	s_waitcnt lgkmcnt(1)
	v_lshlrev_b32_e32 v34, 16, v78
	v_mul_f32_e32 v35, v77, v79
	v_mul_f32_e32 v77, v35, v34
	v_mul_f32_e32 v78, v76, v37
	ds_read_b128 v[34:37], v89 offset:16896
	v_mul_f32_e32 v76, v76, v77
	v_fmac_f32_e32 v76, v81, v80
	v_mul_f32_e32 v77, v39, v78
	v_mul_f32_e32 v39, v39, v76
	v_fmac_f32_e32 v39, v41, v40
	v_mul_f32_e32 v136, v38, v77
	v_mul_f32_e32 v137, v38, v39
	ds_read_b128 v[38:41], v89 offset:16960
	s_waitcnt lgkmcnt(1)
	v_mfma_f32_16x16x32_bf16 v[76:79], v[34:37], v[26:29], 0
	v_fmac_f32_e32 v137, v75, v73
	ds_bpermute_b32 v132, v68, v136
	ds_bpermute_b32 v131, v68, v137
	s_waitcnt lgkmcnt(2)
	v_mfma_f32_16x16x32_bf16 v[76:79], v[38:41], v[18:21], v[76:79]
	ds_bpermute_b32 v134, v68, v136 offset:64
	ds_bpermute_b32 v133, v68, v137 offset:64
	ds_bpermute_b32 v73, v68, v136 offset:128
	s_nop 4
	v_fma_f32 v77, v77, s98, v153
	s_nop 0
	v_exp_f32_e32 v77, v77
	v_fma_f32 v76, v76, s98, v153
	v_mfma_f32_16x16x32_bf16 v[80:83], v[34:37], v[30:33], 0
	s_nop 0
	v_exp_f32_e32 v76, v76
	v_add_f32_e32 v77, 1.0, v77
	v_fma_f32 v78, v78, s98, v153
	v_fma_f32 v79, v79, s98, v153
	v_rcp_f32_e32 v77, v77
	s_nop 0
	s_nop 0
	v_mfma_f32_16x16x32_bf16 v[80:83], v[38:41], v[22:25], v[80:83]
	v_exp_f32_e32 v78, v78
	v_exp_f32_e32 v79, v79
	v_add_f32_e32 v76, 1.0, v76
	v_rcp_f32_e32 v76, v76
	v_mul_f32_e32 v77, v74, v77
	s_nop 2
	v_fma_f32 v81, v81, s98, v152
	s_nop 0
	v_add_f32_e32 v78, 1.0, v78
	v_add_f32_e32 v79, 1.0, v79
	s_nop 0
	v_exp_f32_e32 v77, v77
	v_rcp_f32_e32 v78, v78
	v_rcp_f32_e32 v79, v79
	v_mul_f32_e32 v76, v74, v76
	v_exp_f32_e32 v81, v81
	v_fma_f32 v80, v80, s98, v152
	s_nop 0
	s_nop 0
	v_exp_f32_e32 v76, v76
	v_exp_f32_e32 v80, v80
	v_fma_f32 v140, -v77, v77, 1.0
	v_mul_f32_e32 v78, v74, v78
	v_mul_f32_e32 v79, v74, v79
	v_add_f32_e32 v81, 1.0, v81
	v_max_f32_e32 v140, 0, v140
	v_fma_f32 v82, v82, s98, v152
	s_nop 0
	v_fma_f32 v83, v83, s98, v152
	s_nop 0
	v_rcp_f32_e32 v81, v81
	v_sqrt_f32_e32 v140, v140
	s_nop 0
	v_exp_f32_e32 v78, v78
	s_nop 0
	v_exp_f32_e32 v79, v79
	v_fma_f32 v138, -v76, v76, 1.0
	v_exp_f32_e32 v82, v82
	v_exp_f32_e32 v83, v83
	v_add_f32_e32 v80, 1.0, v80
	v_max_f32_e32 v138, 0, v138
	v_rcp_f32_e32 v80, v80
	v_sqrt_f32_e32 v138, v138
	v_mul_f32_e32 v81, v81, v140
	v_fma_f32 v140, -v78, v78, 1.0
	v_fma_f32 v142, -v79, v79, 1.0
	v_add_f32_e32 v82, 1.0, v82
	v_max_f32_e32 v140, 0, v140
	v_add_f32_e32 v83, 1.0, v83
	v_max_f32_e32 v142, 0, v142
	v_rcp_f32_e32 v82, v82
	v_sqrt_f32_e32 v140, v140
	v_rcp_f32_e32 v83, v83
	v_sqrt_f32_e32 v142, v142
	v_mul_f32_e32 v138, v80, v138
	v_lshlrev_b32_e32 v80, 16, v139
	ds_read_u16 v139, v70 offset:17952
	v_mul_f32_e32 v82, v82, v140
	v_lshlrev_b32_e32 v140, 16, v141
	v_mul_f32_e32 v83, v83, v142
	v_mul_f32_e32 v83, v83, v140
	s_waitcnt lgkmcnt(0)
	v_lshlrev_b32_e32 v139, 16, v139
	v_mul_f32_e32 v79, v78, v79
	v_mul_f32_e32 v78, v78, v83
	v_fmac_f32_e32 v78, v82, v139
	v_mul_f32_e32 v79, v77, v79
	v_mul_f32_e32 v77, v77, v78
	v_fmac_f32_e32 v77, v81, v80
	v_mfma_f32_16x16x32_bf16 v[80:83], v[34:37], v[6:9], 0
	ds_bpermute_b32 v135, v68, v137 offset:128
	ds_bpermute_b32 v75, v68, v136 offset:192
	ds_bpermute_b32 v136, v68, v137 offset:192
	v_mfma_f32_16x16x32_bf16 v[34:37], v[34:37], v[14:17], 0
	ds_read_u16 v137, v70 offset:16896
	ds_read_u16 v141, v70 offset:17456
	v_mul_f32_e32 v140, v76, v77
	v_mfma_f32_16x16x32_bf16 v[80:83], v[38:41], v[2:5], v[80:83]
	v_mul_f32_e32 v79, v76, v79
	ds_bpermute_b32 v63, v68, v63 offset:192
	ds_bpermute_b32 v64, v68, v67
	v_mfma_f32_16x16x32_bf16 v[34:37], v[38:41], v[10:13], v[34:37]
	ds_read_u16 v40, v70 offset:16928
	s_nop 2
	v_fma_f32 v38, v80, s98, v151
	s_nop 0
	v_exp_f32_e32 v38, v38
	v_fma_f32 v39, v81, s98, v151
	s_nop 0
	v_exp_f32_e32 v39, v39
	v_add_f32_e32 v38, 1.0, v38
	v_rcp_f32_e32 v38, v38
	v_fma_f32 v34, v34, s98, v150
	s_nop 0
	v_add_f32_e32 v39, 1.0, v39
	v_mul_f32_e32 v38, v72, v38
	s_nop 0
	v_exp_f32_e32 v38, v38
	v_exp_f32_e32 v34, v34
	v_rcp_f32_e32 v39, v39
	v_fma_f32 v35, v35, s98, v150
	v_fma_f32 v41, -v38, v38, 1.0
	v_add_f32_e32 v34, 1.0, v34
	v_max_f32_e32 v41, 0, v41
	v_mul_f32_e32 v39, v72, v39
	v_rcp_f32_e32 v34, v34
	v_sqrt_f32_e32 v41, v41
	s_nop 0
	s_nop 0
	v_exp_f32_e32 v39, v39
	v_exp_f32_e32 v35, v35
	v_mul_f32_e32 v81, v34, v41
	v_fma_f32 v34, v82, s98, v151
	v_fma_f32 v80, -v39, v39, 1.0
	s_nop 0
	v_add_f32_e32 v35, 1.0, v35
	v_max_f32_e32 v80, 0, v80
	v_exp_f32_e32 v34, v34
	v_rcp_f32_e32 v35, v35
	v_sqrt_f32_e32 v142, v80
	v_fma_f32 v37, v37, s98, v150
	v_add_f32_e32 v34, 1.0, v34
	s_nop 0
	v_mul_f32_e32 v41, v35, v142
	v_fma_f32 v35, v36, s98, v150
	v_rcp_f32_e32 v36, v34
	ds_read_u16 v34, v70 offset:17984
	s_waitcnt lgkmcnt(1)
; #define LAS __attribute__((address_space(3)))
; __device__ __forceinline__ float fsig(float x) { return frcp(1.0f + __expf(-x)); }
; template <int DIR, int MODE>
; __device__ __forceinline__ void lru_pass(const Args& a, const LAS bf16_t* cxb, LAS bf16_t* gyb, const LAS float* carry, const bf16x8 (&Bw)[2][2][2], const float (&prm)[2][3], int l, int tt, float (&hf)[8][2][4]) {
;     ...
;         for (int ks = 0; ks < 2; ++ks) Af[ks] = *(const LAS bf16x8*)(cxb + (m * 16 + fr) * CXS + 64 * h + 32 * ks + 8 * fq);
; #pragma unroll
;         for (int nt = 0; nt < 2; ++nt) {
;             f32x4 pr = (f32x4){0.f, 0.f, 0.f, 0.f}, pi = (f32x4){0.f, 0.f, 0.f, 0.f};
; #pragma unroll
;             for (int ks = 0; ks < 2; ++ks) { pr = __builtin_amdgcn_mfma_f32_16x16x32_bf16(Af[ks], Bw[0][nt][ks], pr, 0, 0, 0); pi = __builtin_amdgcn_mfma_f32_16x16x32_bf16(Af[ks], Bw[1][nt][ks], pi, 0, 0, 0); }
;             float av[4], bv[4];
; #pragma unroll
;             for (int reg = 0; reg < 4; ++reg) {
;                 const int tok = m * 16 + 4 * fq + reg;
;                 const float x = bf2f(cxb[tok * CXS + cc[nt]]);
;                 const float r = fsig(pr[reg] + ba[nt]), ig = fsig(pi[reg] + bxv[nt]);
;                 const float aa = __expf(k8[nt] * r);
;                 av[reg] = aa; bv[reg] = __builtin_amdgcn_sqrtf(fmaxf(1.0f - aa * aa, 0.f)) * ig * x;
;             }
;             float cum[4], hl[4];
;             if (DIR == 0) { cum[0] = av[0]; hl[0] = bv[0];
; #pragma unroll
;                 for (int reg = 1; reg < 4; ++reg) { cum[reg] = cum[reg - 1] * av[reg]; hl[reg] = av[reg] * hl[reg - 1] + bv[reg]; } }
;             else { cum[3] = av[3]; hl[3] = bv[3];
; #pragma unroll
;     ...
;             const float A4 = DIR ? cum[0] : cum[3], H4 = DIR ? hl[0] : hl[3];
;             float Aq[4], Hq[4];
; #pragma unroll
;             for (int q = 0; q < 4; ++q) { Aq[q] = __shfl(A4, fr + 16 * q); Hq[q] = __shfl(H4, fr + 16 * q); }
	v_lshlrev_b32_e32 v80, 16, v40
	v_lshlrev_b32_e32 v40, 16, v141
	v_mul_f32_e32 v36, v72, v36
	s_nop 0
	v_exp_f32_e32 v82, v36
	v_fma_f32 v36, v83, s98, v151
	s_nop 0
	v_exp_f32_e32 v83, v36
	s_nop 0
	v_exp_f32_e32 v35, v35
	v_fma_f32 v36, -v82, v82, 1.0
	v_add_f32_e32 v83, 1.0, v83
	v_rcp_f32_e32 v141, v83
	v_exp_f32_e32 v83, v37
	v_add_f32_e32 v35, 1.0, v35
	v_max_f32_e32 v36, 0, v36
	v_mul_f32_e32 v37, v72, v141
	s_nop 0
	v_exp_f32_e32 v37, v37
	ds_read_u16 v141, v70 offset:18512
	v_add_f32_e32 v83, 1.0, v83
	v_rcp_f32_e32 v35, v35
	v_fma_f32 v142, -v37, v37, 1.0
	v_max_f32_e32 v142, 0, v142
	v_sqrt_f32_e32 v36, v36
	v_rcp_f32_e32 v83, v83
	v_sqrt_f32_e32 v142, v142
	s_waitcnt lgkmcnt(1)
	v_lshlrev_b32_e32 v143, 16, v34
	v_mul_f32_e32 v144, v35, v36
	s_waitcnt lgkmcnt(0)
	v_lshlrev_b32_e32 v34, 16, v141
	v_mul_f32_e32 v35, v83, v142
	v_mul_f32_e32 v83, v35, v34
	v_mul_f32_e32 v141, v82, v37
	ds_read_b128 v[34:37], v89 offset:8448
	v_mul_f32_e32 v82, v82, v83
	v_fmac_f32_e32 v82, v144, v143
	v_mul_f32_e32 v83, v39, v141
	v_mul_f32_e32 v39, v39, v82
	v_fmac_f32_e32 v39, v41, v40
	v_mul_f32_e32 v83, v38, v83
	v_mul_f32_e32 v158, v38, v39
	ds_read_b128 v[38:41], v89 offset:8512
	s_waitcnt lgkmcnt(1)
	v_mfma_f32_16x16x32_bf16 v[144:147], v[34:37], v[26:29], 0
	v_fmac_f32_e32 v158, v81, v80
	ds_bpermute_b32 v141, v68, v158
	ds_bpermute_b32 v142, v68, v158 offset:64
	s_waitcnt lgkmcnt(2)
	v_mfma_f32_16x16x32_bf16 v[146:149], v[38:41], v[18:21], v[144:147]
	ds_bpermute_b32 v143, v68, v158 offset:128
	s_nop 1
	ds_bpermute_b32 v144, v68, v158 offset:192
	ds_bpermute_b32 v66, v68, v67 offset:64
	s_nop 2
	v_fma_f32 v145, v146, s98, v153
	v_fma_f32 v147, v147, s98, v153
	s_nop 0
	s_nop 0
	v_exp_f32_e32 v145, v145
	v_exp_f32_e32 v147, v147
	v_mfma_f32_16x16x32_bf16 v[154:157], v[34:37], v[30:33], 0
	v_fma_f32 v148, v148, s98, v153
	v_add_f32_e32 v145, 1.0, v145
	v_add_f32_e32 v147, 1.0, v147
	v_fma_f32 v149, v149, s98, v153
	v_rcp_f32_e32 v145, v145
	v_rcp_f32_e32 v147, v147
	s_nop 0
	s_nop 0
	v_mfma_f32_16x16x32_bf16 v[154:157], v[38:41], v[22:25], v[154:157]
	v_exp_f32_e32 v148, v148
	v_exp_f32_e32 v149, v149
	v_mul_f32_e32 v145, v74, v145
	v_mul_f32_e32 v147, v74, v147
	s_nop 0
	s_nop 2
	v_fma_f32 v146, v154, s98, v152
	v_fma_f32 v155, v155, s98, v152
	s_nop 0
	v_add_f32_e32 v148, 1.0, v148
	v_add_f32_e32 v149, 1.0, v149
	s_nop 0
	v_exp_f32_e32 v145, v145
	s_nop 0
	v_exp_f32_e32 v147, v147
	v_rcp_f32_e32 v148, v148
	v_rcp_f32_e32 v149, v149
	v_exp_f32_e32 v146, v146
	v_exp_f32_e32 v155, v155
	v_fma_f32 v158, -v145, v145, 1.0
	v_fma_f32 v160, -v147, v147, 1.0
	v_mul_f32_e32 v148, v74, v148
	v_mul_f32_e32 v149, v74, v149
	ds_read_u16 v154, v70 offset:8448
	v_add_f32_e32 v146, 1.0, v146
	v_max_f32_e32 v158, 0, v158
	v_add_f32_e32 v155, 1.0, v155
	v_max_f32_e32 v160, 0, v160
	v_fma_f32 v156, v156, s98, v152
	s_nop 0
	v_fma_f32 v157, v157, s98, v152
	s_nop 0
	v_rcp_f32_e32 v146, v146
	v_sqrt_f32_e32 v158, v158
	v_rcp_f32_e32 v155, v155
	v_sqrt_f32_e32 v160, v160
	s_nop 0
	v_exp_f32_e32 v148, v148
	s_nop 0
	v_exp_f32_e32 v149, v149
	v_exp_f32_e32 v156, v156
	v_exp_f32_e32 v157, v157
	v_mul_f32_e32 v146, v146, v158
	v_mul_f32_e32 v155, v155, v160
	ds_read_u16 v158, v70 offset:9504
	ds_read_u16 v160, v70 offset:10032
	s_waitcnt lgkmcnt(2)
	v_lshlrev_b32_e32 v161, 16, v154
	v_lshlrev_b32_e32 v154, 16, v159
	v_fma_f32 v159, -v148, v148, 1.0
	v_fma_f32 v162, -v149, v149, 1.0
	v_add_f32_e32 v156, 1.0, v156
	v_max_f32_e32 v159, 0, v159
	v_add_f32_e32 v157, 1.0, v157
	v_max_f32_e32 v162, 0, v162
	v_rcp_f32_e32 v156, v156
	v_sqrt_f32_e32 v159, v159
	v_rcp_f32_e32 v157, v157
	v_sqrt_f32_e32 v162, v162
	s_waitcnt lgkmcnt(1)
	v_lshlrev_b32_e32 v158, 16, v158
	v_mul_f32_e32 v156, v156, v159
	s_waitcnt lgkmcnt(0)
	v_lshlrev_b32_e32 v159, 16, v160
	v_mul_f32_e32 v157, v157, v162
	v_mul_f32_e32 v157, v157, v159
	v_mul_f32_e32 v149, v148, v149
	v_mul_f32_e32 v148, v148, v157
	v_fmac_f32_e32 v148, v156, v158
	v_mul_f32_e32 v149, v147, v149
	v_mul_f32_e32 v147, v147, v148
	v_fmac_f32_e32 v147, v155, v154
	v_mfma_f32_16x16x32_bf16 v[154:157], v[34:37], v[6:9], 0
	v_mul_f32_e32 v163, v145, v147
	v_fmac_f32_e32 v163, v146, v161
	v_mul_f32_e32 v162, v145, v149
	v_mfma_f32_16x16x32_bf16 v[34:37], v[34:37], v[14:17], 0
	ds_bpermute_b32 v146, v68, v162
	ds_bpermute_b32 v148, v68, v162 offset:64
	ds_bpermute_b32 v149, v68, v162 offset:128
	v_mfma_f32_16x16x32_bf16 v[158:161], v[38:41], v[2:5], v[154:157]
	ds_bpermute_b32 v145, v68, v163
	ds_bpermute_b32 v147, v68, v163 offset:64
	ds_bpermute_b32 v65, v68, v67 offset:128
	v_mfma_f32_16x16x32_bf16 v[34:37], v[38:41], v[10:13], v[34:37]
	ds_bpermute_b32 v156, v68, v162 offset:192
	s_nop 2
	v_fma_f32 v38, v158, s98, v151
	s_nop 0
	v_exp_f32_e32 v38, v38
	v_fma_f32 v39, v159, s98, v151
	s_nop 0
	v_exp_f32_e32 v39, v39
	v_add_f32_e32 v38, 1.0, v38
	v_rcp_f32_e32 v38, v38
	v_fma_f32 v34, v34, s98, v150
	s_nop 0
	v_add_f32_e32 v39, 1.0, v39
	v_mul_f32_e32 v38, v72, v38
	s_nop 0
	v_exp_f32_e32 v38, v38
	v_exp_f32_e32 v34, v34
	v_rcp_f32_e32 v39, v39
	v_fma_f32 v35, v35, s98, v150
	v_fma_f32 v41, -v38, v38, 1.0
	v_add_f32_e32 v34, 1.0, v34
	v_max_f32_e32 v41, 0, v41
	v_mul_f32_e32 v39, v72, v39
	v_rcp_f32_e32 v34, v34
	v_sqrt_f32_e32 v41, v41
	s_nop 0
	s_nop 0
	v_exp_f32_e32 v39, v39
	v_exp_f32_e32 v35, v35
	v_mul_f32_e32 v158, v34, v41
	v_fma_f32 v34, v160, s98, v151
	v_fma_f32 v157, -v39, v39, 1.0
	s_nop 0
	v_add_f32_e32 v35, 1.0, v35
	v_max_f32_e32 v157, 0, v157
	v_exp_f32_e32 v34, v34
	v_rcp_f32_e32 v35, v35
	v_sqrt_f32_e32 v162, v157
	ds_read_u16 v40, v70 offset:8480
	ds_read_u16 v159, v70 offset:9008
	v_add_f32_e32 v34, 1.0, v34
	v_mul_f32_e32 v41, v35, v162
	v_fma_f32 v35, v36, s98, v150
	v_rcp_f32_e32 v36, v34
	ds_read_u16 v34, v70 offset:9536
	s_waitcnt lgkmcnt(2)
; #define LAS __attribute__((address_space(3)))
; __device__ __forceinline__ float fsig(float x) { return frcp(1.0f + __expf(-x)); }
; template <int DIR, int MODE>
; __device__ __forceinline__ void lru_pass(const Args& a, const LAS bf16_t* cxb, LAS bf16_t* gyb, const LAS float* carry, const bf16x8 (&Bw)[2][2][2], const float (&prm)[2][3], int l, int tt, float (&hf)[8][2][4]) {
;     ...
;         for (int ks = 0; ks < 2; ++ks) Af[ks] = *(const LAS bf16x8*)(cxb + (m * 16 + fr) * CXS + 64 * h + 32 * ks + 8 * fq);
; #pragma unroll
;         for (int nt = 0; nt < 2; ++nt) {
;             f32x4 pr = (f32x4){0.f, 0.f, 0.f, 0.f}, pi = (f32x4){0.f, 0.f, 0.f, 0.f};
; #pragma unroll
;             for (int ks = 0; ks < 2; ++ks) { pr = __builtin_amdgcn_mfma_f32_16x16x32_bf16(Af[ks], Bw[0][nt][ks], pr, 0, 0, 0); pi = __builtin_amdgcn_mfma_f32_16x16x32_bf16(Af[ks], Bw[1][nt][ks], pi, 0, 0, 0); }
;             float av[4], bv[4];
; #pragma unroll
;             for (int reg = 0; reg < 4; ++reg) {
;                 const int tok = m * 16 + 4 * fq + reg;
;                 const float x = bf2f(cxb[tok * CXS + cc[nt]]);
;                 const float r = fsig(pr[reg] + ba[nt]), ig = fsig(pi[reg] + bxv[nt]);
;                 const float aa = __expf(k8[nt] * r);
;                 av[reg] = aa; bv[reg] = __builtin_amdgcn_sqrtf(fmaxf(1.0f - aa * aa, 0.f)) * ig * x;
;             }
;             float cum[4], hl[4];
;             if (DIR == 0) { cum[0] = av[0]; hl[0] = bv[0];
; #pragma unroll
;                 for (int reg = 1; reg < 4; ++reg) { cum[reg] = cum[reg - 1] * av[reg]; hl[reg] = av[reg] * hl[reg - 1] + bv[reg]; } }
;             else { cum[3] = av[3]; hl[3] = bv[3];
; #pragma unroll
;     ...
;             const float A4 = DIR ? cum[0] : cum[3], H4 = DIR ? hl[0] : hl[3];
;             float Aq[4], Hq[4];
; #pragma unroll
;             for (int q = 0; q < 4; ++q) { Aq[q] = __shfl(A4, fr + 16 * q); Hq[q] = __shfl(H4, fr + 16 * q); }
	v_lshlrev_b32_e32 v157, 16, v40
	s_waitcnt lgkmcnt(1)
	v_lshlrev_b32_e32 v40, 16, v159
	v_mul_f32_e32 v36, v72, v36
	s_nop 0
	v_exp_f32_e32 v159, v36
	v_fma_f32 v36, v161, s98, v151
	s_nop 0
	v_exp_f32_e32 v160, v36
	v_fma_f32 v37, v37, s98, v150
	s_nop 0
	s_nop 0
	v_add_f32_e32 v160, 1.0, v160
	v_rcp_f32_e32 v161, v160
	v_exp_f32_e32 v160, v37
	v_exp_f32_e32 v35, v35
	v_fma_f32 v36, -v159, v159, 1.0
	v_mul_f32_e32 v37, v72, v161
	s_nop 0
	v_exp_f32_e32 v37, v37
	v_add_f32_e32 v35, 1.0, v35
	v_max_f32_e32 v36, 0, v36
	ds_read_u16 v161, v70 offset:10064
	v_fma_f32 v162, -v37, v37, 1.0
	v_add_f32_e32 v160, 1.0, v160
	v_max_f32_e32 v162, 0, v162
	v_rcp_f32_e32 v35, v35
	v_sqrt_f32_e32 v36, v36
	v_rcp_f32_e32 v160, v160
	v_sqrt_f32_e32 v162, v162
	ds_bpermute_b32 v154, v68, v163 offset:128
	ds_bpermute_b32 v155, v68, v163 offset:192
	s_waitcnt lgkmcnt(3)
	v_lshlrev_b32_e32 v163, 16, v34
	v_mul_f32_e32 v164, v35, v36
	s_waitcnt lgkmcnt(2)
	v_lshlrev_b32_e32 v34, 16, v161
	v_mul_f32_e32 v35, v160, v162
	v_mul_f32_e32 v160, v35, v34
	v_mul_f32_e32 v161, v159, v37
	ds_read_b128 v[34:37], v89
	v_mul_f32_e32 v159, v159, v160
	v_fmac_f32_e32 v159, v164, v163
	v_mul_f32_e32 v160, v39, v161
	v_mul_f32_e32 v39, v39, v159
	v_fmac_f32_e32 v39, v41, v40
	v_mul_f32_e32 v168, v38, v160
	v_mul_f32_e32 v169, v38, v39
	ds_read_b128 v[38:41], v89 offset:64
	s_waitcnt lgkmcnt(1)
	v_mfma_f32_16x16x32_bf16 v[160:163], v[34:37], v[26:29], 0
	v_fmac_f32_e32 v169, v158, v157
	ds_read_u16 v89, v70 offset:32
	ds_read_u16 v157, v70 offset:528
	s_waitcnt lgkmcnt(2)
	v_mfma_f32_16x16x32_bf16 v[158:161], v[38:41], v[18:21], v[160:163]
	ds_read_u16 v21, v70
	ds_bpermute_b32 v67, v68, v67 offset:192
	ds_bpermute_b32 v76, v68, v79
	v_mfma_f32_16x16x32_bf16 v[164:167], v[34:37], v[30:33], 0
	s_nop 3
	v_fma_f32 v31, v158, s98, v153
	v_fma_f32 v32, v159, s98, v153
	s_nop 0
	s_nop 0
	v_exp_f32_e32 v31, v31
	v_exp_f32_e32 v32, v32
	v_mfma_f32_16x16x32_bf16 v[22:25], v[38:41], v[22:25], v[164:167]
	ds_bpermute_b32 v78, v68, v79 offset:64
	v_add_f32_e32 v31, 1.0, v31
	v_add_f32_e32 v32, 1.0, v32
	v_rcp_f32_e32 v31, v31
	v_rcp_f32_e32 v32, v32
	s_nop 2
	v_fma_f32 v22, v22, s98, v152
	v_fma_f32 v23, v23, s98, v152
	v_mul_f32_e32 v31, v74, v31
	v_mul_f32_e32 v32, v74, v32
	s_nop 0
	s_nop 0
	s_nop 0
	v_exp_f32_e32 v31, v31
	s_nop 0
	v_exp_f32_e32 v32, v32
	v_exp_f32_e32 v22, v22
	v_exp_f32_e32 v23, v23
	v_fma_f32 v33, -v31, v31, 1.0
	v_fma_f32 v158, -v32, v32, 1.0
	v_add_f32_e32 v22, 1.0, v22
	v_max_f32_e32 v33, 0, v33
	v_add_f32_e32 v23, 1.0, v23
	v_max_f32_e32 v158, 0, v158
	v_rcp_f32_e32 v22, v22
	v_sqrt_f32_e32 v33, v33
	v_rcp_f32_e32 v23, v23
	v_sqrt_f32_e32 v158, v158
	v_fma_f32 v24, v24, s98, v152
	v_mul_f32_e32 v33, v22, v33
	v_fma_f32 v25, v25, s98, v152
	v_mul_f32_e32 v23, v23, v158
	ds_read_u16 v158, v70 offset:1056
	ds_read_u16 v152, v70 offset:1584
	s_waitcnt lgkmcnt(6)
	v_lshlrev_b32_e32 v22, 16, v157
	v_fma_f32 v157, v160, s98, v153
	v_fma_f32 v153, v161, s98, v153
	s_nop 0
	s_nop 0
	v_exp_f32_e32 v157, v157
	v_exp_f32_e32 v153, v153
	s_nop 0
	v_exp_f32_e32 v25, v25
	v_add_f32_e32 v157, 1.0, v157
	v_add_f32_e32 v153, 1.0, v153
	v_rcp_f32_e32 v157, v157
	v_rcp_f32_e32 v153, v153
	s_nop 0
	v_exp_f32_e32 v24, v24
	v_mul_f32_e32 v157, v74, v157
	v_mul_f32_e32 v74, v74, v153
	s_nop 0
	v_exp_f32_e32 v74, v74
	s_nop 0
	v_exp_f32_e32 v157, v157
	v_add_f32_e32 v25, 1.0, v25
	v_fma_f32 v153, -v74, v74, 1.0
	v_max_f32_e32 v153, 0, v153
	v_fma_f32 v159, -v157, v157, 1.0
	v_rcp_f32_e32 v25, v25
	v_sqrt_f32_e32 v153, v153
	v_add_f32_e32 v24, 1.0, v24
	v_max_f32_e32 v159, 0, v159
	v_rcp_f32_e32 v24, v24
	v_sqrt_f32_e32 v159, v159
	s_waitcnt lgkmcnt(0)
	v_lshlrev_b32_e32 v152, 16, v152
	v_mul_f32_e32 v25, v25, v153
	v_mul_f32_e32 v25, v25, v152
	v_lshlrev_b32_e32 v158, 16, v158
	v_mul_f32_e32 v24, v24, v159
	v_mul_f32_e32 v25, v157, v25
	v_mul_f32_e32 v74, v157, v74
	v_fmac_f32_e32 v25, v24, v158
	v_mul_f32_e32 v24, v32, v74
	v_mul_f32_e32 v32, v32, v25
	v_fmac_f32_e32 v32, v23, v22
	v_mul_f32_e32 v74, v31, v24
	v_mfma_f32_16x16x32_bf16 v[22:25], v[34:37], v[6:9], 0
	v_lshlrev_b32_e32 v21, 16, v21
	v_mul_f32_e32 v6, v31, v32
	v_fmac_f32_e32 v6, v33, v21
	v_mfma_f32_16x16x32_bf16 v[32:35], v[34:37], v[14:17], 0
	ds_bpermute_b32 v7, v68, v6
	ds_bpermute_b32 v14, v68, v6 offset:64
	ds_bpermute_b32 v16, v68, v6 offset:128
	v_mfma_f32_16x16x32_bf16 v[22:25], v[38:41], v[2:5], v[22:25]
	ds_bpermute_b32 v77, v68, v79 offset:128
	ds_bpermute_b32 v79, v68, v79 offset:192
	ds_bpermute_b32 v80, v68, v83
	v_mfma_f32_16x16x32_bf16 v[32:35], v[38:41], v[10:13], v[32:35]
	ds_bpermute_b32 v12, v68, v6 offset:192
	s_nop 2
	v_fma_f32 v2, v22, s98, v151
	s_nop 0
	v_exp_f32_e32 v2, v2
	ds_read_u16 v10, v70 offset:560
	v_fma_f32 v4, v32, s98, v150
	s_nop 0
	v_exp_f32_e32 v4, v4
	v_add_f32_e32 v2, 1.0, v2
	v_rcp_f32_e32 v2, v2
	v_fma_f32 v22, v25, s98, v151
	v_add_f32_e32 v4, 1.0, v4
	v_rcp_f32_e32 v8, v4
	v_fma_f32 v4, v23, s98, v151
	s_nop 0
	v_mul_f32_e32 v2, v72, v2
	v_exp_f32_e32 v4, v4
	s_nop 0
	v_exp_f32_e32 v2, v2
	ds_read_u16 v25, v70 offset:1616
	v_add_f32_e32 v4, 1.0, v4
	v_rcp_f32_e32 v4, v4
	v_fma_f32 v6, -v2, v2, 1.0
	v_max_f32_e32 v6, 0, v6
	v_sqrt_f32_e32 v9, v6
	v_fma_f32 v6, v33, s98, v150
	s_nop 0
	v_mul_f32_e32 v4, v72, v4
	v_exp_f32_e32 v6, v6
	s_nop 0
	v_exp_f32_e32 v4, v4
	v_mul_f32_e32 v8, v8, v9
	v_add_f32_e32 v6, 1.0, v6
	v_rcp_f32_e32 v11, v6
	v_fma_f32 v6, -v4, v4, 1.0
	v_max_f32_e32 v6, 0, v6
	v_sqrt_f32_e32 v13, v6
	s_waitcnt lgkmcnt(1)
; __device__ __forceinline__ float fsig(float x) { return frcp(1.0f + __expf(-x)); }
; template <int DIR, int MODE>
; __device__ __forceinline__ void lru_pass(const Args& a, const LAS bf16_t* cxb, LAS bf16_t* gyb, const LAS float* carry, const bf16x8 (&Bw)[2][2][2], const float (&prm)[2][3], int l, int tt, float (&hf)[8][2][4]) {
;     ...
; #pragma unroll
;             for (int reg = 0; reg < 4; ++reg) {
;                 const int tok = m * 16 + 4 * fq + reg;
;                 const float x = bf2f(cxb[tok * CXS + cc[nt]]);
;                 const float r = fsig(pr[reg] + ba[nt]), ig = fsig(pi[reg] + bxv[nt]);
;                 const float aa = __expf(k8[nt] * r);
;                 av[reg] = aa; bv[reg] = __builtin_amdgcn_sqrtf(fmaxf(1.0f - aa * aa, 0.f)) * ig * x;
;             }
;             float cum[4], hl[4];
;             if (DIR == 0) { cum[0] = av[0]; hl[0] = bv[0];
; #pragma unroll
;                 for (int reg = 1; reg < 4; ++reg) { cum[reg] = cum[reg - 1] * av[reg]; hl[reg] = av[reg] * hl[reg - 1] + bv[reg]; } }
;             else { cum[3] = av[3]; hl[3] = bv[3];
; #pragma unroll
;     ...
;             const float A4 = DIR ? cum[0] : cum[3], H4 = DIR ? hl[0] : hl[3];
;             float Aq[4], Hq[4];
; #pragma unroll
;             for (int q = 0; q < 4; ++q) { Aq[q] = __shfl(A4, fr + 16 * q); Hq[q] = __shfl(H4, fr + 16 * q); }
;     ...
;     if (MODE == 0 && fq == 0) {
	v_lshlrev_b32_e32 v9, 16, v10
	s_nop 0
	v_exp_f32_e32 v23, v22
	v_mul_f32_e32 v10, v11, v13
	v_fma_f32 v11, v24, s98, v151
	s_nop 0
	v_exp_f32_e32 v11, v11
	v_add_f32_e32 v23, 1.0, v23
	v_rcp_f32_e32 v23, v23
	v_fma_f32 v13, v34, s98, v150
	v_add_f32_e32 v11, 1.0, v11
	v_rcp_f32_e32 v11, v11
	v_mul_f32_e32 v23, v72, v23
	v_fma_f32 v24, v35, s98, v150
	s_nop 0
	v_mul_f32_e32 v11, v72, v11
	s_nop 0
	s_nop 0
	v_exp_f32_e32 v11, v11
	s_nop 0
	v_exp_f32_e32 v23, v23
	v_exp_f32_e32 v17, v13
	v_exp_f32_e32 v24, v24
	v_fma_f32 v22, -v11, v11, 1.0
	v_fma_f32 v31, -v23, v23, 1.0
	v_add_f32_e32 v17, 1.0, v17
	v_max_f32_e32 v22, 0, v22
	v_add_f32_e32 v24, 1.0, v24
	v_max_f32_e32 v31, 0, v31
	v_rcp_f32_e32 v17, v17
	v_sqrt_f32_e32 v22, v22
	v_rcp_f32_e32 v24, v24
	v_sqrt_f32_e32 v31, v31
	ds_read_u16 v13, v70 offset:1088
	v_mul_f32_e32 v17, v17, v22
	s_waitcnt lgkmcnt(1)
	v_lshlrev_b32_e32 v22, 16, v25
	v_mul_f32_e32 v24, v24, v31
	v_mul_f32_e32 v22, v24, v22
	s_waitcnt lgkmcnt(0)
	v_lshlrev_b32_e32 v13, 16, v13
	v_mul_f32_e32 v23, v11, v23
	v_mul_f32_e32 v11, v11, v22
	v_fmac_f32_e32 v11, v17, v13
	v_mul_f32_e32 v13, v4, v23
	v_mul_f32_e32 v4, v4, v11
	v_fmac_f32_e32 v4, v10, v9
	v_lshlrev_b32_e32 v137, 16, v137
	v_lshlrev_b32_e32 v6, 16, v89
	v_mul_f32_e32 v23, v2, v4
	v_fmac_f32_e32 v140, v138, v137
	v_mul_f32_e32 v10, v2, v13
	v_fmac_f32_e32 v23, v8, v6
	ds_bpermute_b32 v137, v68, v140
	ds_bpermute_b32 v138, v68, v140 offset:64
	ds_bpermute_b32 v139, v68, v140 offset:128
	ds_bpermute_b32 v140, v68, v140 offset:192
	ds_bpermute_b32 v82, v68, v83 offset:64
	ds_bpermute_b32 v81, v68, v83 offset:128
	ds_bpermute_b32 v83, v68, v83 offset:192
	ds_bpermute_b32 v27, v68, v168
	ds_bpermute_b32 v26, v68, v169
	ds_bpermute_b32 v29, v68, v168 offset:64
	ds_bpermute_b32 v28, v68, v169 offset:64
	ds_bpermute_b32 v30, v68, v168 offset:128
	ds_bpermute_b32 v18, v68, v169 offset:128
	ds_bpermute_b32 v20, v68, v168 offset:192
	ds_bpermute_b32 v19, v68, v169 offset:192
	ds_bpermute_b32 v21, v68, v74
	ds_bpermute_b32 v15, v68, v74 offset:64
	ds_bpermute_b32 v3, v68, v74 offset:128
	ds_bpermute_b32 v5, v68, v74 offset:192
	ds_bpermute_b32 v2, v68, v10
	ds_bpermute_b32 v13, v68, v23
	ds_bpermute_b32 v17, v68, v10 offset:64
	ds_bpermute_b32 v4, v68, v23 offset:64
	ds_bpermute_b32 v9, v68, v10 offset:128
	ds_bpermute_b32 v22, v68, v23 offset:128
	ds_bpermute_b32 v11, v68, v10 offset:192
	ds_bpermute_b32 v23, v68, v23 offset:192
	v_cmp_eq_u32_e32 vcc, 0, v43
	s_and_saveexec_b64 s[0:1], vcc
	s_cbranch_execz .LBB0_775
; template <int DIR, int MODE>
; __device__ __forceinline__ void lru_pass(const Args& a, const LAS bf16_t* cxb, LAS bf16_t* gyb, const LAS float* carry, const bf16x8 (&Bw)[2][2][2], const float (&prm)[2][3], int l, int tt, float (&hf)[8][2][4]) {
;     ...
;             if (DIR == 0) { const float s0 = C[nt], s1 = Aq[0] * s0 + Hq[0], s2 = Aq[1] * s1 + Hq[1], s3 = Aq[2] * s2 + Hq[2]; C[nt] = Aq[3] * s3 + Hq[3]; hin = fq == 0 ? s0 : (fq == 1 ? s1 : (fq == 2 ? s2 : s3)); }
;             else { const float s3 = C[nt], s2 = Aq[3] * s3 + Hq[3], s1 = Aq[2] * s2 + Hq[2], s0 = Aq[1] * s1 + Hq[1]; C[nt] = Aq[0] * s0 + Hq[0]; hin = fq == 3 ? s3 : (fq == 2 ? s2 : (fq == 1 ? s1 : s0)); }
;             if (MODE == 0) At[nt] *= (Aq[0] * Aq[1]) * (Aq[2] * Aq[3]);
;     ...
;     if (MODE == 0 && fq == 0) {
; #pragma unroll
;         for (int nt = 0; nt < 2; ++nt) { f32x2 sm; sm[0] = At[nt]; sm[1] = C[nt]; *(f32x2*)(SUM + ((size_t)(tt * 2 + DIR) * 256 + cc[nt]) * 2) = sm; }
	v_fmac_f32_e32 v92, 0, v58
	v_fmac_f32_e32 v91, v92, v56
	v_fmac_f32_e32 v90, v91, v54
	v_fmac_f32_e32 v88, v90, v52
	v_fmac_f32_e32 v100, v88, v59
	v_fmac_f32_e32 v99, v100, v57
	v_fmac_f32_e32 v98, v99, v55
	v_fmac_f32_e32 v97, v98, v53
	v_fmac_f32_e32 v108, v97, v67
	v_fmac_f32_e32 v107, v108, v65
	v_fmac_f32_e32 v87, 0, v50
	v_fmac_f32_e32 v106, v107, v66
	v_fmac_f32_e32 v86, v87, v48
	v_fmac_f32_e32 v105, v106, v64
	v_fmac_f32_e32 v85, v86, v46
	v_fmac_f32_e32 v123, v105, v124
	v_fmac_f32_e32 v84, v85, v44
	v_fmac_f32_e32 v122, v123, v121
	v_fmac_f32_e32 v96, v84, v51
	v_fmac_f32_e32 v119, v122, v120
	v_fmac_f32_e32 v95, v96, v49
	v_fmac_f32_e32 v117, v119, v118
	v_fmac_f32_e32 v94, v95, v47
	v_fmac_f32_e32 v136, v117, v75
	v_fmac_f32_e32 v93, v94, v45
	v_fmac_f32_e32 v135, v136, v73
	v_fmac_f32_e32 v104, v93, v63
	v_fmac_f32_e32 v133, v135, v134
	v_fmac_f32_e32 v103, v104, v61
	v_fmac_f32_e32 v131, v133, v132
	v_fmac_f32_e32 v102, v103, v62
	s_waitcnt lgkmcnt(14)
	v_fmac_f32_e32 v144, v131, v83
	v_fmac_f32_e32 v101, v102, v60
	v_fmac_f32_e32 v143, v144, v81
	v_fmac_f32_e32 v115, v101, v116
	v_fmac_f32_e32 v142, v143, v82
	v_fmac_f32_e32 v114, v115, v113
	v_fmac_f32_e32 v141, v142, v80
	v_fmac_f32_e32 v111, v114, v112
	s_waitcnt lgkmcnt(12)
	v_fmac_f32_e32 v19, v141, v20
	v_fmac_f32_e32 v109, v111, v110
	v_fmac_f32_e32 v18, v19, v30
	v_fmac_f32_e32 v130, v109, v71
	v_fmac_f32_e32 v28, v18, v29
	v_fmac_f32_e32 v129, v130, v69
	v_pk_mul_f32 v[34:35], v[52:53], v[54:55]
	v_pk_mul_f32 v[36:37], v[56:57], v[58:59]
	v_fmac_f32_e32 v26, v28, v27
	v_fmac_f32_e32 v127, v129, v128
	v_pk_mul_f32 v[32:33], v[64:65], v[66:67]
	v_pk_mul_f32 v[34:35], v[34:35], v[36:37]
	s_waitcnt lgkmcnt(0)
	v_fmac_f32_e32 v23, v26, v11
	v_fmac_f32_e32 v125, v127, v126
	v_pk_mul_f32 v[34:35], v[34:35], v[34:35] op_sel:[0,1] op_sel_hi:[1,0]
	v_pk_mul_f32 v[32:33], v[32:33], v[32:33] op_sel:[0,1] op_sel_hi:[1,0]
	v_fmac_f32_e32 v22, v23, v9
	v_fmac_f32_e32 v140, v125, v79
	v_mul_f32_e32 v8, v27, v29
	v_mul_f32_e32 v10, v30, v20
	v_mov_b32_e32 v35, v132
	v_mov_b32_e32 v33, v134
	v_fmac_f32_e32 v4, v22, v17
	v_pk_mul_f32 v[18:19], v[44:45], v[46:47]
	v_pk_mul_f32 v[22:23], v[48:49], v[50:51]
	v_fmac_f32_e32 v139, v140, v77
	v_pk_mul_f32 v[32:33], v[34:35], v[32:33]
	v_pk_mul_f32 v[34:35], v[8:9], v[10:11]
	v_pk_mul_f32 v[10:11], v[60:61], v[62:63]
	v_pk_mul_f32 v[18:19], v[18:19], v[22:23]
	v_fmac_f32_e32 v138, v139, v78
	v_pk_mul_f32 v[18:19], v[18:19], v[18:19] op_sel:[0,1] op_sel_hi:[1,0]
	v_pk_mul_f32 v[10:11], v[10:11], v[10:11] op_sel:[0,1] op_sel_hi:[1,0]
	v_fmac_f32_e32 v137, v138, v76
	v_mul_f32_e32 v72, v118, v120
	v_mul_f32_e32 v74, v121, v124
	v_mul_f32_e32 v68, v110, v112
	v_mul_f32_e32 v70, v113, v116
	v_mov_b32_e32 v19, v126
	v_mov_b32_e32 v11, v128
	v_fmac_f32_e32 v155, v137, v156
	v_pk_mul_f32 v[36:37], v[72:73], v[74:75]
	v_pk_mul_f32 v[22:23], v[68:69], v[70:71]
	v_pk_mul_f32 v[10:11], v[18:19], v[10:11]
	v_fmac_f32_e32 v154, v155, v149
	v_pk_mul_f32 v[32:33], v[32:33], v[36:37]
	v_pk_mul_f32 v[8:9], v[76:77], v[78:79]
	v_pk_mul_f32 v[10:11], v[10:11], v[22:23]
	v_fmac_f32_e32 v147, v154, v148
	s_lshl_b32 s4, s82, 1
	v_pk_mul_f32 v[32:33], v[32:33], v[32:33] op_sel:[0,1] op_sel_hi:[1,0]
	v_pk_mul_f32 v[10:11], v[10:11], v[10:11] op_sel:[0,1] op_sel_hi:[1,0]
	v_pk_mul_f32 v[8:9], v[8:9], v[8:9] op_sel:[0,1] op_sel_hi:[1,0]
	v_fmac_f32_e32 v145, v147, v146
	s_or_b32 s4, s4, 1
	v_pk_mul_f32 v[24:25], v[80:81], v[82:83]
	v_mov_b32_e32 v33, v2
	v_fmac_f32_e32 v13, v4, v2
	v_mul_f32_e32 v2, v146, v148
	v_mul_f32_e32 v4, v149, v156
	v_mov_b32_e32 v11, v21
	v_mov_b32_e32 v9, v15
	v_fmac_f32_e32 v12, v145, v5
	s_ashr_i32 s5, s4, 31
	v_pk_mul_f32 v[24:25], v[24:25], v[24:25] op_sel:[0,1] op_sel_hi:[1,0]
	v_pk_mul_f32 v[18:19], v[2:3], v[4:5]
	v_pk_mul_f32 v[8:9], v[10:11], v[8:9]
	v_fmac_f32_e32 v16, v12, v3
	s_lshl_b64 s[4:5], s[4:5], 11
	v_readlane_b32 s28, v253, 43
	v_mov_b32_e32 v25, v17
	v_pk_mul_f32 v[8:9], v[8:9], v[18:19]
	v_fmac_f32_e32 v14, v16, v15
	v_readlane_b32 s29, v253, 44
	s_add_u32 s4, s28, s4
	v_pk_mul_f32 v[24:25], v[32:33], v[24:25]
	v_fmac_f32_e32 v7, v14, v21
	s_addc_u32 s5, s29, s5
	v_pk_mul_f32 v[2:3], v[8:9], v[8:9] op_sel:[0,1] op_sel_hi:[1,0]
	v_ashrrev_i32_e32 v43, 31, v42
	v_or_b32_e32 v6, 16, v42
	v_pk_mul_f32 v[24:25], v[24:25], v[34:35]
	v_mov_b32_e32 v3, v7
	v_lshl_add_u64 v[4:5], v[42:43], 3, s[4:5]
	global_store_dwordx2 v[4:5], v[2:3], off
	v_pk_mul_f32 v[2:3], v[24:25], v[24:25] op_sel:[0,1] op_sel_hi:[1,0]
	v_ashrrev_i32_e32 v7, 31, v6
	v_mov_b32_e32 v3, v13
	v_lshl_add_u64 v[4:5], v[6:7], 3, s[4:5]
	global_store_dwordx2 v[4:5], v[2:3], off
